# GEMM K-loops: per-phase s_setprio flips removed (timing-only experiment)
# speedup vs baseline: 1.0261x; 1.0180x over previous
; #define PG8_STAGE(bufoff, gbase, voff) do { _Pragma("unroll") for (int _i = 0; _i < 2; ++_i) \
;         __builtin_amdgcn_global_load_lds((const unsigned*)((const char*)(gbase) + (voff)[_i]), (PG8_LAS unsigned*)(lds + (bufoff) + ldsw + _i * 8192), 16, 0, 0); } while (0)
; #define PG8_LDA(dst, b, h) do { _Pragma("unroll") for (int m = 0; m < 4; ++m) _Pragma("unroll") for (int k = 0; k < 2; ++k) dst[m][k] = *(const PG8_LAS bf16x8*)(lds + PG8_SA(b, h) + aoff + m * 2048 + k * 1024); } while (0)
; #define PG8_LDB(dst, b, h) do { _Pragma("unroll") for (int n = 0; n < 2; ++n) _Pragma("unroll") for (int k = 0; k < 2; ++k) dst[n][k] = *(const PG8_LAS bf16x8*)(lds + PG8_SB(b, h) + boff + n * 2048 + k * 1024); } while (0)
; #define PG8_MMA(ai, bj, At, Bt) do { __builtin_amdgcn_s_setprio(1); _Pragma("unroll") for (int m = 0; m < 4; ++m) _Pragma("unroll") for (int n = 0; n < 2; ++n) _Pragma("unroll") for (int k = 0; k < 2; ++k) \
;         acc[ai][bj][m][n] = __builtin_amdgcn_mfma_f32_16x16x32_bf16(Bt[n][k], At[m][k], acc[ai][bj][m][n], 0, 0, 0); __builtin_amdgcn_s_setprio(0); } while (0)
; #define PG8_WAIT_V(n) asm volatile("s_waitcnt vmcnt(" #n ")" ::: "memory")
; #define PG8_WAIT_L(n) asm volatile("s_waitcnt lgkmcnt(" #n ")" ::: "memory")
; #define PG8_BAR __builtin_amdgcn_s_barrier()
; #define PG8_SCHED __builtin_amdgcn_sched_barrier(0)
; template <class Epi, class Sched>
; __device__ __forceinline__ void gemm_phase(PG8_LAS unsigned char* lds, const Gemm g, const Sched& S, const Epi& E) {
;     ...
;             PG8_LDB(B0, 0, 0); PG8_SCHED; PG8_LDA(At, 0, 0); PG8_STAGE(PG8_SA(1, 1), a1 + hstep, voffA);
;             PG8_WAIT_L(8); PG8_BAR; PG8_WAIT_L(0); PG8_MMA(0, 0, At, B0); PG8_BAR; PG8_SCHED;
;             PG8_LDB(B1, 0, 1); PG8_STAGE(PG8_SB(0, 0), b2, voffB);
;             PG8_BAR; PG8_WAIT_L(0); PG8_MMA(0, 1, At, B1); PG8_BAR;
;             PG8_LDA(At, 0, 1); PG8_STAGE(PG8_SA(0, 0), a2, voffA);
;             PG8_BAR; PG8_WAIT_L(0); PG8_MMA(1, 0, At, B0); PG8_BAR; PG8_SCHED;
;             PG8_STAGE(PG8_SB(0, 1), b2 + hstep, voffB);
;             PG8_WAIT_V(6); PG8_BAR; PG8_MMA(1, 1, At, B1); PG8_BAR;
.LBB0_195:
	ds_read_b128 v[144:147], v151
	ds_read_b128 v[156:159], v151 offset:1024
	ds_read_b128 v[160:163], v151 offset:2048
	ds_read_b128 v[166:169], v151 offset:3072
	s_add_u32 s30, s28, 0xfffc0080
	s_addc_u32 s31, s29, -1
	s_cmp_eq_u32 s58, 12
	s_cselect_b32 s35, s17, s31
	s_cselect_b32 s34, s54, s30
	s_cselect_b32 s31, s15, s57
	s_cselect_b32 s30, s55, s56
	v_lshl_add_u64 v[174:175], s[28:29], 0, v[136:137]
	s_add_i32 m0, s27, 0xc000
	ds_read_b128 v[170:173], v153
	ds_read_b128 v[182:185], v153 offset:1024
	ds_read_b128 v[190:193], v153 offset:2048
	ds_read_b128 v[194:197], v153 offset:3072
	ds_read_b128 v[198:201], v153 offset:4096
	ds_read_b128 v[202:205], v153 offset:5120
	ds_read_b128 v[206:209], v153 offset:6144
	ds_read_b128 v[210:213], v153 offset:7168
	global_load_lds_dwordx4 v[174:175], off
	v_lshl_add_u64 v[174:175], s[28:29], 0, v[138:139]
	s_add_i32 m0, s27, 0xe000
	s_nop 0
	global_load_lds_dwordx4 v[174:175], off
	s_waitcnt lgkmcnt(8)
	s_barrier
	s_waitcnt lgkmcnt(0)
	s_waitcnt lgkmcnt(0)
	v_mfma_f32_16x16x32_bf16 v[124:127], v[144:147], v[170:173], v[124:127]
	v_mfma_f32_16x16x32_bf16 v[120:123], v[160:163], v[170:173], v[120:123]
	v_mfma_f32_16x16x32_bf16 v[108:111], v[144:147], v[190:193], v[108:111]
	v_mfma_f32_16x16x32_bf16 v[104:107], v[160:163], v[190:193], v[104:107]
	v_mfma_f32_16x16x32_bf16 v[92:95], v[144:147], v[198:201], v[92:95]
	v_mfma_f32_16x16x32_bf16 v[88:91], v[160:163], v[198:201], v[88:91]
	v_mfma_f32_16x16x32_bf16 v[76:79], v[144:147], v[206:209], v[76:79]
	v_mfma_f32_16x16x32_bf16 v[72:75], v[160:163], v[206:209], v[72:75]
	v_mfma_f32_16x16x32_bf16 v[124:127], v[156:159], v[182:185], v[124:127]
	v_mfma_f32_16x16x32_bf16 v[120:123], v[166:169], v[182:185], v[120:123]
	v_mfma_f32_16x16x32_bf16 v[108:111], v[156:159], v[194:197], v[108:111]
	v_mfma_f32_16x16x32_bf16 v[104:107], v[166:169], v[194:197], v[104:107]
	v_mfma_f32_16x16x32_bf16 v[92:95], v[156:159], v[202:205], v[92:95]
	v_mfma_f32_16x16x32_bf16 v[88:91], v[166:169], v[202:205], v[88:91]
	v_mfma_f32_16x16x32_bf16 v[76:79], v[156:159], v[210:213], v[76:79]
	v_mfma_f32_16x16x32_bf16 v[72:75], v[166:169], v[210:213], v[72:75]
	s_barrier
	s_add_i32 s59, s50, s40
	v_lshl_add_u64 v[174:175], s[30:31], 0, v[132:133]
	s_mov_b32 m0, s59
	ds_read_b128 v[214:217], v154
	ds_read_b128 v[218:221], v154 offset:1024
	ds_read_b128 v[222:225], v154 offset:2048
	ds_read_b128 v[226:229], v154 offset:3072
	global_load_lds_dwordx4 v[174:175], off
	v_lshl_add_u64 v[178:179], s[30:31], 0, v[128:129]
	s_add_i32 m0, s59, 0x2000
	s_nop 0
	global_load_lds_dwordx4 v[178:179], off
	s_barrier
	s_waitcnt lgkmcnt(0)
	s_waitcnt lgkmcnt(0)
	v_mfma_f32_16x16x32_bf16 v[116:119], v[214:217], v[170:173], v[116:119]
	v_mfma_f32_16x16x32_bf16 v[112:115], v[222:225], v[170:173], v[112:115]
	v_mfma_f32_16x16x32_bf16 v[100:103], v[214:217], v[190:193], v[100:103]
	v_mfma_f32_16x16x32_bf16 v[96:99], v[222:225], v[190:193], v[96:99]
	v_mfma_f32_16x16x32_bf16 v[84:87], v[214:217], v[198:201], v[84:87]
	v_mfma_f32_16x16x32_bf16 v[80:83], v[222:225], v[198:201], v[80:83]
	v_mfma_f32_16x16x32_bf16 v[68:71], v[214:217], v[206:209], v[68:71]
	v_mfma_f32_16x16x32_bf16 v[64:67], v[222:225], v[206:209], v[64:67]
	v_mfma_f32_16x16x32_bf16 v[116:119], v[218:221], v[182:185], v[116:119]
	v_mfma_f32_16x16x32_bf16 v[112:115], v[226:229], v[182:185], v[112:115]
	v_mfma_f32_16x16x32_bf16 v[100:103], v[218:221], v[194:197], v[100:103]
	v_mfma_f32_16x16x32_bf16 v[96:99], v[226:229], v[194:197], v[96:99]
	v_mfma_f32_16x16x32_bf16 v[84:87], v[218:221], v[202:205], v[84:87]
	v_mfma_f32_16x16x32_bf16 v[80:83], v[226:229], v[202:205], v[80:83]
	v_mfma_f32_16x16x32_bf16 v[68:71], v[218:221], v[210:213], v[68:71]
	v_mfma_f32_16x16x32_bf16 v[64:67], v[226:229], v[210:213], v[64:67]
	s_mov_b32 m0, s27
	v_lshl_add_u64 v[186:187], s[34:35], 0, v[134:135]
	s_barrier
	ds_read_b128 v[170:173], v153 offset:16384
	ds_read_b128 v[182:185], v153 offset:17408
	ds_read_b128 v[190:193], v153 offset:18432
	ds_read_b128 v[194:197], v153 offset:19456
	ds_read_b128 v[198:201], v153 offset:20480
	ds_read_b128 v[202:205], v153 offset:21504
	ds_read_b128 v[206:209], v153 offset:22528
	ds_read_b128 v[210:213], v153 offset:23552
	global_load_lds_dwordx4 v[186:187], off
	v_lshl_add_u64 v[230:231], s[34:35], 0, v[130:131]
	s_mov_b32 m0, s43
	s_nop 0
	global_load_lds_dwordx4 v[230:231], off
	s_barrier
	s_waitcnt lgkmcnt(0)
	s_waitcnt lgkmcnt(0)
	v_mfma_f32_16x16x32_bf16 v[60:63], v[144:147], v[170:173], v[60:63]
	v_mfma_f32_16x16x32_bf16 v[56:59], v[160:163], v[170:173], v[56:59]
	v_mfma_f32_16x16x32_bf16 v[44:47], v[144:147], v[190:193], v[44:47]
	v_mfma_f32_16x16x32_bf16 v[40:43], v[160:163], v[190:193], v[40:43]
	v_mfma_f32_16x16x32_bf16 v[28:31], v[144:147], v[198:201], v[28:31]
	v_mfma_f32_16x16x32_bf16 v[24:27], v[160:163], v[198:201], v[24:27]
	v_mfma_f32_16x16x32_bf16 v[12:15], v[144:147], v[206:209], v[12:15]
	v_mfma_f32_16x16x32_bf16 v[8:11], v[160:163], v[206:209], v[8:11]
	v_mfma_f32_16x16x32_bf16 v[60:63], v[156:159], v[182:185], v[60:63]
	v_mfma_f32_16x16x32_bf16 v[56:59], v[166:169], v[182:185], v[56:59]
	v_mfma_f32_16x16x32_bf16 v[44:47], v[156:159], v[194:197], v[44:47]
	v_mfma_f32_16x16x32_bf16 v[40:43], v[166:169], v[194:197], v[40:43]
	v_mfma_f32_16x16x32_bf16 v[28:31], v[156:159], v[202:205], v[28:31]
	v_mfma_f32_16x16x32_bf16 v[24:27], v[166:169], v[202:205], v[24:27]
	v_mfma_f32_16x16x32_bf16 v[12:15], v[156:159], v[210:213], v[12:15]
	v_mfma_f32_16x16x32_bf16 v[8:11], v[166:169], v[210:213], v[8:11]
	s_barrier
; #define PG8_STAGE(bufoff, gbase, voff) do { _Pragma("unroll") for (int _i = 0; _i < 2; ++_i) \
;         __builtin_amdgcn_global_load_lds((const unsigned*)((const char*)(gbase) + (voff)[_i]), (PG8_LAS unsigned*)(lds + (bufoff) + ldsw + _i * 8192), 16, 0, 0); } while (0)
; #define PG8_LDA(dst, b, h) do { _Pragma("unroll") for (int m = 0; m < 4; ++m) _Pragma("unroll") for (int k = 0; k < 2; ++k) dst[m][k] = *(const PG8_LAS bf16x8*)(lds + PG8_SA(b, h) + aoff + m * 2048 + k * 1024); } while (0)
; #define PG8_LDB(dst, b, h) do { _Pragma("unroll") for (int n = 0; n < 2; ++n) _Pragma("unroll") for (int k = 0; k < 2; ++k) dst[n][k] = *(const PG8_LAS bf16x8*)(lds + PG8_SB(b, h) + boff + n * 2048 + k * 1024); } while (0)
; #define PG8_MMA(ai, bj, At, Bt) do { __builtin_amdgcn_s_setprio(1); _Pragma("unroll") for (int m = 0; m < 4; ++m) _Pragma("unroll") for (int n = 0; n < 2; ++n) _Pragma("unroll") for (int k = 0; k < 2; ++k) \
;         acc[ai][bj][m][n] = __builtin_amdgcn_mfma_f32_16x16x32_bf16(Bt[n][k], At[m][k], acc[ai][bj][m][n], 0, 0, 0); __builtin_amdgcn_s_setprio(0); } while (0)
; #define PG8_WAIT_V(n) asm volatile("s_waitcnt vmcnt(" #n ")" ::: "memory")
; #define PG8_WAIT_L(n) asm volatile("s_waitcnt lgkmcnt(" #n ")" ::: "memory")
; #define PG8_BAR __builtin_amdgcn_s_barrier()
; #define PG8_SCHED __builtin_amdgcn_sched_barrier(0)
; template <class Epi, class Sched>
; __device__ __forceinline__ void gemm_phase(PG8_LAS unsigned char* lds, const Gemm g, const Sched& S, const Epi& E) {
;     ...
;             PG8_STAGE(PG8_SB(0, 1), b2 + hstep, voffB);
;             PG8_WAIT_V(6); PG8_BAR; PG8_MMA(1, 1, At, B1); PG8_BAR;
;             PG8_LDB(B0, 1, 0); PG8_SCHED; PG8_LDA(At, 1, 0); PG8_STAGE(PG8_SA(0, 1), a2 + hstep, voffA);
;             PG8_WAIT_L(8); PG8_BAR; PG8_WAIT_L(0); PG8_MMA(0, 0, At, B0); PG8_BAR; PG8_SCHED;
;             PG8_LDB(B1, 1, 1); PG8_STAGE(PG8_SB(1, 0), b3, voffB);
;             PG8_BAR; PG8_WAIT_L(0); PG8_MMA(0, 1, At, B1); PG8_BAR;
;             PG8_LDA(At, 1, 1); PG8_STAGE(PG8_SA(1, 0), a3, voffA);
;             PG8_BAR; PG8_WAIT_L(0); PG8_MMA(1, 0, At, B0); PG8_BAR; PG8_SCHED;
	s_add_u32 s60, s30, 0x40000
	s_addc_u32 s61, s31, 0
	s_add_i32 s59, s51, s40
	v_lshl_add_u64 v[144:145], s[60:61], 0, v[132:133]
	s_mov_b32 m0, s59
	s_nop 0
	global_load_lds_dwordx4 v[144:145], off
	v_lshl_add_u64 v[144:145], s[60:61], 0, v[128:129]
	s_add_i32 m0, s59, 0x2000
	s_nop 0
	global_load_lds_dwordx4 v[144:145], off
	s_waitcnt vmcnt(6)
	s_barrier
	v_mfma_f32_16x16x32_bf16 v[52:55], v[214:217], v[170:173], v[52:55]
	v_mfma_f32_16x16x32_bf16 v[48:51], v[222:225], v[170:173], v[48:51]
	v_mfma_f32_16x16x32_bf16 v[36:39], v[214:217], v[190:193], v[36:39]
	v_mfma_f32_16x16x32_bf16 v[32:35], v[222:225], v[190:193], v[32:35]
	v_mfma_f32_16x16x32_bf16 v[20:23], v[214:217], v[198:201], v[20:23]
	v_mfma_f32_16x16x32_bf16 v[16:19], v[222:225], v[198:201], v[16:19]
	v_mfma_f32_16x16x32_bf16 v[4:7], v[214:217], v[206:209], v[4:7]
	v_mfma_f32_16x16x32_bf16 v[0:3], v[222:225], v[206:209], v[0:3]
	v_mfma_f32_16x16x32_bf16 v[52:55], v[218:221], v[182:185], v[52:55]
	v_mfma_f32_16x16x32_bf16 v[48:51], v[226:229], v[182:185], v[48:51]
	v_mfma_f32_16x16x32_bf16 v[36:39], v[218:221], v[194:197], v[36:39]
	v_mfma_f32_16x16x32_bf16 v[32:35], v[226:229], v[194:197], v[32:35]
	v_mfma_f32_16x16x32_bf16 v[20:23], v[218:221], v[202:205], v[20:23]
	v_mfma_f32_16x16x32_bf16 v[16:19], v[226:229], v[202:205], v[16:19]
	v_mfma_f32_16x16x32_bf16 v[4:7], v[218:221], v[210:213], v[4:7]
	v_mfma_f32_16x16x32_bf16 v[0:3], v[226:229], v[210:213], v[0:3]
	s_add_i32 s59, 0, 0x18000
	v_add_u32_e32 v155, s59, v149
	s_barrier
	ds_read_b128 v[144:147], v155
	ds_read_b128 v[156:159], v155 offset:1024
	ds_read_b128 v[160:163], v155 offset:2048
	ds_read_b128 v[166:169], v155 offset:3072
	s_add_u32 s34, s34, 0x40000
	s_addc_u32 s35, s35, 0
	s_mov_b32 m0, s44
	v_lshl_add_u64 v[214:215], s[34:35], 0, v[134:135]
	ds_read_b128 v[170:173], v153 offset:32768
	ds_read_b128 v[182:185], v153 offset:33792
	ds_read_b128 v[190:193], v153 offset:34816
	ds_read_b128 v[194:197], v153 offset:35840
	ds_read_b128 v[198:201], v153 offset:36864
	ds_read_b128 v[202:205], v153 offset:37888
	ds_read_b128 v[206:209], v153 offset:38912
	ds_read_b128 v[210:213], v153 offset:39936
	global_load_lds_dwordx4 v[214:215], off
	v_lshl_add_u64 v[214:215], s[34:35], 0, v[130:131]
	s_mov_b32 m0, s45
	s_nop 0
	global_load_lds_dwordx4 v[214:215], off
	s_waitcnt lgkmcnt(8)
	s_barrier
	s_waitcnt lgkmcnt(0)
	s_waitcnt lgkmcnt(0)
	v_mfma_f32_16x16x32_bf16 v[124:127], v[144:147], v[170:173], v[124:127]
	v_mfma_f32_16x16x32_bf16 v[120:123], v[160:163], v[170:173], v[120:123]
	v_mfma_f32_16x16x32_bf16 v[108:111], v[144:147], v[190:193], v[108:111]
	v_mfma_f32_16x16x32_bf16 v[104:107], v[160:163], v[190:193], v[104:107]
	v_mfma_f32_16x16x32_bf16 v[92:95], v[144:147], v[198:201], v[92:95]
	v_mfma_f32_16x16x32_bf16 v[88:91], v[160:163], v[198:201], v[88:91]
	v_mfma_f32_16x16x32_bf16 v[76:79], v[144:147], v[206:209], v[76:79]
	v_mfma_f32_16x16x32_bf16 v[72:75], v[160:163], v[206:209], v[72:75]
	v_mfma_f32_16x16x32_bf16 v[124:127], v[156:159], v[182:185], v[124:127]
	v_mfma_f32_16x16x32_bf16 v[120:123], v[166:169], v[182:185], v[120:123]
	v_mfma_f32_16x16x32_bf16 v[108:111], v[156:159], v[194:197], v[108:111]
	v_mfma_f32_16x16x32_bf16 v[104:107], v[166:169], v[194:197], v[104:107]
	v_mfma_f32_16x16x32_bf16 v[92:95], v[156:159], v[202:205], v[92:95]
	v_mfma_f32_16x16x32_bf16 v[88:91], v[166:169], v[202:205], v[88:91]
	v_mfma_f32_16x16x32_bf16 v[76:79], v[156:159], v[210:213], v[76:79]
	v_mfma_f32_16x16x32_bf16 v[72:75], v[166:169], v[210:213], v[72:75]
	s_barrier
	s_add_i32 s34, 0, 0x1c000
	s_add_i32 s35, s59, s40
	v_add_u32_e32 v155, s34, v149
	v_lshl_add_u64 v[174:175], v[174:175], 0, s[10:11]
	s_mov_b32 m0, s35
	ds_read_b128 v[214:217], v155
	ds_read_b128 v[218:221], v155 offset:1024
	ds_read_b128 v[222:225], v155 offset:2048
	ds_read_b128 v[226:229], v155 offset:3072
	global_load_lds_dwordx4 v[174:175], off
	v_lshl_add_u64 v[174:175], v[178:179], 0, s[10:11]
	s_add_i32 m0, s35, 0x2000
	s_nop 0
	global_load_lds_dwordx4 v[174:175], off
	s_barrier
	s_waitcnt lgkmcnt(0)
	s_waitcnt lgkmcnt(0)
	v_mfma_f32_16x16x32_bf16 v[116:119], v[214:217], v[170:173], v[116:119]
	v_mfma_f32_16x16x32_bf16 v[112:115], v[222:225], v[170:173], v[112:115]
	v_mfma_f32_16x16x32_bf16 v[100:103], v[214:217], v[190:193], v[100:103]
	v_mfma_f32_16x16x32_bf16 v[96:99], v[222:225], v[190:193], v[96:99]
	v_mfma_f32_16x16x32_bf16 v[84:87], v[214:217], v[198:201], v[84:87]
	v_mfma_f32_16x16x32_bf16 v[80:83], v[222:225], v[198:201], v[80:83]
	v_mfma_f32_16x16x32_bf16 v[68:71], v[214:217], v[206:209], v[68:71]
	v_mfma_f32_16x16x32_bf16 v[64:67], v[222:225], v[206:209], v[64:67]
	v_mfma_f32_16x16x32_bf16 v[116:119], v[218:221], v[182:185], v[116:119]
	v_mfma_f32_16x16x32_bf16 v[112:115], v[226:229], v[182:185], v[112:115]
	v_mfma_f32_16x16x32_bf16 v[100:103], v[218:221], v[194:197], v[100:103]
	v_mfma_f32_16x16x32_bf16 v[96:99], v[226:229], v[194:197], v[96:99]
	v_mfma_f32_16x16x32_bf16 v[84:87], v[218:221], v[202:205], v[84:87]
	v_mfma_f32_16x16x32_bf16 v[80:83], v[226:229], v[202:205], v[80:83]
	v_mfma_f32_16x16x32_bf16 v[68:71], v[218:221], v[210:213], v[68:71]
	v_mfma_f32_16x16x32_bf16 v[64:67], v[226:229], v[210:213], v[64:67]
	s_mov_b32 m0, s47
	v_lshl_add_u64 v[174:175], v[186:187], 0, s[10:11]
	s_barrier
	ds_read_b128 v[170:173], v153 offset:49152
	ds_read_b128 v[182:185], v153 offset:50176
	ds_read_b128 v[190:193], v153 offset:51200
	ds_read_b128 v[194:197], v153 offset:52224
	ds_read_b128 v[198:201], v153 offset:53248
	ds_read_b128 v[202:205], v153 offset:54272
	ds_read_b128 v[206:209], v153 offset:55296
	ds_read_b128 v[210:213], v153 offset:56320
	global_load_lds_dwordx4 v[174:175], off
	v_lshl_add_u64 v[174:175], v[230:231], 0, s[10:11]
	s_mov_b32 m0, s48
	s_nop 0
	global_load_lds_dwordx4 v[174:175], off
	s_barrier
; __device__ __forceinline__ unsigned cvt_pk_bf16(float lo, float hi) { unsigned r; asm volatile("v_cvt_pk_bf16_f32 %0, %1, %2" : "=v"(r) : "v"(lo), "v"(hi)); return r; }
; __device__ __forceinline__ f32x4 sigmoid4(f32x4 x) {
;     f32x4 d;
; #pragma unroll
;     for (int j = 0; j < 4; ++j) d[j] = 1.0f + __expf(-fmaxf(x[j], -20.0f));
;     const float p01 = d[0] * d[1], p23 = d[2] * d[3], r = __builtin_amdgcn_rcpf(p01 * p23), r01 = r * p23, r23 = r * p01;
;     return (f32x4){r01 * d[1], r01 * d[0], r23 * d[3], r23 * d[2]};
; }
;     __device__ __forceinline__ void operator()(const f32x4 (&acc)[2][2][4][2], const Unit& u, int wr, int wc, int fr, int fq) const {
;         const int row0 = u.pm * BM + wr * 64 + fr, col0 = u.pn * HALF + wc * 32 + 8 * fq;
; #pragma unroll
;         for (int ai = 0; ai < 2; ++ai)
; #pragma unroll
;             for (int m = 0; m < 4; ++m) { bf16_t* rowp = O + (size_t)(row0 + ai * HALF + m * 16) * ldc + col0;
;                 f32x4 v0, v1;
; #pragma unroll
;                 for (int j = 0; j < 1; ++j) { v0 = acc[ai][0][m][0] * sigmoid4(acc[ai][0][m][0]) * acc[ai][1][m][0]; v1 = acc[ai][0][m][1] * sigmoid4(acc[ai][0][m][1]) * acc[ai][1][m][1]; }
;                 u32x4 w; w.x = cvt_pk_bf16(v0[0], v0[1]); w.y = cvt_pk_bf16(v0[2], v0[3]); w.z = cvt_pk_bf16(v1[0], v1[1]); w.w = cvt_pk_bf16(v1[2], v1[3]);
;                 *(u32x4*)rowp = w; }
	s_waitcnt lgkmcnt(0)
	s_waitcnt lgkmcnt(0)
	v_mfma_f32_16x16x32_bf16 v[60:63], v[144:147], v[170:173], v[60:63]
	v_mfma_f32_16x16x32_bf16 v[56:59], v[160:163], v[170:173], v[56:59]
	v_mfma_f32_16x16x32_bf16 v[44:47], v[144:147], v[190:193], v[44:47]
	v_mfma_f32_16x16x32_bf16 v[40:43], v[160:163], v[190:193], v[40:43]
	v_mfma_f32_16x16x32_bf16 v[28:31], v[144:147], v[198:201], v[28:31]
	v_mfma_f32_16x16x32_bf16 v[24:27], v[160:163], v[198:201], v[24:27]
	v_mfma_f32_16x16x32_bf16 v[12:15], v[144:147], v[206:209], v[12:15]
	v_mfma_f32_16x16x32_bf16 v[8:11], v[160:163], v[206:209], v[8:11]
	v_mfma_f32_16x16x32_bf16 v[60:63], v[156:159], v[182:185], v[60:63]
	v_mfma_f32_16x16x32_bf16 v[56:59], v[166:169], v[182:185], v[56:59]
	v_mfma_f32_16x16x32_bf16 v[44:47], v[156:159], v[194:197], v[44:47]
	v_mfma_f32_16x16x32_bf16 v[40:43], v[166:169], v[194:197], v[40:43]
	v_mfma_f32_16x16x32_bf16 v[28:31], v[156:159], v[202:205], v[28:31]
	v_mfma_f32_16x16x32_bf16 v[24:27], v[166:169], v[202:205], v[24:27]
	v_mfma_f32_16x16x32_bf16 v[12:15], v[156:159], v[210:213], v[12:15]
	v_mfma_f32_16x16x32_bf16 v[8:11], v[166:169], v[210:213], v[8:11]
	s_barrier
	s_add_u32 s30, s30, 0x40080
	s_addc_u32 s31, s31, 0
	s_add_i32 s34, s34, s40
	v_lshl_add_u64 v[144:145], s[30:31], 0, v[132:133]
	s_mov_b32 m0, s34
	s_nop 0
	global_load_lds_dwordx4 v[144:145], off
	v_lshl_add_u64 v[144:145], s[30:31], 0, v[128:129]
	s_add_i32 m0, s34, 0x2000
	s_nop 0
	global_load_lds_dwordx4 v[144:145], off
	s_waitcnt vmcnt(6)
	s_barrier
	v_mfma_f32_16x16x32_bf16 v[52:55], v[214:217], v[170:173], v[52:55]
	v_mfma_f32_16x16x32_bf16 v[48:51], v[222:225], v[170:173], v[48:51]
	v_mfma_f32_16x16x32_bf16 v[36:39], v[214:217], v[190:193], v[36:39]
	v_mfma_f32_16x16x32_bf16 v[32:35], v[222:225], v[190:193], v[32:35]
	v_mfma_f32_16x16x32_bf16 v[20:23], v[214:217], v[198:201], v[20:23]
	v_mfma_f32_16x16x32_bf16 v[16:19], v[222:225], v[198:201], v[16:19]
	v_mfma_f32_16x16x32_bf16 v[4:7], v[214:217], v[206:209], v[4:7]
	v_mfma_f32_16x16x32_bf16 v[0:3], v[222:225], v[206:209], v[0:3]
	v_mfma_f32_16x16x32_bf16 v[52:55], v[218:221], v[182:185], v[52:55]
	v_mfma_f32_16x16x32_bf16 v[48:51], v[226:229], v[182:185], v[48:51]
	v_mfma_f32_16x16x32_bf16 v[36:39], v[218:221], v[194:197], v[36:39]
	v_mfma_f32_16x16x32_bf16 v[32:35], v[226:229], v[194:197], v[32:35]
	v_mfma_f32_16x16x32_bf16 v[20:23], v[218:221], v[202:205], v[20:23]
	v_mfma_f32_16x16x32_bf16 v[16:19], v[226:229], v[202:205], v[16:19]
	v_mfma_f32_16x16x32_bf16 v[4:7], v[218:221], v[210:213], v[4:7]
	v_mfma_f32_16x16x32_bf16 v[0:3], v[226:229], v[210:213], v[0:3]
	s_add_i32 s58, s58, 2
	s_add_u32 s28, s28, 0x100
	s_addc_u32 s29, s29, 0
	s_add_u32 s56, s56, 0x100
	s_addc_u32 s57, s57, 0
	s_cmp_gt_u32 s58, 13
	s_barrier
	s_cbranch_scc0 .LBB0_195
	v_max_f32_e32 v144, v124, v124
	v_max_f32_e32 v144, 0xc1a00000, v144
	v_mul_f32_e32 v144, 0xbfb8aa3b, v144
	v_exp_f32_e32 v157, v144
	v_max_f32_e32 v144, v125, v125
	v_max_f32_e32 v144, 0xc1a00000, v144
	v_mul_f32_e32 v144, 0xbfb8aa3b, v144
	v_exp_f32_e32 v156, v144
	v_max_f32_e32 v144, v126, v126
	v_max_f32_e32 v144, 0xc1a00000, v144
	v_mul_f32_e32 v144, 0xbfb8aa3b, v144
	v_exp_f32_e32 v159, v144
	v_max_f32_e32 v144, v127, v127
	v_max_f32_e32 v144, 0xc1a00000, v144
	v_mul_f32_e32 v144, 0xbfb8aa3b, v144
	v_exp_f32_e32 v158, v144
	v_pk_add_f32 v[156:157], v[156:157], 1.0 op_sel_hi:[1,0]
	v_lshl_or_b32 v146, s53, 7, v150
	v_mov_b32_e32 v160, v157
	v_pk_add_f32 v[158:159], v[158:159], 1.0 op_sel_hi:[1,0]
	v_mov_b32_e32 v162, v156
	v_mov_b32_e32 v161, v159
	v_mov_b32_e32 v163, v158
	v_pk_mul_f32 v[160:161], v[160:161], v[162:163]
	v_lshl_add_u32 v155, s26, 8, v148
	v_mul_f32_e32 v162, v160, v161
	v_rcp_f32_e32 v166, v162
	v_ashrrev_i32_e32 v147, 31, v146
	v_mov_b64_e32 v[144:145], s[4:5]
	v_mad_i64_i32 v[162:163], s[28:29], v155, s52, v[144:145]
	v_mul_f32_e32 v160, v160, v166
	v_mul_f32_e32 v164, v161, v166
	v_pk_mul_f32 v[158:159], v[158:159], v[160:161] op_sel_hi:[1,0]
	v_max_f32_e32 v160, v120, v120
	v_max_f32_e32 v166, v122, v122
	v_max_f32_e32 v160, 0xc1a00000, v160
	v_max_f32_e32 v166, 0xc1a00000, v166
	v_mul_f32_e32 v160, 0xbfb8aa3b, v160
	v_mul_f32_e32 v166, 0xbfb8aa3b, v166
	v_exp_f32_e32 v161, v160
	v_max_f32_e32 v160, v121, v121
	v_exp_f32_e32 v167, v166
	v_max_f32_e32 v166, v123, v123
	v_max_f32_e32 v160, 0xc1a00000, v160
	v_max_f32_e32 v166, 0xc1a00000, v166
	v_mul_f32_e32 v160, 0xbfb8aa3b, v160
	v_mul_f32_e32 v166, 0xbfb8aa3b, v166
	v_exp_f32_e32 v160, v160
	v_exp_f32_e32 v166, v166
	v_pk_mul_f32 v[156:157], v[156:157], v[164:165] op_sel_hi:[1,0]
	v_pk_mul_f32 v[126:127], v[126:127], v[158:159]
	v_pk_mul_f32 v[124:125], v[124:125], v[156:157]
	v_pk_add_f32 v[156:157], v[160:161], 1.0 op_sel_hi:[1,0]
	v_pk_add_f32 v[160:161], v[166:167], 1.0 op_sel_hi:[1,0]
	v_mov_b32_e32 v166, v157
	v_mov_b32_e32 v167, v161
	v_mov_b32_e32 v168, v156
	v_mov_b32_e32 v169, v160
	v_pk_mul_f32 v[166:167], v[166:167], v[168:169]
	v_pk_mul_f32 v[118:119], v[126:127], v[118:119]
	v_mul_f32_e32 v164, v166, v167
	v_rcp_f32_e32 v164, v164
	v_pk_mul_f32 v[116:117], v[124:125], v[116:117]
	v_lshlrev_b64 v[146:147], 1, v[146:147]
	v_lshl_add_u64 v[162:163], v[162:163], 0, v[146:147]
	v_mul_f32_e32 v124, v167, v164
	v_mul_f32_e32 v126, v166, v164
	v_pk_mul_f32 v[126:127], v[160:161], v[126:127] op_sel_hi:[1,0]
	v_pk_mul_f32 v[124:125], v[156:157], v[124:125] op_sel_hi:[1,0]
	v_pk_mul_f32 v[122:123], v[122:123], v[126:127]
	v_pk_mul_f32 v[120:121], v[120:121], v[124:125]
	v_pk_mul_f32 v[122:123], v[122:123], v[114:115]
	v_pk_mul_f32 v[114:115], v[120:121], v[112:113]
	v_cvt_pk_bf16_f32 v112, v116, v117
	v_cvt_pk_bf16_f32 v113, v118, v119
; __device__ __forceinline__ unsigned cvt_pk_bf16(float lo, float hi) { unsigned r; asm volatile("v_cvt_pk_bf16_f32 %0, %1, %2" : "=v"(r) : "v"(lo), "v"(hi)); return r; }
; __device__ __forceinline__ f32x4 sigmoid4(f32x4 x) {
;     f32x4 d;
; #pragma unroll
;     for (int j = 0; j < 4; ++j) d[j] = 1.0f + __expf(-fmaxf(x[j], -20.0f));
;     const float p01 = d[0] * d[1], p23 = d[2] * d[3], r = __builtin_amdgcn_rcpf(p01 * p23), r01 = r * p23, r23 = r * p01;
;     return (f32x4){r01 * d[1], r01 * d[0], r23 * d[3], r23 * d[2]};
; }
;     __device__ __forceinline__ void operator()(const f32x4 (&acc)[2][2][4][2], const Unit& u, int wr, int wc, int fr, int fq) const {
;         const int row0 = u.pm * BM + wr * 64 + fr, col0 = u.pn * HALF + wc * 32 + 8 * fq;
; #pragma unroll
;         for (int ai = 0; ai < 2; ++ai)
; #pragma unroll
;             for (int m = 0; m < 4; ++m) { bf16_t* rowp = O + (size_t)(row0 + ai * HALF + m * 16) * ldc + col0;
;                 f32x4 v0, v1;
; #pragma unroll
;                 for (int j = 0; j < 1; ++j) { v0 = acc[ai][0][m][0] * sigmoid4(acc[ai][0][m][0]) * acc[ai][1][m][0]; v1 = acc[ai][0][m][1] * sigmoid4(acc[ai][0][m][1]) * acc[ai][1][m][1]; }
;                 u32x4 w; w.x = cvt_pk_bf16(v0[0], v0[1]); w.y = cvt_pk_bf16(v0[2], v0[3]); w.z = cvt_pk_bf16(v1[0], v1[1]); w.w = cvt_pk_bf16(v1[2], v1[3]);
;                 *(u32x4*)rowp = w; }
	v_max_f32_e32 v116, v108, v108
	v_max_f32_e32 v118, v110, v110
	v_max_f32_e32 v116, 0xc1a00000, v116
	v_max_f32_e32 v118, 0xc1a00000, v118
	v_mul_f32_e32 v116, 0xbfb8aa3b, v116
	v_mul_f32_e32 v118, 0xbfb8aa3b, v118
	v_exp_f32_e32 v117, v116
	v_max_f32_e32 v116, v109, v109
	v_exp_f32_e32 v119, v118
	v_max_f32_e32 v118, v111, v111
	v_max_f32_e32 v116, 0xc1a00000, v116
	v_max_f32_e32 v118, 0xc1a00000, v118
	v_mul_f32_e32 v116, 0xbfb8aa3b, v116
	v_mul_f32_e32 v118, 0xbfb8aa3b, v118
	v_exp_f32_e32 v116, v116
	v_exp_f32_e32 v118, v118
	v_cvt_pk_bf16_f32 v114, v114, v115
	v_cvt_pk_bf16_f32 v115, v122, v123
	global_store_dwordx4 v[162:163], v[112:115], off
	v_or_b32_e32 v120, 16, v155
	s_and_b64 vcc, exec, s[2:3]
	v_pk_add_f32 v[112:113], v[116:117], 1.0 op_sel_hi:[1,0]
	v_pk_add_f32 v[114:115], v[118:119], 1.0 op_sel_hi:[1,0]
	v_mov_b32_e32 v116, v113
	v_mov_b32_e32 v117, v115
	v_mov_b32_e32 v118, v112
	v_mov_b32_e32 v119, v114
	v_pk_mul_f32 v[116:117], v[116:117], v[118:119]
	s_mov_b32 s53, s14
	v_mul_f32_e32 v118, v116, v117
	v_rcp_f32_e32 v121, v118
	v_mad_i64_i32 v[118:119], s[28:29], v120, s52, v[144:145]
	v_lshl_add_u64 v[118:119], v[118:119], 0, v[146:147]
	v_mul_f32_e32 v116, v116, v121
	v_mul_f32_e32 v120, v117, v121
	v_pk_mul_f32 v[114:115], v[114:115], v[116:117] op_sel_hi:[1,0]
	v_max_f32_e32 v116, v104, v104
	v_max_f32_e32 v121, v106, v106
	v_max_f32_e32 v116, 0xc1a00000, v116
	v_max_f32_e32 v121, 0xc1a00000, v121
	v_mul_f32_e32 v116, 0xbfb8aa3b, v116
	v_mul_f32_e32 v121, 0xbfb8aa3b, v121
	v_exp_f32_e32 v117, v116
	v_max_f32_e32 v116, v105, v105
	v_exp_f32_e32 v123, v121
	v_max_f32_e32 v121, v107, v107
	v_max_f32_e32 v116, 0xc1a00000, v116
	v_max_f32_e32 v121, 0xc1a00000, v121
	v_mul_f32_e32 v116, 0xbfb8aa3b, v116
	v_mul_f32_e32 v121, 0xbfb8aa3b, v121
	v_exp_f32_e32 v116, v116
	v_exp_f32_e32 v122, v121
	v_pk_mul_f32 v[112:113], v[112:113], v[120:121] op_sel_hi:[1,0]
	v_pk_mul_f32 v[110:111], v[110:111], v[114:115]
	v_pk_mul_f32 v[108:109], v[108:109], v[112:113]
	v_pk_add_f32 v[112:113], v[116:117], 1.0 op_sel_hi:[1,0]
	v_pk_add_f32 v[116:117], v[122:123], 1.0 op_sel_hi:[1,0]
	v_mov_b32_e32 v120, v113
	v_mov_b32_e32 v121, v117
	v_mov_b32_e32 v122, v112
	v_mov_b32_e32 v123, v116
	v_pk_mul_f32 v[120:121], v[120:121], v[122:123]
	v_pk_mul_f32 v[102:103], v[110:111], v[102:103]
	v_mul_f32_e32 v122, v120, v121
	v_rcp_f32_e32 v122, v122
	v_pk_mul_f32 v[100:101], v[108:109], v[100:101]
	s_mov_b32 s26, s16
	s_mov_b64 s[30:31], s[24:25]
	v_mul_f32_e32 v108, v121, v122
	v_mul_f32_e32 v110, v120, v122
	v_pk_mul_f32 v[110:111], v[116:117], v[110:111] op_sel_hi:[1,0]
	v_pk_mul_f32 v[108:109], v[112:113], v[108:109] op_sel_hi:[1,0]
	v_pk_mul_f32 v[106:107], v[106:107], v[110:111]
	v_pk_mul_f32 v[104:105], v[104:105], v[108:109]
	v_pk_mul_f32 v[106:107], v[106:107], v[98:99]
	v_pk_mul_f32 v[98:99], v[104:105], v[96:97]
	v_cvt_pk_bf16_f32 v96, v100, v101
	v_cvt_pk_bf16_f32 v97, v102, v103
	v_max_f32_e32 v100, v92, v92
	v_max_f32_e32 v102, v94, v94
	v_max_f32_e32 v100, 0xc1a00000, v100
	v_max_f32_e32 v102, 0xc1a00000, v102
	v_mul_f32_e32 v100, 0xbfb8aa3b, v100
	v_mul_f32_e32 v102, 0xbfb8aa3b, v102
	v_exp_f32_e32 v101, v100
	v_max_f32_e32 v100, v93, v93
	v_exp_f32_e32 v103, v102
	v_max_f32_e32 v102, v95, v95
	v_max_f32_e32 v100, 0xc1a00000, v100
	v_max_f32_e32 v102, 0xc1a00000, v102
	v_mul_f32_e32 v100, 0xbfb8aa3b, v100
	v_mul_f32_e32 v102, 0xbfb8aa3b, v102
	v_exp_f32_e32 v100, v100
	v_exp_f32_e32 v102, v102
	v_cvt_pk_bf16_f32 v98, v98, v99
	v_cvt_pk_bf16_f32 v99, v106, v107
	global_store_dwordx4 v[118:119], v[96:99], off
	v_or_b32_e32 v104, 32, v155
	s_nop 0
	v_pk_add_f32 v[96:97], v[100:101], 1.0 op_sel_hi:[1,0]
	v_pk_add_f32 v[98:99], v[102:103], 1.0 op_sel_hi:[1,0]
	v_mov_b32_e32 v100, v97
	v_mov_b32_e32 v101, v99
	v_mov_b32_e32 v102, v96
	v_mov_b32_e32 v103, v98
	v_pk_mul_f32 v[100:101], v[100:101], v[102:103]
	s_nop 0
	v_mul_f32_e32 v102, v100, v101
	v_rcp_f32_e32 v105, v102
	v_mad_i64_i32 v[102:103], s[28:29], v104, s52, v[144:145]
	v_lshl_add_u64 v[102:103], v[102:103], 0, v[146:147]
	v_mul_f32_e32 v100, v100, v105
	v_mul_f32_e32 v104, v101, v105
	v_pk_mul_f32 v[98:99], v[98:99], v[100:101] op_sel_hi:[1,0]
	v_max_f32_e32 v100, v88, v88
	v_max_f32_e32 v105, v90, v90
	v_max_f32_e32 v100, 0xc1a00000, v100
	v_max_f32_e32 v105, 0xc1a00000, v105
	v_mul_f32_e32 v100, 0xbfb8aa3b, v100
	v_mul_f32_e32 v105, 0xbfb8aa3b, v105
	v_exp_f32_e32 v101, v100
	v_max_f32_e32 v100, v89, v89
	v_exp_f32_e32 v107, v105
	v_max_f32_e32 v105, v91, v91
	v_max_f32_e32 v100, 0xc1a00000, v100
	v_max_f32_e32 v105, 0xc1a00000, v105
	v_mul_f32_e32 v100, 0xbfb8aa3b, v100
	v_mul_f32_e32 v105, 0xbfb8aa3b, v105
	v_exp_f32_e32 v100, v100
	v_exp_f32_e32 v106, v105
	v_pk_mul_f32 v[96:97], v[96:97], v[104:105] op_sel_hi:[1,0]
	v_pk_mul_f32 v[94:95], v[94:95], v[98:99]
	v_pk_mul_f32 v[92:93], v[92:93], v[96:97]
	v_pk_add_f32 v[96:97], v[100:101], 1.0 op_sel_hi:[1,0]
	v_pk_add_f32 v[100:101], v[106:107], 1.0 op_sel_hi:[1,0]
	v_mov_b32_e32 v104, v97
	v_mov_b32_e32 v105, v101
	v_mov_b32_e32 v106, v96
	v_mov_b32_e32 v107, v100
	v_pk_mul_f32 v[104:105], v[104:105], v[106:107]
	v_pk_mul_f32 v[86:87], v[94:95], v[86:87]
	v_mul_f32_e32 v106, v104, v105
	v_rcp_f32_e32 v106, v106
	v_pk_mul_f32 v[84:85], v[92:93], v[84:85]
	v_mul_f32_e32 v92, v105, v106
	v_mul_f32_e32 v94, v104, v106
	v_pk_mul_f32 v[94:95], v[100:101], v[94:95] op_sel_hi:[1,0]
	v_pk_mul_f32 v[92:93], v[96:97], v[92:93] op_sel_hi:[1,0]
	v_pk_mul_f32 v[90:91], v[90:91], v[94:95]
	v_pk_mul_f32 v[88:89], v[88:89], v[92:93]
	v_pk_mul_f32 v[90:91], v[90:91], v[82:83]
	v_pk_mul_f32 v[82:83], v[88:89], v[80:81]
	v_cvt_pk_bf16_f32 v80, v84, v85
; __device__ __forceinline__ unsigned cvt_pk_bf16(float lo, float hi) { unsigned r; asm volatile("v_cvt_pk_bf16_f32 %0, %1, %2" : "=v"(r) : "v"(lo), "v"(hi)); return r; }
; __device__ __forceinline__ f32x4 sigmoid4(f32x4 x) {
;     f32x4 d;
; #pragma unroll
;     for (int j = 0; j < 4; ++j) d[j] = 1.0f + __expf(-fmaxf(x[j], -20.0f));
;     const float p01 = d[0] * d[1], p23 = d[2] * d[3], r = __builtin_amdgcn_rcpf(p01 * p23), r01 = r * p23, r23 = r * p01;
;     return (f32x4){r01 * d[1], r01 * d[0], r23 * d[3], r23 * d[2]};
; }
;     __device__ __forceinline__ void operator()(const f32x4 (&acc)[2][2][4][2], const Unit& u, int wr, int wc, int fr, int fq) const {
;         const int row0 = u.pm * BM + wr * 64 + fr, col0 = u.pn * HALF + wc * 32 + 8 * fq;
; #pragma unroll
;         for (int ai = 0; ai < 2; ++ai)
; #pragma unroll
;             for (int m = 0; m < 4; ++m) { bf16_t* rowp = O + (size_t)(row0 + ai * HALF + m * 16) * ldc + col0;
;                 f32x4 v0, v1;
; #pragma unroll
;                 for (int j = 0; j < 1; ++j) { v0 = acc[ai][0][m][0] * sigmoid4(acc[ai][0][m][0]) * acc[ai][1][m][0]; v1 = acc[ai][0][m][1] * sigmoid4(acc[ai][0][m][1]) * acc[ai][1][m][1]; }
;                 u32x4 w; w.x = cvt_pk_bf16(v0[0], v0[1]); w.y = cvt_pk_bf16(v0[2], v0[3]); w.z = cvt_pk_bf16(v1[0], v1[1]); w.w = cvt_pk_bf16(v1[2], v1[3]);
;                 *(u32x4*)rowp = w; }
	v_cvt_pk_bf16_f32 v81, v86, v87
	v_max_f32_e32 v84, v76, v76
	v_max_f32_e32 v86, v78, v78
	v_max_f32_e32 v84, 0xc1a00000, v84
	v_max_f32_e32 v86, 0xc1a00000, v86
	v_mul_f32_e32 v84, 0xbfb8aa3b, v84
	v_mul_f32_e32 v86, 0xbfb8aa3b, v86
	v_exp_f32_e32 v85, v84
	v_max_f32_e32 v84, v77, v77
	v_exp_f32_e32 v87, v86
	v_max_f32_e32 v86, v79, v79
	v_max_f32_e32 v84, 0xc1a00000, v84
	v_max_f32_e32 v86, 0xc1a00000, v86
	v_mul_f32_e32 v84, 0xbfb8aa3b, v84
	v_mul_f32_e32 v86, 0xbfb8aa3b, v86
	v_exp_f32_e32 v84, v84
	v_exp_f32_e32 v86, v86
	v_cvt_pk_bf16_f32 v82, v82, v83
	v_cvt_pk_bf16_f32 v83, v90, v91
	global_store_dwordx4 v[102:103], v[80:83], off
	v_or_b32_e32 v88, 48, v155
	s_nop 0
	v_pk_add_f32 v[80:81], v[84:85], 1.0 op_sel_hi:[1,0]
	v_pk_add_f32 v[82:83], v[86:87], 1.0 op_sel_hi:[1,0]
	v_mov_b32_e32 v84, v81
	v_mov_b32_e32 v85, v83
	v_mov_b32_e32 v86, v80
	v_mov_b32_e32 v87, v82
	v_pk_mul_f32 v[84:85], v[84:85], v[86:87]
	s_nop 0
	v_mul_f32_e32 v86, v84, v85
	v_rcp_f32_e32 v89, v86
	v_mad_i64_i32 v[86:87], s[28:29], v88, s52, v[144:145]
	v_lshl_add_u64 v[86:87], v[86:87], 0, v[146:147]
	v_mul_f32_e32 v84, v84, v89
	v_mul_f32_e32 v88, v85, v89
	v_pk_mul_f32 v[82:83], v[82:83], v[84:85] op_sel_hi:[1,0]
	v_max_f32_e32 v84, v72, v72
	v_max_f32_e32 v89, v74, v74
	v_max_f32_e32 v84, 0xc1a00000, v84
	v_max_f32_e32 v89, 0xc1a00000, v89
	v_mul_f32_e32 v84, 0xbfb8aa3b, v84
	v_mul_f32_e32 v89, 0xbfb8aa3b, v89
	v_exp_f32_e32 v85, v84
	v_max_f32_e32 v84, v73, v73
	v_exp_f32_e32 v91, v89
	v_max_f32_e32 v89, v75, v75
	v_max_f32_e32 v84, 0xc1a00000, v84
	v_max_f32_e32 v89, 0xc1a00000, v89
	v_mul_f32_e32 v84, 0xbfb8aa3b, v84
	v_mul_f32_e32 v89, 0xbfb8aa3b, v89
	v_exp_f32_e32 v84, v84
	v_exp_f32_e32 v90, v89
	v_pk_mul_f32 v[80:81], v[80:81], v[88:89] op_sel_hi:[1,0]
	v_pk_mul_f32 v[78:79], v[78:79], v[82:83]
	v_pk_mul_f32 v[76:77], v[76:77], v[80:81]
	v_pk_add_f32 v[80:81], v[84:85], 1.0 op_sel_hi:[1,0]
	v_pk_add_f32 v[84:85], v[90:91], 1.0 op_sel_hi:[1,0]
	v_mov_b32_e32 v88, v81
	v_mov_b32_e32 v89, v85
	v_mov_b32_e32 v90, v80
	v_mov_b32_e32 v91, v84
	v_pk_mul_f32 v[88:89], v[88:89], v[90:91]
	v_pk_mul_f32 v[70:71], v[78:79], v[70:71]
	v_mul_f32_e32 v90, v88, v89
	v_rcp_f32_e32 v90, v90
	v_pk_mul_f32 v[68:69], v[76:77], v[68:69]
	v_mul_f32_e32 v76, v89, v90
	v_mul_f32_e32 v78, v88, v90
	v_pk_mul_f32 v[78:79], v[84:85], v[78:79] op_sel_hi:[1,0]
	v_pk_mul_f32 v[76:77], v[80:81], v[76:77] op_sel_hi:[1,0]
	v_pk_mul_f32 v[74:75], v[74:75], v[78:79]
	v_pk_mul_f32 v[72:73], v[72:73], v[76:77]
	v_pk_mul_f32 v[74:75], v[74:75], v[66:67]
	v_pk_mul_f32 v[66:67], v[72:73], v[64:65]
	v_cvt_pk_bf16_f32 v64, v68, v69
	v_cvt_pk_bf16_f32 v65, v70, v71
	v_max_f32_e32 v68, v60, v60
	v_max_f32_e32 v70, v62, v62
	v_max_f32_e32 v68, 0xc1a00000, v68
	v_max_f32_e32 v70, 0xc1a00000, v70
	v_mul_f32_e32 v68, 0xbfb8aa3b, v68
	v_mul_f32_e32 v70, 0xbfb8aa3b, v70
	v_exp_f32_e32 v69, v68
	v_max_f32_e32 v68, v61, v61
	v_exp_f32_e32 v71, v70
	v_max_f32_e32 v70, v63, v63
	v_max_f32_e32 v68, 0xc1a00000, v68
	v_max_f32_e32 v70, 0xc1a00000, v70
	v_mul_f32_e32 v68, 0xbfb8aa3b, v68
	v_mul_f32_e32 v70, 0xbfb8aa3b, v70
	v_exp_f32_e32 v68, v68
	v_exp_f32_e32 v70, v70
	v_cvt_pk_bf16_f32 v66, v66, v67
	v_cvt_pk_bf16_f32 v67, v74, v75
	global_store_dwordx4 v[86:87], v[64:67], off
	v_add_u32_e32 v72, 0x80, v155
	s_nop 0
	v_pk_add_f32 v[64:65], v[68:69], 1.0 op_sel_hi:[1,0]
	v_pk_add_f32 v[66:67], v[70:71], 1.0 op_sel_hi:[1,0]
	v_mov_b32_e32 v68, v65
	v_mov_b32_e32 v69, v67
	v_mov_b32_e32 v70, v64
	v_mov_b32_e32 v71, v66
	v_pk_mul_f32 v[68:69], v[68:69], v[70:71]
	s_nop 0
	v_mul_f32_e32 v70, v68, v69
	v_rcp_f32_e32 v73, v70
	v_mad_i64_i32 v[70:71], s[28:29], v72, s52, v[144:145]
	v_lshl_add_u64 v[70:71], v[70:71], 0, v[146:147]
	v_mul_f32_e32 v68, v68, v73
	v_mul_f32_e32 v72, v69, v73
	v_pk_mul_f32 v[66:67], v[66:67], v[68:69] op_sel_hi:[1,0]
	v_max_f32_e32 v68, v56, v56
	v_max_f32_e32 v73, v58, v58
	v_max_f32_e32 v68, 0xc1a00000, v68
	v_max_f32_e32 v73, 0xc1a00000, v73
	v_mul_f32_e32 v68, 0xbfb8aa3b, v68
	v_mul_f32_e32 v73, 0xbfb8aa3b, v73
	v_exp_f32_e32 v69, v68
	v_max_f32_e32 v68, v57, v57
	v_exp_f32_e32 v75, v73
	v_max_f32_e32 v73, v59, v59
	v_max_f32_e32 v68, 0xc1a00000, v68
	v_max_f32_e32 v73, 0xc1a00000, v73
	v_mul_f32_e32 v68, 0xbfb8aa3b, v68
	v_mul_f32_e32 v73, 0xbfb8aa3b, v73
	v_exp_f32_e32 v68, v68
	v_exp_f32_e32 v74, v73
	v_pk_mul_f32 v[64:65], v[64:65], v[72:73] op_sel_hi:[1,0]
	v_pk_mul_f32 v[62:63], v[62:63], v[66:67]
	v_pk_mul_f32 v[60:61], v[60:61], v[64:65]
	v_pk_add_f32 v[64:65], v[68:69], 1.0 op_sel_hi:[1,0]
	v_pk_add_f32 v[68:69], v[74:75], 1.0 op_sel_hi:[1,0]
	v_mov_b32_e32 v72, v65
	v_mov_b32_e32 v73, v69
	v_mov_b32_e32 v74, v64
	v_mov_b32_e32 v75, v68
	v_pk_mul_f32 v[72:73], v[72:73], v[74:75]
	v_pk_mul_f32 v[54:55], v[62:63], v[54:55]
	v_mul_f32_e32 v74, v72, v73
	v_rcp_f32_e32 v74, v74
	v_pk_mul_f32 v[52:53], v[60:61], v[52:53]
	v_mul_f32_e32 v60, v73, v74
	v_mul_f32_e32 v62, v72, v74
	v_pk_mul_f32 v[62:63], v[68:69], v[62:63] op_sel_hi:[1,0]
	v_pk_mul_f32 v[60:61], v[64:65], v[60:61] op_sel_hi:[1,0]
	v_pk_mul_f32 v[58:59], v[58:59], v[62:63]
	v_pk_mul_f32 v[56:57], v[56:57], v[60:61]
	v_pk_mul_f32 v[58:59], v[58:59], v[50:51]
	v_pk_mul_f32 v[50:51], v[56:57], v[48:49]
	v_cvt_pk_bf16_f32 v48, v52, v53
	v_cvt_pk_bf16_f32 v49, v54, v55
	v_max_f32_e32 v52, v44, v44
	v_max_f32_e32 v54, v46, v46
	v_max_f32_e32 v52, 0xc1a00000, v52
	v_max_f32_e32 v54, 0xc1a00000, v54
	v_mul_f32_e32 v52, 0xbfb8aa3b, v52
	v_mul_f32_e32 v54, 0xbfb8aa3b, v54
	v_exp_f32_e32 v53, v52
	v_max_f32_e32 v52, v45, v45
	v_exp_f32_e32 v55, v54
	v_max_f32_e32 v54, v47, v47
	v_max_f32_e32 v52, 0xc1a00000, v52
; __device__ __forceinline__ unsigned cvt_pk_bf16(float lo, float hi) { unsigned r; asm volatile("v_cvt_pk_bf16_f32 %0, %1, %2" : "=v"(r) : "v"(lo), "v"(hi)); return r; }
; __device__ __forceinline__ f32x4 sigmoid4(f32x4 x) {
;     f32x4 d;
; #pragma unroll
;     for (int j = 0; j < 4; ++j) d[j] = 1.0f + __expf(-fmaxf(x[j], -20.0f));
;     const float p01 = d[0] * d[1], p23 = d[2] * d[3], r = __builtin_amdgcn_rcpf(p01 * p23), r01 = r * p23, r23 = r * p01;
;     return (f32x4){r01 * d[1], r01 * d[0], r23 * d[3], r23 * d[2]};
; }
;     __device__ __forceinline__ void operator()(const f32x4 (&acc)[2][2][4][2], const Unit& u, int wr, int wc, int fr, int fq) const {
;         const int row0 = u.pm * BM + wr * 64 + fr, col0 = u.pn * HALF + wc * 32 + 8 * fq;
; #pragma unroll
;         for (int ai = 0; ai < 2; ++ai)
; #pragma unroll
;             for (int m = 0; m < 4; ++m) { bf16_t* rowp = O + (size_t)(row0 + ai * HALF + m * 16) * ldc + col0;
;                 f32x4 v0, v1;
; #pragma unroll
;                 for (int j = 0; j < 1; ++j) { v0 = acc[ai][0][m][0] * sigmoid4(acc[ai][0][m][0]) * acc[ai][1][m][0]; v1 = acc[ai][0][m][1] * sigmoid4(acc[ai][0][m][1]) * acc[ai][1][m][1]; }
;                 u32x4 w; w.x = cvt_pk_bf16(v0[0], v0[1]); w.y = cvt_pk_bf16(v0[2], v0[3]); w.z = cvt_pk_bf16(v1[0], v1[1]); w.w = cvt_pk_bf16(v1[2], v1[3]);
;                 *(u32x4*)rowp = w; }
	v_max_f32_e32 v54, 0xc1a00000, v54
	v_mul_f32_e32 v52, 0xbfb8aa3b, v52
	v_mul_f32_e32 v54, 0xbfb8aa3b, v54
	v_exp_f32_e32 v52, v52
	v_exp_f32_e32 v54, v54
	v_cvt_pk_bf16_f32 v50, v50, v51
	v_cvt_pk_bf16_f32 v51, v58, v59
	global_store_dwordx4 v[70:71], v[48:51], off
	v_add_u32_e32 v56, 0x90, v155
	s_nop 0
	v_pk_add_f32 v[48:49], v[52:53], 1.0 op_sel_hi:[1,0]
	v_pk_add_f32 v[50:51], v[54:55], 1.0 op_sel_hi:[1,0]
	v_mov_b32_e32 v52, v49
	v_mov_b32_e32 v53, v51
	v_mov_b32_e32 v54, v48
	v_mov_b32_e32 v55, v50
	v_pk_mul_f32 v[52:53], v[52:53], v[54:55]
	s_nop 0
	v_mul_f32_e32 v54, v52, v53
	v_rcp_f32_e32 v57, v54
	v_mad_i64_i32 v[54:55], s[28:29], v56, s52, v[144:145]
	v_lshl_add_u64 v[54:55], v[54:55], 0, v[146:147]
	v_mul_f32_e32 v52, v52, v57
	v_mul_f32_e32 v56, v53, v57
	v_pk_mul_f32 v[50:51], v[50:51], v[52:53] op_sel_hi:[1,0]
	v_max_f32_e32 v52, v40, v40
	v_max_f32_e32 v57, v42, v42
	v_max_f32_e32 v52, 0xc1a00000, v52
	v_max_f32_e32 v57, 0xc1a00000, v57
	v_mul_f32_e32 v52, 0xbfb8aa3b, v52
	v_mul_f32_e32 v57, 0xbfb8aa3b, v57
	v_exp_f32_e32 v53, v52
	v_max_f32_e32 v52, v41, v41
	v_exp_f32_e32 v59, v57
	v_max_f32_e32 v57, v43, v43
	v_max_f32_e32 v52, 0xc1a00000, v52
	v_max_f32_e32 v57, 0xc1a00000, v57
	v_mul_f32_e32 v52, 0xbfb8aa3b, v52
	v_mul_f32_e32 v57, 0xbfb8aa3b, v57
	v_exp_f32_e32 v52, v52
	v_exp_f32_e32 v58, v57
	v_pk_mul_f32 v[48:49], v[48:49], v[56:57] op_sel_hi:[1,0]
	v_pk_mul_f32 v[46:47], v[46:47], v[50:51]
	v_pk_mul_f32 v[44:45], v[44:45], v[48:49]
	v_pk_add_f32 v[48:49], v[52:53], 1.0 op_sel_hi:[1,0]
	v_pk_add_f32 v[52:53], v[58:59], 1.0 op_sel_hi:[1,0]
	v_mov_b32_e32 v56, v49
	v_mov_b32_e32 v57, v53
	v_mov_b32_e32 v58, v48
	v_mov_b32_e32 v59, v52
	v_pk_mul_f32 v[56:57], v[56:57], v[58:59]
	v_pk_mul_f32 v[38:39], v[46:47], v[38:39]
	v_mul_f32_e32 v58, v56, v57
	v_rcp_f32_e32 v58, v58
	v_pk_mul_f32 v[36:37], v[44:45], v[36:37]
	v_mul_f32_e32 v44, v57, v58
	v_mul_f32_e32 v46, v56, v58
	v_pk_mul_f32 v[46:47], v[52:53], v[46:47] op_sel_hi:[1,0]
	v_pk_mul_f32 v[44:45], v[48:49], v[44:45] op_sel_hi:[1,0]
	v_pk_mul_f32 v[42:43], v[42:43], v[46:47]
	v_pk_mul_f32 v[40:41], v[40:41], v[44:45]
	v_pk_mul_f32 v[42:43], v[42:43], v[34:35]
	v_pk_mul_f32 v[34:35], v[40:41], v[32:33]
	v_cvt_pk_bf16_f32 v32, v36, v37
	v_cvt_pk_bf16_f32 v33, v38, v39
	v_max_f32_e32 v36, v28, v28
	v_max_f32_e32 v38, v30, v30
	v_max_f32_e32 v36, 0xc1a00000, v36
	v_max_f32_e32 v38, 0xc1a00000, v38
	v_mul_f32_e32 v36, 0xbfb8aa3b, v36
	v_mul_f32_e32 v38, 0xbfb8aa3b, v38
	v_exp_f32_e32 v37, v36
	v_max_f32_e32 v36, v29, v29
	v_exp_f32_e32 v39, v38
	v_max_f32_e32 v38, v31, v31
	v_max_f32_e32 v36, 0xc1a00000, v36
	v_max_f32_e32 v38, 0xc1a00000, v38
	v_mul_f32_e32 v36, 0xbfb8aa3b, v36
	v_mul_f32_e32 v38, 0xbfb8aa3b, v38
	v_exp_f32_e32 v36, v36
	v_exp_f32_e32 v38, v38
	v_cvt_pk_bf16_f32 v34, v34, v35
	v_cvt_pk_bf16_f32 v35, v42, v43
	global_store_dwordx4 v[54:55], v[32:35], off
	v_add_u32_e32 v40, 0xa0, v155
	s_nop 0
	v_pk_add_f32 v[32:33], v[36:37], 1.0 op_sel_hi:[1,0]
	v_pk_add_f32 v[34:35], v[38:39], 1.0 op_sel_hi:[1,0]
	v_mov_b32_e32 v36, v33
	v_mov_b32_e32 v37, v35
	v_mov_b32_e32 v38, v32
	v_mov_b32_e32 v39, v34
	v_pk_mul_f32 v[36:37], v[36:37], v[38:39]
	s_nop 0
	v_mul_f32_e32 v38, v36, v37
	v_rcp_f32_e32 v41, v38
	v_mad_i64_i32 v[38:39], s[28:29], v40, s52, v[144:145]
	v_lshl_add_u64 v[38:39], v[38:39], 0, v[146:147]
	v_mul_f32_e32 v36, v36, v41
	v_mul_f32_e32 v40, v37, v41
	v_pk_mul_f32 v[34:35], v[34:35], v[36:37] op_sel_hi:[1,0]
	v_max_f32_e32 v36, v24, v24
	v_max_f32_e32 v41, v26, v26
	v_max_f32_e32 v36, 0xc1a00000, v36
	v_max_f32_e32 v41, 0xc1a00000, v41
	v_mul_f32_e32 v36, 0xbfb8aa3b, v36
	v_mul_f32_e32 v41, 0xbfb8aa3b, v41
	v_exp_f32_e32 v37, v36
	v_max_f32_e32 v36, v25, v25
	v_exp_f32_e32 v43, v41
	v_max_f32_e32 v41, v27, v27
	v_max_f32_e32 v36, 0xc1a00000, v36
	v_max_f32_e32 v41, 0xc1a00000, v41
	v_mul_f32_e32 v36, 0xbfb8aa3b, v36
; __device__ __forceinline__ unsigned cvt_pk_bf16(float lo, float hi) { unsigned r; asm volatile("v_cvt_pk_bf16_f32 %0, %1, %2" : "=v"(r) : "v"(lo), "v"(hi)); return r; }
; __device__ __forceinline__ f32x4 sigmoid4(f32x4 x) {
;     f32x4 d;
; #pragma unroll
;     for (int j = 0; j < 4; ++j) d[j] = 1.0f + __expf(-fmaxf(x[j], -20.0f));
;     const float p01 = d[0] * d[1], p23 = d[2] * d[3], r = __builtin_amdgcn_rcpf(p01 * p23), r01 = r * p23, r23 = r * p01;
;     return (f32x4){r01 * d[1], r01 * d[0], r23 * d[3], r23 * d[2]};
; }
;     __device__ __forceinline__ void operator()(const f32x4 (&acc)[2][2][4][2], const Unit& u, int wr, int wc, int fr, int fq) const {
;         const int row0 = u.pm * BM + wr * 64 + fr, col0 = u.pn * HALF + wc * 32 + 8 * fq;
; #pragma unroll
;         for (int ai = 0; ai < 2; ++ai)
; #pragma unroll
;             for (int m = 0; m < 4; ++m) { bf16_t* rowp = O + (size_t)(row0 + ai * HALF + m * 16) * ldc + col0;
;                 f32x4 v0, v1;
; #pragma unroll
;                 for (int j = 0; j < 1; ++j) { v0 = acc[ai][0][m][0] * sigmoid4(acc[ai][0][m][0]) * acc[ai][1][m][0]; v1 = acc[ai][0][m][1] * sigmoid4(acc[ai][0][m][1]) * acc[ai][1][m][1]; }
;                 u32x4 w; w.x = cvt_pk_bf16(v0[0], v0[1]); w.y = cvt_pk_bf16(v0[2], v0[3]); w.z = cvt_pk_bf16(v1[0], v1[1]); w.w = cvt_pk_bf16(v1[2], v1[3]);
;                 *(u32x4*)rowp = w; }
	v_mul_f32_e32 v41, 0xbfb8aa3b, v41
	v_exp_f32_e32 v36, v36
	v_exp_f32_e32 v42, v41
	v_pk_mul_f32 v[32:33], v[32:33], v[40:41] op_sel_hi:[1,0]
	v_pk_mul_f32 v[30:31], v[30:31], v[34:35]
	v_pk_mul_f32 v[28:29], v[28:29], v[32:33]
	v_pk_add_f32 v[32:33], v[36:37], 1.0 op_sel_hi:[1,0]
	v_pk_add_f32 v[36:37], v[42:43], 1.0 op_sel_hi:[1,0]
	v_mov_b32_e32 v40, v33
	v_mov_b32_e32 v41, v37
	v_mov_b32_e32 v42, v32
	v_mov_b32_e32 v43, v36
	v_pk_mul_f32 v[40:41], v[40:41], v[42:43]
	v_pk_mul_f32 v[22:23], v[30:31], v[22:23]
	v_mul_f32_e32 v42, v40, v41
	v_rcp_f32_e32 v42, v42
	v_pk_mul_f32 v[20:21], v[28:29], v[20:21]
	v_mul_f32_e32 v28, v41, v42
	v_mul_f32_e32 v30, v40, v42
	v_pk_mul_f32 v[30:31], v[36:37], v[30:31] op_sel_hi:[1,0]
	v_pk_mul_f32 v[28:29], v[32:33], v[28:29] op_sel_hi:[1,0]
	v_pk_mul_f32 v[26:27], v[26:27], v[30:31]
	v_pk_mul_f32 v[24:25], v[24:25], v[28:29]
	v_pk_mul_f32 v[26:27], v[26:27], v[18:19]
	v_pk_mul_f32 v[18:19], v[24:25], v[16:17]
	v_cvt_pk_bf16_f32 v16, v20, v21
	v_cvt_pk_bf16_f32 v17, v22, v23
	v_max_f32_e32 v20, v12, v12
	v_max_f32_e32 v22, v14, v14
	v_max_f32_e32 v20, 0xc1a00000, v20
	v_max_f32_e32 v22, 0xc1a00000, v22
	v_mul_f32_e32 v20, 0xbfb8aa3b, v20
	v_mul_f32_e32 v22, 0xbfb8aa3b, v22
	v_exp_f32_e32 v21, v20
	v_max_f32_e32 v20, v13, v13
	v_exp_f32_e32 v23, v22
	v_max_f32_e32 v22, v15, v15
	v_max_f32_e32 v20, 0xc1a00000, v20
	v_max_f32_e32 v22, 0xc1a00000, v22
	v_mul_f32_e32 v20, 0xbfb8aa3b, v20
	v_mul_f32_e32 v22, 0xbfb8aa3b, v22
	v_exp_f32_e32 v20, v20
	v_exp_f32_e32 v22, v22
	v_cvt_pk_bf16_f32 v18, v18, v19
	v_cvt_pk_bf16_f32 v19, v26, v27
	global_store_dwordx4 v[38:39], v[16:19], off
	v_add_u32_e32 v24, 0xb0, v155
	s_nop 0
	v_pk_add_f32 v[16:17], v[20:21], 1.0 op_sel_hi:[1,0]
	v_pk_add_f32 v[18:19], v[22:23], 1.0 op_sel_hi:[1,0]
	v_mov_b32_e32 v20, v17
	v_mov_b32_e32 v21, v19
	v_mov_b32_e32 v22, v16
	v_mov_b32_e32 v23, v18
	v_pk_mul_f32 v[20:21], v[20:21], v[22:23]
	s_nop 0
	v_mul_f32_e32 v22, v20, v21
	v_rcp_f32_e32 v25, v22
	v_mad_i64_i32 v[22:23], s[28:29], v24, s52, v[144:145]
	v_lshl_add_u64 v[22:23], v[22:23], 0, v[146:147]
	v_mul_f32_e32 v20, v20, v25
	v_mul_f32_e32 v24, v21, v25
	v_pk_mul_f32 v[18:19], v[18:19], v[20:21] op_sel_hi:[1,0]
	v_max_f32_e32 v20, v8, v8
	v_max_f32_e32 v25, v10, v10
	v_max_f32_e32 v20, 0xc1a00000, v20
	v_max_f32_e32 v25, 0xc1a00000, v25
	v_mul_f32_e32 v20, 0xbfb8aa3b, v20
	v_mul_f32_e32 v25, 0xbfb8aa3b, v25
	v_exp_f32_e32 v21, v20
	v_max_f32_e32 v20, v9, v9
	v_exp_f32_e32 v27, v25
	v_max_f32_e32 v25, v11, v11
	v_max_f32_e32 v20, 0xc1a00000, v20
	v_max_f32_e32 v25, 0xc1a00000, v25
	v_mul_f32_e32 v20, 0xbfb8aa3b, v20
	v_mul_f32_e32 v25, 0xbfb8aa3b, v25
	v_exp_f32_e32 v20, v20
	v_exp_f32_e32 v26, v25
	v_pk_mul_f32 v[16:17], v[16:17], v[24:25] op_sel_hi:[1,0]
	v_pk_mul_f32 v[14:15], v[14:15], v[18:19]
	v_pk_mul_f32 v[12:13], v[12:13], v[16:17]
	v_pk_add_f32 v[16:17], v[20:21], 1.0 op_sel_hi:[1,0]
	v_pk_add_f32 v[20:21], v[26:27], 1.0 op_sel_hi:[1,0]
	v_mov_b32_e32 v24, v17
	v_mov_b32_e32 v25, v21
	v_mov_b32_e32 v26, v16
	v_mov_b32_e32 v27, v20
	v_pk_mul_f32 v[24:25], v[24:25], v[26:27]
	v_pk_mul_f32 v[6:7], v[14:15], v[6:7]
	v_mul_f32_e32 v26, v24, v25
	v_rcp_f32_e32 v26, v26
	v_pk_mul_f32 v[4:5], v[12:13], v[4:5]
	s_mov_b64 s[28:29], s[18:19]
	v_mul_f32_e32 v12, v25, v26
	v_mul_f32_e32 v14, v24, v26
	v_pk_mul_f32 v[14:15], v[20:21], v[14:15] op_sel_hi:[1,0]
	v_pk_mul_f32 v[12:13], v[16:17], v[12:13] op_sel_hi:[1,0]
	v_pk_mul_f32 v[10:11], v[10:11], v[14:15]
	v_pk_mul_f32 v[8:9], v[8:9], v[12:13]
	v_pk_mul_f32 v[10:11], v[10:11], v[2:3]
	v_pk_mul_f32 v[2:3], v[8:9], v[0:1]
	v_cvt_pk_bf16_f32 v0, v4, v5
	v_cvt_pk_bf16_f32 v1, v6, v7
	s_nop 0
	v_cvt_pk_bf16_f32 v2, v2, v3
	v_cvt_pk_bf16_f32 v3, v10, v11
	global_store_dwordx4 v[22:23], v[0:3], off
	s_cbranch_vccz .LBB0_192
	s_waitcnt vmcnt(0)
	s_cmpk_gt_u32 s37, 0xff
	s_cbranch_scc1 .LBB0_199
	s_barrier

; #define PG8_STAGE(bufoff, gbase, voff) do { _Pragma("unroll") for (int _i = 0; _i < 2; ++_i) \
;         __builtin_amdgcn_global_load_lds((const unsigned*)((const char*)(gbase) + (voff)[_i]), (PG8_LAS unsigned*)(lds + (bufoff) + ldsw + _i * 8192), 16, 0, 0); } while (0)
; #define PG8_LDA(dst, b, h) do { _Pragma("unroll") for (int m = 0; m < 4; ++m) _Pragma("unroll") for (int k = 0; k < 2; ++k) dst[m][k] = *(const PG8_LAS bf16x8*)(lds + PG8_SA(b, h) + aoff + m * 2048 + k * 1024); } while (0)
; #define PG8_LDB(dst, b, h) do { _Pragma("unroll") for (int n = 0; n < 2; ++n) _Pragma("unroll") for (int k = 0; k < 2; ++k) dst[n][k] = *(const PG8_LAS bf16x8*)(lds + PG8_SB(b, h) + boff + n * 2048 + k * 1024); } while (0)
; #define PG8_MMA(ai, bj, At, Bt) do { __builtin_amdgcn_s_setprio(1); _Pragma("unroll") for (int m = 0; m < 4; ++m) _Pragma("unroll") for (int n = 0; n < 2; ++n) _Pragma("unroll") for (int k = 0; k < 2; ++k) \
;         acc[ai][bj][m][n] = __builtin_amdgcn_mfma_f32_16x16x32_bf16(Bt[n][k], At[m][k], acc[ai][bj][m][n], 0, 0, 0); __builtin_amdgcn_s_setprio(0); } while (0)
; #define PG8_WAIT_V(n) asm volatile("s_waitcnt vmcnt(" #n ")" ::: "memory")
; #define PG8_WAIT_L(n) asm volatile("s_waitcnt lgkmcnt(" #n ")" ::: "memory")
; #define PG8_BAR __builtin_amdgcn_s_barrier()
; #define PG8_SCHED __builtin_amdgcn_sched_barrier(0)
; template <class Epi, class Sched>
; __device__ __forceinline__ void gemm_phase(PG8_LAS unsigned char* lds, const Gemm g, const Sched& S, const Epi& E) {
;     ...
;             PG8_LDB(B0, 0, 0); PG8_SCHED; PG8_LDA(At, 0, 0); PG8_STAGE(PG8_SA(1, 1), a1 + hstep, voffA);
;             PG8_WAIT_L(8); PG8_BAR; PG8_WAIT_L(0); PG8_MMA(0, 0, At, B0); PG8_BAR; PG8_SCHED;
;             PG8_LDB(B1, 0, 1); PG8_STAGE(PG8_SB(0, 0), b2, voffB);
;             PG8_BAR; PG8_WAIT_L(0); PG8_MMA(0, 1, At, B1); PG8_BAR;
;             PG8_LDA(At, 0, 1); PG8_STAGE(PG8_SA(0, 0), a2, voffA);
;             PG8_BAR; PG8_WAIT_L(0); PG8_MMA(1, 0, At, B0); PG8_BAR; PG8_SCHED;
;             PG8_STAGE(PG8_SB(0, 1), b2 + hstep, voffB);
;             PG8_WAIT_V(6); PG8_BAR; PG8_MMA(1, 1, At, B1); PG8_BAR;
.LBB0_286:
	ds_read_b128 v[154:157], v149
	ds_read_b128 v[158:161], v149 offset:1024
	ds_read_b128 v[166:169], v149 offset:2048
	ds_read_b128 v[170:173], v149 offset:3072
	s_add_u32 s24, s22, 0x100
	s_addc_u32 s25, s23, 0
	s_cmp_eq_u32 s57, 40
	s_cselect_b32 s29, s1, s25
	s_cselect_b32 s28, s0, s24
	s_cselect_b32 s27, s5, s56
	s_cselect_b32 s26, s4, s55
	v_lshl_add_u64 v[144:145], s[22:23], 0, v[136:137]
	s_add_i32 m0, s38, 0xc000
	ds_read_b128 v[182:185], v150
	ds_read_b128 v[190:193], v150 offset:1024
	ds_read_b128 v[194:197], v150 offset:2048
	ds_read_b128 v[198:201], v150 offset:3072
	ds_read_b128 v[202:205], v150 offset:4096
	ds_read_b128 v[206:209], v150 offset:5120
	ds_read_b128 v[210:213], v150 offset:6144
	ds_read_b128 v[214:217], v150 offset:7168
	global_load_lds_dwordx4 v[144:145], off
	v_lshl_add_u64 v[144:145], s[22:23], 0, v[138:139]
	s_add_i32 m0, s38, 0xe000
	s_nop 0
	global_load_lds_dwordx4 v[144:145], off
	s_waitcnt lgkmcnt(8)
	s_barrier
	s_waitcnt lgkmcnt(0)
	s_waitcnt lgkmcnt(0)
	v_mfma_f32_16x16x32_bf16 v[124:127], v[154:157], v[182:185], v[124:127]
	v_mfma_f32_16x16x32_bf16 v[120:123], v[166:169], v[182:185], v[120:123]
	v_mfma_f32_16x16x32_bf16 v[108:111], v[154:157], v[194:197], v[108:111]
	v_mfma_f32_16x16x32_bf16 v[104:107], v[166:169], v[194:197], v[104:107]
	v_mfma_f32_16x16x32_bf16 v[92:95], v[154:157], v[202:205], v[92:95]
	v_mfma_f32_16x16x32_bf16 v[88:91], v[166:169], v[202:205], v[88:91]
	v_mfma_f32_16x16x32_bf16 v[76:79], v[154:157], v[210:213], v[76:79]
	v_mfma_f32_16x16x32_bf16 v[72:75], v[166:169], v[210:213], v[72:75]
	v_mfma_f32_16x16x32_bf16 v[124:127], v[158:161], v[190:193], v[124:127]
	v_mfma_f32_16x16x32_bf16 v[120:123], v[170:173], v[190:193], v[120:123]
	v_mfma_f32_16x16x32_bf16 v[108:111], v[158:161], v[198:201], v[108:111]
	v_mfma_f32_16x16x32_bf16 v[104:107], v[170:173], v[198:201], v[104:107]
	v_mfma_f32_16x16x32_bf16 v[92:95], v[158:161], v[206:209], v[92:95]
	v_mfma_f32_16x16x32_bf16 v[88:91], v[170:173], v[206:209], v[88:91]
	v_mfma_f32_16x16x32_bf16 v[76:79], v[158:161], v[214:217], v[76:79]
	v_mfma_f32_16x16x32_bf16 v[72:75], v[170:173], v[214:217], v[72:75]
	s_barrier
	s_add_i32 s22, s46, s37
	v_lshl_add_u64 v[144:145], s[26:27], 0, v[130:131]
	s_mov_b32 m0, s22
	ds_read_b128 v[218:221], v151
	ds_read_b128 v[222:225], v151 offset:1024
	ds_read_b128 v[226:229], v151 offset:2048
	ds_read_b128 v[230:233], v151 offset:3072
	global_load_lds_dwordx4 v[144:145], off
	v_lshl_add_u64 v[162:163], s[26:27], 0, v[134:135]
	s_add_i32 m0, s22, 0x2000
	s_nop 0
	global_load_lds_dwordx4 v[162:163], off
	s_barrier
	s_waitcnt lgkmcnt(0)
	s_waitcnt lgkmcnt(0)
	v_mfma_f32_16x16x32_bf16 v[116:119], v[218:221], v[182:185], v[116:119]
	v_mfma_f32_16x16x32_bf16 v[112:115], v[226:229], v[182:185], v[112:115]
	v_mfma_f32_16x16x32_bf16 v[100:103], v[218:221], v[194:197], v[100:103]
	v_mfma_f32_16x16x32_bf16 v[96:99], v[226:229], v[194:197], v[96:99]
	v_mfma_f32_16x16x32_bf16 v[84:87], v[218:221], v[202:205], v[84:87]
	v_mfma_f32_16x16x32_bf16 v[80:83], v[226:229], v[202:205], v[80:83]
	v_mfma_f32_16x16x32_bf16 v[68:71], v[218:221], v[210:213], v[68:71]
	v_mfma_f32_16x16x32_bf16 v[64:67], v[226:229], v[210:213], v[64:67]
	v_mfma_f32_16x16x32_bf16 v[116:119], v[222:225], v[190:193], v[116:119]
	v_mfma_f32_16x16x32_bf16 v[112:115], v[230:233], v[190:193], v[112:115]
	v_mfma_f32_16x16x32_bf16 v[100:103], v[222:225], v[198:201], v[100:103]
	v_mfma_f32_16x16x32_bf16 v[96:99], v[230:233], v[198:201], v[96:99]
	v_mfma_f32_16x16x32_bf16 v[84:87], v[222:225], v[206:209], v[84:87]
	v_mfma_f32_16x16x32_bf16 v[80:83], v[230:233], v[206:209], v[80:83]
	v_mfma_f32_16x16x32_bf16 v[68:71], v[222:225], v[214:217], v[68:71]
	v_mfma_f32_16x16x32_bf16 v[64:67], v[230:233], v[214:217], v[64:67]
	s_mov_b32 m0, s38
	v_lshl_add_u64 v[174:175], s[28:29], 0, v[128:129]
	s_barrier
	ds_read_b128 v[182:185], v150 offset:16384
	ds_read_b128 v[190:193], v150 offset:17408
	ds_read_b128 v[194:197], v150 offset:18432
	ds_read_b128 v[198:201], v150 offset:19456
	ds_read_b128 v[202:205], v150 offset:20480
	ds_read_b128 v[206:209], v150 offset:21504
	ds_read_b128 v[210:213], v150 offset:22528
	ds_read_b128 v[214:217], v150 offset:23552
	global_load_lds_dwordx4 v[174:175], off
	v_lshl_add_u64 v[178:179], s[28:29], 0, v[132:133]
	s_mov_b32 m0, s39
	s_nop 0
	global_load_lds_dwordx4 v[178:179], off
	s_barrier
	s_waitcnt lgkmcnt(0)
	s_waitcnt lgkmcnt(0)
	v_mfma_f32_16x16x32_bf16 v[60:63], v[154:157], v[182:185], v[60:63]
	v_mfma_f32_16x16x32_bf16 v[56:59], v[166:169], v[182:185], v[56:59]
	v_mfma_f32_16x16x32_bf16 v[48:51], v[154:157], v[194:197], v[48:51]
	v_mfma_f32_16x16x32_bf16 v[40:43], v[166:169], v[194:197], v[40:43]
	v_mfma_f32_16x16x32_bf16 v[32:35], v[154:157], v[202:205], v[32:35]
	v_mfma_f32_16x16x32_bf16 v[24:27], v[166:169], v[202:205], v[24:27]
	v_mfma_f32_16x16x32_bf16 v[16:19], v[154:157], v[210:213], v[16:19]
	v_mfma_f32_16x16x32_bf16 v[8:11], v[166:169], v[210:213], v[8:11]
	v_mfma_f32_16x16x32_bf16 v[60:63], v[158:161], v[190:193], v[60:63]
	v_mfma_f32_16x16x32_bf16 v[56:59], v[170:173], v[190:193], v[56:59]
	v_mfma_f32_16x16x32_bf16 v[48:51], v[158:161], v[198:201], v[48:51]
	v_mfma_f32_16x16x32_bf16 v[40:43], v[170:173], v[198:201], v[40:43]
	v_mfma_f32_16x16x32_bf16 v[32:35], v[158:161], v[206:209], v[32:35]
	v_mfma_f32_16x16x32_bf16 v[24:27], v[170:173], v[206:209], v[24:27]
	v_mfma_f32_16x16x32_bf16 v[16:19], v[158:161], v[214:217], v[16:19]
	v_mfma_f32_16x16x32_bf16 v[8:11], v[170:173], v[214:217], v[8:11]
	s_barrier
; #define PG8_STAGE(bufoff, gbase, voff) do { _Pragma("unroll") for (int _i = 0; _i < 2; ++_i) \
;         __builtin_amdgcn_global_load_lds((const unsigned*)((const char*)(gbase) + (voff)[_i]), (PG8_LAS unsigned*)(lds + (bufoff) + ldsw + _i * 8192), 16, 0, 0); } while (0)
; #define PG8_LDA(dst, b, h) do { _Pragma("unroll") for (int m = 0; m < 4; ++m) _Pragma("unroll") for (int k = 0; k < 2; ++k) dst[m][k] = *(const PG8_LAS bf16x8*)(lds + PG8_SA(b, h) + aoff + m * 2048 + k * 1024); } while (0)
; #define PG8_LDB(dst, b, h) do { _Pragma("unroll") for (int n = 0; n < 2; ++n) _Pragma("unroll") for (int k = 0; k < 2; ++k) dst[n][k] = *(const PG8_LAS bf16x8*)(lds + PG8_SB(b, h) + boff + n * 2048 + k * 1024); } while (0)
; #define PG8_MMA(ai, bj, At, Bt) do { __builtin_amdgcn_s_setprio(1); _Pragma("unroll") for (int m = 0; m < 4; ++m) _Pragma("unroll") for (int n = 0; n < 2; ++n) _Pragma("unroll") for (int k = 0; k < 2; ++k) \
;         acc[ai][bj][m][n] = __builtin_amdgcn_mfma_f32_16x16x32_bf16(Bt[n][k], At[m][k], acc[ai][bj][m][n], 0, 0, 0); __builtin_amdgcn_s_setprio(0); } while (0)
; #define PG8_WAIT_V(n) asm volatile("s_waitcnt vmcnt(" #n ")" ::: "memory")
; #define PG8_WAIT_L(n) asm volatile("s_waitcnt lgkmcnt(" #n ")" ::: "memory")
; #define PG8_BAR __builtin_amdgcn_s_barrier()
; #define PG8_SCHED __builtin_amdgcn_sched_barrier(0)
; template <class Epi, class Sched>
; __device__ __forceinline__ void gemm_phase(PG8_LAS unsigned char* lds, const Gemm g, const Sched& S, const Epi& E) {
;     ...
;             PG8_STAGE(PG8_SB(0, 1), b2 + hstep, voffB);
;             PG8_WAIT_V(6); PG8_BAR; PG8_MMA(1, 1, At, B1); PG8_BAR;
;             PG8_LDB(B0, 1, 0); PG8_SCHED; PG8_LDA(At, 1, 0); PG8_STAGE(PG8_SA(0, 1), a2 + hstep, voffA);
;             PG8_WAIT_L(8); PG8_BAR; PG8_WAIT_L(0); PG8_MMA(0, 0, At, B0); PG8_BAR; PG8_SCHED;
;             PG8_LDB(B1, 1, 1); PG8_STAGE(PG8_SB(1, 0), b3, voffB);
;             PG8_BAR; PG8_WAIT_L(0); PG8_MMA(0, 1, At, B1); PG8_BAR;
;             PG8_LDA(At, 1, 1); PG8_STAGE(PG8_SA(1, 0), a3, voffA);
;             PG8_BAR; PG8_WAIT_L(0); PG8_MMA(1, 0, At, B0); PG8_BAR; PG8_SCHED;
	s_add_u32 s22, s26, 0xb0000
	s_addc_u32 s23, s27, 0
	s_add_i32 s58, s47, s37
	v_lshl_add_u64 v[154:155], s[22:23], 0, v[130:131]
	s_mov_b32 m0, s58
	s_nop 0
	global_load_lds_dwordx4 v[154:155], off
	v_lshl_add_u64 v[154:155], s[22:23], 0, v[134:135]
	s_add_i32 m0, s58, 0x2000
	s_nop 0
	global_load_lds_dwordx4 v[154:155], off
	s_waitcnt vmcnt(6)
	s_barrier
	v_mfma_f32_16x16x32_bf16 v[52:55], v[218:221], v[182:185], v[52:55]
	v_mfma_f32_16x16x32_bf16 v[44:47], v[226:229], v[182:185], v[44:47]
	v_mfma_f32_16x16x32_bf16 v[36:39], v[218:221], v[194:197], v[36:39]
	v_mfma_f32_16x16x32_bf16 v[28:31], v[226:229], v[194:197], v[28:31]
	v_mfma_f32_16x16x32_bf16 v[20:23], v[218:221], v[202:205], v[20:23]
	v_mfma_f32_16x16x32_bf16 v[12:15], v[226:229], v[202:205], v[12:15]
	v_mfma_f32_16x16x32_bf16 v[4:7], v[218:221], v[210:213], v[4:7]
	v_mfma_f32_16x16x32_bf16 v[0:3], v[226:229], v[210:213], v[0:3]
	v_mfma_f32_16x16x32_bf16 v[52:55], v[222:225], v[190:193], v[52:55]
	v_mfma_f32_16x16x32_bf16 v[44:47], v[230:233], v[190:193], v[44:47]
	v_mfma_f32_16x16x32_bf16 v[36:39], v[222:225], v[198:201], v[36:39]
	v_mfma_f32_16x16x32_bf16 v[28:31], v[230:233], v[198:201], v[28:31]
	v_mfma_f32_16x16x32_bf16 v[20:23], v[222:225], v[206:209], v[20:23]
	v_mfma_f32_16x16x32_bf16 v[12:15], v[230:233], v[206:209], v[12:15]
	v_mfma_f32_16x16x32_bf16 v[4:7], v[222:225], v[214:217], v[4:7]
	v_mfma_f32_16x16x32_bf16 v[0:3], v[230:233], v[214:217], v[0:3]
	s_add_i32 s58, 0, 0x18000
	v_add_u32_e32 v153, s58, v147
	s_barrier
	ds_read_b128 v[154:157], v153
	ds_read_b128 v[158:161], v153 offset:1024
	ds_read_b128 v[166:169], v153 offset:2048
	ds_read_b128 v[170:173], v153 offset:3072
	s_add_u32 s22, s28, 0xb0000
	s_addc_u32 s23, s29, 0
	s_mov_b32 m0, s40
	v_lshl_add_u64 v[186:187], s[22:23], 0, v[128:129]
	ds_read_b128 v[182:185], v150 offset:32768
	ds_read_b128 v[190:193], v150 offset:33792
	ds_read_b128 v[194:197], v150 offset:34816
	ds_read_b128 v[198:201], v150 offset:35840
	ds_read_b128 v[202:205], v150 offset:36864
	ds_read_b128 v[206:209], v150 offset:37888
	ds_read_b128 v[210:213], v150 offset:38912
	ds_read_b128 v[214:217], v150 offset:39936
	global_load_lds_dwordx4 v[186:187], off
	v_lshl_add_u64 v[186:187], s[22:23], 0, v[132:133]
	s_mov_b32 m0, s41
	s_nop 0
	global_load_lds_dwordx4 v[186:187], off
	s_waitcnt lgkmcnt(8)
	s_barrier
	s_waitcnt lgkmcnt(0)
	s_waitcnt lgkmcnt(0)
	v_mfma_f32_16x16x32_bf16 v[124:127], v[154:157], v[182:185], v[124:127]
	v_mfma_f32_16x16x32_bf16 v[120:123], v[166:169], v[182:185], v[120:123]
	v_mfma_f32_16x16x32_bf16 v[108:111], v[154:157], v[194:197], v[108:111]
	v_mfma_f32_16x16x32_bf16 v[104:107], v[166:169], v[194:197], v[104:107]
	v_mfma_f32_16x16x32_bf16 v[92:95], v[154:157], v[202:205], v[92:95]
	v_mfma_f32_16x16x32_bf16 v[88:91], v[166:169], v[202:205], v[88:91]
	v_mfma_f32_16x16x32_bf16 v[76:79], v[154:157], v[210:213], v[76:79]
	v_mfma_f32_16x16x32_bf16 v[72:75], v[166:169], v[210:213], v[72:75]
	v_mfma_f32_16x16x32_bf16 v[124:127], v[158:161], v[190:193], v[124:127]
	v_mfma_f32_16x16x32_bf16 v[120:123], v[170:173], v[190:193], v[120:123]
	v_mfma_f32_16x16x32_bf16 v[108:111], v[158:161], v[198:201], v[108:111]
	v_mfma_f32_16x16x32_bf16 v[104:107], v[170:173], v[198:201], v[104:107]
	v_mfma_f32_16x16x32_bf16 v[92:95], v[158:161], v[206:209], v[92:95]
	v_mfma_f32_16x16x32_bf16 v[88:91], v[170:173], v[206:209], v[88:91]
	v_mfma_f32_16x16x32_bf16 v[76:79], v[158:161], v[214:217], v[76:79]
	v_mfma_f32_16x16x32_bf16 v[72:75], v[170:173], v[214:217], v[72:75]
	s_barrier
	s_add_i32 s28, 0, 0x1c000
	s_add_i32 s22, s58, s37
	v_add_u32_e32 v153, s28, v147
	v_lshl_add_u64 v[144:145], v[144:145], 0, s[14:15]
	s_mov_b32 m0, s22
	ds_read_b128 v[218:221], v153
	ds_read_b128 v[222:225], v153 offset:1024
	ds_read_b128 v[226:229], v153 offset:2048
	ds_read_b128 v[230:233], v153 offset:3072
	global_load_lds_dwordx4 v[144:145], off
	v_lshl_add_u64 v[144:145], v[162:163], 0, s[14:15]
	s_add_i32 m0, s22, 0x2000
	s_nop 0
	global_load_lds_dwordx4 v[144:145], off
	s_barrier
	s_waitcnt lgkmcnt(0)
	s_waitcnt lgkmcnt(0)
	v_mfma_f32_16x16x32_bf16 v[116:119], v[218:221], v[182:185], v[116:119]
	v_mfma_f32_16x16x32_bf16 v[112:115], v[226:229], v[182:185], v[112:115]
	v_mfma_f32_16x16x32_bf16 v[100:103], v[218:221], v[194:197], v[100:103]
	v_mfma_f32_16x16x32_bf16 v[96:99], v[226:229], v[194:197], v[96:99]
	v_mfma_f32_16x16x32_bf16 v[84:87], v[218:221], v[202:205], v[84:87]
	v_mfma_f32_16x16x32_bf16 v[80:83], v[226:229], v[202:205], v[80:83]
	v_mfma_f32_16x16x32_bf16 v[68:71], v[218:221], v[210:213], v[68:71]
	v_mfma_f32_16x16x32_bf16 v[64:67], v[226:229], v[210:213], v[64:67]
	v_mfma_f32_16x16x32_bf16 v[116:119], v[222:225], v[190:193], v[116:119]
	v_mfma_f32_16x16x32_bf16 v[112:115], v[230:233], v[190:193], v[112:115]
	v_mfma_f32_16x16x32_bf16 v[100:103], v[222:225], v[198:201], v[100:103]
	v_mfma_f32_16x16x32_bf16 v[96:99], v[230:233], v[198:201], v[96:99]
	v_mfma_f32_16x16x32_bf16 v[84:87], v[222:225], v[206:209], v[84:87]
	v_mfma_f32_16x16x32_bf16 v[80:83], v[230:233], v[206:209], v[80:83]
	v_mfma_f32_16x16x32_bf16 v[68:71], v[222:225], v[214:217], v[68:71]
	v_mfma_f32_16x16x32_bf16 v[64:67], v[230:233], v[214:217], v[64:67]
	s_mov_b32 m0, s43
	v_lshl_add_u64 v[144:145], v[174:175], 0, s[14:15]
	s_barrier
	ds_read_b128 v[182:185], v150 offset:49152
	ds_read_b128 v[190:193], v150 offset:50176
	ds_read_b128 v[194:197], v150 offset:51200
	ds_read_b128 v[198:201], v150 offset:52224
	ds_read_b128 v[202:205], v150 offset:53248
	ds_read_b128 v[206:209], v150 offset:54272
	ds_read_b128 v[210:213], v150 offset:55296
	ds_read_b128 v[214:217], v150 offset:56320
	global_load_lds_dwordx4 v[144:145], off
	v_lshl_add_u64 v[144:145], v[178:179], 0, s[14:15]
	s_mov_b32 m0, s44
	s_nop 0
	global_load_lds_dwordx4 v[144:145], off
	s_barrier
	s_waitcnt lgkmcnt(0)
	s_waitcnt lgkmcnt(0)
	v_mfma_f32_16x16x32_bf16 v[60:63], v[154:157], v[182:185], v[60:63]
	v_mfma_f32_16x16x32_bf16 v[56:59], v[166:169], v[182:185], v[56:59]
	v_mfma_f32_16x16x32_bf16 v[48:51], v[154:157], v[194:197], v[48:51]
	v_mfma_f32_16x16x32_bf16 v[40:43], v[166:169], v[194:197], v[40:43]
	v_mfma_f32_16x16x32_bf16 v[32:35], v[154:157], v[202:205], v[32:35]
	v_mfma_f32_16x16x32_bf16 v[24:27], v[166:169], v[202:205], v[24:27]
	v_mfma_f32_16x16x32_bf16 v[16:19], v[154:157], v[210:213], v[16:19]
	v_mfma_f32_16x16x32_bf16 v[8:11], v[166:169], v[210:213], v[8:11]
	v_mfma_f32_16x16x32_bf16 v[60:63], v[158:161], v[190:193], v[60:63]
	v_mfma_f32_16x16x32_bf16 v[56:59], v[170:173], v[190:193], v[56:59]
	v_mfma_f32_16x16x32_bf16 v[48:51], v[158:161], v[198:201], v[48:51]
	v_mfma_f32_16x16x32_bf16 v[40:43], v[170:173], v[198:201], v[40:43]
	v_mfma_f32_16x16x32_bf16 v[32:35], v[158:161], v[206:209], v[32:35]
	v_mfma_f32_16x16x32_bf16 v[24:27], v[170:173], v[206:209], v[24:27]
	v_mfma_f32_16x16x32_bf16 v[16:19], v[158:161], v[214:217], v[16:19]
	v_mfma_f32_16x16x32_bf16 v[8:11], v[170:173], v[214:217], v[8:11]
	s_barrier
	s_add_u32 s22, s26, 0xb0080
	s_addc_u32 s23, s27, 0
	s_add_i32 s26, s28, s37
	v_lshl_add_u64 v[144:145], s[22:23], 0, v[130:131]
	s_mov_b32 m0, s26
	s_nop 0
	global_load_lds_dwordx4 v[144:145], off
	v_lshl_add_u64 v[144:145], s[22:23], 0, v[134:135]
	s_add_i32 m0, s26, 0x2000
	s_nop 0
	global_load_lds_dwordx4 v[144:145], off
	s_waitcnt vmcnt(6)
	s_barrier
	v_mfma_f32_16x16x32_bf16 v[52:55], v[218:221], v[182:185], v[52:55]
	v_mfma_f32_16x16x32_bf16 v[44:47], v[226:229], v[182:185], v[44:47]
	v_mfma_f32_16x16x32_bf16 v[36:39], v[218:221], v[194:197], v[36:39]
	v_mfma_f32_16x16x32_bf16 v[28:31], v[226:229], v[194:197], v[28:31]
	v_mfma_f32_16x16x32_bf16 v[20:23], v[218:221], v[202:205], v[20:23]
	v_mfma_f32_16x16x32_bf16 v[12:15], v[226:229], v[202:205], v[12:15]
	v_mfma_f32_16x16x32_bf16 v[4:7], v[218:221], v[210:213], v[4:7]
	v_mfma_f32_16x16x32_bf16 v[0:3], v[226:229], v[210:213], v[0:3]
	v_mfma_f32_16x16x32_bf16 v[52:55], v[222:225], v[190:193], v[52:55]
	v_mfma_f32_16x16x32_bf16 v[44:47], v[230:233], v[190:193], v[44:47]
	v_mfma_f32_16x16x32_bf16 v[36:39], v[222:225], v[198:201], v[36:39]
	v_mfma_f32_16x16x32_bf16 v[28:31], v[230:233], v[198:201], v[28:31]
	v_mfma_f32_16x16x32_bf16 v[20:23], v[222:225], v[206:209], v[20:23]
	v_mfma_f32_16x16x32_bf16 v[12:15], v[230:233], v[206:209], v[12:15]
	v_mfma_f32_16x16x32_bf16 v[4:7], v[222:225], v[214:217], v[4:7]
	v_mfma_f32_16x16x32_bf16 v[0:3], v[230:233], v[214:217], v[0:3]
	s_add_i32 s57, s57, 2
	s_add_u32 s55, s55, 0x100
	s_addc_u32 s56, s56, 0
	s_cmp_gt_u32 s57, 41
	s_mov_b64 s[22:23], s[24:25]
	s_barrier
	s_cbranch_scc0 .LBB0_286
	v_lshl_add_u32 v154, s53, 8, v146
	v_lshl_or_b32 v144, s54, 8, v148
	v_ashrrev_i32_e32 v155, 31, v154
	v_ashrrev_i32_e32 v145, 31, v144
	v_lshlrev_b64 v[156:157], 11, v[154:155]
	v_lshl_add_u64 v[156:157], s[10:11], 0, v[156:157]
	v_lshlrev_b64 v[158:159], 1, v[144:145]
	v_lshl_add_u64 v[144:145], v[156:157], 0, v[158:159]
	v_pk_add_f32 v[126:127], v[126:127], 0 op_sel_hi:[1,0]
	v_pk_add_f32 v[124:125], v[124:125], 0 op_sel_hi:[1,0]
	v_pk_add_f32 v[156:157], v[122:123], 0 op_sel_hi:[1,0]
	v_pk_add_f32 v[122:123], v[120:121], 0 op_sel_hi:[1,0]
	v_cvt_pk_bf16_f32 v120, v124, v125
	v_cvt_pk_bf16_f32 v121, v126, v127
	v_pk_add_f32 v[116:117], v[116:117], 0 op_sel_hi:[1,0]
	v_cvt_pk_bf16_f32 v122, v122, v123
	v_cvt_pk_bf16_f32 v123, v156, v157
	global_store_dwordx4 v[144:145], v[120:123], off
	v_pk_add_f32 v[118:119], v[118:119], 0 op_sel_hi:[1,0]
	v_pk_add_f32 v[110:111], v[110:111], 0 op_sel_hi:[1,0]
	v_pk_add_f32 v[120:121], v[114:115], 0 op_sel_hi:[1,0]
	v_pk_add_f32 v[114:115], v[112:113], 0 op_sel_hi:[1,0]
	v_cvt_pk_bf16_f32 v112, v116, v117
	v_cvt_pk_bf16_f32 v113, v118, v119
	v_pk_add_f32 v[108:109], v[108:109], 0 op_sel_hi:[1,0]
	v_cvt_pk_bf16_f32 v114, v114, v115
	v_cvt_pk_bf16_f32 v115, v120, v121
	global_store_dwordx4 v[144:145], v[112:115], off offset:256
	v_pk_add_f32 v[100:101], v[100:101], 0 op_sel_hi:[1,0]
	v_pk_add_f32 v[102:103], v[102:103], 0 op_sel_hi:[1,0]
	v_or_b32_e32 v112, 16, v154
	v_ashrrev_i32_e32 v113, 31, v112
	v_lshlrev_b64 v[112:113], 11, v[112:113]
	v_lshl_add_u64 v[112:113], s[10:11], 0, v[112:113]
	v_lshl_add_u64 v[112:113], v[112:113], 0, v[158:159]
	v_pk_add_f32 v[114:115], v[106:107], 0 op_sel_hi:[1,0]
	v_pk_add_f32 v[106:107], v[104:105], 0 op_sel_hi:[1,0]
	v_cvt_pk_bf16_f32 v104, v108, v109
	v_cvt_pk_bf16_f32 v105, v110, v111
	v_pk_add_f32 v[94:95], v[94:95], 0 op_sel_hi:[1,0]
	v_cvt_pk_bf16_f32 v106, v106, v107
	v_cvt_pk_bf16_f32 v107, v114, v115
	global_store_dwordx4 v[112:113], v[104:107], off
	v_pk_add_f32 v[92:93], v[92:93], 0 op_sel_hi:[1,0]
	v_pk_add_f32 v[84:85], v[84:85], 0 op_sel_hi:[1,0]
	v_pk_add_f32 v[104:105], v[98:99], 0 op_sel_hi:[1,0]
	v_pk_add_f32 v[98:99], v[96:97], 0 op_sel_hi:[1,0]
	v_cvt_pk_bf16_f32 v96, v100, v101
	v_cvt_pk_bf16_f32 v97, v102, v103
	v_pk_add_f32 v[86:87], v[86:87], 0 op_sel_hi:[1,0]
	v_cvt_pk_bf16_f32 v98, v98, v99
	v_cvt_pk_bf16_f32 v99, v104, v105
	global_store_dwordx4 v[112:113], v[96:99], off offset:256
	v_pk_add_f32 v[78:79], v[78:79], 0 op_sel_hi:[1,0]
	v_pk_add_f32 v[76:77], v[76:77], 0 op_sel_hi:[1,0]
	v_or_b32_e32 v96, 32, v154
	v_ashrrev_i32_e32 v97, 31, v96
	v_lshlrev_b64 v[96:97], 11, v[96:97]
	v_lshl_add_u64 v[96:97], s[10:11], 0, v[96:97]
	v_lshl_add_u64 v[96:97], v[96:97], 0, v[158:159]
	v_pk_add_f32 v[98:99], v[90:91], 0 op_sel_hi:[1,0]
	v_pk_add_f32 v[90:91], v[88:89], 0 op_sel_hi:[1,0]
	v_cvt_pk_bf16_f32 v88, v92, v93
	v_cvt_pk_bf16_f32 v89, v94, v95
	v_pk_add_f32 v[70:71], v[70:71], 0 op_sel_hi:[1,0]
	v_cvt_pk_bf16_f32 v90, v90, v91
	v_cvt_pk_bf16_f32 v91, v98, v99
	global_store_dwordx4 v[96:97], v[88:91], off
	v_pk_add_f32 v[68:69], v[68:69], 0 op_sel_hi:[1,0]
	s_mov_b64 s[22:23], 0x40000
	v_pk_add_f32 v[88:89], v[82:83], 0 op_sel_hi:[1,0]
	v_pk_add_f32 v[82:83], v[80:81], 0 op_sel_hi:[1,0]
	v_cvt_pk_bf16_f32 v80, v84, v85
	v_cvt_pk_bf16_f32 v81, v86, v87
	v_pk_add_f32 v[60:61], v[60:61], 0 op_sel_hi:[1,0]
	v_cvt_pk_bf16_f32 v82, v82, v83
	v_cvt_pk_bf16_f32 v83, v88, v89
	global_store_dwordx4 v[96:97], v[80:83], off offset:256
	v_pk_add_f32 v[62:63], v[62:63], 0 op_sel_hi:[1,0]
	v_pk_add_f32 v[54:55], v[54:55], 0 op_sel_hi:[1,0]
	v_or_b32_e32 v80, 48, v154
	v_ashrrev_i32_e32 v81, 31, v80
	v_lshlrev_b64 v[80:81], 11, v[80:81]
	v_lshl_add_u64 v[80:81], s[10:11], 0, v[80:81]
	v_lshl_add_u64 v[80:81], v[80:81], 0, v[158:159]
	v_pk_add_f32 v[82:83], v[74:75], 0 op_sel_hi:[1,0]
	v_pk_add_f32 v[74:75], v[72:73], 0 op_sel_hi:[1,0]
	v_cvt_pk_bf16_f32 v72, v76, v77
	v_cvt_pk_bf16_f32 v73, v78, v79
	v_pk_add_f32 v[52:53], v[52:53], 0 op_sel_hi:[1,0]
	v_cvt_pk_bf16_f32 v74, v74, v75
	v_cvt_pk_bf16_f32 v75, v82, v83
	global_store_dwordx4 v[80:81], v[72:75], off
	v_pk_add_f32 v[48:49], v[48:49], 0 op_sel_hi:[1,0]
	v_pk_add_f32 v[38:39], v[38:39], 0 op_sel_hi:[1,0]
	v_pk_add_f32 v[72:73], v[66:67], 0 op_sel_hi:[1,0]
	v_pk_add_f32 v[66:67], v[64:65], 0 op_sel_hi:[1,0]
	v_cvt_pk_bf16_f32 v64, v68, v69
	v_cvt_pk_bf16_f32 v65, v70, v71
	v_pk_add_f32 v[36:37], v[36:37], 0 op_sel_hi:[1,0]
	v_cvt_pk_bf16_f32 v66, v66, v67
	v_cvt_pk_bf16_f32 v67, v72, v73
	global_store_dwordx4 v[80:81], v[64:67], off offset:256
	v_pk_add_f32 v[32:33], v[32:33], 0 op_sel_hi:[1,0]
	v_pk_add_f32 v[22:23], v[22:23], 0 op_sel_hi:[1,0]
	v_lshl_add_u64 v[64:65], v[144:145], 0, s[22:23]
	s_mov_b32 s22, 0x40000
	v_pk_add_f32 v[66:67], v[58:59], 0 op_sel_hi:[1,0]
	v_pk_add_f32 v[58:59], v[56:57], 0 op_sel_hi:[1,0]
	v_cvt_pk_bf16_f32 v56, v60, v61
	v_add_co_u32_e32 v60, vcc, s22, v144
	v_cvt_pk_bf16_f32 v57, v62, v63
	v_cvt_pk_bf16_f32 v58, v58, v59
	v_cvt_pk_bf16_f32 v59, v66, v67
	s_mov_b64 s[22:23], 0x48000
	s_nop 0
	v_addc_co_u32_e32 v61, vcc, 0, v145, vcc
	global_store_dwordx4 v[60:61], v[56:59], off
	v_pk_add_f32 v[20:21], v[20:21], 0 op_sel_hi:[1,0]
	v_pk_add_f32 v[16:17], v[16:17], 0 op_sel_hi:[1,0]
	v_pk_add_f32 v[56:57], v[46:47], 0 op_sel_hi:[1,0]
	v_pk_add_f32 v[46:47], v[44:45], 0 op_sel_hi:[1,0]
	v_cvt_pk_bf16_f32 v44, v52, v53
	v_cvt_pk_bf16_f32 v45, v54, v55
	s_mov_b32 s54, s51
	v_cvt_pk_bf16_f32 v46, v46, v47
	v_cvt_pk_bf16_f32 v47, v56, v57
	global_store_dwordx4 v[64:65], v[44:47], off offset:256
	s_mov_b32 s53, s52
	s_mov_b64 s[24:25], s[4:5]
	v_pk_add_f32 v[46:47], v[50:51], 0 op_sel_hi:[1,0]
	v_pk_add_f32 v[50:51], v[42:43], 0 op_sel_hi:[1,0]
	v_pk_add_f32 v[42:43], v[40:41], 0 op_sel_hi:[1,0]
	v_cvt_pk_bf16_f32 v40, v48, v49
	v_cvt_pk_bf16_f32 v41, v46, v47
	v_add_co_u32_e32 v46, vcc, s48, v144
	v_cvt_pk_bf16_f32 v42, v42, v43
	v_cvt_pk_bf16_f32 v43, v50, v51
	v_lshl_add_u64 v[44:45], v[144:145], 0, s[22:23]
	s_nop 0
	v_addc_co_u32_e32 v47, vcc, 0, v145, vcc
	global_store_dwordx4 v[46:47], v[40:43], off
	s_mov_b64 s[22:23], s[0:1]
	v_pk_add_f32 v[6:7], v[6:7], 0 op_sel_hi:[1,0]
	v_pk_add_f32 v[40:41], v[30:31], 0 op_sel_hi:[1,0]
	v_pk_add_f32 v[30:31], v[28:29], 0 op_sel_hi:[1,0]
	v_cvt_pk_bf16_f32 v28, v36, v37
	v_cvt_pk_bf16_f32 v29, v38, v39
	v_pk_add_f32 v[4:5], v[4:5], 0 op_sel_hi:[1,0]
	v_cvt_pk_bf16_f32 v30, v30, v31
	v_cvt_pk_bf16_f32 v31, v40, v41
	global_store_dwordx4 v[44:45], v[28:31], off offset:256
	s_nop 1
	v_pk_add_f32 v[30:31], v[34:35], 0 op_sel_hi:[1,0]
	v_pk_add_f32 v[34:35], v[26:27], 0 op_sel_hi:[1,0]
	v_pk_add_f32 v[26:27], v[24:25], 0 op_sel_hi:[1,0]
	v_cvt_pk_bf16_f32 v24, v32, v33
	v_cvt_pk_bf16_f32 v25, v30, v31
	v_add_co_u32_e32 v30, vcc, s49, v144
	v_cvt_pk_bf16_f32 v26, v26, v27
	v_cvt_pk_bf16_f32 v27, v34, v35
	v_lshl_add_u64 v[28:29], v[144:145], 0, s[16:17]
	s_nop 0
	v_addc_co_u32_e32 v31, vcc, 0, v145, vcc
	global_store_dwordx4 v[30:31], v[24:27], off
	s_nop 1
	v_pk_add_f32 v[24:25], v[14:15], 0 op_sel_hi:[1,0]
	v_pk_add_f32 v[14:15], v[12:13], 0 op_sel_hi:[1,0]
	v_cvt_pk_bf16_f32 v12, v20, v21
	v_cvt_pk_bf16_f32 v13, v22, v23
	s_nop 0
	v_cvt_pk_bf16_f32 v14, v14, v15
	v_cvt_pk_bf16_f32 v15, v24, v25
	global_store_dwordx4 v[28:29], v[12:15], off offset:256
	s_nop 1
	v_pk_add_f32 v[14:15], v[18:19], 0 op_sel_hi:[1,0]
	v_pk_add_f32 v[18:19], v[10:11], 0 op_sel_hi:[1,0]
	v_pk_add_f32 v[10:11], v[8:9], 0 op_sel_hi:[1,0]
	v_cvt_pk_bf16_f32 v8, v16, v17
	v_cvt_pk_bf16_f32 v9, v14, v15
	v_add_co_u32_e32 v14, vcc, s50, v144
	v_lshl_add_u64 v[12:13], v[144:145], 0, s[18:19]
	s_nop 0
	v_addc_co_u32_e32 v15, vcc, 0, v145, vcc
	v_cvt_pk_bf16_f32 v10, v10, v11
	v_cvt_pk_bf16_f32 v11, v18, v19
	global_store_dwordx4 v[14:15], v[8:11], off
	s_and_b64 vcc, exec, s[2:3]
	s_nop 0
	v_pk_add_f32 v[8:9], v[2:3], 0 op_sel_hi:[1,0]
	v_pk_add_f32 v[2:3], v[0:1], 0 op_sel_hi:[1,0]
	v_cvt_pk_bf16_f32 v0, v4, v5
	v_cvt_pk_bf16_f32 v1, v6, v7
	s_nop 0
	v_cvt_pk_bf16_f32 v2, v2, v3
	v_cvt_pk_bf16_f32 v3, v8, v9
	global_store_dwordx4 v[12:13], v[0:3], off offset:256
	s_cbranch_vccz .LBB0_275
	s_waitcnt vmcnt(0)
	s_cmpk_gt_u32 s31, 0xff
	s_cbranch_scc1 .LBB0_290
	s_barrier

.LBB0_416:
	ds_read_b128 v[24:27], v186
	ds_read_b128 v[28:31], v186 offset:1024
	ds_read_b128 v[40:43], v186 offset:2048
	ds_read_b128 v[44:47], v186 offset:3072
	s_add_u32 s4, s0, 0xfffc0080
	s_addc_u32 s5, s1, -1
	s_cmp_eq_u32 s53, 12
	s_cselect_b32 s29, s7, s5
	s_cselect_b32 s28, s10, s4
	s_cselect_b32 s5, s19, s52
	s_cselect_b32 s4, s21, s51
	v_lshl_add_u64 v[174:175], s[0:1], 0, v[166:167]
	s_add_i32 m0, s27, 0xc000
	ds_read_b128 v[144:147], v187
	ds_read_b128 v[148:151], v187 offset:1024
	ds_read_b128 v[182:185], v187 offset:2048
	ds_read_b128 v[192:195], v187 offset:3072
	ds_read_b128 v[196:199], v187 offset:4096
	ds_read_b128 v[200:203], v187 offset:5120
	ds_read_b128 v[204:207], v187 offset:6144
	ds_read_b128 v[208:211], v187 offset:7168
	global_load_lds_dwordx4 v[174:175], off
	v_lshl_add_u64 v[174:175], s[0:1], 0, v[168:169]
	s_add_i32 m0, s27, 0xe000
	s_nop 0
	global_load_lds_dwordx4 v[174:175], off
	s_waitcnt lgkmcnt(8)
	s_barrier
	s_waitcnt lgkmcnt(0)
	s_waitcnt lgkmcnt(0)
	v_mfma_f32_16x16x32_bf16 v[140:143], v[24:27], v[144:147], v[140:143]
	v_mfma_f32_16x16x32_bf16 v[136:139], v[40:43], v[144:147], v[136:139]
	v_mfma_f32_16x16x32_bf16 v[124:127], v[24:27], v[182:185], v[124:127]
	v_mfma_f32_16x16x32_bf16 v[120:123], v[40:43], v[182:185], v[120:123]
	v_mfma_f32_16x16x32_bf16 v[108:111], v[24:27], v[196:199], v[108:111]
	v_mfma_f32_16x16x32_bf16 v[104:107], v[40:43], v[196:199], v[104:107]
	v_mfma_f32_16x16x32_bf16 v[92:95], v[24:27], v[204:207], v[92:95]
	v_mfma_f32_16x16x32_bf16 v[88:91], v[40:43], v[204:207], v[88:91]
	v_mfma_f32_16x16x32_bf16 v[140:143], v[28:31], v[148:151], v[140:143]
	v_mfma_f32_16x16x32_bf16 v[136:139], v[44:47], v[148:151], v[136:139]
	v_mfma_f32_16x16x32_bf16 v[124:127], v[28:31], v[192:195], v[124:127]
	v_mfma_f32_16x16x32_bf16 v[120:123], v[44:47], v[192:195], v[120:123]
	v_mfma_f32_16x16x32_bf16 v[108:111], v[28:31], v[200:203], v[108:111]
	v_mfma_f32_16x16x32_bf16 v[104:107], v[44:47], v[200:203], v[104:107]
	v_mfma_f32_16x16x32_bf16 v[92:95], v[28:31], v[208:211], v[92:95]
	v_mfma_f32_16x16x32_bf16 v[88:91], v[44:47], v[208:211], v[88:91]
	s_barrier
	s_add_i32 s54, s43, s35
	v_lshl_add_u64 v[174:175], s[4:5], 0, v[156:157]
	s_mov_b32 m0, s54
	ds_read_b128 v[212:215], v189
	ds_read_b128 v[216:219], v189 offset:1024
	ds_read_b128 v[220:223], v189 offset:2048
	ds_read_b128 v[224:227], v189 offset:3072
	global_load_lds_dwordx4 v[174:175], off
	v_lshl_add_u64 v[228:229], s[4:5], 0, v[160:161]
	s_add_i32 m0, s54, 0x2000
	s_nop 0
	global_load_lds_dwordx4 v[228:229], off
	s_barrier
	s_waitcnt lgkmcnt(0)
	s_waitcnt lgkmcnt(0)
	v_mfma_f32_16x16x32_bf16 v[132:135], v[212:215], v[144:147], v[132:135]
	v_mfma_f32_16x16x32_bf16 v[128:131], v[220:223], v[144:147], v[128:131]
	v_mfma_f32_16x16x32_bf16 v[116:119], v[212:215], v[182:185], v[116:119]
	v_mfma_f32_16x16x32_bf16 v[112:115], v[220:223], v[182:185], v[112:115]
	v_mfma_f32_16x16x32_bf16 v[100:103], v[212:215], v[196:199], v[100:103]
	v_mfma_f32_16x16x32_bf16 v[96:99], v[220:223], v[196:199], v[96:99]
	v_mfma_f32_16x16x32_bf16 v[84:87], v[212:215], v[204:207], v[84:87]
	v_mfma_f32_16x16x32_bf16 v[80:83], v[220:223], v[204:207], v[80:83]
	v_mfma_f32_16x16x32_bf16 v[132:135], v[216:219], v[148:151], v[132:135]
	v_mfma_f32_16x16x32_bf16 v[128:131], v[224:227], v[148:151], v[128:131]
	v_mfma_f32_16x16x32_bf16 v[116:119], v[216:219], v[192:195], v[116:119]
	v_mfma_f32_16x16x32_bf16 v[112:115], v[224:227], v[192:195], v[112:115]
	v_mfma_f32_16x16x32_bf16 v[100:103], v[216:219], v[200:203], v[100:103]
	v_mfma_f32_16x16x32_bf16 v[96:99], v[224:227], v[200:203], v[96:99]
	v_mfma_f32_16x16x32_bf16 v[84:87], v[216:219], v[208:211], v[84:87]
	v_mfma_f32_16x16x32_bf16 v[80:83], v[224:227], v[208:211], v[80:83]
	s_mov_b32 m0, s27
	v_lshl_add_u64 v[230:231], s[28:29], 0, v[154:155]
	s_barrier
	ds_read_b128 v[144:147], v187 offset:16384
	ds_read_b128 v[148:151], v187 offset:17408
	ds_read_b128 v[182:185], v187 offset:18432
	ds_read_b128 v[192:195], v187 offset:19456
	ds_read_b128 v[196:199], v187 offset:20480
	ds_read_b128 v[200:203], v187 offset:21504
	ds_read_b128 v[204:207], v187 offset:22528
	ds_read_b128 v[208:211], v187 offset:23552
	global_load_lds_dwordx4 v[230:231], off
	v_lshl_add_u64 v[232:233], s[28:29], 0, v[158:159]
	s_mov_b32 m0, s36
	s_nop 0
	global_load_lds_dwordx4 v[232:233], off
	s_barrier
	s_waitcnt lgkmcnt(0)
	s_waitcnt lgkmcnt(0)
	v_mfma_f32_16x16x32_bf16 v[76:79], v[24:27], v[144:147], v[76:79]
	v_mfma_f32_16x16x32_bf16 v[72:75], v[40:43], v[144:147], v[72:75]
	v_mfma_f32_16x16x32_bf16 v[60:63], v[24:27], v[182:185], v[60:63]
	v_mfma_f32_16x16x32_bf16 v[56:59], v[40:43], v[182:185], v[56:59]
	v_mfma_f32_16x16x32_bf16 v[36:39], v[24:27], v[196:199], v[36:39]
	v_mfma_f32_16x16x32_bf16 v[32:35], v[40:43], v[196:199], v[32:35]
	v_mfma_f32_16x16x32_bf16 v[12:15], v[24:27], v[204:207], v[12:15]
	v_mfma_f32_16x16x32_bf16 v[8:11], v[40:43], v[204:207], v[8:11]
	v_mfma_f32_16x16x32_bf16 v[76:79], v[28:31], v[148:151], v[76:79]
	v_mfma_f32_16x16x32_bf16 v[72:75], v[44:47], v[148:151], v[72:75]
	v_mfma_f32_16x16x32_bf16 v[60:63], v[28:31], v[192:195], v[60:63]
	v_mfma_f32_16x16x32_bf16 v[56:59], v[44:47], v[192:195], v[56:59]
	v_mfma_f32_16x16x32_bf16 v[36:39], v[28:31], v[200:203], v[36:39]
	v_mfma_f32_16x16x32_bf16 v[32:35], v[44:47], v[200:203], v[32:35]
	v_mfma_f32_16x16x32_bf16 v[12:15], v[28:31], v[208:211], v[12:15]
	v_mfma_f32_16x16x32_bf16 v[8:11], v[44:47], v[208:211], v[8:11]
	s_barrier
	s_add_u32 s54, s4, 0x40000
	s_addc_u32 s55, s5, 0
	s_add_i32 s56, s44, s35
	v_lshl_add_u64 v[24:25], s[54:55], 0, v[156:157]
	s_mov_b32 m0, s56
	s_nop 0
	global_load_lds_dwordx4 v[24:25], off
	v_lshl_add_u64 v[24:25], s[54:55], 0, v[160:161]
	s_add_i32 m0, s56, 0x2000
	s_nop 0
	global_load_lds_dwordx4 v[24:25], off
	s_waitcnt vmcnt(6)
	s_barrier
	v_mfma_f32_16x16x32_bf16 v[20:23], v[212:215], v[196:199], v[20:23]
	v_mfma_f32_16x16x32_bf16 v[16:19], v[220:223], v[196:199], v[16:19]
	v_mfma_f32_16x16x32_bf16 v[4:7], v[212:215], v[204:207], v[4:7]
	v_mfma_f32_16x16x32_bf16 v[0:3], v[220:223], v[204:207], v[0:3]
	v_mfma_f32_16x16x32_bf16 v[24:27], v[212:215], v[144:147], v[68:71]
	v_mfma_f32_16x16x32_bf16 v[28:31], v[220:223], v[144:147], v[64:67]
	v_mfma_f32_16x16x32_bf16 v[40:43], v[212:215], v[182:185], v[52:55]
	v_mfma_f32_16x16x32_bf16 v[44:47], v[220:223], v[182:185], v[48:51]
	v_mfma_f32_16x16x32_bf16 v[20:23], v[216:219], v[200:203], v[20:23]
	v_mfma_f32_16x16x32_bf16 v[16:19], v[224:227], v[200:203], v[16:19]
	v_mfma_f32_16x16x32_bf16 v[4:7], v[216:219], v[208:211], v[4:7]
	v_mfma_f32_16x16x32_bf16 v[0:3], v[224:227], v[208:211], v[0:3]
	v_mfma_f32_16x16x32_bf16 v[24:27], v[216:219], v[148:151], v[24:27]
	v_mfma_f32_16x16x32_bf16 v[28:31], v[224:227], v[148:151], v[28:31]
	v_mfma_f32_16x16x32_bf16 v[40:43], v[216:219], v[192:195], v[40:43]
	v_mfma_f32_16x16x32_bf16 v[44:47], v[224:227], v[192:195], v[44:47]
	s_add_i32 s54, 0, 0x18000
	v_add_u32_e32 v68, s54, v179
	s_barrier
	ds_read_b128 v[48:51], v68
	ds_read_b128 v[52:55], v68 offset:1024
	ds_read_b128 v[64:67], v68 offset:2048
	ds_read_b128 v[68:71], v68 offset:3072
	s_add_u32 s28, s28, 0x40000
	s_addc_u32 s29, s29, 0
	s_mov_b32 m0, s37
	v_lshl_add_u64 v[212:213], s[28:29], 0, v[154:155]
	ds_read_b128 v[144:147], v187 offset:32768
	ds_read_b128 v[148:151], v187 offset:33792
	ds_read_b128 v[182:185], v187 offset:34816
	ds_read_b128 v[192:195], v187 offset:35840
	ds_read_b128 v[196:199], v187 offset:36864
	ds_read_b128 v[200:203], v187 offset:37888
	ds_read_b128 v[204:207], v187 offset:38912
	ds_read_b128 v[208:211], v187 offset:39936
	global_load_lds_dwordx4 v[212:213], off
	v_lshl_add_u64 v[212:213], s[28:29], 0, v[158:159]
	s_mov_b32 m0, s38
	s_nop 0
	global_load_lds_dwordx4 v[212:213], off
	s_waitcnt lgkmcnt(8)
	s_barrier
	s_waitcnt lgkmcnt(0)
	s_waitcnt lgkmcnt(0)
	v_mfma_f32_16x16x32_bf16 v[140:143], v[48:51], v[144:147], v[140:143]
	v_mfma_f32_16x16x32_bf16 v[136:139], v[64:67], v[144:147], v[136:139]
	v_mfma_f32_16x16x32_bf16 v[124:127], v[48:51], v[182:185], v[124:127]
	v_mfma_f32_16x16x32_bf16 v[120:123], v[64:67], v[182:185], v[120:123]
	v_mfma_f32_16x16x32_bf16 v[108:111], v[48:51], v[196:199], v[108:111]
	v_mfma_f32_16x16x32_bf16 v[104:107], v[64:67], v[196:199], v[104:107]
	v_mfma_f32_16x16x32_bf16 v[92:95], v[48:51], v[204:207], v[92:95]
	v_mfma_f32_16x16x32_bf16 v[88:91], v[64:67], v[204:207], v[88:91]
	v_mfma_f32_16x16x32_bf16 v[140:143], v[52:55], v[148:151], v[140:143]
	v_mfma_f32_16x16x32_bf16 v[136:139], v[68:71], v[148:151], v[136:139]
	v_mfma_f32_16x16x32_bf16 v[124:127], v[52:55], v[192:195], v[124:127]
	v_mfma_f32_16x16x32_bf16 v[120:123], v[68:71], v[192:195], v[120:123]
	v_mfma_f32_16x16x32_bf16 v[108:111], v[52:55], v[200:203], v[108:111]
	v_mfma_f32_16x16x32_bf16 v[104:107], v[68:71], v[200:203], v[104:107]
	v_mfma_f32_16x16x32_bf16 v[92:95], v[52:55], v[208:211], v[92:95]
	v_mfma_f32_16x16x32_bf16 v[88:91], v[68:71], v[208:211], v[88:91]
	s_barrier
	s_add_i32 s28, 0, 0x1c000
	s_add_i32 s29, s54, s35
	v_add_u32_e32 v162, s28, v179
	v_lshl_add_u64 v[174:175], v[174:175], 0, s[14:15]
	s_mov_b32 m0, s29
	ds_read_b128 v[212:215], v162
	ds_read_b128 v[216:219], v162 offset:1024
	ds_read_b128 v[220:223], v162 offset:2048
	ds_read_b128 v[224:227], v162 offset:3072
	global_load_lds_dwordx4 v[174:175], off
	v_lshl_add_u64 v[174:175], v[228:229], 0, s[14:15]
	s_add_i32 m0, s29, 0x2000
	s_nop 0
	global_load_lds_dwordx4 v[174:175], off
	s_barrier
	s_waitcnt lgkmcnt(0)
	s_waitcnt lgkmcnt(0)
	v_mfma_f32_16x16x32_bf16 v[132:135], v[212:215], v[144:147], v[132:135]
	v_mfma_f32_16x16x32_bf16 v[128:131], v[220:223], v[144:147], v[128:131]
	v_mfma_f32_16x16x32_bf16 v[116:119], v[212:215], v[182:185], v[116:119]
	v_mfma_f32_16x16x32_bf16 v[112:115], v[220:223], v[182:185], v[112:115]
	v_mfma_f32_16x16x32_bf16 v[100:103], v[212:215], v[196:199], v[100:103]
	v_mfma_f32_16x16x32_bf16 v[96:99], v[220:223], v[196:199], v[96:99]
	v_mfma_f32_16x16x32_bf16 v[84:87], v[212:215], v[204:207], v[84:87]
	v_mfma_f32_16x16x32_bf16 v[80:83], v[220:223], v[204:207], v[80:83]
	v_mfma_f32_16x16x32_bf16 v[132:135], v[216:219], v[148:151], v[132:135]
	v_mfma_f32_16x16x32_bf16 v[128:131], v[224:227], v[148:151], v[128:131]
	v_mfma_f32_16x16x32_bf16 v[116:119], v[216:219], v[192:195], v[116:119]
	v_mfma_f32_16x16x32_bf16 v[112:115], v[224:227], v[192:195], v[112:115]
	v_mfma_f32_16x16x32_bf16 v[100:103], v[216:219], v[200:203], v[100:103]
	v_mfma_f32_16x16x32_bf16 v[96:99], v[224:227], v[200:203], v[96:99]
	v_mfma_f32_16x16x32_bf16 v[84:87], v[216:219], v[208:211], v[84:87]
	v_mfma_f32_16x16x32_bf16 v[80:83], v[224:227], v[208:211], v[80:83]
	s_mov_b32 m0, s39
	v_lshl_add_u64 v[174:175], v[230:231], 0, s[14:15]
	s_barrier
	ds_read_b128 v[144:147], v187 offset:49152
	ds_read_b128 v[148:151], v187 offset:50176
	ds_read_b128 v[182:185], v187 offset:51200
	ds_read_b128 v[192:195], v187 offset:52224
	ds_read_b128 v[196:199], v187 offset:53248
	ds_read_b128 v[200:203], v187 offset:54272
	ds_read_b128 v[204:207], v187 offset:55296
	ds_read_b128 v[208:211], v187 offset:56320
	global_load_lds_dwordx4 v[174:175], off
	v_lshl_add_u64 v[174:175], v[232:233], 0, s[14:15]
	s_mov_b32 m0, s40
	s_nop 0
	global_load_lds_dwordx4 v[174:175], off
	s_barrier
	s_waitcnt lgkmcnt(0)
	s_waitcnt lgkmcnt(0)
	v_mfma_f32_16x16x32_bf16 v[76:79], v[48:51], v[144:147], v[76:79]
	v_mfma_f32_16x16x32_bf16 v[72:75], v[64:67], v[144:147], v[72:75]
	v_mfma_f32_16x16x32_bf16 v[60:63], v[48:51], v[182:185], v[60:63]
	v_mfma_f32_16x16x32_bf16 v[56:59], v[64:67], v[182:185], v[56:59]
	v_mfma_f32_16x16x32_bf16 v[36:39], v[48:51], v[196:199], v[36:39]
	v_mfma_f32_16x16x32_bf16 v[32:35], v[64:67], v[196:199], v[32:35]
	v_mfma_f32_16x16x32_bf16 v[12:15], v[48:51], v[204:207], v[12:15]
	v_mfma_f32_16x16x32_bf16 v[8:11], v[64:67], v[204:207], v[8:11]
	v_mfma_f32_16x16x32_bf16 v[76:79], v[52:55], v[148:151], v[76:79]
	v_mfma_f32_16x16x32_bf16 v[72:75], v[68:71], v[148:151], v[72:75]
	v_mfma_f32_16x16x32_bf16 v[60:63], v[52:55], v[192:195], v[60:63]
	v_mfma_f32_16x16x32_bf16 v[56:59], v[68:71], v[192:195], v[56:59]
	v_mfma_f32_16x16x32_bf16 v[36:39], v[52:55], v[200:203], v[36:39]
	v_mfma_f32_16x16x32_bf16 v[32:35], v[68:71], v[200:203], v[32:35]
	v_mfma_f32_16x16x32_bf16 v[12:15], v[52:55], v[208:211], v[12:15]
	v_mfma_f32_16x16x32_bf16 v[8:11], v[68:71], v[208:211], v[8:11]
	s_barrier
	s_add_u32 s4, s4, 0x40080
	s_addc_u32 s5, s5, 0
	s_add_i32 s28, s28, s35
	v_lshl_add_u64 v[48:49], s[4:5], 0, v[156:157]
	s_mov_b32 m0, s28
	s_nop 0
	global_load_lds_dwordx4 v[48:49], off
	v_lshl_add_u64 v[48:49], s[4:5], 0, v[160:161]
	s_add_i32 m0, s28, 0x2000
	s_nop 0
	global_load_lds_dwordx4 v[48:49], off
	s_waitcnt vmcnt(6)
	s_barrier
	v_mfma_f32_16x16x32_bf16 v[24:27], v[212:215], v[144:147], v[24:27]
	v_mfma_f32_16x16x32_bf16 v[68:71], v[216:219], v[148:151], v[24:27]
	v_mfma_f32_16x16x32_bf16 v[24:27], v[220:223], v[144:147], v[28:31]
	v_mfma_f32_16x16x32_bf16 v[64:67], v[224:227], v[148:151], v[24:27]
	v_mfma_f32_16x16x32_bf16 v[24:27], v[212:215], v[182:185], v[40:43]
	v_mfma_f32_16x16x32_bf16 v[52:55], v[216:219], v[192:195], v[24:27]
	v_mfma_f32_16x16x32_bf16 v[24:27], v[220:223], v[182:185], v[44:47]
	v_mfma_f32_16x16x32_bf16 v[20:23], v[212:215], v[196:199], v[20:23]
	v_mfma_f32_16x16x32_bf16 v[16:19], v[220:223], v[196:199], v[16:19]
	v_mfma_f32_16x16x32_bf16 v[4:7], v[212:215], v[204:207], v[4:7]
	v_mfma_f32_16x16x32_bf16 v[0:3], v[220:223], v[204:207], v[0:3]
	v_mfma_f32_16x16x32_bf16 v[48:51], v[224:227], v[192:195], v[24:27]
	v_mfma_f32_16x16x32_bf16 v[20:23], v[216:219], v[200:203], v[20:23]
	v_mfma_f32_16x16x32_bf16 v[16:19], v[224:227], v[200:203], v[16:19]
	v_mfma_f32_16x16x32_bf16 v[4:7], v[216:219], v[208:211], v[4:7]
	v_mfma_f32_16x16x32_bf16 v[0:3], v[224:227], v[208:211], v[0:3]
	s_add_i32 s53, s53, 2
	s_add_u32 s0, s0, 0x100
	s_addc_u32 s1, s1, 0
	s_add_u32 s51, s51, 0x100
	s_addc_u32 s52, s52, 0
	s_cmp_gt_u32 s53, 13
	s_barrier
	s_cbranch_scc0 .LBB0_416
	s_cmp_gt_i32 s26, 11
	s_cselect_b64 s[4:5], -1, 0
	s_cmp_lt_i32 s26, 12
	s_mov_b64 s[0:1], 0
	s_cbranch_scc1 .LBB0_422
	s_lshl_b32 s10, s26, 8
	s_cmp_lt_u32 s26, 14
	s_mov_b64 s[28:29], -1
	s_cbranch_scc0 .LBB0_420
	s_lshl_b64 s[0:1], s[10:11], 2
	v_readlane_b32 s52, v245, 0
	v_readlane_b32 s53, v245, 1
	s_add_u32 s0, s52, s0
	s_addc_u32 s1, s53, s1
	s_add_u32 s0, s0, 0xffffd000
	v_readlane_b32 s54, v245, 2
	v_readlane_b32 s55, v245, 3
	v_readlane_b32 s56, v245, 4
	v_readlane_b32 s57, v245, 5
	v_readlane_b32 s58, v245, 6
	v_readlane_b32 s59, v245, 7
	v_readlane_b32 s60, v245, 8
	v_readlane_b32 s61, v245, 9
	v_readlane_b32 s62, v245, 10
	v_readlane_b32 s63, v245, 11
	v_readlane_b32 s64, v245, 12
	v_readlane_b32 s65, v245, 13
	v_readlane_b32 s66, v245, 14
	v_readlane_b32 s67, v245, 15
	s_addc_u32 s1, s1, -1
	s_mov_b64 s[28:29], 0

.LBB0_724:
	ds_read_b128 v[144:147], v151
	ds_read_b128 v[156:159], v151 offset:1024
	ds_read_b128 v[160:163], v151 offset:2048
	ds_read_b128 v[166:169], v151 offset:3072
	s_add_u32 s20, s18, 0xfffc0080
	s_addc_u32 s21, s19, -1
	s_cmp_eq_u32 s48, 12
	s_cselect_b32 s23, s5, s21
	s_cselect_b32 s22, s11, s20
	s_cselect_b32 s21, s9, s47
	s_cselect_b32 s20, s45, s46
	v_lshl_add_u64 v[174:175], s[18:19], 0, v[136:137]
	s_add_i32 m0, s17, 0xc000
	ds_read_b128 v[170:173], v153
	ds_read_b128 v[182:185], v153 offset:1024
	ds_read_b128 v[190:193], v153 offset:2048
	ds_read_b128 v[194:197], v153 offset:3072
	ds_read_b128 v[198:201], v153 offset:4096
	ds_read_b128 v[202:205], v153 offset:5120
	ds_read_b128 v[206:209], v153 offset:6144
	ds_read_b128 v[210:213], v153 offset:7168
	global_load_lds_dwordx4 v[174:175], off
	v_lshl_add_u64 v[174:175], s[18:19], 0, v[138:139]
	s_add_i32 m0, s17, 0xe000
	s_nop 0
	global_load_lds_dwordx4 v[174:175], off
	s_waitcnt lgkmcnt(8)
	s_barrier
	s_waitcnt lgkmcnt(0)
	s_waitcnt lgkmcnt(0)
	v_mfma_f32_16x16x32_bf16 v[124:127], v[144:147], v[170:173], v[124:127]
	v_mfma_f32_16x16x32_bf16 v[120:123], v[160:163], v[170:173], v[120:123]
	v_mfma_f32_16x16x32_bf16 v[108:111], v[144:147], v[190:193], v[108:111]
	v_mfma_f32_16x16x32_bf16 v[104:107], v[160:163], v[190:193], v[104:107]
	v_mfma_f32_16x16x32_bf16 v[92:95], v[144:147], v[198:201], v[92:95]
	v_mfma_f32_16x16x32_bf16 v[88:91], v[160:163], v[198:201], v[88:91]
	v_mfma_f32_16x16x32_bf16 v[76:79], v[144:147], v[206:209], v[76:79]
	v_mfma_f32_16x16x32_bf16 v[72:75], v[160:163], v[206:209], v[72:75]
	v_mfma_f32_16x16x32_bf16 v[124:127], v[156:159], v[182:185], v[124:127]
	v_mfma_f32_16x16x32_bf16 v[120:123], v[166:169], v[182:185], v[120:123]
	v_mfma_f32_16x16x32_bf16 v[108:111], v[156:159], v[194:197], v[108:111]
	v_mfma_f32_16x16x32_bf16 v[104:107], v[166:169], v[194:197], v[104:107]
	v_mfma_f32_16x16x32_bf16 v[92:95], v[156:159], v[202:205], v[92:95]
	v_mfma_f32_16x16x32_bf16 v[88:91], v[166:169], v[202:205], v[88:91]
	v_mfma_f32_16x16x32_bf16 v[76:79], v[156:159], v[210:213], v[76:79]
	v_mfma_f32_16x16x32_bf16 v[72:75], v[166:169], v[210:213], v[72:75]
	s_barrier
	s_add_i32 s49, s42, s30
	v_lshl_add_u64 v[174:175], s[20:21], 0, v[130:131]
	s_mov_b32 m0, s49
	ds_read_b128 v[214:217], v154
	ds_read_b128 v[218:221], v154 offset:1024
	ds_read_b128 v[222:225], v154 offset:2048
	ds_read_b128 v[226:229], v154 offset:3072
	global_load_lds_dwordx4 v[174:175], off
	v_lshl_add_u64 v[186:187], s[20:21], 0, v[134:135]
	s_add_i32 m0, s49, 0x2000
	s_nop 0
	global_load_lds_dwordx4 v[186:187], off
	s_barrier
	s_waitcnt lgkmcnt(0)
	s_waitcnt lgkmcnt(0)
	v_mfma_f32_16x16x32_bf16 v[116:119], v[214:217], v[170:173], v[116:119]
	v_mfma_f32_16x16x32_bf16 v[112:115], v[222:225], v[170:173], v[112:115]
	v_mfma_f32_16x16x32_bf16 v[100:103], v[214:217], v[190:193], v[100:103]
	v_mfma_f32_16x16x32_bf16 v[96:99], v[222:225], v[190:193], v[96:99]
	v_mfma_f32_16x16x32_bf16 v[84:87], v[214:217], v[198:201], v[84:87]
	v_mfma_f32_16x16x32_bf16 v[80:83], v[222:225], v[198:201], v[80:83]
	v_mfma_f32_16x16x32_bf16 v[68:71], v[214:217], v[206:209], v[68:71]
	v_mfma_f32_16x16x32_bf16 v[64:67], v[222:225], v[206:209], v[64:67]
	v_mfma_f32_16x16x32_bf16 v[116:119], v[218:221], v[182:185], v[116:119]
	v_mfma_f32_16x16x32_bf16 v[112:115], v[226:229], v[182:185], v[112:115]
	v_mfma_f32_16x16x32_bf16 v[100:103], v[218:221], v[194:197], v[100:103]
	v_mfma_f32_16x16x32_bf16 v[96:99], v[226:229], v[194:197], v[96:99]
	v_mfma_f32_16x16x32_bf16 v[84:87], v[218:221], v[202:205], v[84:87]
	v_mfma_f32_16x16x32_bf16 v[80:83], v[226:229], v[202:205], v[80:83]
	v_mfma_f32_16x16x32_bf16 v[68:71], v[218:221], v[210:213], v[68:71]
	v_mfma_f32_16x16x32_bf16 v[64:67], v[226:229], v[210:213], v[64:67]
	s_mov_b32 m0, s17
	v_lshl_add_u64 v[230:231], s[22:23], 0, v[128:129]
	s_barrier
	ds_read_b128 v[170:173], v153 offset:16384
	ds_read_b128 v[182:185], v153 offset:17408
	ds_read_b128 v[190:193], v153 offset:18432
	ds_read_b128 v[194:197], v153 offset:19456
	ds_read_b128 v[198:201], v153 offset:20480
	ds_read_b128 v[202:205], v153 offset:21504
	ds_read_b128 v[206:209], v153 offset:22528
	ds_read_b128 v[210:213], v153 offset:23552
	global_load_lds_dwordx4 v[230:231], off
	v_lshl_add_u64 v[232:233], s[22:23], 0, v[132:133]
	s_mov_b32 m0, s31
	s_nop 0
	global_load_lds_dwordx4 v[232:233], off
	s_barrier
	s_waitcnt lgkmcnt(0)
	s_waitcnt lgkmcnt(0)
	v_mfma_f32_16x16x32_bf16 v[60:63], v[144:147], v[170:173], v[60:63]
	v_mfma_f32_16x16x32_bf16 v[56:59], v[160:163], v[170:173], v[56:59]
	v_mfma_f32_16x16x32_bf16 v[44:47], v[144:147], v[190:193], v[44:47]
	v_mfma_f32_16x16x32_bf16 v[40:43], v[160:163], v[190:193], v[40:43]
	v_mfma_f32_16x16x32_bf16 v[28:31], v[144:147], v[198:201], v[28:31]
	v_mfma_f32_16x16x32_bf16 v[24:27], v[160:163], v[198:201], v[24:27]
	v_mfma_f32_16x16x32_bf16 v[12:15], v[144:147], v[206:209], v[12:15]
	v_mfma_f32_16x16x32_bf16 v[8:11], v[160:163], v[206:209], v[8:11]
	v_mfma_f32_16x16x32_bf16 v[60:63], v[156:159], v[182:185], v[60:63]
	v_mfma_f32_16x16x32_bf16 v[56:59], v[166:169], v[182:185], v[56:59]
	v_mfma_f32_16x16x32_bf16 v[44:47], v[156:159], v[194:197], v[44:47]
	v_mfma_f32_16x16x32_bf16 v[40:43], v[166:169], v[194:197], v[40:43]
	v_mfma_f32_16x16x32_bf16 v[28:31], v[156:159], v[202:205], v[28:31]
	v_mfma_f32_16x16x32_bf16 v[24:27], v[166:169], v[202:205], v[24:27]
	v_mfma_f32_16x16x32_bf16 v[12:15], v[156:159], v[210:213], v[12:15]
	v_mfma_f32_16x16x32_bf16 v[8:11], v[166:169], v[210:213], v[8:11]
	s_barrier
	s_add_u32 s50, s20, 0x40000
	s_addc_u32 s51, s21, 0
	s_add_i32 s49, s43, s30
	v_lshl_add_u64 v[144:145], s[50:51], 0, v[130:131]
	s_mov_b32 m0, s49
	s_nop 0
	global_load_lds_dwordx4 v[144:145], off
	v_lshl_add_u64 v[144:145], s[50:51], 0, v[134:135]
	s_add_i32 m0, s49, 0x2000
	s_nop 0
	global_load_lds_dwordx4 v[144:145], off
	s_waitcnt vmcnt(6)
	s_barrier
	v_mfma_f32_16x16x32_bf16 v[52:55], v[214:217], v[170:173], v[52:55]
	v_mfma_f32_16x16x32_bf16 v[48:51], v[222:225], v[170:173], v[48:51]
	v_mfma_f32_16x16x32_bf16 v[36:39], v[214:217], v[190:193], v[36:39]
	v_mfma_f32_16x16x32_bf16 v[32:35], v[222:225], v[190:193], v[32:35]
	v_mfma_f32_16x16x32_bf16 v[20:23], v[214:217], v[198:201], v[20:23]
	v_mfma_f32_16x16x32_bf16 v[16:19], v[222:225], v[198:201], v[16:19]
	v_mfma_f32_16x16x32_bf16 v[4:7], v[214:217], v[206:209], v[4:7]
	v_mfma_f32_16x16x32_bf16 v[0:3], v[222:225], v[206:209], v[0:3]
	v_mfma_f32_16x16x32_bf16 v[52:55], v[218:221], v[182:185], v[52:55]
	v_mfma_f32_16x16x32_bf16 v[48:51], v[226:229], v[182:185], v[48:51]
	v_mfma_f32_16x16x32_bf16 v[36:39], v[218:221], v[194:197], v[36:39]
	v_mfma_f32_16x16x32_bf16 v[32:35], v[226:229], v[194:197], v[32:35]
	v_mfma_f32_16x16x32_bf16 v[20:23], v[218:221], v[202:205], v[20:23]
	v_mfma_f32_16x16x32_bf16 v[16:19], v[226:229], v[202:205], v[16:19]
	v_mfma_f32_16x16x32_bf16 v[4:7], v[218:221], v[210:213], v[4:7]
	v_mfma_f32_16x16x32_bf16 v[0:3], v[226:229], v[210:213], v[0:3]
	s_add_i32 s49, 0, 0x18000
	v_add_u32_e32 v155, s49, v149
	s_barrier
	ds_read_b128 v[144:147], v155
	ds_read_b128 v[156:159], v155 offset:1024
	ds_read_b128 v[160:163], v155 offset:2048
	ds_read_b128 v[166:169], v155 offset:3072
	s_add_u32 s22, s22, 0x40000
	s_addc_u32 s23, s23, 0
	s_mov_b32 m0, s34
	v_lshl_add_u64 v[214:215], s[22:23], 0, v[128:129]
	ds_read_b128 v[170:173], v153 offset:32768
	ds_read_b128 v[182:185], v153 offset:33792
	ds_read_b128 v[190:193], v153 offset:34816
	ds_read_b128 v[194:197], v153 offset:35840
	ds_read_b128 v[198:201], v153 offset:36864
	ds_read_b128 v[202:205], v153 offset:37888
	ds_read_b128 v[206:209], v153 offset:38912
	ds_read_b128 v[210:213], v153 offset:39936
	global_load_lds_dwordx4 v[214:215], off
	v_lshl_add_u64 v[214:215], s[22:23], 0, v[132:133]
	s_mov_b32 m0, s35
	s_nop 0
	global_load_lds_dwordx4 v[214:215], off
	s_waitcnt lgkmcnt(8)
	s_barrier
	s_waitcnt lgkmcnt(0)
	s_waitcnt lgkmcnt(0)
	v_mfma_f32_16x16x32_bf16 v[124:127], v[144:147], v[170:173], v[124:127]
	v_mfma_f32_16x16x32_bf16 v[120:123], v[160:163], v[170:173], v[120:123]
	v_mfma_f32_16x16x32_bf16 v[108:111], v[144:147], v[190:193], v[108:111]
	v_mfma_f32_16x16x32_bf16 v[104:107], v[160:163], v[190:193], v[104:107]
	v_mfma_f32_16x16x32_bf16 v[92:95], v[144:147], v[198:201], v[92:95]
	v_mfma_f32_16x16x32_bf16 v[88:91], v[160:163], v[198:201], v[88:91]
	v_mfma_f32_16x16x32_bf16 v[76:79], v[144:147], v[206:209], v[76:79]
	v_mfma_f32_16x16x32_bf16 v[72:75], v[160:163], v[206:209], v[72:75]
	v_mfma_f32_16x16x32_bf16 v[124:127], v[156:159], v[182:185], v[124:127]
	v_mfma_f32_16x16x32_bf16 v[120:123], v[166:169], v[182:185], v[120:123]
	v_mfma_f32_16x16x32_bf16 v[108:111], v[156:159], v[194:197], v[108:111]
	v_mfma_f32_16x16x32_bf16 v[104:107], v[166:169], v[194:197], v[104:107]
	v_mfma_f32_16x16x32_bf16 v[92:95], v[156:159], v[202:205], v[92:95]
	v_mfma_f32_16x16x32_bf16 v[88:91], v[166:169], v[202:205], v[88:91]
	v_mfma_f32_16x16x32_bf16 v[76:79], v[156:159], v[210:213], v[76:79]
	v_mfma_f32_16x16x32_bf16 v[72:75], v[166:169], v[210:213], v[72:75]
	s_barrier
	s_add_i32 s22, 0, 0x1c000
	s_add_i32 s23, s49, s30
	v_add_u32_e32 v155, s22, v149
	v_lshl_add_u64 v[174:175], v[174:175], 0, s[6:7]
	s_mov_b32 m0, s23
	ds_read_b128 v[214:217], v155
	ds_read_b128 v[218:221], v155 offset:1024
	ds_read_b128 v[222:225], v155 offset:2048
	ds_read_b128 v[226:229], v155 offset:3072
	global_load_lds_dwordx4 v[174:175], off
	v_lshl_add_u64 v[174:175], v[186:187], 0, s[6:7]
	s_add_i32 m0, s23, 0x2000
	s_nop 0
	global_load_lds_dwordx4 v[174:175], off
	s_barrier
	s_waitcnt lgkmcnt(0)
	s_waitcnt lgkmcnt(0)
	v_mfma_f32_16x16x32_bf16 v[116:119], v[214:217], v[170:173], v[116:119]
	v_mfma_f32_16x16x32_bf16 v[112:115], v[222:225], v[170:173], v[112:115]
	v_mfma_f32_16x16x32_bf16 v[100:103], v[214:217], v[190:193], v[100:103]
	v_mfma_f32_16x16x32_bf16 v[96:99], v[222:225], v[190:193], v[96:99]
	v_mfma_f32_16x16x32_bf16 v[84:87], v[214:217], v[198:201], v[84:87]
	v_mfma_f32_16x16x32_bf16 v[80:83], v[222:225], v[198:201], v[80:83]
	v_mfma_f32_16x16x32_bf16 v[68:71], v[214:217], v[206:209], v[68:71]
	v_mfma_f32_16x16x32_bf16 v[64:67], v[222:225], v[206:209], v[64:67]
	v_mfma_f32_16x16x32_bf16 v[116:119], v[218:221], v[182:185], v[116:119]
	v_mfma_f32_16x16x32_bf16 v[112:115], v[226:229], v[182:185], v[112:115]
	v_mfma_f32_16x16x32_bf16 v[100:103], v[218:221], v[194:197], v[100:103]
	v_mfma_f32_16x16x32_bf16 v[96:99], v[226:229], v[194:197], v[96:99]
	v_mfma_f32_16x16x32_bf16 v[84:87], v[218:221], v[202:205], v[84:87]
	v_mfma_f32_16x16x32_bf16 v[80:83], v[226:229], v[202:205], v[80:83]
	v_mfma_f32_16x16x32_bf16 v[68:71], v[218:221], v[210:213], v[68:71]
	v_mfma_f32_16x16x32_bf16 v[64:67], v[226:229], v[210:213], v[64:67]
	s_mov_b32 m0, s37
	v_lshl_add_u64 v[174:175], v[230:231], 0, s[6:7]
	s_barrier
	ds_read_b128 v[170:173], v153 offset:49152
	ds_read_b128 v[182:185], v153 offset:50176
	ds_read_b128 v[190:193], v153 offset:51200
	ds_read_b128 v[194:197], v153 offset:52224
	ds_read_b128 v[198:201], v153 offset:53248
	ds_read_b128 v[202:205], v153 offset:54272
	ds_read_b128 v[206:209], v153 offset:55296
	ds_read_b128 v[210:213], v153 offset:56320
	global_load_lds_dwordx4 v[174:175], off
	v_lshl_add_u64 v[174:175], v[232:233], 0, s[6:7]
	s_mov_b32 m0, s38
	s_nop 0
	global_load_lds_dwordx4 v[174:175], off
	s_barrier
	s_waitcnt lgkmcnt(0)
	s_waitcnt lgkmcnt(0)
	v_mfma_f32_16x16x32_bf16 v[60:63], v[144:147], v[170:173], v[60:63]
	v_mfma_f32_16x16x32_bf16 v[56:59], v[160:163], v[170:173], v[56:59]
	v_mfma_f32_16x16x32_bf16 v[44:47], v[144:147], v[190:193], v[44:47]
	v_mfma_f32_16x16x32_bf16 v[40:43], v[160:163], v[190:193], v[40:43]
	v_mfma_f32_16x16x32_bf16 v[28:31], v[144:147], v[198:201], v[28:31]
	v_mfma_f32_16x16x32_bf16 v[24:27], v[160:163], v[198:201], v[24:27]
	v_mfma_f32_16x16x32_bf16 v[12:15], v[144:147], v[206:209], v[12:15]
	v_mfma_f32_16x16x32_bf16 v[8:11], v[160:163], v[206:209], v[8:11]
	v_mfma_f32_16x16x32_bf16 v[60:63], v[156:159], v[182:185], v[60:63]
	v_mfma_f32_16x16x32_bf16 v[56:59], v[166:169], v[182:185], v[56:59]
	v_mfma_f32_16x16x32_bf16 v[44:47], v[156:159], v[194:197], v[44:47]
	v_mfma_f32_16x16x32_bf16 v[40:43], v[166:169], v[194:197], v[40:43]
	v_mfma_f32_16x16x32_bf16 v[28:31], v[156:159], v[202:205], v[28:31]
	v_mfma_f32_16x16x32_bf16 v[24:27], v[166:169], v[202:205], v[24:27]
	v_mfma_f32_16x16x32_bf16 v[12:15], v[156:159], v[210:213], v[12:15]
	v_mfma_f32_16x16x32_bf16 v[8:11], v[166:169], v[210:213], v[8:11]
	s_barrier
	s_add_u32 s20, s20, 0x40080
	s_addc_u32 s21, s21, 0
	s_add_i32 s22, s22, s30
	v_lshl_add_u64 v[144:145], s[20:21], 0, v[130:131]
	s_mov_b32 m0, s22
	s_nop 0
	global_load_lds_dwordx4 v[144:145], off
	v_lshl_add_u64 v[144:145], s[20:21], 0, v[134:135]
	s_add_i32 m0, s22, 0x2000
	s_nop 0
	global_load_lds_dwordx4 v[144:145], off
	s_waitcnt vmcnt(6)
	s_barrier
	v_mfma_f32_16x16x32_bf16 v[52:55], v[214:217], v[170:173], v[52:55]
	v_mfma_f32_16x16x32_bf16 v[48:51], v[222:225], v[170:173], v[48:51]
	v_mfma_f32_16x16x32_bf16 v[36:39], v[214:217], v[190:193], v[36:39]
	v_mfma_f32_16x16x32_bf16 v[32:35], v[222:225], v[190:193], v[32:35]
	v_mfma_f32_16x16x32_bf16 v[20:23], v[214:217], v[198:201], v[20:23]
	v_mfma_f32_16x16x32_bf16 v[16:19], v[222:225], v[198:201], v[16:19]
	v_mfma_f32_16x16x32_bf16 v[4:7], v[214:217], v[206:209], v[4:7]
	v_mfma_f32_16x16x32_bf16 v[0:3], v[222:225], v[206:209], v[0:3]
	v_mfma_f32_16x16x32_bf16 v[52:55], v[218:221], v[182:185], v[52:55]
	v_mfma_f32_16x16x32_bf16 v[48:51], v[226:229], v[182:185], v[48:51]
	v_mfma_f32_16x16x32_bf16 v[36:39], v[218:221], v[194:197], v[36:39]
	v_mfma_f32_16x16x32_bf16 v[32:35], v[226:229], v[194:197], v[32:35]
	v_mfma_f32_16x16x32_bf16 v[20:23], v[218:221], v[202:205], v[20:23]
	v_mfma_f32_16x16x32_bf16 v[16:19], v[226:229], v[202:205], v[16:19]
	v_mfma_f32_16x16x32_bf16 v[4:7], v[218:221], v[210:213], v[4:7]
	v_mfma_f32_16x16x32_bf16 v[0:3], v[226:229], v[210:213], v[0:3]
	s_add_i32 s48, s48, 2
	s_add_u32 s18, s18, 0x100
	s_addc_u32 s19, s19, 0
	s_add_u32 s46, s46, 0x100
	s_addc_u32 s47, s47, 0
	s_cmp_gt_u32 s48, 13
	s_barrier
	s_cbranch_scc0 .LBB0_724
	s_cmp_gt_i32 s4, 5
	s_cselect_b64 s[18:19], -1, 0
	s_cmp_lt_i32 s4, 6
	v_pk_add_f32 v[144:145], v[126:127], 0 op_sel_hi:[1,0]
	v_pk_add_f32 v[146:147], v[124:125], 0 op_sel_hi:[1,0]
	v_pk_add_f32 v[124:125], v[122:123], 0 op_sel_hi:[1,0]
	v_pk_add_f32 v[126:127], v[120:121], 0 op_sel_hi:[1,0]
	s_cbranch_scc1 .LBB0_727
	v_max_f32_e32 v122, v144, v144
	v_max_f32_e32 v122, 0xc1a00000, v122
	v_mul_f32_e32 v122, 0xbfb8aa3b, v122
	v_max_f32_e32 v120, v146, v146
	v_max_f32_e32 v121, v147, v147
	v_exp_f32_e32 v123, v122
	v_max_f32_e32 v122, v145, v145
	v_max_f32_e32 v120, 0xc1a00000, v120
	v_max_f32_e32 v121, 0xc1a00000, v121
	v_max_f32_e32 v122, 0xc1a00000, v122
	v_mul_f32_e32 v120, 0xbfb8aa3b, v120
	v_mul_f32_e32 v121, 0xbfb8aa3b, v121
	v_mul_f32_e32 v122, 0xbfb8aa3b, v122
	v_exp_f32_e32 v120, v120
	v_exp_f32_e32 v121, v121
	v_exp_f32_e32 v122, v122
	v_max_f32_e32 v124, v124, v124
	v_max_f32_e32 v124, 0xc1a00000, v124
	v_pk_add_f32 v[120:121], v[120:121], 1.0 op_sel_hi:[1,0]
	v_pk_add_f32 v[122:123], v[122:123], 1.0 op_sel_hi:[1,0]
	v_mov_b32_e32 v144, v120
	v_mov_b32_e32 v145, v123
	v_pk_mov_b32 v[146:147], v[120:121], v[122:123] op_sel:[1,0]
	v_mul_f32_e32 v124, 0xbfb8aa3b, v124
	v_pk_mul_f32 v[144:145], v[144:145], v[146:147]
	v_max_f32_e32 v126, v126, v126
	v_max_f32_e32 v127, v127, v127
	v_exp_f32_e32 v147, v124
	v_max_f32_e32 v124, v125, v125
	v_max_f32_e32 v126, 0xc1a00000, v126
	v_max_f32_e32 v127, 0xc1a00000, v127
	v_max_f32_e32 v124, 0xc1a00000, v124
	v_mul_f32_e32 v146, v144, v145
	v_mul_f32_e32 v126, 0xbfb8aa3b, v126
	v_mul_f32_e32 v127, 0xbfb8aa3b, v127
	v_mul_f32_e32 v124, 0xbfb8aa3b, v124
	v_rcp_f32_e32 v155, v146
	v_exp_f32_e32 v126, v126
	v_exp_f32_e32 v127, v127
	v_exp_f32_e32 v146, v124
	v_mul_f32_e32 v124, v145, v155
	v_mul_f32_e32 v144, v144, v155
	v_pk_add_f32 v[126:127], v[126:127], 1.0 op_sel_hi:[1,0]
	v_pk_add_f32 v[156:157], v[146:147], 1.0 op_sel_hi:[1,0]
	v_mov_b32_e32 v146, v126
	v_mov_b32_e32 v147, v157
	v_pk_mov_b32 v[158:159], v[126:127], v[156:157] op_sel:[1,0]
	v_pk_mul_f32 v[144:145], v[122:123], v[144:145] op_sel_hi:[1,0]
	v_pk_mul_f32 v[158:159], v[146:147], v[158:159]
	s_nop 0
	v_mul_f32_e32 v125, v158, v159
	v_rcp_f32_e32 v125, v125
	s_nop 0
	v_pk_mul_f32 v[146:147], v[120:121], v[124:125] op_sel:[1,0] op_sel_hi:[0,0]
	v_mul_f32_e32 v120, v159, v125
	v_mul_f32_e32 v122, v158, v125
	v_pk_mul_f32 v[124:125], v[156:157], v[122:123] op_sel_hi:[1,0]
	v_pk_mul_f32 v[126:127], v[126:127], v[120:121] op_sel:[1,0] op_sel_hi:[0,0]

.LBB0_991:
	ds_read_b128 v[144:147], v153
	ds_read_b128 v[156:159], v153 offset:1024
	ds_read_b128 v[160:163], v153 offset:2048
	ds_read_b128 v[164:167], v153 offset:3072
	s_add_u32 s20, s18, 0xfffc0080
	s_addc_u32 s21, s19, -1
	s_cmp_eq_u32 s47, 12
	s_cselect_b32 s23, s11, s21
	s_cselect_b32 s22, s43, s20
	s_cselect_b32 s21, s9, s46
	s_cselect_b32 s20, s44, s45
	v_lshl_add_u64 v[148:149], s[18:19], 0, v[136:137]
	s_add_i32 m0, s17, 0xc000
	ds_read_b128 v[168:171], v154
	ds_read_b128 v[172:175], v154 offset:1024
	ds_read_b128 v[182:185], v154 offset:2048
	ds_read_b128 v[190:193], v154 offset:3072
	ds_read_b128 v[194:197], v154 offset:4096
	ds_read_b128 v[198:201], v154 offset:5120
	ds_read_b128 v[202:205], v154 offset:6144
	ds_read_b128 v[206:209], v154 offset:7168
	global_load_lds_dwordx4 v[148:149], off
	v_lshl_add_u64 v[148:149], s[18:19], 0, v[138:139]
	s_add_i32 m0, s17, 0xe000
	s_nop 0
	global_load_lds_dwordx4 v[148:149], off
	s_waitcnt lgkmcnt(8)
	s_barrier
	s_waitcnt lgkmcnt(0)
	s_waitcnt lgkmcnt(0)
	v_mfma_f32_16x16x32_bf16 v[124:127], v[144:147], v[168:171], v[124:127]
	v_mfma_f32_16x16x32_bf16 v[120:123], v[160:163], v[168:171], v[120:123]
	v_mfma_f32_16x16x32_bf16 v[112:115], v[144:147], v[182:185], v[112:115]
	v_mfma_f32_16x16x32_bf16 v[104:107], v[160:163], v[182:185], v[104:107]
	v_mfma_f32_16x16x32_bf16 v[96:99], v[144:147], v[194:197], v[96:99]
	v_mfma_f32_16x16x32_bf16 v[88:91], v[160:163], v[194:197], v[88:91]
	v_mfma_f32_16x16x32_bf16 v[80:83], v[144:147], v[202:205], v[80:83]
	v_mfma_f32_16x16x32_bf16 v[72:75], v[160:163], v[202:205], v[72:75]
	v_mfma_f32_16x16x32_bf16 v[124:127], v[156:159], v[172:175], v[124:127]
	v_mfma_f32_16x16x32_bf16 v[120:123], v[164:167], v[172:175], v[120:123]
	v_mfma_f32_16x16x32_bf16 v[112:115], v[156:159], v[190:193], v[112:115]
	v_mfma_f32_16x16x32_bf16 v[104:107], v[164:167], v[190:193], v[104:107]
	v_mfma_f32_16x16x32_bf16 v[96:99], v[156:159], v[198:201], v[96:99]
	v_mfma_f32_16x16x32_bf16 v[88:91], v[164:167], v[198:201], v[88:91]
	v_mfma_f32_16x16x32_bf16 v[80:83], v[156:159], v[206:209], v[80:83]
	v_mfma_f32_16x16x32_bf16 v[72:75], v[164:167], v[206:209], v[72:75]
	s_barrier
	s_add_i32 s48, s39, s29
	v_lshl_add_u64 v[148:149], s[20:21], 0, v[130:131]
	s_mov_b32 m0, s48
	ds_read_b128 v[210:213], v155
	ds_read_b128 v[214:217], v155 offset:1024
	ds_read_b128 v[218:221], v155 offset:2048
	ds_read_b128 v[222:225], v155 offset:3072
	global_load_lds_dwordx4 v[148:149], off
	v_lshl_add_u64 v[186:187], s[20:21], 0, v[134:135]
	s_add_i32 m0, s48, 0x2000
	s_nop 0
	global_load_lds_dwordx4 v[186:187], off
	s_barrier
	s_waitcnt lgkmcnt(0)
	s_waitcnt lgkmcnt(0)
	v_mfma_f32_16x16x32_bf16 v[116:119], v[210:213], v[168:171], v[116:119]
	v_mfma_f32_16x16x32_bf16 v[108:111], v[218:221], v[168:171], v[108:111]
	v_mfma_f32_16x16x32_bf16 v[100:103], v[210:213], v[182:185], v[100:103]
	v_mfma_f32_16x16x32_bf16 v[92:95], v[218:221], v[182:185], v[92:95]
	v_mfma_f32_16x16x32_bf16 v[84:87], v[210:213], v[194:197], v[84:87]
	v_mfma_f32_16x16x32_bf16 v[76:79], v[218:221], v[194:197], v[76:79]
	v_mfma_f32_16x16x32_bf16 v[68:71], v[210:213], v[202:205], v[68:71]
	v_mfma_f32_16x16x32_bf16 v[64:67], v[218:221], v[202:205], v[64:67]
	v_mfma_f32_16x16x32_bf16 v[116:119], v[214:217], v[172:175], v[116:119]
	v_mfma_f32_16x16x32_bf16 v[108:111], v[222:225], v[172:175], v[108:111]
	v_mfma_f32_16x16x32_bf16 v[100:103], v[214:217], v[190:193], v[100:103]
	v_mfma_f32_16x16x32_bf16 v[92:95], v[222:225], v[190:193], v[92:95]
	v_mfma_f32_16x16x32_bf16 v[84:87], v[214:217], v[198:201], v[84:87]
	v_mfma_f32_16x16x32_bf16 v[76:79], v[222:225], v[198:201], v[76:79]
	v_mfma_f32_16x16x32_bf16 v[68:71], v[214:217], v[206:209], v[68:71]
	v_mfma_f32_16x16x32_bf16 v[64:67], v[222:225], v[206:209], v[64:67]
	s_mov_b32 m0, s17
	v_lshl_add_u64 v[226:227], s[22:23], 0, v[128:129]
	s_barrier
	ds_read_b128 v[168:171], v154 offset:16384
	ds_read_b128 v[172:175], v154 offset:17408
	ds_read_b128 v[182:185], v154 offset:18432
	ds_read_b128 v[190:193], v154 offset:19456
	ds_read_b128 v[194:197], v154 offset:20480
	ds_read_b128 v[198:201], v154 offset:21504
	ds_read_b128 v[202:205], v154 offset:22528
	ds_read_b128 v[206:209], v154 offset:23552
	global_load_lds_dwordx4 v[226:227], off
	v_lshl_add_u64 v[228:229], s[22:23], 0, v[132:133]
	s_mov_b32 m0, s30
	s_nop 0
	global_load_lds_dwordx4 v[228:229], off
	s_barrier
	s_waitcnt lgkmcnt(0)
	s_waitcnt lgkmcnt(0)
	v_mfma_f32_16x16x32_bf16 v[60:63], v[144:147], v[168:171], v[60:63]
	v_mfma_f32_16x16x32_bf16 v[56:59], v[160:163], v[168:171], v[56:59]
	v_mfma_f32_16x16x32_bf16 v[48:51], v[144:147], v[182:185], v[48:51]
	v_mfma_f32_16x16x32_bf16 v[40:43], v[160:163], v[182:185], v[40:43]
	v_mfma_f32_16x16x32_bf16 v[32:35], v[144:147], v[194:197], v[32:35]
	v_mfma_f32_16x16x32_bf16 v[24:27], v[160:163], v[194:197], v[24:27]
	v_mfma_f32_16x16x32_bf16 v[16:19], v[144:147], v[202:205], v[16:19]
	v_mfma_f32_16x16x32_bf16 v[8:11], v[160:163], v[202:205], v[8:11]
	v_mfma_f32_16x16x32_bf16 v[60:63], v[156:159], v[172:175], v[60:63]
	v_mfma_f32_16x16x32_bf16 v[56:59], v[164:167], v[172:175], v[56:59]
	v_mfma_f32_16x16x32_bf16 v[48:51], v[156:159], v[190:193], v[48:51]
	v_mfma_f32_16x16x32_bf16 v[40:43], v[164:167], v[190:193], v[40:43]
	v_mfma_f32_16x16x32_bf16 v[32:35], v[156:159], v[198:201], v[32:35]
	v_mfma_f32_16x16x32_bf16 v[24:27], v[164:167], v[198:201], v[24:27]
	v_mfma_f32_16x16x32_bf16 v[16:19], v[156:159], v[206:209], v[16:19]
	v_mfma_f32_16x16x32_bf16 v[8:11], v[164:167], v[206:209], v[8:11]
	s_barrier
	s_add_u32 s48, s20, 0x40000
	s_addc_u32 s49, s21, 0
	s_add_i32 s50, s40, s29
	v_lshl_add_u64 v[144:145], s[48:49], 0, v[130:131]
	s_mov_b32 m0, s50
	s_nop 0
	global_load_lds_dwordx4 v[144:145], off
	v_lshl_add_u64 v[144:145], s[48:49], 0, v[134:135]
	s_add_i32 m0, s50, 0x2000
	s_nop 0
	global_load_lds_dwordx4 v[144:145], off
	s_waitcnt vmcnt(6)
	s_barrier
	v_mfma_f32_16x16x32_bf16 v[52:55], v[210:213], v[168:171], v[52:55]
	v_mfma_f32_16x16x32_bf16 v[44:47], v[218:221], v[168:171], v[44:47]
	v_mfma_f32_16x16x32_bf16 v[36:39], v[210:213], v[182:185], v[36:39]
	v_mfma_f32_16x16x32_bf16 v[28:31], v[218:221], v[182:185], v[28:31]
	v_mfma_f32_16x16x32_bf16 v[20:23], v[210:213], v[194:197], v[20:23]
	v_mfma_f32_16x16x32_bf16 v[12:15], v[218:221], v[194:197], v[12:15]
	v_mfma_f32_16x16x32_bf16 v[4:7], v[210:213], v[202:205], v[4:7]
	v_mfma_f32_16x16x32_bf16 v[0:3], v[218:221], v[202:205], v[0:3]
	v_mfma_f32_16x16x32_bf16 v[52:55], v[214:217], v[172:175], v[52:55]
	v_mfma_f32_16x16x32_bf16 v[44:47], v[222:225], v[172:175], v[44:47]
	v_mfma_f32_16x16x32_bf16 v[36:39], v[214:217], v[190:193], v[36:39]
	v_mfma_f32_16x16x32_bf16 v[28:31], v[222:225], v[190:193], v[28:31]
	v_mfma_f32_16x16x32_bf16 v[20:23], v[214:217], v[198:201], v[20:23]
	v_mfma_f32_16x16x32_bf16 v[12:15], v[222:225], v[198:201], v[12:15]
	v_mfma_f32_16x16x32_bf16 v[4:7], v[214:217], v[206:209], v[4:7]
	v_mfma_f32_16x16x32_bf16 v[0:3], v[222:225], v[206:209], v[0:3]
	s_add_i32 s48, 0, 0x18000
	v_add_u32_e32 v164, s48, v151
	s_barrier
	ds_read_b128 v[144:147], v164
	ds_read_b128 v[156:159], v164 offset:1024
	ds_read_b128 v[160:163], v164 offset:2048
	ds_read_b128 v[164:167], v164 offset:3072
	s_add_u32 s22, s22, 0x40000
	s_addc_u32 s23, s23, 0
	s_mov_b32 m0, s31
	v_lshl_add_u64 v[210:211], s[22:23], 0, v[128:129]
	ds_read_b128 v[168:171], v154 offset:32768
	ds_read_b128 v[172:175], v154 offset:33792
	ds_read_b128 v[182:185], v154 offset:34816
	ds_read_b128 v[190:193], v154 offset:35840
	ds_read_b128 v[194:197], v154 offset:36864
	ds_read_b128 v[198:201], v154 offset:37888
	ds_read_b128 v[202:205], v154 offset:38912
	ds_read_b128 v[206:209], v154 offset:39936
	global_load_lds_dwordx4 v[210:211], off
	v_lshl_add_u64 v[210:211], s[22:23], 0, v[132:133]
	s_mov_b32 m0, s34
	s_nop 0
	global_load_lds_dwordx4 v[210:211], off
	s_waitcnt lgkmcnt(8)
	s_barrier
	s_waitcnt lgkmcnt(0)
	s_waitcnt lgkmcnt(0)
	v_mfma_f32_16x16x32_bf16 v[124:127], v[144:147], v[168:171], v[124:127]
	v_mfma_f32_16x16x32_bf16 v[120:123], v[160:163], v[168:171], v[120:123]
	v_mfma_f32_16x16x32_bf16 v[112:115], v[144:147], v[182:185], v[112:115]
	v_mfma_f32_16x16x32_bf16 v[104:107], v[160:163], v[182:185], v[104:107]
	v_mfma_f32_16x16x32_bf16 v[96:99], v[144:147], v[194:197], v[96:99]
	v_mfma_f32_16x16x32_bf16 v[88:91], v[160:163], v[194:197], v[88:91]
	v_mfma_f32_16x16x32_bf16 v[80:83], v[144:147], v[202:205], v[80:83]
	v_mfma_f32_16x16x32_bf16 v[72:75], v[160:163], v[202:205], v[72:75]
	v_mfma_f32_16x16x32_bf16 v[124:127], v[156:159], v[172:175], v[124:127]
	v_mfma_f32_16x16x32_bf16 v[120:123], v[164:167], v[172:175], v[120:123]
	v_mfma_f32_16x16x32_bf16 v[112:115], v[156:159], v[190:193], v[112:115]
	v_mfma_f32_16x16x32_bf16 v[104:107], v[164:167], v[190:193], v[104:107]
	v_mfma_f32_16x16x32_bf16 v[96:99], v[156:159], v[198:201], v[96:99]
	v_mfma_f32_16x16x32_bf16 v[88:91], v[164:167], v[198:201], v[88:91]
	v_mfma_f32_16x16x32_bf16 v[80:83], v[156:159], v[206:209], v[80:83]
	v_mfma_f32_16x16x32_bf16 v[72:75], v[164:167], v[206:209], v[72:75]
	s_barrier
	s_add_i32 s22, 0, 0x1c000
	s_add_i32 s23, s48, s29
	v_add_u32_e32 v179, s22, v151
	v_lshl_add_u64 v[148:149], v[148:149], 0, s[6:7]
	s_mov_b32 m0, s23
	ds_read_b128 v[210:213], v179
	ds_read_b128 v[214:217], v179 offset:1024
	ds_read_b128 v[218:221], v179 offset:2048
	ds_read_b128 v[222:225], v179 offset:3072
	global_load_lds_dwordx4 v[148:149], off
	v_lshl_add_u64 v[148:149], v[186:187], 0, s[6:7]
	s_add_i32 m0, s23, 0x2000
	s_nop 0
	global_load_lds_dwordx4 v[148:149], off
	s_barrier
	s_waitcnt lgkmcnt(0)
	s_waitcnt lgkmcnt(0)
	v_mfma_f32_16x16x32_bf16 v[116:119], v[210:213], v[168:171], v[116:119]
	v_mfma_f32_16x16x32_bf16 v[108:111], v[218:221], v[168:171], v[108:111]
	v_mfma_f32_16x16x32_bf16 v[100:103], v[210:213], v[182:185], v[100:103]
	v_mfma_f32_16x16x32_bf16 v[92:95], v[218:221], v[182:185], v[92:95]
	v_mfma_f32_16x16x32_bf16 v[84:87], v[210:213], v[194:197], v[84:87]
	v_mfma_f32_16x16x32_bf16 v[76:79], v[218:221], v[194:197], v[76:79]
	v_mfma_f32_16x16x32_bf16 v[68:71], v[210:213], v[202:205], v[68:71]
	v_mfma_f32_16x16x32_bf16 v[64:67], v[218:221], v[202:205], v[64:67]
	v_mfma_f32_16x16x32_bf16 v[116:119], v[214:217], v[172:175], v[116:119]
	v_mfma_f32_16x16x32_bf16 v[108:111], v[222:225], v[172:175], v[108:111]
	v_mfma_f32_16x16x32_bf16 v[100:103], v[214:217], v[190:193], v[100:103]
	v_mfma_f32_16x16x32_bf16 v[92:95], v[222:225], v[190:193], v[92:95]
	v_mfma_f32_16x16x32_bf16 v[84:87], v[214:217], v[198:201], v[84:87]
	v_mfma_f32_16x16x32_bf16 v[76:79], v[222:225], v[198:201], v[76:79]
	v_mfma_f32_16x16x32_bf16 v[68:71], v[214:217], v[206:209], v[68:71]
	v_mfma_f32_16x16x32_bf16 v[64:67], v[222:225], v[206:209], v[64:67]
	s_mov_b32 m0, s36
	v_lshl_add_u64 v[148:149], v[226:227], 0, s[6:7]
	s_barrier
	ds_read_b128 v[168:171], v154 offset:49152
	ds_read_b128 v[172:175], v154 offset:50176
	ds_read_b128 v[182:185], v154 offset:51200
	ds_read_b128 v[190:193], v154 offset:52224
	ds_read_b128 v[194:197], v154 offset:53248
	ds_read_b128 v[198:201], v154 offset:54272
	ds_read_b128 v[202:205], v154 offset:55296
	ds_read_b128 v[206:209], v154 offset:56320
	global_load_lds_dwordx4 v[148:149], off
	v_lshl_add_u64 v[148:149], v[228:229], 0, s[6:7]
	s_mov_b32 m0, s37
	s_nop 0
	global_load_lds_dwordx4 v[148:149], off
	s_barrier
	s_waitcnt lgkmcnt(0)
	s_waitcnt lgkmcnt(0)
	v_mfma_f32_16x16x32_bf16 v[60:63], v[144:147], v[168:171], v[60:63]
	v_mfma_f32_16x16x32_bf16 v[56:59], v[160:163], v[168:171], v[56:59]
	v_mfma_f32_16x16x32_bf16 v[48:51], v[144:147], v[182:185], v[48:51]
	v_mfma_f32_16x16x32_bf16 v[40:43], v[160:163], v[182:185], v[40:43]
	v_mfma_f32_16x16x32_bf16 v[32:35], v[144:147], v[194:197], v[32:35]
	v_mfma_f32_16x16x32_bf16 v[24:27], v[160:163], v[194:197], v[24:27]
	v_mfma_f32_16x16x32_bf16 v[16:19], v[144:147], v[202:205], v[16:19]
	v_mfma_f32_16x16x32_bf16 v[8:11], v[160:163], v[202:205], v[8:11]
	v_mfma_f32_16x16x32_bf16 v[60:63], v[156:159], v[172:175], v[60:63]
	v_mfma_f32_16x16x32_bf16 v[56:59], v[164:167], v[172:175], v[56:59]
	v_mfma_f32_16x16x32_bf16 v[48:51], v[156:159], v[190:193], v[48:51]
	v_mfma_f32_16x16x32_bf16 v[40:43], v[164:167], v[190:193], v[40:43]
	v_mfma_f32_16x16x32_bf16 v[32:35], v[156:159], v[198:201], v[32:35]
	v_mfma_f32_16x16x32_bf16 v[24:27], v[164:167], v[198:201], v[24:27]
	v_mfma_f32_16x16x32_bf16 v[16:19], v[156:159], v[206:209], v[16:19]
	v_mfma_f32_16x16x32_bf16 v[8:11], v[164:167], v[206:209], v[8:11]
	s_barrier
	s_add_u32 s20, s20, 0x40080
	s_addc_u32 s21, s21, 0
	s_add_i32 s22, s22, s29
	v_lshl_add_u64 v[144:145], s[20:21], 0, v[130:131]
	s_mov_b32 m0, s22
	s_nop 0
	global_load_lds_dwordx4 v[144:145], off
	v_lshl_add_u64 v[144:145], s[20:21], 0, v[134:135]
	s_add_i32 m0, s22, 0x2000
	s_nop 0
	global_load_lds_dwordx4 v[144:145], off
	s_waitcnt vmcnt(6)
	s_barrier
	v_mfma_f32_16x16x32_bf16 v[52:55], v[210:213], v[168:171], v[52:55]
	v_mfma_f32_16x16x32_bf16 v[44:47], v[218:221], v[168:171], v[44:47]
	v_mfma_f32_16x16x32_bf16 v[36:39], v[210:213], v[182:185], v[36:39]
	v_mfma_f32_16x16x32_bf16 v[28:31], v[218:221], v[182:185], v[28:31]
	v_mfma_f32_16x16x32_bf16 v[20:23], v[210:213], v[194:197], v[20:23]
	v_mfma_f32_16x16x32_bf16 v[12:15], v[218:221], v[194:197], v[12:15]
	v_mfma_f32_16x16x32_bf16 v[4:7], v[210:213], v[202:205], v[4:7]
	v_mfma_f32_16x16x32_bf16 v[0:3], v[218:221], v[202:205], v[0:3]
	v_mfma_f32_16x16x32_bf16 v[52:55], v[214:217], v[172:175], v[52:55]
	v_mfma_f32_16x16x32_bf16 v[44:47], v[222:225], v[172:175], v[44:47]
	v_mfma_f32_16x16x32_bf16 v[36:39], v[214:217], v[190:193], v[36:39]
	v_mfma_f32_16x16x32_bf16 v[28:31], v[222:225], v[190:193], v[28:31]
	v_mfma_f32_16x16x32_bf16 v[20:23], v[214:217], v[198:201], v[20:23]
	v_mfma_f32_16x16x32_bf16 v[12:15], v[222:225], v[198:201], v[12:15]
	v_mfma_f32_16x16x32_bf16 v[4:7], v[214:217], v[206:209], v[4:7]
	v_mfma_f32_16x16x32_bf16 v[0:3], v[222:225], v[206:209], v[0:3]
	s_add_i32 s47, s47, 2
	s_add_u32 s18, s18, 0x100
	s_addc_u32 s19, s19, 0
	s_add_u32 s45, s45, 0x100
	s_addc_u32 s46, s46, 0
	s_cmp_gt_u32 s47, 13
	s_barrier
	s_cbranch_scc0 .LBB0_991
	v_lshl_or_b32 v144, s42, 8, v152
	v_lshl_add_u32 v146, s16, 8, v150
	v_ashrrev_i32_e32 v145, 31, v144
	v_mov_b64_e32 v[148:149], s[4:5]
	v_lshlrev_b64 v[144:145], 1, v[144:145]
	v_mad_i64_i32 v[156:157], s[18:19], v146, s41, v[148:149]
	v_lshl_add_u64 v[160:161], v[156:157], 0, v[144:145]
	global_load_dwordx4 v[156:159], v[160:161], off offset:3072
	s_and_b64 vcc, exec, s[2:3]
	s_mov_b32 s42, s8
	s_mov_b32 s16, s10
	s_mov_b64 s[20:21], s[14:15]
	s_waitcnt vmcnt(0)
	v_lshlrev_b32_e32 v147, 16, v156
	v_and_b32_e32 v156, 0xffff0000, v156
	v_lshlrev_b32_e32 v162, 16, v157
	v_and_b32_e32 v157, 0xffff0000, v157
	v_lshlrev_b32_e32 v164, 16, v159
	v_and_b32_e32 v159, 0xffff0000, v159
	v_lshlrev_b32_e32 v163, 16, v158
	v_and_b32_e32 v158, 0xffff0000, v158
	v_mul_f32_e32 v124, v124, v147
	v_mul_f32_e32 v125, v125, v156
	v_mul_f32_e32 v126, v126, v162
	v_mul_f32_e32 v127, v127, v157
	v_mul_f32_e32 v123, v123, v159
	v_mul_f32_e32 v147, v120, v163
	v_mul_f32_e32 v156, v121, v158
	v_mul_f32_e32 v157, v122, v164
	v_cvt_pk_bf16_f32 v120, v124, v125
	v_cvt_pk_bf16_f32 v121, v126, v127
	v_cvt_pk_bf16_f32 v122, v147, v156
	v_cvt_pk_bf16_f32 v123, v157, v123
	global_load_dwordx4 v[124:127], v[160:161], off offset:3328
	v_ashrrev_i32_e32 v147, 31, v146
	v_lshlrev_b64 v[158:159], 11, v[146:147]
	v_lshl_add_u64 v[158:159], s[0:1], 0, v[158:159]
	v_or_b32_e32 v156, 16, v146
	v_lshl_add_u64 v[158:159], v[158:159], 0, v[144:145]
	v_mad_i64_i32 v[160:161], s[18:19], v156, s41, v[148:149]
	global_store_dwordx4 v[158:159], v[120:123], off
	v_lshl_add_u64 v[160:161], v[160:161], 0, v[144:145]
	v_ashrrev_i32_e32 v157, 31, v156
	s_waitcnt vmcnt(0)
	v_lshlrev_b32_e32 v120, 16, v124
	v_and_b32_e32 v121, 0xffff0000, v124
	v_lshlrev_b32_e32 v122, 16, v125
	v_and_b32_e32 v123, 0xffff0000, v125
	v_lshlrev_b32_e32 v124, 16, v126
	v_and_b32_e32 v125, 0xffff0000, v126
	v_lshlrev_b32_e32 v126, 16, v127
	v_and_b32_e32 v127, 0xffff0000, v127
	v_mul_f32_e32 v116, v116, v120
	v_mul_f32_e32 v117, v117, v121
	v_mul_f32_e32 v118, v118, v122
	v_mul_f32_e32 v119, v119, v123
	v_mul_f32_e32 v111, v111, v127
	v_mul_f32_e32 v120, v108, v124
	v_mul_f32_e32 v121, v109, v125
	v_mul_f32_e32 v122, v110, v126
	v_cvt_pk_bf16_f32 v108, v116, v117
	v_cvt_pk_bf16_f32 v109, v118, v119
	v_cvt_pk_bf16_f32 v110, v120, v121
	v_cvt_pk_bf16_f32 v111, v122, v111
	global_load_dwordx4 v[116:119], v[160:161], off offset:3072
	s_nop 0
	global_store_dwordx4 v[158:159], v[108:111], off offset:256
	s_waitcnt vmcnt(0)
	s_nop 0
	v_lshlrev_b32_e32 v108, 16, v116
	v_and_b32_e32 v109, 0xffff0000, v116
	v_lshlrev_b32_e32 v110, 16, v117
	v_and_b32_e32 v111, 0xffff0000, v117
	v_lshlrev_b32_e32 v116, 16, v118
	v_and_b32_e32 v117, 0xffff0000, v118
	v_lshlrev_b32_e32 v118, 16, v119
	v_and_b32_e32 v119, 0xffff0000, v119
	v_mul_f32_e32 v108, v112, v108
	v_mul_f32_e32 v109, v113, v109
	v_mul_f32_e32 v110, v114, v110
	v_mul_f32_e32 v111, v115, v111
	v_mul_f32_e32 v107, v107, v119
	v_mul_f32_e32 v112, v104, v116
	v_mul_f32_e32 v113, v105, v117
	v_mul_f32_e32 v114, v106, v118
	v_cvt_pk_bf16_f32 v104, v108, v109
	v_cvt_pk_bf16_f32 v105, v110, v111
	v_cvt_pk_bf16_f32 v106, v112, v113
	v_cvt_pk_bf16_f32 v107, v114, v107
	global_load_dwordx4 v[108:111], v[160:161], off offset:3328
	v_lshlrev_b64 v[116:117], 11, v[156:157]
	v_lshl_add_u64 v[116:117], s[0:1], 0, v[116:117]
	v_or_b32_e32 v112, 32, v146
	v_lshl_add_u64 v[116:117], v[116:117], 0, v[144:145]
	v_mad_i64_i32 v[114:115], s[18:19], v112, s41, v[148:149]
	global_store_dwordx4 v[116:117], v[104:107], off
	v_lshl_add_u64 v[114:115], v[114:115], 0, v[144:145]
	v_ashrrev_i32_e32 v113, 31, v112
	s_waitcnt vmcnt(0)
	v_lshlrev_b32_e32 v104, 16, v108
	v_and_b32_e32 v105, 0xffff0000, v108
	v_lshlrev_b32_e32 v106, 16, v109
	v_and_b32_e32 v107, 0xffff0000, v109
	v_lshlrev_b32_e32 v108, 16, v110
	v_and_b32_e32 v109, 0xffff0000, v110
	v_lshlrev_b32_e32 v110, 16, v111
	v_and_b32_e32 v111, 0xffff0000, v111
	v_mul_f32_e32 v100, v100, v104
	v_mul_f32_e32 v101, v101, v105
	v_mul_f32_e32 v102, v102, v106
	v_mul_f32_e32 v103, v103, v107
	v_mul_f32_e32 v95, v95, v111
	v_mul_f32_e32 v104, v92, v108
	v_mul_f32_e32 v105, v93, v109
	v_mul_f32_e32 v106, v94, v110
	v_cvt_pk_bf16_f32 v92, v100, v101
	v_cvt_pk_bf16_f32 v93, v102, v103
	v_cvt_pk_bf16_f32 v94, v104, v105
	v_cvt_pk_bf16_f32 v95, v106, v95
	global_load_dwordx4 v[100:103], v[114:115], off offset:3072
	s_nop 0
	global_store_dwordx4 v[116:117], v[92:95], off offset:256
	s_waitcnt vmcnt(0)
	s_nop 0
	v_lshlrev_b32_e32 v92, 16, v100
	v_and_b32_e32 v93, 0xffff0000, v100
	v_lshlrev_b32_e32 v94, 16, v101
	v_and_b32_e32 v95, 0xffff0000, v101
	v_lshlrev_b32_e32 v100, 16, v102
	v_and_b32_e32 v101, 0xffff0000, v102
	v_lshlrev_b32_e32 v102, 16, v103
	v_and_b32_e32 v103, 0xffff0000, v103
	v_mul_f32_e32 v92, v96, v92
	v_mul_f32_e32 v93, v97, v93
	v_mul_f32_e32 v94, v98, v94
	v_mul_f32_e32 v95, v99, v95
	v_mul_f32_e32 v91, v91, v103
	v_mul_f32_e32 v96, v88, v100
	v_mul_f32_e32 v97, v89, v101
	v_mul_f32_e32 v98, v90, v102
	v_cvt_pk_bf16_f32 v88, v92, v93
	v_cvt_pk_bf16_f32 v89, v94, v95
	v_cvt_pk_bf16_f32 v90, v96, v97
	v_cvt_pk_bf16_f32 v91, v98, v91
	global_load_dwordx4 v[92:95], v[114:115], off offset:3328
	v_lshlrev_b64 v[100:101], 11, v[112:113]
	v_lshl_add_u64 v[100:101], s[0:1], 0, v[100:101]
	v_or_b32_e32 v96, 48, v146
	v_lshl_add_u64 v[100:101], v[100:101], 0, v[144:145]
	v_mad_i64_i32 v[98:99], s[18:19], v96, s41, v[148:149]
	global_store_dwordx4 v[100:101], v[88:91], off
	v_lshl_add_u64 v[98:99], v[98:99], 0, v[144:145]
	v_ashrrev_i32_e32 v97, 31, v96
	s_waitcnt vmcnt(0)
	v_lshlrev_b32_e32 v88, 16, v92
	v_and_b32_e32 v89, 0xffff0000, v92
	v_lshlrev_b32_e32 v90, 16, v93
	v_and_b32_e32 v91, 0xffff0000, v93
	v_lshlrev_b32_e32 v92, 16, v94
	v_and_b32_e32 v93, 0xffff0000, v94
	v_lshlrev_b32_e32 v94, 16, v95
	v_and_b32_e32 v95, 0xffff0000, v95
	v_mul_f32_e32 v84, v84, v88
	v_mul_f32_e32 v85, v85, v89
	v_mul_f32_e32 v86, v86, v90
	v_mul_f32_e32 v87, v87, v91
	v_mul_f32_e32 v79, v79, v95
	v_mul_f32_e32 v88, v76, v92
	v_mul_f32_e32 v89, v77, v93
	v_mul_f32_e32 v90, v78, v94
	v_cvt_pk_bf16_f32 v76, v84, v85
	v_cvt_pk_bf16_f32 v77, v86, v87
	v_cvt_pk_bf16_f32 v78, v88, v89
	v_cvt_pk_bf16_f32 v79, v90, v79
	global_load_dwordx4 v[84:87], v[98:99], off offset:3072
	s_nop 0
	global_store_dwordx4 v[100:101], v[76:79], off offset:256
	s_waitcnt vmcnt(0)
	s_nop 0
	v_lshlrev_b32_e32 v76, 16, v84
	v_and_b32_e32 v77, 0xffff0000, v84
	v_lshlrev_b32_e32 v78, 16, v85
	v_and_b32_e32 v79, 0xffff0000, v85
	v_lshlrev_b32_e32 v84, 16, v86
	v_and_b32_e32 v85, 0xffff0000, v86
	v_lshlrev_b32_e32 v86, 16, v87
	v_and_b32_e32 v87, 0xffff0000, v87
	v_mul_f32_e32 v76, v80, v76
	v_mul_f32_e32 v77, v81, v77
	v_mul_f32_e32 v78, v82, v78
	v_mul_f32_e32 v79, v83, v79
	v_mul_f32_e32 v75, v75, v87
	v_mul_f32_e32 v80, v72, v84
	v_mul_f32_e32 v81, v73, v85
	v_mul_f32_e32 v82, v74, v86
	v_cvt_pk_bf16_f32 v72, v76, v77
	v_cvt_pk_bf16_f32 v73, v78, v79
	v_cvt_pk_bf16_f32 v74, v80, v81
	v_cvt_pk_bf16_f32 v75, v82, v75
	global_load_dwordx4 v[76:79], v[98:99], off offset:3328
	v_lshlrev_b64 v[84:85], 11, v[96:97]
	v_lshl_add_u64 v[84:85], s[0:1], 0, v[84:85]
	v_add_u32_e32 v80, 0x80, v146
	v_lshl_add_u64 v[84:85], v[84:85], 0, v[144:145]
	v_mad_i64_i32 v[82:83], s[18:19], v80, s41, v[148:149]
	global_store_dwordx4 v[84:85], v[72:75], off
	v_lshl_add_u64 v[82:83], v[82:83], 0, v[144:145]
	v_ashrrev_i32_e32 v81, 31, v80
	s_waitcnt vmcnt(0)
	v_lshlrev_b32_e32 v72, 16, v76
	v_and_b32_e32 v73, 0xffff0000, v76
	v_lshlrev_b32_e32 v74, 16, v77
	v_and_b32_e32 v75, 0xffff0000, v77
	v_lshlrev_b32_e32 v76, 16, v78
	v_and_b32_e32 v77, 0xffff0000, v78
	v_lshlrev_b32_e32 v78, 16, v79
	v_and_b32_e32 v79, 0xffff0000, v79
	v_mul_f32_e32 v68, v68, v72
	v_mul_f32_e32 v69, v69, v73
	v_mul_f32_e32 v70, v70, v74
	v_mul_f32_e32 v71, v71, v75
	v_mul_f32_e32 v67, v67, v79
	v_mul_f32_e32 v72, v64, v76
	v_mul_f32_e32 v73, v65, v77
	v_mul_f32_e32 v74, v66, v78
	v_cvt_pk_bf16_f32 v64, v68, v69
	v_cvt_pk_bf16_f32 v65, v70, v71
	v_cvt_pk_bf16_f32 v66, v72, v73
	v_cvt_pk_bf16_f32 v67, v74, v67
	global_load_dwordx4 v[68:71], v[82:83], off offset:3072
	s_nop 0
	global_store_dwordx4 v[84:85], v[64:67], off offset:256
	s_waitcnt vmcnt(0)
	s_nop 0
	v_lshlrev_b32_e32 v64, 16, v68
	v_and_b32_e32 v65, 0xffff0000, v68
	v_lshlrev_b32_e32 v66, 16, v69
	v_and_b32_e32 v67, 0xffff0000, v69
	v_lshlrev_b32_e32 v68, 16, v70
	v_and_b32_e32 v69, 0xffff0000, v70
	v_lshlrev_b32_e32 v70, 16, v71
	v_and_b32_e32 v71, 0xffff0000, v71
	v_mul_f32_e32 v60, v60, v64
	v_mul_f32_e32 v61, v61, v65
	v_mul_f32_e32 v62, v62, v66
	v_mul_f32_e32 v63, v63, v67
	v_mul_f32_e32 v59, v59, v71
	v_mul_f32_e32 v64, v56, v68
	v_mul_f32_e32 v65, v57, v69
	v_mul_f32_e32 v66, v58, v70
	v_cvt_pk_bf16_f32 v56, v60, v61
	v_cvt_pk_bf16_f32 v57, v62, v63
	v_cvt_pk_bf16_f32 v58, v64, v65
	v_cvt_pk_bf16_f32 v59, v66, v59
	global_load_dwordx4 v[60:63], v[82:83], off offset:3328
	v_lshlrev_b64 v[68:69], 11, v[80:81]
	v_lshl_add_u64 v[68:69], s[0:1], 0, v[68:69]
	v_add_u32_e32 v64, 0x90, v146
	v_lshl_add_u64 v[68:69], v[68:69], 0, v[144:145]
	v_mad_i64_i32 v[66:67], s[18:19], v64, s41, v[148:149]
	global_store_dwordx4 v[68:69], v[56:59], off
	v_lshl_add_u64 v[66:67], v[66:67], 0, v[144:145]
	v_ashrrev_i32_e32 v65, 31, v64
	s_waitcnt vmcnt(0)
	v_lshlrev_b32_e32 v56, 16, v60
	v_and_b32_e32 v57, 0xffff0000, v60
	v_lshlrev_b32_e32 v58, 16, v61
	v_and_b32_e32 v59, 0xffff0000, v61
	v_lshlrev_b32_e32 v60, 16, v62
	v_and_b32_e32 v61, 0xffff0000, v62
	v_lshlrev_b32_e32 v62, 16, v63
	v_and_b32_e32 v63, 0xffff0000, v63
	v_mul_f32_e32 v52, v52, v56
	v_mul_f32_e32 v53, v53, v57
	v_mul_f32_e32 v54, v54, v58
	v_mul_f32_e32 v55, v55, v59
	v_mul_f32_e32 v47, v47, v63
	v_mul_f32_e32 v56, v44, v60
	v_mul_f32_e32 v57, v45, v61
	v_mul_f32_e32 v58, v46, v62
	v_cvt_pk_bf16_f32 v44, v52, v53
	v_cvt_pk_bf16_f32 v45, v54, v55
	v_cvt_pk_bf16_f32 v46, v56, v57
	v_cvt_pk_bf16_f32 v47, v58, v47
	global_load_dwordx4 v[52:55], v[66:67], off offset:3072
	s_nop 0
	global_store_dwordx4 v[68:69], v[44:47], off offset:256
	s_waitcnt vmcnt(0)
	s_nop 0
	v_lshlrev_b32_e32 v44, 16, v52
	v_and_b32_e32 v45, 0xffff0000, v52
	v_lshlrev_b32_e32 v46, 16, v53
	v_and_b32_e32 v47, 0xffff0000, v53
	v_lshlrev_b32_e32 v52, 16, v54
	v_and_b32_e32 v53, 0xffff0000, v54
	v_lshlrev_b32_e32 v54, 16, v55
	v_and_b32_e32 v55, 0xffff0000, v55
	v_mul_f32_e32 v44, v48, v44
	v_mul_f32_e32 v45, v49, v45
	v_mul_f32_e32 v46, v50, v46
	v_mul_f32_e32 v47, v51, v47
	v_mul_f32_e32 v43, v43, v55
	v_mul_f32_e32 v48, v40, v52
	v_mul_f32_e32 v49, v41, v53
	v_mul_f32_e32 v50, v42, v54
	v_cvt_pk_bf16_f32 v40, v44, v45
	v_cvt_pk_bf16_f32 v41, v46, v47
	v_cvt_pk_bf16_f32 v42, v48, v49
	v_cvt_pk_bf16_f32 v43, v50, v43
	global_load_dwordx4 v[44:47], v[66:67], off offset:3328
	v_lshlrev_b64 v[52:53], 11, v[64:65]
	v_lshl_add_u64 v[52:53], s[0:1], 0, v[52:53]
	v_add_u32_e32 v48, 0xa0, v146
	v_lshl_add_u64 v[52:53], v[52:53], 0, v[144:145]
	v_mad_i64_i32 v[50:51], s[18:19], v48, s41, v[148:149]
	global_store_dwordx4 v[52:53], v[40:43], off
	v_lshl_add_u64 v[50:51], v[50:51], 0, v[144:145]
	v_ashrrev_i32_e32 v49, 31, v48
	s_waitcnt vmcnt(0)
	v_lshlrev_b32_e32 v40, 16, v44
	v_and_b32_e32 v41, 0xffff0000, v44
	v_lshlrev_b32_e32 v42, 16, v45
	v_and_b32_e32 v43, 0xffff0000, v45
	v_lshlrev_b32_e32 v44, 16, v46
	v_and_b32_e32 v45, 0xffff0000, v46
	v_lshlrev_b32_e32 v46, 16, v47
	v_and_b32_e32 v47, 0xffff0000, v47
	v_mul_f32_e32 v36, v36, v40
	v_mul_f32_e32 v37, v37, v41
	v_mul_f32_e32 v38, v38, v42
	v_mul_f32_e32 v39, v39, v43
	v_mul_f32_e32 v31, v31, v47
	v_mul_f32_e32 v40, v28, v44
	v_mul_f32_e32 v41, v29, v45
	v_mul_f32_e32 v42, v30, v46
	v_cvt_pk_bf16_f32 v28, v36, v37
	v_cvt_pk_bf16_f32 v29, v38, v39
	v_cvt_pk_bf16_f32 v30, v40, v41
	v_cvt_pk_bf16_f32 v31, v42, v31
	global_load_dwordx4 v[36:39], v[50:51], off offset:3072
	s_nop 0
	global_store_dwordx4 v[52:53], v[28:31], off offset:256
	s_waitcnt vmcnt(0)
	s_nop 0
	v_lshlrev_b32_e32 v28, 16, v36
	v_and_b32_e32 v29, 0xffff0000, v36
	v_lshlrev_b32_e32 v30, 16, v37
	v_and_b32_e32 v31, 0xffff0000, v37
	v_lshlrev_b32_e32 v36, 16, v38
	v_and_b32_e32 v37, 0xffff0000, v38
	v_lshlrev_b32_e32 v38, 16, v39
	v_and_b32_e32 v39, 0xffff0000, v39
	v_mul_f32_e32 v28, v32, v28
	v_mul_f32_e32 v29, v33, v29
	v_mul_f32_e32 v30, v34, v30
	v_mul_f32_e32 v31, v35, v31
	v_mul_f32_e32 v27, v27, v39
	v_mul_f32_e32 v32, v24, v36
	v_mul_f32_e32 v33, v25, v37
	v_mul_f32_e32 v34, v26, v38
	v_cvt_pk_bf16_f32 v24, v28, v29
	v_cvt_pk_bf16_f32 v25, v30, v31
	v_cvt_pk_bf16_f32 v26, v32, v33
	v_cvt_pk_bf16_f32 v27, v34, v27
	global_load_dwordx4 v[28:31], v[50:51], off offset:3328
	v_lshlrev_b64 v[36:37], 11, v[48:49]
	v_lshl_add_u64 v[36:37], s[0:1], 0, v[36:37]
	v_add_u32_e32 v32, 0xb0, v146
	v_lshl_add_u64 v[36:37], v[36:37], 0, v[144:145]
	v_mad_i64_i32 v[34:35], s[18:19], v32, s41, v[148:149]
	global_store_dwordx4 v[36:37], v[24:27], off
	v_lshl_add_u64 v[34:35], v[34:35], 0, v[144:145]
	v_ashrrev_i32_e32 v33, 31, v32
	s_mov_b64 s[18:19], s[12:13]
	s_waitcnt vmcnt(0)
	v_lshlrev_b32_e32 v24, 16, v28
	v_and_b32_e32 v25, 0xffff0000, v28
	v_lshlrev_b32_e32 v26, 16, v29
	v_and_b32_e32 v27, 0xffff0000, v29
	v_lshlrev_b32_e32 v28, 16, v30
	v_and_b32_e32 v29, 0xffff0000, v30
	v_lshlrev_b32_e32 v30, 16, v31
	v_and_b32_e32 v31, 0xffff0000, v31
	v_mul_f32_e32 v20, v20, v24
	v_mul_f32_e32 v21, v21, v25
	v_mul_f32_e32 v22, v22, v26
	v_mul_f32_e32 v23, v23, v27
	v_mul_f32_e32 v15, v15, v31
	v_mul_f32_e32 v24, v12, v28
	v_mul_f32_e32 v25, v13, v29
	v_mul_f32_e32 v26, v14, v30
	v_cvt_pk_bf16_f32 v12, v20, v21
	v_cvt_pk_bf16_f32 v13, v22, v23
	v_cvt_pk_bf16_f32 v14, v24, v25
	v_cvt_pk_bf16_f32 v15, v26, v15
	global_load_dwordx4 v[20:23], v[34:35], off offset:3072
	s_nop 0
	global_store_dwordx4 v[36:37], v[12:15], off offset:256
	s_waitcnt vmcnt(0)
	s_nop 0
	v_lshlrev_b32_e32 v12, 16, v20
	v_and_b32_e32 v13, 0xffff0000, v20
	v_lshlrev_b32_e32 v14, 16, v21
	v_and_b32_e32 v15, 0xffff0000, v21
	v_lshlrev_b32_e32 v20, 16, v22
	v_and_b32_e32 v21, 0xffff0000, v22
	v_lshlrev_b32_e32 v22, 16, v23
	v_and_b32_e32 v23, 0xffff0000, v23
	v_mul_f32_e32 v12, v16, v12
	v_mul_f32_e32 v13, v17, v13
	v_mul_f32_e32 v14, v18, v14
	v_mul_f32_e32 v15, v19, v15
	v_mul_f32_e32 v11, v11, v23
	v_mul_f32_e32 v16, v8, v20
	v_mul_f32_e32 v17, v9, v21
	v_mul_f32_e32 v18, v10, v22
	v_cvt_pk_bf16_f32 v8, v12, v13
	v_cvt_pk_bf16_f32 v9, v14, v15
	v_cvt_pk_bf16_f32 v10, v16, v17
	v_cvt_pk_bf16_f32 v11, v18, v11
	global_load_dwordx4 v[12:15], v[34:35], off offset:3328
	v_lshlrev_b64 v[16:17], 11, v[32:33]
	v_lshl_add_u64 v[16:17], s[0:1], 0, v[16:17]
	v_lshl_add_u64 v[16:17], v[16:17], 0, v[144:145]
	global_store_dwordx4 v[16:17], v[8:11], off
	s_waitcnt vmcnt(0)
	s_nop 0
	v_lshlrev_b32_e32 v8, 16, v12
	v_and_b32_e32 v9, 0xffff0000, v12
	v_lshlrev_b32_e32 v10, 16, v13
	v_and_b32_e32 v11, 0xffff0000, v13
	v_lshlrev_b32_e32 v12, 16, v14
	v_and_b32_e32 v13, 0xffff0000, v14
	v_lshlrev_b32_e32 v14, 16, v15
	v_and_b32_e32 v15, 0xffff0000, v15
	v_mul_f32_e32 v3, v3, v15
	v_mul_f32_e32 v4, v4, v8
	v_mul_f32_e32 v5, v5, v9
	v_mul_f32_e32 v6, v6, v10
	v_mul_f32_e32 v7, v7, v11
	v_mul_f32_e32 v8, v0, v12
	v_mul_f32_e32 v9, v1, v13
	v_mul_f32_e32 v10, v2, v14
	v_cvt_pk_bf16_f32 v0, v4, v5
	v_cvt_pk_bf16_f32 v1, v6, v7
	v_cvt_pk_bf16_f32 v2, v8, v9
	v_cvt_pk_bf16_f32 v3, v10, v3
	global_store_dwordx4 v[16:17], v[0:3], off offset:256
	s_cbranch_vccz .LBB0_984
	s_waitcnt vmcnt(0)
	s_cmpk_gt_u32 s25, 0xff
	s_cbranch_scc1 .LBB0_995
	s_barrier

.LBB0_1011:
	ds_read_b128 v[144:147], v153
	ds_read_b128 v[156:159], v153 offset:1024
	ds_read_b128 v[160:163], v153 offset:2048
	ds_read_b128 v[164:167], v153 offset:3072
	s_add_u32 s20, s18, 0xfffc0080
	s_addc_u32 s21, s19, -1
	s_cmp_eq_u32 s47, 12
	s_cselect_b32 s23, s11, s21
	s_cselect_b32 s22, s43, s20
	s_cselect_b32 s21, s9, s46
	s_cselect_b32 s20, s44, s45
	v_lshl_add_u64 v[148:149], s[18:19], 0, v[136:137]
	s_add_i32 m0, s17, 0xc000
	ds_read_b128 v[168:171], v154
	ds_read_b128 v[172:175], v154 offset:1024
	ds_read_b128 v[182:185], v154 offset:2048
	ds_read_b128 v[190:193], v154 offset:3072
	ds_read_b128 v[194:197], v154 offset:4096
	ds_read_b128 v[198:201], v154 offset:5120
	ds_read_b128 v[202:205], v154 offset:6144
	ds_read_b128 v[206:209], v154 offset:7168
	global_load_lds_dwordx4 v[148:149], off
	v_lshl_add_u64 v[148:149], s[18:19], 0, v[138:139]
	s_add_i32 m0, s17, 0xe000
	s_nop 0
	global_load_lds_dwordx4 v[148:149], off
	s_waitcnt lgkmcnt(8)
	s_barrier
	s_waitcnt lgkmcnt(0)
	s_waitcnt lgkmcnt(0)
	v_mfma_f32_16x16x32_bf16 v[124:127], v[144:147], v[168:171], v[124:127]
	v_mfma_f32_16x16x32_bf16 v[120:123], v[160:163], v[168:171], v[120:123]
	v_mfma_f32_16x16x32_bf16 v[108:111], v[144:147], v[182:185], v[108:111]
	v_mfma_f32_16x16x32_bf16 v[104:107], v[160:163], v[182:185], v[104:107]
	v_mfma_f32_16x16x32_bf16 v[92:95], v[144:147], v[194:197], v[92:95]
	v_mfma_f32_16x16x32_bf16 v[88:91], v[160:163], v[194:197], v[88:91]
	v_mfma_f32_16x16x32_bf16 v[76:79], v[144:147], v[202:205], v[76:79]
	v_mfma_f32_16x16x32_bf16 v[72:75], v[160:163], v[202:205], v[72:75]
	v_mfma_f32_16x16x32_bf16 v[124:127], v[156:159], v[172:175], v[124:127]
	v_mfma_f32_16x16x32_bf16 v[120:123], v[164:167], v[172:175], v[120:123]
	v_mfma_f32_16x16x32_bf16 v[108:111], v[156:159], v[190:193], v[108:111]
	v_mfma_f32_16x16x32_bf16 v[104:107], v[164:167], v[190:193], v[104:107]
	v_mfma_f32_16x16x32_bf16 v[92:95], v[156:159], v[198:201], v[92:95]
	v_mfma_f32_16x16x32_bf16 v[88:91], v[164:167], v[198:201], v[88:91]
	v_mfma_f32_16x16x32_bf16 v[76:79], v[156:159], v[206:209], v[76:79]
	v_mfma_f32_16x16x32_bf16 v[72:75], v[164:167], v[206:209], v[72:75]
	s_barrier
	s_add_i32 s48, s39, s29
	v_lshl_add_u64 v[148:149], s[20:21], 0, v[130:131]
	s_mov_b32 m0, s48
	ds_read_b128 v[210:213], v155
	ds_read_b128 v[214:217], v155 offset:1024
	ds_read_b128 v[218:221], v155 offset:2048
	ds_read_b128 v[222:225], v155 offset:3072
	global_load_lds_dwordx4 v[148:149], off
	v_lshl_add_u64 v[186:187], s[20:21], 0, v[134:135]
	s_add_i32 m0, s48, 0x2000
	s_nop 0
	global_load_lds_dwordx4 v[186:187], off
	s_barrier
	s_waitcnt lgkmcnt(0)
	s_waitcnt lgkmcnt(0)
	v_mfma_f32_16x16x32_bf16 v[116:119], v[210:213], v[168:171], v[116:119]
	v_mfma_f32_16x16x32_bf16 v[112:115], v[218:221], v[168:171], v[112:115]
	v_mfma_f32_16x16x32_bf16 v[100:103], v[210:213], v[182:185], v[100:103]
	v_mfma_f32_16x16x32_bf16 v[96:99], v[218:221], v[182:185], v[96:99]
	v_mfma_f32_16x16x32_bf16 v[84:87], v[210:213], v[194:197], v[84:87]
	v_mfma_f32_16x16x32_bf16 v[80:83], v[218:221], v[194:197], v[80:83]
	v_mfma_f32_16x16x32_bf16 v[68:71], v[210:213], v[202:205], v[68:71]
	v_mfma_f32_16x16x32_bf16 v[64:67], v[218:221], v[202:205], v[64:67]
	v_mfma_f32_16x16x32_bf16 v[116:119], v[214:217], v[172:175], v[116:119]
	v_mfma_f32_16x16x32_bf16 v[112:115], v[222:225], v[172:175], v[112:115]
	v_mfma_f32_16x16x32_bf16 v[100:103], v[214:217], v[190:193], v[100:103]
	v_mfma_f32_16x16x32_bf16 v[96:99], v[222:225], v[190:193], v[96:99]
	v_mfma_f32_16x16x32_bf16 v[84:87], v[214:217], v[198:201], v[84:87]
	v_mfma_f32_16x16x32_bf16 v[80:83], v[222:225], v[198:201], v[80:83]
	v_mfma_f32_16x16x32_bf16 v[68:71], v[214:217], v[206:209], v[68:71]
	v_mfma_f32_16x16x32_bf16 v[64:67], v[222:225], v[206:209], v[64:67]
	s_mov_b32 m0, s17
	v_lshl_add_u64 v[226:227], s[22:23], 0, v[128:129]
	s_barrier
	ds_read_b128 v[168:171], v154 offset:16384
	ds_read_b128 v[172:175], v154 offset:17408
	ds_read_b128 v[182:185], v154 offset:18432
	ds_read_b128 v[190:193], v154 offset:19456
	ds_read_b128 v[194:197], v154 offset:20480
	ds_read_b128 v[198:201], v154 offset:21504
	ds_read_b128 v[202:205], v154 offset:22528
	ds_read_b128 v[206:209], v154 offset:23552
	global_load_lds_dwordx4 v[226:227], off
	v_lshl_add_u64 v[228:229], s[22:23], 0, v[132:133]
	s_mov_b32 m0, s30
	s_nop 0
	global_load_lds_dwordx4 v[228:229], off
	s_barrier
	s_waitcnt lgkmcnt(0)
	s_waitcnt lgkmcnt(0)
	v_mfma_f32_16x16x32_bf16 v[60:63], v[144:147], v[168:171], v[60:63]
	v_mfma_f32_16x16x32_bf16 v[56:59], v[160:163], v[168:171], v[56:59]
	v_mfma_f32_16x16x32_bf16 v[44:47], v[144:147], v[182:185], v[44:47]
	v_mfma_f32_16x16x32_bf16 v[40:43], v[160:163], v[182:185], v[40:43]
	v_mfma_f32_16x16x32_bf16 v[28:31], v[144:147], v[194:197], v[28:31]
	v_mfma_f32_16x16x32_bf16 v[24:27], v[160:163], v[194:197], v[24:27]
	v_mfma_f32_16x16x32_bf16 v[12:15], v[144:147], v[202:205], v[12:15]
	v_mfma_f32_16x16x32_bf16 v[8:11], v[160:163], v[202:205], v[8:11]
	v_mfma_f32_16x16x32_bf16 v[60:63], v[156:159], v[172:175], v[60:63]
	v_mfma_f32_16x16x32_bf16 v[56:59], v[164:167], v[172:175], v[56:59]
	v_mfma_f32_16x16x32_bf16 v[44:47], v[156:159], v[190:193], v[44:47]
	v_mfma_f32_16x16x32_bf16 v[40:43], v[164:167], v[190:193], v[40:43]
	v_mfma_f32_16x16x32_bf16 v[28:31], v[156:159], v[198:201], v[28:31]
	v_mfma_f32_16x16x32_bf16 v[24:27], v[164:167], v[198:201], v[24:27]
	v_mfma_f32_16x16x32_bf16 v[12:15], v[156:159], v[206:209], v[12:15]
	v_mfma_f32_16x16x32_bf16 v[8:11], v[164:167], v[206:209], v[8:11]
	s_barrier
	s_add_u32 s48, s20, 0x40000
	s_addc_u32 s49, s21, 0
	s_add_i32 s50, s40, s29
	v_lshl_add_u64 v[144:145], s[48:49], 0, v[130:131]
	s_mov_b32 m0, s50
	s_nop 0
	global_load_lds_dwordx4 v[144:145], off
	v_lshl_add_u64 v[144:145], s[48:49], 0, v[134:135]
	s_add_i32 m0, s50, 0x2000
	s_nop 0
	global_load_lds_dwordx4 v[144:145], off
	s_waitcnt vmcnt(6)
	s_barrier
	v_mfma_f32_16x16x32_bf16 v[52:55], v[210:213], v[168:171], v[52:55]
	v_mfma_f32_16x16x32_bf16 v[48:51], v[218:221], v[168:171], v[48:51]
	v_mfma_f32_16x16x32_bf16 v[36:39], v[210:213], v[182:185], v[36:39]
	v_mfma_f32_16x16x32_bf16 v[32:35], v[218:221], v[182:185], v[32:35]
	v_mfma_f32_16x16x32_bf16 v[20:23], v[210:213], v[194:197], v[20:23]
	v_mfma_f32_16x16x32_bf16 v[16:19], v[218:221], v[194:197], v[16:19]
	v_mfma_f32_16x16x32_bf16 v[4:7], v[210:213], v[202:205], v[4:7]
	v_mfma_f32_16x16x32_bf16 v[0:3], v[218:221], v[202:205], v[0:3]
	v_mfma_f32_16x16x32_bf16 v[52:55], v[214:217], v[172:175], v[52:55]
	v_mfma_f32_16x16x32_bf16 v[48:51], v[222:225], v[172:175], v[48:51]
	v_mfma_f32_16x16x32_bf16 v[36:39], v[214:217], v[190:193], v[36:39]
	v_mfma_f32_16x16x32_bf16 v[32:35], v[222:225], v[190:193], v[32:35]
	v_mfma_f32_16x16x32_bf16 v[20:23], v[214:217], v[198:201], v[20:23]
	v_mfma_f32_16x16x32_bf16 v[16:19], v[222:225], v[198:201], v[16:19]
	v_mfma_f32_16x16x32_bf16 v[4:7], v[214:217], v[206:209], v[4:7]
	v_mfma_f32_16x16x32_bf16 v[0:3], v[222:225], v[206:209], v[0:3]
	s_add_i32 s48, 0, 0x18000
	v_add_u32_e32 v164, s48, v151
	s_barrier
	ds_read_b128 v[144:147], v164
	ds_read_b128 v[156:159], v164 offset:1024
	ds_read_b128 v[160:163], v164 offset:2048
	ds_read_b128 v[164:167], v164 offset:3072
	s_add_u32 s22, s22, 0x40000
	s_addc_u32 s23, s23, 0
	s_mov_b32 m0, s31
	v_lshl_add_u64 v[210:211], s[22:23], 0, v[128:129]
	ds_read_b128 v[168:171], v154 offset:32768
	ds_read_b128 v[172:175], v154 offset:33792
	ds_read_b128 v[182:185], v154 offset:34816
	ds_read_b128 v[190:193], v154 offset:35840
	ds_read_b128 v[194:197], v154 offset:36864
	ds_read_b128 v[198:201], v154 offset:37888
	ds_read_b128 v[202:205], v154 offset:38912
	ds_read_b128 v[206:209], v154 offset:39936
	global_load_lds_dwordx4 v[210:211], off
	v_lshl_add_u64 v[210:211], s[22:23], 0, v[132:133]
	s_mov_b32 m0, s34
	s_nop 0
	global_load_lds_dwordx4 v[210:211], off
	s_waitcnt lgkmcnt(8)
	s_barrier
	s_waitcnt lgkmcnt(0)
	s_waitcnt lgkmcnt(0)
	v_mfma_f32_16x16x32_bf16 v[124:127], v[144:147], v[168:171], v[124:127]
	v_mfma_f32_16x16x32_bf16 v[120:123], v[160:163], v[168:171], v[120:123]
	v_mfma_f32_16x16x32_bf16 v[108:111], v[144:147], v[182:185], v[108:111]
	v_mfma_f32_16x16x32_bf16 v[104:107], v[160:163], v[182:185], v[104:107]
	v_mfma_f32_16x16x32_bf16 v[92:95], v[144:147], v[194:197], v[92:95]
	v_mfma_f32_16x16x32_bf16 v[88:91], v[160:163], v[194:197], v[88:91]
	v_mfma_f32_16x16x32_bf16 v[76:79], v[144:147], v[202:205], v[76:79]
	v_mfma_f32_16x16x32_bf16 v[72:75], v[160:163], v[202:205], v[72:75]
	v_mfma_f32_16x16x32_bf16 v[124:127], v[156:159], v[172:175], v[124:127]
	v_mfma_f32_16x16x32_bf16 v[120:123], v[164:167], v[172:175], v[120:123]
	v_mfma_f32_16x16x32_bf16 v[108:111], v[156:159], v[190:193], v[108:111]
	v_mfma_f32_16x16x32_bf16 v[104:107], v[164:167], v[190:193], v[104:107]
	v_mfma_f32_16x16x32_bf16 v[92:95], v[156:159], v[198:201], v[92:95]
	v_mfma_f32_16x16x32_bf16 v[88:91], v[164:167], v[198:201], v[88:91]
	v_mfma_f32_16x16x32_bf16 v[76:79], v[156:159], v[206:209], v[76:79]
	v_mfma_f32_16x16x32_bf16 v[72:75], v[164:167], v[206:209], v[72:75]
	s_barrier
	s_add_i32 s22, 0, 0x1c000
	s_add_i32 s23, s48, s29
	v_add_u32_e32 v179, s22, v151
	v_lshl_add_u64 v[148:149], v[148:149], 0, s[6:7]
	s_mov_b32 m0, s23
	ds_read_b128 v[210:213], v179
	ds_read_b128 v[214:217], v179 offset:1024
	ds_read_b128 v[218:221], v179 offset:2048
	ds_read_b128 v[222:225], v179 offset:3072
	global_load_lds_dwordx4 v[148:149], off
	v_lshl_add_u64 v[148:149], v[186:187], 0, s[6:7]
	s_add_i32 m0, s23, 0x2000
	s_nop 0
	global_load_lds_dwordx4 v[148:149], off
	s_barrier
	s_waitcnt lgkmcnt(0)
	s_waitcnt lgkmcnt(0)
	v_mfma_f32_16x16x32_bf16 v[116:119], v[210:213], v[168:171], v[116:119]
	v_mfma_f32_16x16x32_bf16 v[112:115], v[218:221], v[168:171], v[112:115]
	v_mfma_f32_16x16x32_bf16 v[100:103], v[210:213], v[182:185], v[100:103]
	v_mfma_f32_16x16x32_bf16 v[96:99], v[218:221], v[182:185], v[96:99]
	v_mfma_f32_16x16x32_bf16 v[84:87], v[210:213], v[194:197], v[84:87]
	v_mfma_f32_16x16x32_bf16 v[80:83], v[218:221], v[194:197], v[80:83]
	v_mfma_f32_16x16x32_bf16 v[68:71], v[210:213], v[202:205], v[68:71]
	v_mfma_f32_16x16x32_bf16 v[64:67], v[218:221], v[202:205], v[64:67]
	v_mfma_f32_16x16x32_bf16 v[116:119], v[214:217], v[172:175], v[116:119]
	v_mfma_f32_16x16x32_bf16 v[112:115], v[222:225], v[172:175], v[112:115]
	v_mfma_f32_16x16x32_bf16 v[100:103], v[214:217], v[190:193], v[100:103]
	v_mfma_f32_16x16x32_bf16 v[96:99], v[222:225], v[190:193], v[96:99]
	v_mfma_f32_16x16x32_bf16 v[84:87], v[214:217], v[198:201], v[84:87]
	v_mfma_f32_16x16x32_bf16 v[80:83], v[222:225], v[198:201], v[80:83]
	v_mfma_f32_16x16x32_bf16 v[68:71], v[214:217], v[206:209], v[68:71]
	v_mfma_f32_16x16x32_bf16 v[64:67], v[222:225], v[206:209], v[64:67]
	s_mov_b32 m0, s36
	v_lshl_add_u64 v[148:149], v[226:227], 0, s[6:7]
	s_barrier
	ds_read_b128 v[168:171], v154 offset:49152
	ds_read_b128 v[172:175], v154 offset:50176
	ds_read_b128 v[182:185], v154 offset:51200
	ds_read_b128 v[190:193], v154 offset:52224
	ds_read_b128 v[194:197], v154 offset:53248
	ds_read_b128 v[198:201], v154 offset:54272
	ds_read_b128 v[202:205], v154 offset:55296
	ds_read_b128 v[206:209], v154 offset:56320
	global_load_lds_dwordx4 v[148:149], off
	v_lshl_add_u64 v[148:149], v[228:229], 0, s[6:7]
	s_mov_b32 m0, s37
	s_nop 0
	global_load_lds_dwordx4 v[148:149], off
	s_barrier
	s_waitcnt lgkmcnt(0)
	s_waitcnt lgkmcnt(0)
	v_mfma_f32_16x16x32_bf16 v[60:63], v[144:147], v[168:171], v[60:63]
	v_mfma_f32_16x16x32_bf16 v[56:59], v[160:163], v[168:171], v[56:59]
	v_mfma_f32_16x16x32_bf16 v[44:47], v[144:147], v[182:185], v[44:47]
	v_mfma_f32_16x16x32_bf16 v[40:43], v[160:163], v[182:185], v[40:43]
	v_mfma_f32_16x16x32_bf16 v[28:31], v[144:147], v[194:197], v[28:31]
	v_mfma_f32_16x16x32_bf16 v[24:27], v[160:163], v[194:197], v[24:27]
	v_mfma_f32_16x16x32_bf16 v[12:15], v[144:147], v[202:205], v[12:15]
	v_mfma_f32_16x16x32_bf16 v[8:11], v[160:163], v[202:205], v[8:11]
	v_mfma_f32_16x16x32_bf16 v[60:63], v[156:159], v[172:175], v[60:63]
	v_mfma_f32_16x16x32_bf16 v[56:59], v[164:167], v[172:175], v[56:59]
	v_mfma_f32_16x16x32_bf16 v[44:47], v[156:159], v[190:193], v[44:47]
	v_mfma_f32_16x16x32_bf16 v[40:43], v[164:167], v[190:193], v[40:43]
	v_mfma_f32_16x16x32_bf16 v[28:31], v[156:159], v[198:201], v[28:31]
	v_mfma_f32_16x16x32_bf16 v[24:27], v[164:167], v[198:201], v[24:27]
	v_mfma_f32_16x16x32_bf16 v[12:15], v[156:159], v[206:209], v[12:15]
	v_mfma_f32_16x16x32_bf16 v[8:11], v[164:167], v[206:209], v[8:11]
	s_barrier
	s_add_u32 s20, s20, 0x40080
	s_addc_u32 s21, s21, 0
	s_add_i32 s22, s22, s29
	v_lshl_add_u64 v[144:145], s[20:21], 0, v[130:131]
	s_mov_b32 m0, s22
	s_nop 0
	global_load_lds_dwordx4 v[144:145], off
	v_lshl_add_u64 v[144:145], s[20:21], 0, v[134:135]
	s_add_i32 m0, s22, 0x2000
	s_nop 0
	global_load_lds_dwordx4 v[144:145], off
	s_waitcnt vmcnt(6)
	s_barrier
	v_mfma_f32_16x16x32_bf16 v[52:55], v[210:213], v[168:171], v[52:55]
	v_mfma_f32_16x16x32_bf16 v[48:51], v[218:221], v[168:171], v[48:51]
	v_mfma_f32_16x16x32_bf16 v[36:39], v[210:213], v[182:185], v[36:39]
	v_mfma_f32_16x16x32_bf16 v[32:35], v[218:221], v[182:185], v[32:35]
	v_mfma_f32_16x16x32_bf16 v[20:23], v[210:213], v[194:197], v[20:23]
	v_mfma_f32_16x16x32_bf16 v[16:19], v[218:221], v[194:197], v[16:19]
	v_mfma_f32_16x16x32_bf16 v[4:7], v[210:213], v[202:205], v[4:7]
	v_mfma_f32_16x16x32_bf16 v[0:3], v[218:221], v[202:205], v[0:3]
	v_mfma_f32_16x16x32_bf16 v[52:55], v[214:217], v[172:175], v[52:55]
	v_mfma_f32_16x16x32_bf16 v[48:51], v[222:225], v[172:175], v[48:51]
	v_mfma_f32_16x16x32_bf16 v[36:39], v[214:217], v[190:193], v[36:39]
	v_mfma_f32_16x16x32_bf16 v[32:35], v[222:225], v[190:193], v[32:35]
	v_mfma_f32_16x16x32_bf16 v[20:23], v[214:217], v[198:201], v[20:23]
	v_mfma_f32_16x16x32_bf16 v[16:19], v[222:225], v[198:201], v[16:19]
	v_mfma_f32_16x16x32_bf16 v[4:7], v[214:217], v[206:209], v[4:7]
	v_mfma_f32_16x16x32_bf16 v[0:3], v[222:225], v[206:209], v[0:3]
	s_add_i32 s47, s47, 2
	s_add_u32 s18, s18, 0x100
	s_addc_u32 s19, s19, 0
	s_add_u32 s45, s45, 0x100
	s_addc_u32 s46, s46, 0
	s_cmp_gt_u32 s47, 13
	s_barrier
	s_cbranch_scc0 .LBB0_1011
	v_lshl_add_u32 v146, s16, 8, v150
	v_lshl_or_b32 v144, s42, 8, v152
	v_ashrrev_i32_e32 v147, 31, v146
	v_ashrrev_i32_e32 v145, 31, v144
	v_mov_b64_e32 v[148:149], s[4:5]
	v_lshlrev_b64 v[160:161], 11, v[146:147]
	v_lshlrev_b64 v[144:145], 1, v[144:145]
	v_mad_i64_i32 v[156:157], s[18:19], v146, s41, v[148:149]
	v_lshl_add_u64 v[160:161], s[0:1], 0, v[160:161]
	v_lshl_add_u64 v[164:165], v[156:157], 0, v[144:145]
	v_lshl_add_u64 v[166:167], v[160:161], 0, v[144:145]
	global_load_dwordx4 v[156:159], v[164:165], off
	global_load_dwordx4 v[160:163], v[166:167], off
	s_and_b64 vcc, exec, s[2:3]
	s_mov_b32 s42, s8
	s_mov_b32 s16, s10
	s_mov_b64 s[20:21], s[14:15]
	s_waitcnt vmcnt(0)
	v_lshlrev_b32_e32 v147, 16, v156
	v_and_b32_e32 v156, 0xffff0000, v156
	v_lshlrev_b32_e32 v168, 16, v157
	v_and_b32_e32 v157, 0xffff0000, v157
	v_lshlrev_b32_e32 v169, 16, v158
	v_and_b32_e32 v158, 0xffff0000, v158
	v_lshlrev_b32_e32 v170, 16, v159
	v_and_b32_e32 v159, 0xffff0000, v159
	v_lshlrev_b32_e32 v171, 16, v160
	v_and_b32_e32 v160, 0xffff0000, v160
	v_lshlrev_b32_e32 v172, 16, v161
	v_and_b32_e32 v161, 0xffff0000, v161
	v_lshlrev_b32_e32 v173, 16, v162
	v_and_b32_e32 v162, 0xffff0000, v162
	v_lshlrev_b32_e32 v174, 16, v163
	v_and_b32_e32 v163, 0xffff0000, v163
	v_fmac_f32_e32 v171, v124, v147
	v_fmac_f32_e32 v160, v125, v156
	v_fmac_f32_e32 v172, v126, v168
	v_fmac_f32_e32 v161, v127, v157
	v_fmac_f32_e32 v173, v120, v169
	v_fmac_f32_e32 v162, v121, v158
	v_fmac_f32_e32 v174, v122, v170
	v_fmac_f32_e32 v163, v123, v159
	v_cvt_pk_bf16_f32 v120, v171, v160
	v_cvt_pk_bf16_f32 v121, v172, v161
	v_cvt_pk_bf16_f32 v122, v173, v162
	v_cvt_pk_bf16_f32 v123, v174, v163
	global_load_dwordx4 v[124:127], v[164:165], off offset:256
	global_load_dwordx4 v[156:159], v[166:167], off offset:256
	v_or_b32_e32 v160, 16, v146
	global_store_dwordx4 v[166:167], v[120:123], off
	v_mad_i64_i32 v[162:163], s[18:19], v160, s41, v[148:149]
	v_lshl_add_u64 v[162:163], v[162:163], 0, v[144:145]
	s_waitcnt vmcnt(0)
	v_lshlrev_b32_e32 v122, 16, v125
	v_lshlrev_b32_e32 v161, 16, v157
	v_lshlrev_b32_e32 v120, 16, v124
	v_and_b32_e32 v121, 0xffff0000, v124
	v_and_b32_e32 v123, 0xffff0000, v125
	v_lshlrev_b32_e32 v124, 16, v126
	v_and_b32_e32 v125, 0xffff0000, v126
	v_lshlrev_b32_e32 v147, 16, v156
	v_and_b32_e32 v156, 0xffff0000, v156
	v_and_b32_e32 v157, 0xffff0000, v157
	v_lshlrev_b32_e32 v164, 16, v158
	v_and_b32_e32 v158, 0xffff0000, v158
	v_fmac_f32_e32 v161, v118, v122
	v_fmac_f32_e32 v147, v116, v120
	v_fmac_f32_e32 v156, v117, v121
	v_fmac_f32_e32 v157, v119, v123
	v_fmac_f32_e32 v164, v112, v124
	v_fmac_f32_e32 v158, v113, v125
	v_cvt_pk_bf16_f32 v112, v147, v156
	v_cvt_pk_bf16_f32 v113, v161, v157
	v_ashrrev_i32_e32 v161, 31, v160
	v_lshlrev_b64 v[120:121], 11, v[160:161]
	v_lshl_add_u64 v[120:121], s[0:1], 0, v[120:121]
	v_lshlrev_b32_e32 v126, 16, v127
	v_and_b32_e32 v127, 0xffff0000, v127
	v_lshlrev_b32_e32 v165, 16, v159
	v_and_b32_e32 v159, 0xffff0000, v159
	v_lshl_add_u64 v[124:125], v[120:121], 0, v[144:145]
	v_fmac_f32_e32 v165, v114, v126
	v_fmac_f32_e32 v159, v115, v127
	v_cvt_pk_bf16_f32 v114, v164, v158
	v_cvt_pk_bf16_f32 v115, v165, v159
	global_load_dwordx4 v[116:119], v[162:163], off
	global_load_dwordx4 v[120:123], v[124:125], off
	s_waitcnt vmcnt(0)
	v_lshlrev_b32_e32 v126, 16, v120
	global_store_dwordx4 v[166:167], v[112:115], off offset:256
	v_and_b32_e32 v120, 0xffff0000, v120
	v_lshlrev_b32_e32 v127, 16, v121
	v_lshlrev_b32_e32 v112, 16, v116
	v_and_b32_e32 v113, 0xffff0000, v116
	v_lshlrev_b32_e32 v114, 16, v117
	v_and_b32_e32 v115, 0xffff0000, v117
	v_lshlrev_b32_e32 v116, 16, v118
	v_and_b32_e32 v117, 0xffff0000, v118
	v_lshlrev_b32_e32 v118, 16, v119
	v_and_b32_e32 v119, 0xffff0000, v119
	v_and_b32_e32 v121, 0xffff0000, v121
	v_lshlrev_b32_e32 v147, 16, v122
	v_and_b32_e32 v122, 0xffff0000, v122
	v_lshlrev_b32_e32 v156, 16, v123
	v_and_b32_e32 v123, 0xffff0000, v123
	v_fmac_f32_e32 v126, v108, v112
	v_fmac_f32_e32 v120, v109, v113
	v_fmac_f32_e32 v127, v110, v114
	v_fmac_f32_e32 v121, v111, v115
	v_fmac_f32_e32 v147, v104, v116
	v_fmac_f32_e32 v122, v105, v117
	v_fmac_f32_e32 v156, v106, v118
	v_fmac_f32_e32 v123, v107, v119
	v_cvt_pk_bf16_f32 v104, v126, v120
	v_cvt_pk_bf16_f32 v105, v127, v121
	v_cvt_pk_bf16_f32 v106, v147, v122
	v_cvt_pk_bf16_f32 v107, v156, v123
	global_load_dwordx4 v[108:111], v[162:163], off offset:256
	global_load_dwordx4 v[112:115], v[124:125], off offset:256
	v_or_b32_e32 v116, 32, v146
	global_store_dwordx4 v[124:125], v[104:107], off
	v_mad_i64_i32 v[118:119], s[18:19], v116, s41, v[148:149]
	v_lshl_add_u64 v[118:119], v[118:119], 0, v[144:145]
	s_waitcnt vmcnt(0)
	v_lshlrev_b32_e32 v104, 16, v108
	v_lshlrev_b32_e32 v117, 16, v112
	v_and_b32_e32 v105, 0xffff0000, v108
	v_lshlrev_b32_e32 v108, 16, v110
	v_and_b32_e32 v112, 0xffff0000, v112
	v_lshlrev_b32_e32 v121, 16, v114
	v_fmac_f32_e32 v117, v100, v104
	v_fmac_f32_e32 v112, v101, v105
	v_fmac_f32_e32 v121, v96, v108
	v_cvt_pk_bf16_f32 v96, v117, v112
	v_ashrrev_i32_e32 v117, 31, v116
	v_lshlrev_b64 v[104:105], 11, v[116:117]
	v_lshlrev_b32_e32 v106, 16, v109
	v_and_b32_e32 v107, 0xffff0000, v109
	v_and_b32_e32 v109, 0xffff0000, v110
	v_and_b32_e32 v114, 0xffff0000, v114
	v_lshl_add_u64 v[104:105], s[0:1], 0, v[104:105]
	v_lshlrev_b32_e32 v110, 16, v111
	v_and_b32_e32 v111, 0xffff0000, v111
	v_lshlrev_b32_e32 v120, 16, v113
	v_and_b32_e32 v113, 0xffff0000, v113
	v_lshlrev_b32_e32 v122, 16, v115
	v_and_b32_e32 v115, 0xffff0000, v115
	v_fmac_f32_e32 v114, v97, v109
	v_lshl_add_u64 v[108:109], v[104:105], 0, v[144:145]
	v_fmac_f32_e32 v120, v102, v106
	v_fmac_f32_e32 v113, v103, v107
	v_fmac_f32_e32 v122, v98, v110
	v_fmac_f32_e32 v115, v99, v111
	v_cvt_pk_bf16_f32 v97, v120, v113
	v_cvt_pk_bf16_f32 v98, v121, v114
	v_cvt_pk_bf16_f32 v99, v122, v115
	global_load_dwordx4 v[100:103], v[118:119], off
	global_load_dwordx4 v[104:107], v[108:109], off
	s_waitcnt vmcnt(0)
	v_lshlrev_b32_e32 v110, 16, v104
	global_store_dwordx4 v[124:125], v[96:99], off offset:256
	v_and_b32_e32 v104, 0xffff0000, v104
	v_lshlrev_b32_e32 v111, 16, v105
	v_lshlrev_b32_e32 v96, 16, v100
	v_and_b32_e32 v97, 0xffff0000, v100
	v_lshlrev_b32_e32 v98, 16, v101
	v_and_b32_e32 v99, 0xffff0000, v101
	v_lshlrev_b32_e32 v100, 16, v102
	v_and_b32_e32 v101, 0xffff0000, v102
	v_lshlrev_b32_e32 v102, 16, v103
	v_and_b32_e32 v103, 0xffff0000, v103
	v_and_b32_e32 v105, 0xffff0000, v105
	v_lshlrev_b32_e32 v112, 16, v106
	v_and_b32_e32 v106, 0xffff0000, v106
	v_lshlrev_b32_e32 v113, 16, v107
	v_and_b32_e32 v107, 0xffff0000, v107
	v_fmac_f32_e32 v110, v92, v96
	v_fmac_f32_e32 v104, v93, v97
	v_fmac_f32_e32 v111, v94, v98
	v_fmac_f32_e32 v105, v95, v99
	v_fmac_f32_e32 v112, v88, v100
	v_fmac_f32_e32 v106, v89, v101
	v_fmac_f32_e32 v113, v90, v102
	v_fmac_f32_e32 v107, v91, v103
	v_cvt_pk_bf16_f32 v88, v110, v104
	v_cvt_pk_bf16_f32 v89, v111, v105
	v_cvt_pk_bf16_f32 v90, v112, v106
	v_cvt_pk_bf16_f32 v91, v113, v107
	global_load_dwordx4 v[92:95], v[118:119], off offset:256
	global_load_dwordx4 v[96:99], v[108:109], off offset:256
	v_or_b32_e32 v100, 48, v146
	global_store_dwordx4 v[108:109], v[88:91], off
	v_mad_i64_i32 v[102:103], s[18:19], v100, s41, v[148:149]
	v_lshl_add_u64 v[102:103], v[102:103], 0, v[144:145]
	s_waitcnt vmcnt(0)
	v_lshlrev_b32_e32 v88, 16, v92
	v_lshlrev_b32_e32 v101, 16, v96
	v_and_b32_e32 v89, 0xffff0000, v92
	v_lshlrev_b32_e32 v92, 16, v94
	v_and_b32_e32 v96, 0xffff0000, v96
	v_lshlrev_b32_e32 v105, 16, v98
	v_fmac_f32_e32 v101, v84, v88
	v_fmac_f32_e32 v96, v85, v89
	v_fmac_f32_e32 v105, v80, v92
	v_cvt_pk_bf16_f32 v80, v101, v96
	v_ashrrev_i32_e32 v101, 31, v100
	v_lshlrev_b64 v[88:89], 11, v[100:101]
	v_lshlrev_b32_e32 v90, 16, v93
	v_and_b32_e32 v91, 0xffff0000, v93
	v_and_b32_e32 v93, 0xffff0000, v94
	v_and_b32_e32 v98, 0xffff0000, v98
	v_lshl_add_u64 v[88:89], s[0:1], 0, v[88:89]
	v_lshlrev_b32_e32 v94, 16, v95
	v_and_b32_e32 v95, 0xffff0000, v95
	v_lshlrev_b32_e32 v104, 16, v97
	v_and_b32_e32 v97, 0xffff0000, v97
	v_lshlrev_b32_e32 v106, 16, v99
	v_and_b32_e32 v99, 0xffff0000, v99
	v_fmac_f32_e32 v98, v81, v93
	v_lshl_add_u64 v[92:93], v[88:89], 0, v[144:145]
	v_fmac_f32_e32 v104, v86, v90
	v_fmac_f32_e32 v97, v87, v91
	v_fmac_f32_e32 v106, v82, v94
	v_fmac_f32_e32 v99, v83, v95
	v_cvt_pk_bf16_f32 v81, v104, v97
	v_cvt_pk_bf16_f32 v82, v105, v98
	v_cvt_pk_bf16_f32 v83, v106, v99
	global_load_dwordx4 v[84:87], v[102:103], off
	global_load_dwordx4 v[88:91], v[92:93], off
	s_waitcnt vmcnt(0)
	v_lshlrev_b32_e32 v94, 16, v88
	global_store_dwordx4 v[108:109], v[80:83], off offset:256
	v_and_b32_e32 v88, 0xffff0000, v88
	v_lshlrev_b32_e32 v95, 16, v89
	v_lshlrev_b32_e32 v80, 16, v84
	v_and_b32_e32 v81, 0xffff0000, v84
	v_lshlrev_b32_e32 v82, 16, v85
	v_and_b32_e32 v83, 0xffff0000, v85
	v_lshlrev_b32_e32 v84, 16, v86
	v_and_b32_e32 v85, 0xffff0000, v86
	v_lshlrev_b32_e32 v86, 16, v87
	v_and_b32_e32 v87, 0xffff0000, v87
	v_and_b32_e32 v89, 0xffff0000, v89
	v_lshlrev_b32_e32 v96, 16, v90
	v_and_b32_e32 v90, 0xffff0000, v90
	v_lshlrev_b32_e32 v97, 16, v91
	v_and_b32_e32 v91, 0xffff0000, v91
	v_fmac_f32_e32 v94, v76, v80
	v_fmac_f32_e32 v88, v77, v81
	v_fmac_f32_e32 v95, v78, v82
	v_fmac_f32_e32 v89, v79, v83
	v_fmac_f32_e32 v96, v72, v84
	v_fmac_f32_e32 v90, v73, v85
	v_fmac_f32_e32 v97, v74, v86
	v_fmac_f32_e32 v91, v75, v87
	v_cvt_pk_bf16_f32 v72, v94, v88
	v_cvt_pk_bf16_f32 v73, v95, v89
	v_cvt_pk_bf16_f32 v74, v96, v90
	v_cvt_pk_bf16_f32 v75, v97, v91
	global_load_dwordx4 v[76:79], v[102:103], off offset:256
	global_load_dwordx4 v[80:83], v[92:93], off offset:256
	v_add_u32_e32 v84, 0x80, v146
	global_store_dwordx4 v[92:93], v[72:75], off
	v_mad_i64_i32 v[86:87], s[18:19], v84, s41, v[148:149]
	v_lshl_add_u64 v[86:87], v[86:87], 0, v[144:145]
	s_waitcnt vmcnt(0)
	v_lshlrev_b32_e32 v72, 16, v76
	v_lshlrev_b32_e32 v85, 16, v80
	v_and_b32_e32 v73, 0xffff0000, v76
	v_lshlrev_b32_e32 v76, 16, v78
	v_and_b32_e32 v80, 0xffff0000, v80
	v_lshlrev_b32_e32 v89, 16, v82
	v_fmac_f32_e32 v85, v68, v72
	v_fmac_f32_e32 v80, v69, v73
	v_fmac_f32_e32 v89, v64, v76
	v_cvt_pk_bf16_f32 v64, v85, v80
	v_ashrrev_i32_e32 v85, 31, v84
	v_lshlrev_b64 v[72:73], 11, v[84:85]
	v_lshlrev_b32_e32 v74, 16, v77
	v_and_b32_e32 v75, 0xffff0000, v77
	v_and_b32_e32 v77, 0xffff0000, v78
	v_and_b32_e32 v82, 0xffff0000, v82
	v_lshl_add_u64 v[72:73], s[0:1], 0, v[72:73]
	v_lshlrev_b32_e32 v78, 16, v79
	v_and_b32_e32 v79, 0xffff0000, v79
	v_lshlrev_b32_e32 v88, 16, v81
	v_and_b32_e32 v81, 0xffff0000, v81
	v_lshlrev_b32_e32 v90, 16, v83
	v_and_b32_e32 v83, 0xffff0000, v83
	v_fmac_f32_e32 v82, v65, v77
	v_lshl_add_u64 v[76:77], v[72:73], 0, v[144:145]
	v_fmac_f32_e32 v88, v70, v74
	v_fmac_f32_e32 v81, v71, v75
	v_fmac_f32_e32 v90, v66, v78
	v_fmac_f32_e32 v83, v67, v79
	v_cvt_pk_bf16_f32 v65, v88, v81
	v_cvt_pk_bf16_f32 v66, v89, v82
	v_cvt_pk_bf16_f32 v67, v90, v83
	global_load_dwordx4 v[68:71], v[86:87], off
	global_load_dwordx4 v[72:75], v[76:77], off
	s_waitcnt vmcnt(0)
	v_lshlrev_b32_e32 v78, 16, v72
	global_store_dwordx4 v[92:93], v[64:67], off offset:256
	v_and_b32_e32 v72, 0xffff0000, v72
	v_lshlrev_b32_e32 v79, 16, v73
	v_lshlrev_b32_e32 v64, 16, v68
	v_and_b32_e32 v65, 0xffff0000, v68
	v_lshlrev_b32_e32 v66, 16, v69
	v_and_b32_e32 v67, 0xffff0000, v69
	v_lshlrev_b32_e32 v68, 16, v70
	v_and_b32_e32 v69, 0xffff0000, v70
	v_lshlrev_b32_e32 v70, 16, v71
	v_and_b32_e32 v71, 0xffff0000, v71
	v_and_b32_e32 v73, 0xffff0000, v73
	v_lshlrev_b32_e32 v80, 16, v74
	v_and_b32_e32 v74, 0xffff0000, v74
	v_lshlrev_b32_e32 v81, 16, v75
	v_and_b32_e32 v75, 0xffff0000, v75
	v_fmac_f32_e32 v78, v60, v64
	v_fmac_f32_e32 v72, v61, v65
	v_fmac_f32_e32 v79, v62, v66
	v_fmac_f32_e32 v73, v63, v67
	v_fmac_f32_e32 v80, v56, v68
	v_fmac_f32_e32 v74, v57, v69
	v_fmac_f32_e32 v81, v58, v70
	v_fmac_f32_e32 v75, v59, v71
	v_cvt_pk_bf16_f32 v56, v78, v72
	v_cvt_pk_bf16_f32 v57, v79, v73
	v_cvt_pk_bf16_f32 v58, v80, v74
	v_cvt_pk_bf16_f32 v59, v81, v75
	global_load_dwordx4 v[60:63], v[86:87], off offset:256
	global_load_dwordx4 v[64:67], v[76:77], off offset:256
	v_add_u32_e32 v68, 0x90, v146
	global_store_dwordx4 v[76:77], v[56:59], off
	v_mad_i64_i32 v[70:71], s[18:19], v68, s41, v[148:149]
	v_lshl_add_u64 v[70:71], v[70:71], 0, v[144:145]
	s_waitcnt vmcnt(0)
	v_lshlrev_b32_e32 v56, 16, v60
	v_lshlrev_b32_e32 v69, 16, v64
	v_and_b32_e32 v57, 0xffff0000, v60
	v_lshlrev_b32_e32 v60, 16, v62
	v_and_b32_e32 v64, 0xffff0000, v64
	v_lshlrev_b32_e32 v73, 16, v66
	v_fmac_f32_e32 v69, v52, v56
	v_fmac_f32_e32 v64, v53, v57
	v_fmac_f32_e32 v73, v48, v60
	v_cvt_pk_bf16_f32 v48, v69, v64
	v_ashrrev_i32_e32 v69, 31, v68
	v_lshlrev_b64 v[56:57], 11, v[68:69]
	v_lshlrev_b32_e32 v58, 16, v61
	v_and_b32_e32 v59, 0xffff0000, v61
	v_and_b32_e32 v61, 0xffff0000, v62
	v_and_b32_e32 v66, 0xffff0000, v66
	v_lshl_add_u64 v[56:57], s[0:1], 0, v[56:57]
	v_lshlrev_b32_e32 v62, 16, v63
	v_and_b32_e32 v63, 0xffff0000, v63
	v_lshlrev_b32_e32 v72, 16, v65
	v_and_b32_e32 v65, 0xffff0000, v65
	v_lshlrev_b32_e32 v74, 16, v67
	v_and_b32_e32 v67, 0xffff0000, v67
	v_fmac_f32_e32 v66, v49, v61
	v_lshl_add_u64 v[60:61], v[56:57], 0, v[144:145]
	v_fmac_f32_e32 v72, v54, v58
	v_fmac_f32_e32 v65, v55, v59
	v_fmac_f32_e32 v74, v50, v62
	v_fmac_f32_e32 v67, v51, v63
	v_cvt_pk_bf16_f32 v49, v72, v65
	v_cvt_pk_bf16_f32 v50, v73, v66
	v_cvt_pk_bf16_f32 v51, v74, v67
	global_load_dwordx4 v[52:55], v[70:71], off
	global_load_dwordx4 v[56:59], v[60:61], off
	s_waitcnt vmcnt(0)
	v_lshlrev_b32_e32 v62, 16, v56
	global_store_dwordx4 v[76:77], v[48:51], off offset:256
	v_and_b32_e32 v56, 0xffff0000, v56
	v_lshlrev_b32_e32 v63, 16, v57
	v_lshlrev_b32_e32 v48, 16, v52
	v_and_b32_e32 v49, 0xffff0000, v52
	v_lshlrev_b32_e32 v50, 16, v53
	v_and_b32_e32 v51, 0xffff0000, v53
	v_lshlrev_b32_e32 v52, 16, v54
	v_and_b32_e32 v53, 0xffff0000, v54
	v_lshlrev_b32_e32 v54, 16, v55
	v_and_b32_e32 v55, 0xffff0000, v55
	v_and_b32_e32 v57, 0xffff0000, v57
	v_lshlrev_b32_e32 v64, 16, v58
	v_and_b32_e32 v58, 0xffff0000, v58
	v_lshlrev_b32_e32 v65, 16, v59
	v_and_b32_e32 v59, 0xffff0000, v59
	v_fmac_f32_e32 v62, v44, v48
	v_fmac_f32_e32 v56, v45, v49
	v_fmac_f32_e32 v63, v46, v50
	v_fmac_f32_e32 v57, v47, v51
	v_fmac_f32_e32 v64, v40, v52
	v_fmac_f32_e32 v58, v41, v53
	v_fmac_f32_e32 v65, v42, v54
	v_fmac_f32_e32 v59, v43, v55
	v_cvt_pk_bf16_f32 v40, v62, v56
	v_cvt_pk_bf16_f32 v41, v63, v57
	v_cvt_pk_bf16_f32 v42, v64, v58
	v_cvt_pk_bf16_f32 v43, v65, v59
	global_load_dwordx4 v[44:47], v[70:71], off offset:256
	global_load_dwordx4 v[48:51], v[60:61], off offset:256
	v_add_u32_e32 v52, 0xa0, v146
	global_store_dwordx4 v[60:61], v[40:43], off
	v_mad_i64_i32 v[54:55], s[18:19], v52, s41, v[148:149]
	v_lshl_add_u64 v[54:55], v[54:55], 0, v[144:145]
	s_waitcnt vmcnt(0)
	v_lshlrev_b32_e32 v40, 16, v44
	v_lshlrev_b32_e32 v53, 16, v48
	v_and_b32_e32 v41, 0xffff0000, v44
	v_lshlrev_b32_e32 v44, 16, v46
	v_and_b32_e32 v48, 0xffff0000, v48
	v_lshlrev_b32_e32 v57, 16, v50
	v_fmac_f32_e32 v53, v36, v40
	v_fmac_f32_e32 v48, v37, v41
	v_fmac_f32_e32 v57, v32, v44
	v_cvt_pk_bf16_f32 v32, v53, v48
	v_ashrrev_i32_e32 v53, 31, v52
	v_lshlrev_b64 v[40:41], 11, v[52:53]
	v_lshlrev_b32_e32 v42, 16, v45
	v_and_b32_e32 v43, 0xffff0000, v45
	v_and_b32_e32 v45, 0xffff0000, v46
	v_and_b32_e32 v50, 0xffff0000, v50
	v_lshl_add_u64 v[40:41], s[0:1], 0, v[40:41]
	v_lshlrev_b32_e32 v46, 16, v47
	v_and_b32_e32 v47, 0xffff0000, v47
	v_lshlrev_b32_e32 v56, 16, v49
	v_and_b32_e32 v49, 0xffff0000, v49
	v_lshlrev_b32_e32 v58, 16, v51
	v_and_b32_e32 v51, 0xffff0000, v51
	v_fmac_f32_e32 v50, v33, v45
	v_lshl_add_u64 v[44:45], v[40:41], 0, v[144:145]
	v_fmac_f32_e32 v56, v38, v42
	v_fmac_f32_e32 v49, v39, v43
	v_fmac_f32_e32 v58, v34, v46
	v_fmac_f32_e32 v51, v35, v47
	v_cvt_pk_bf16_f32 v33, v56, v49
	v_cvt_pk_bf16_f32 v34, v57, v50
	v_cvt_pk_bf16_f32 v35, v58, v51
	global_load_dwordx4 v[36:39], v[54:55], off
	global_load_dwordx4 v[40:43], v[44:45], off
	s_waitcnt vmcnt(0)
	v_lshlrev_b32_e32 v46, 16, v40
	global_store_dwordx4 v[60:61], v[32:35], off offset:256
	v_and_b32_e32 v40, 0xffff0000, v40
	v_lshlrev_b32_e32 v47, 16, v41
	v_lshlrev_b32_e32 v32, 16, v36
	v_and_b32_e32 v33, 0xffff0000, v36
	v_lshlrev_b32_e32 v34, 16, v37
	v_and_b32_e32 v35, 0xffff0000, v37
	v_lshlrev_b32_e32 v36, 16, v38
	v_and_b32_e32 v37, 0xffff0000, v38
	v_lshlrev_b32_e32 v38, 16, v39
	v_and_b32_e32 v39, 0xffff0000, v39
	v_and_b32_e32 v41, 0xffff0000, v41
	v_lshlrev_b32_e32 v48, 16, v42
	v_and_b32_e32 v42, 0xffff0000, v42
	v_lshlrev_b32_e32 v49, 16, v43
	v_and_b32_e32 v43, 0xffff0000, v43
	v_fmac_f32_e32 v46, v28, v32
	v_fmac_f32_e32 v40, v29, v33
	v_fmac_f32_e32 v47, v30, v34
	v_fmac_f32_e32 v41, v31, v35
	v_fmac_f32_e32 v48, v24, v36
	v_fmac_f32_e32 v42, v25, v37
	v_fmac_f32_e32 v49, v26, v38
	v_fmac_f32_e32 v43, v27, v39
	v_cvt_pk_bf16_f32 v24, v46, v40
	v_cvt_pk_bf16_f32 v25, v47, v41
	v_cvt_pk_bf16_f32 v26, v48, v42
	v_cvt_pk_bf16_f32 v27, v49, v43
	global_load_dwordx4 v[28:31], v[54:55], off offset:256
	global_load_dwordx4 v[32:35], v[44:45], off offset:256
	v_add_u32_e32 v36, 0xb0, v146
	global_store_dwordx4 v[44:45], v[24:27], off
	v_mad_i64_i32 v[38:39], s[18:19], v36, s41, v[148:149]
	v_lshl_add_u64 v[38:39], v[38:39], 0, v[144:145]
	s_mov_b64 s[18:19], s[12:13]
	s_waitcnt vmcnt(0)
	v_lshlrev_b32_e32 v24, 16, v28
	v_lshlrev_b32_e32 v37, 16, v32
	v_and_b32_e32 v25, 0xffff0000, v28
	v_lshlrev_b32_e32 v28, 16, v30
	v_and_b32_e32 v32, 0xffff0000, v32
	v_lshlrev_b32_e32 v41, 16, v34
	v_fmac_f32_e32 v37, v20, v24
	v_fmac_f32_e32 v32, v21, v25
	v_fmac_f32_e32 v41, v16, v28
	v_cvt_pk_bf16_f32 v16, v37, v32
	v_ashrrev_i32_e32 v37, 31, v36
	v_lshlrev_b64 v[24:25], 11, v[36:37]
	v_lshlrev_b32_e32 v26, 16, v29
	v_and_b32_e32 v27, 0xffff0000, v29
	v_and_b32_e32 v29, 0xffff0000, v30
	v_and_b32_e32 v34, 0xffff0000, v34
	v_lshl_add_u64 v[24:25], s[0:1], 0, v[24:25]
	v_lshlrev_b32_e32 v30, 16, v31
	v_and_b32_e32 v31, 0xffff0000, v31
	v_lshlrev_b32_e32 v40, 16, v33
	v_and_b32_e32 v33, 0xffff0000, v33
	v_lshlrev_b32_e32 v42, 16, v35
	v_and_b32_e32 v35, 0xffff0000, v35
	v_fmac_f32_e32 v34, v17, v29
	v_lshl_add_u64 v[28:29], v[24:25], 0, v[144:145]
	v_fmac_f32_e32 v40, v22, v26
	v_fmac_f32_e32 v33, v23, v27
	v_fmac_f32_e32 v42, v18, v30
	v_fmac_f32_e32 v35, v19, v31
	v_cvt_pk_bf16_f32 v17, v40, v33
	v_cvt_pk_bf16_f32 v18, v41, v34
	v_cvt_pk_bf16_f32 v19, v42, v35
	global_load_dwordx4 v[20:23], v[38:39], off
	global_load_dwordx4 v[24:27], v[28:29], off
	s_waitcnt vmcnt(0)
	v_lshlrev_b32_e32 v30, 16, v24
	global_store_dwordx4 v[44:45], v[16:19], off offset:256
	v_and_b32_e32 v24, 0xffff0000, v24
	v_lshlrev_b32_e32 v31, 16, v25
	v_lshlrev_b32_e32 v16, 16, v20
	v_and_b32_e32 v17, 0xffff0000, v20
	v_lshlrev_b32_e32 v18, 16, v21
	v_and_b32_e32 v19, 0xffff0000, v21
	v_lshlrev_b32_e32 v20, 16, v22
	v_and_b32_e32 v21, 0xffff0000, v22
	v_lshlrev_b32_e32 v22, 16, v23
	v_and_b32_e32 v23, 0xffff0000, v23
	v_and_b32_e32 v25, 0xffff0000, v25
	v_lshlrev_b32_e32 v32, 16, v26
	v_and_b32_e32 v26, 0xffff0000, v26
	v_lshlrev_b32_e32 v33, 16, v27
	v_and_b32_e32 v27, 0xffff0000, v27
	v_fmac_f32_e32 v30, v12, v16
	v_fmac_f32_e32 v24, v13, v17
	v_fmac_f32_e32 v31, v14, v18
	v_fmac_f32_e32 v25, v15, v19
	v_fmac_f32_e32 v32, v8, v20
	v_fmac_f32_e32 v26, v9, v21
	v_fmac_f32_e32 v33, v10, v22
	v_fmac_f32_e32 v27, v11, v23
	v_cvt_pk_bf16_f32 v8, v30, v24
	v_cvt_pk_bf16_f32 v9, v31, v25
	v_cvt_pk_bf16_f32 v10, v32, v26
	v_cvt_pk_bf16_f32 v11, v33, v27
	global_load_dwordx4 v[12:15], v[38:39], off offset:256
	global_load_dwordx4 v[16:19], v[28:29], off offset:256
	s_waitcnt vmcnt(0)
	v_lshlrev_b32_e32 v20, 16, v16
	global_store_dwordx4 v[28:29], v[8:11], off
	v_and_b32_e32 v16, 0xffff0000, v16
	v_lshlrev_b32_e32 v21, 16, v17
	v_lshlrev_b32_e32 v8, 16, v12
	v_and_b32_e32 v9, 0xffff0000, v12
	v_lshlrev_b32_e32 v10, 16, v13
	v_and_b32_e32 v11, 0xffff0000, v13
	v_lshlrev_b32_e32 v12, 16, v14
	v_and_b32_e32 v13, 0xffff0000, v14
	v_lshlrev_b32_e32 v14, 16, v15
	v_and_b32_e32 v15, 0xffff0000, v15
	v_and_b32_e32 v17, 0xffff0000, v17
	v_lshlrev_b32_e32 v22, 16, v18
	v_and_b32_e32 v18, 0xffff0000, v18
	v_lshlrev_b32_e32 v23, 16, v19
	v_and_b32_e32 v19, 0xffff0000, v19
	v_fmac_f32_e32 v20, v4, v8
	v_fmac_f32_e32 v16, v5, v9
	v_fmac_f32_e32 v21, v6, v10
	v_fmac_f32_e32 v17, v7, v11
	v_fmac_f32_e32 v22, v0, v12
	v_fmac_f32_e32 v18, v1, v13
	v_fmac_f32_e32 v23, v2, v14
	v_fmac_f32_e32 v19, v3, v15
	v_cvt_pk_bf16_f32 v0, v20, v16
	v_cvt_pk_bf16_f32 v1, v21, v17
	v_cvt_pk_bf16_f32 v2, v22, v18
	v_cvt_pk_bf16_f32 v3, v23, v19
	global_store_dwordx4 v[28:29], v[0:3], off offset:256
	s_cbranch_vccz .LBB0_1004
	s_waitcnt vmcnt(0)
	s_cmpk_gt_u32 s25, 0xff
	s_cbranch_scc1 .LBB0_1015
	s_barrier

.LBB0_1083:
	ds_read_b128 v[152:155], v149
	ds_read_b128 v[156:159], v149 offset:1024
	ds_read_b128 v[160:163], v149 offset:2048
	ds_read_b128 v[164:167], v149 offset:3072
	s_add_u32 s26, s24, 0xfffc0080
	s_addc_u32 s27, s25, -1
	s_cmp_eq_u32 s56, 12
	s_cselect_b32 s29, s17, s27
	s_cselect_b32 s28, s52, s26
	s_cselect_b32 s27, s15, s55
	s_cselect_b32 s26, s53, s54
	v_lshl_add_u64 v[144:145], s[24:25], 0, v[136:137]
	s_add_i32 m0, s23, 0xc000
	ds_read_b128 v[168:171], v150
	ds_read_b128 v[172:175], v150 offset:1024
	ds_read_b128 v[182:185], v150 offset:2048
	ds_read_b128 v[190:193], v150 offset:3072
	ds_read_b128 v[194:197], v150 offset:4096
	ds_read_b128 v[198:201], v150 offset:5120
	ds_read_b128 v[202:205], v150 offset:6144
	ds_read_b128 v[206:209], v150 offset:7168
	global_load_lds_dwordx4 v[144:145], off
	v_lshl_add_u64 v[144:145], s[24:25], 0, v[138:139]
	s_add_i32 m0, s23, 0xe000
	s_nop 0
	global_load_lds_dwordx4 v[144:145], off
	s_waitcnt lgkmcnt(8)
	s_barrier
	s_waitcnt lgkmcnt(0)
	s_waitcnt lgkmcnt(0)
	v_mfma_f32_16x16x32_bf16 v[124:127], v[152:155], v[168:171], v[124:127]
	v_mfma_f32_16x16x32_bf16 v[120:123], v[160:163], v[168:171], v[120:123]
	v_mfma_f32_16x16x32_bf16 v[108:111], v[152:155], v[182:185], v[108:111]
	v_mfma_f32_16x16x32_bf16 v[104:107], v[160:163], v[182:185], v[104:107]
	v_mfma_f32_16x16x32_bf16 v[92:95], v[152:155], v[194:197], v[92:95]
	v_mfma_f32_16x16x32_bf16 v[88:91], v[160:163], v[194:197], v[88:91]
	v_mfma_f32_16x16x32_bf16 v[76:79], v[152:155], v[202:205], v[76:79]
	v_mfma_f32_16x16x32_bf16 v[72:75], v[160:163], v[202:205], v[72:75]
	v_mfma_f32_16x16x32_bf16 v[124:127], v[156:159], v[172:175], v[124:127]
	v_mfma_f32_16x16x32_bf16 v[120:123], v[164:167], v[172:175], v[120:123]
	v_mfma_f32_16x16x32_bf16 v[108:111], v[156:159], v[190:193], v[108:111]
	v_mfma_f32_16x16x32_bf16 v[104:107], v[164:167], v[190:193], v[104:107]
	v_mfma_f32_16x16x32_bf16 v[92:95], v[156:159], v[198:201], v[92:95]
	v_mfma_f32_16x16x32_bf16 v[88:91], v[164:167], v[198:201], v[88:91]
	v_mfma_f32_16x16x32_bf16 v[76:79], v[156:159], v[206:209], v[76:79]
	v_mfma_f32_16x16x32_bf16 v[72:75], v[164:167], v[206:209], v[72:75]
	s_barrier
	s_add_i32 s57, s45, s37
	v_lshl_add_u64 v[144:145], s[26:27], 0, v[130:131]
	s_mov_b32 m0, s57
	ds_read_b128 v[210:213], v151
	ds_read_b128 v[214:217], v151 offset:1024
	ds_read_b128 v[218:221], v151 offset:2048
	ds_read_b128 v[222:225], v151 offset:3072
	global_load_lds_dwordx4 v[144:145], off
	v_lshl_add_u64 v[186:187], s[26:27], 0, v[134:135]
	s_add_i32 m0, s57, 0x2000
	s_nop 0
	global_load_lds_dwordx4 v[186:187], off
	s_barrier
	s_waitcnt lgkmcnt(0)
	s_waitcnt lgkmcnt(0)
	v_mfma_f32_16x16x32_bf16 v[116:119], v[210:213], v[168:171], v[116:119]
	v_mfma_f32_16x16x32_bf16 v[112:115], v[218:221], v[168:171], v[112:115]
	v_mfma_f32_16x16x32_bf16 v[100:103], v[210:213], v[182:185], v[100:103]
	v_mfma_f32_16x16x32_bf16 v[96:99], v[218:221], v[182:185], v[96:99]
	v_mfma_f32_16x16x32_bf16 v[84:87], v[210:213], v[194:197], v[84:87]
	v_mfma_f32_16x16x32_bf16 v[80:83], v[218:221], v[194:197], v[80:83]
	v_mfma_f32_16x16x32_bf16 v[68:71], v[210:213], v[202:205], v[68:71]
	v_mfma_f32_16x16x32_bf16 v[64:67], v[218:221], v[202:205], v[64:67]
	v_mfma_f32_16x16x32_bf16 v[116:119], v[214:217], v[172:175], v[116:119]
	v_mfma_f32_16x16x32_bf16 v[112:115], v[222:225], v[172:175], v[112:115]
	v_mfma_f32_16x16x32_bf16 v[100:103], v[214:217], v[190:193], v[100:103]
	v_mfma_f32_16x16x32_bf16 v[96:99], v[222:225], v[190:193], v[96:99]
	v_mfma_f32_16x16x32_bf16 v[84:87], v[214:217], v[198:201], v[84:87]
	v_mfma_f32_16x16x32_bf16 v[80:83], v[222:225], v[198:201], v[80:83]
	v_mfma_f32_16x16x32_bf16 v[68:71], v[214:217], v[206:209], v[68:71]
	v_mfma_f32_16x16x32_bf16 v[64:67], v[222:225], v[206:209], v[64:67]
	s_mov_b32 m0, s23
	v_lshl_add_u64 v[226:227], s[28:29], 0, v[128:129]
	s_barrier
	ds_read_b128 v[168:171], v150 offset:16384
	ds_read_b128 v[172:175], v150 offset:17408
	ds_read_b128 v[182:185], v150 offset:18432
	ds_read_b128 v[190:193], v150 offset:19456
	ds_read_b128 v[194:197], v150 offset:20480
	ds_read_b128 v[198:201], v150 offset:21504
	ds_read_b128 v[202:205], v150 offset:22528
	ds_read_b128 v[206:209], v150 offset:23552
	global_load_lds_dwordx4 v[226:227], off
	v_lshl_add_u64 v[228:229], s[28:29], 0, v[132:133]
	s_mov_b32 m0, s38
	s_nop 0
	global_load_lds_dwordx4 v[228:229], off
	s_barrier
	s_waitcnt lgkmcnt(0)
	s_waitcnt lgkmcnt(0)
	v_mfma_f32_16x16x32_bf16 v[60:63], v[152:155], v[168:171], v[60:63]
	v_mfma_f32_16x16x32_bf16 v[56:59], v[160:163], v[168:171], v[56:59]
	v_mfma_f32_16x16x32_bf16 v[48:51], v[152:155], v[182:185], v[48:51]
	v_mfma_f32_16x16x32_bf16 v[40:43], v[160:163], v[182:185], v[40:43]
	v_mfma_f32_16x16x32_bf16 v[32:35], v[152:155], v[194:197], v[32:35]
	v_mfma_f32_16x16x32_bf16 v[24:27], v[160:163], v[194:197], v[24:27]
	v_mfma_f32_16x16x32_bf16 v[16:19], v[152:155], v[202:205], v[16:19]
	v_mfma_f32_16x16x32_bf16 v[8:11], v[160:163], v[202:205], v[8:11]
	v_mfma_f32_16x16x32_bf16 v[60:63], v[156:159], v[172:175], v[60:63]
	v_mfma_f32_16x16x32_bf16 v[56:59], v[164:167], v[172:175], v[56:59]
	v_mfma_f32_16x16x32_bf16 v[48:51], v[156:159], v[190:193], v[48:51]
	v_mfma_f32_16x16x32_bf16 v[40:43], v[164:167], v[190:193], v[40:43]
	v_mfma_f32_16x16x32_bf16 v[32:35], v[156:159], v[198:201], v[32:35]
	v_mfma_f32_16x16x32_bf16 v[24:27], v[164:167], v[198:201], v[24:27]
	v_mfma_f32_16x16x32_bf16 v[16:19], v[156:159], v[206:209], v[16:19]
	v_mfma_f32_16x16x32_bf16 v[8:11], v[164:167], v[206:209], v[8:11]
	s_barrier
	s_add_u32 s58, s26, 0x40000
	s_addc_u32 s59, s27, 0
	s_add_i32 s57, s46, s37
	v_lshl_add_u64 v[152:153], s[58:59], 0, v[130:131]
	s_mov_b32 m0, s57
	s_nop 0
	global_load_lds_dwordx4 v[152:153], off
	v_lshl_add_u64 v[152:153], s[58:59], 0, v[134:135]
	s_add_i32 m0, s57, 0x2000
	s_nop 0
	global_load_lds_dwordx4 v[152:153], off
	s_waitcnt vmcnt(6)
	s_barrier
	v_mfma_f32_16x16x32_bf16 v[52:55], v[210:213], v[168:171], v[52:55]
	v_mfma_f32_16x16x32_bf16 v[44:47], v[218:221], v[168:171], v[44:47]
	v_mfma_f32_16x16x32_bf16 v[36:39], v[210:213], v[182:185], v[36:39]
	v_mfma_f32_16x16x32_bf16 v[28:31], v[218:221], v[182:185], v[28:31]
	v_mfma_f32_16x16x32_bf16 v[20:23], v[210:213], v[194:197], v[20:23]
	v_mfma_f32_16x16x32_bf16 v[12:15], v[218:221], v[194:197], v[12:15]
	v_mfma_f32_16x16x32_bf16 v[4:7], v[210:213], v[202:205], v[4:7]
	v_mfma_f32_16x16x32_bf16 v[0:3], v[218:221], v[202:205], v[0:3]
	v_mfma_f32_16x16x32_bf16 v[52:55], v[214:217], v[172:175], v[52:55]
	v_mfma_f32_16x16x32_bf16 v[44:47], v[222:225], v[172:175], v[44:47]
	v_mfma_f32_16x16x32_bf16 v[36:39], v[214:217], v[190:193], v[36:39]
	v_mfma_f32_16x16x32_bf16 v[28:31], v[222:225], v[190:193], v[28:31]
	v_mfma_f32_16x16x32_bf16 v[20:23], v[214:217], v[198:201], v[20:23]
	v_mfma_f32_16x16x32_bf16 v[12:15], v[222:225], v[198:201], v[12:15]
	v_mfma_f32_16x16x32_bf16 v[4:7], v[214:217], v[206:209], v[4:7]
	v_mfma_f32_16x16x32_bf16 v[0:3], v[222:225], v[206:209], v[0:3]
	s_add_i32 s57, 0, 0x18000
	v_add_u32_e32 v164, s57, v147
	s_barrier
	ds_read_b128 v[152:155], v164
	ds_read_b128 v[156:159], v164 offset:1024
	ds_read_b128 v[160:163], v164 offset:2048
	ds_read_b128 v[164:167], v164 offset:3072
	s_add_u32 s28, s28, 0x40000
	s_addc_u32 s29, s29, 0
	s_mov_b32 m0, s39
	v_lshl_add_u64 v[210:211], s[28:29], 0, v[128:129]
	ds_read_b128 v[168:171], v150 offset:32768
	ds_read_b128 v[172:175], v150 offset:33792
	ds_read_b128 v[182:185], v150 offset:34816
	ds_read_b128 v[190:193], v150 offset:35840
	ds_read_b128 v[194:197], v150 offset:36864
	ds_read_b128 v[198:201], v150 offset:37888
	ds_read_b128 v[202:205], v150 offset:38912
	ds_read_b128 v[206:209], v150 offset:39936
	global_load_lds_dwordx4 v[210:211], off
	v_lshl_add_u64 v[210:211], s[28:29], 0, v[132:133]
	s_mov_b32 m0, s40
	s_nop 0
	global_load_lds_dwordx4 v[210:211], off
	s_waitcnt lgkmcnt(8)
	s_barrier
	s_waitcnt lgkmcnt(0)
	s_waitcnt lgkmcnt(0)
	v_mfma_f32_16x16x32_bf16 v[124:127], v[152:155], v[168:171], v[124:127]
	v_mfma_f32_16x16x32_bf16 v[120:123], v[160:163], v[168:171], v[120:123]
	v_mfma_f32_16x16x32_bf16 v[108:111], v[152:155], v[182:185], v[108:111]
	v_mfma_f32_16x16x32_bf16 v[104:107], v[160:163], v[182:185], v[104:107]
	v_mfma_f32_16x16x32_bf16 v[92:95], v[152:155], v[194:197], v[92:95]
	v_mfma_f32_16x16x32_bf16 v[88:91], v[160:163], v[194:197], v[88:91]
	v_mfma_f32_16x16x32_bf16 v[76:79], v[152:155], v[202:205], v[76:79]
	v_mfma_f32_16x16x32_bf16 v[72:75], v[160:163], v[202:205], v[72:75]
	v_mfma_f32_16x16x32_bf16 v[124:127], v[156:159], v[172:175], v[124:127]
	v_mfma_f32_16x16x32_bf16 v[120:123], v[164:167], v[172:175], v[120:123]
	v_mfma_f32_16x16x32_bf16 v[108:111], v[156:159], v[190:193], v[108:111]
	v_mfma_f32_16x16x32_bf16 v[104:107], v[164:167], v[190:193], v[104:107]
	v_mfma_f32_16x16x32_bf16 v[92:95], v[156:159], v[198:201], v[92:95]
	v_mfma_f32_16x16x32_bf16 v[88:91], v[164:167], v[198:201], v[88:91]
	v_mfma_f32_16x16x32_bf16 v[76:79], v[156:159], v[206:209], v[76:79]
	v_mfma_f32_16x16x32_bf16 v[72:75], v[164:167], v[206:209], v[72:75]
	s_barrier
	s_add_i32 s28, 0, 0x1c000
	s_add_i32 s29, s57, s37
	v_add_u32_e32 v179, s28, v147
	v_lshl_add_u64 v[144:145], v[144:145], 0, s[6:7]
	s_mov_b32 m0, s29
	ds_read_b128 v[210:213], v179
	ds_read_b128 v[214:217], v179 offset:1024
	ds_read_b128 v[218:221], v179 offset:2048
	ds_read_b128 v[222:225], v179 offset:3072
	global_load_lds_dwordx4 v[144:145], off
	v_lshl_add_u64 v[144:145], v[186:187], 0, s[6:7]
	s_add_i32 m0, s29, 0x2000
	s_nop 0
	global_load_lds_dwordx4 v[144:145], off
	s_barrier
	s_waitcnt lgkmcnt(0)
	s_waitcnt lgkmcnt(0)
	v_mfma_f32_16x16x32_bf16 v[116:119], v[210:213], v[168:171], v[116:119]
	v_mfma_f32_16x16x32_bf16 v[112:115], v[218:221], v[168:171], v[112:115]
	v_mfma_f32_16x16x32_bf16 v[100:103], v[210:213], v[182:185], v[100:103]
	v_mfma_f32_16x16x32_bf16 v[96:99], v[218:221], v[182:185], v[96:99]
	v_mfma_f32_16x16x32_bf16 v[84:87], v[210:213], v[194:197], v[84:87]
	v_mfma_f32_16x16x32_bf16 v[80:83], v[218:221], v[194:197], v[80:83]
	v_mfma_f32_16x16x32_bf16 v[68:71], v[210:213], v[202:205], v[68:71]
	v_mfma_f32_16x16x32_bf16 v[64:67], v[218:221], v[202:205], v[64:67]
	v_mfma_f32_16x16x32_bf16 v[116:119], v[214:217], v[172:175], v[116:119]
	v_mfma_f32_16x16x32_bf16 v[112:115], v[222:225], v[172:175], v[112:115]
	v_mfma_f32_16x16x32_bf16 v[100:103], v[214:217], v[190:193], v[100:103]
	v_mfma_f32_16x16x32_bf16 v[96:99], v[222:225], v[190:193], v[96:99]
	v_mfma_f32_16x16x32_bf16 v[84:87], v[214:217], v[198:201], v[84:87]
	v_mfma_f32_16x16x32_bf16 v[80:83], v[222:225], v[198:201], v[80:83]
	v_mfma_f32_16x16x32_bf16 v[68:71], v[214:217], v[206:209], v[68:71]
	v_mfma_f32_16x16x32_bf16 v[64:67], v[222:225], v[206:209], v[64:67]
	s_mov_b32 m0, s42
	v_lshl_add_u64 v[144:145], v[226:227], 0, s[6:7]
	s_barrier
	ds_read_b128 v[168:171], v150 offset:49152
	ds_read_b128 v[172:175], v150 offset:50176
	ds_read_b128 v[182:185], v150 offset:51200
	ds_read_b128 v[190:193], v150 offset:52224
	ds_read_b128 v[194:197], v150 offset:53248
	ds_read_b128 v[198:201], v150 offset:54272
	ds_read_b128 v[202:205], v150 offset:55296
	ds_read_b128 v[206:209], v150 offset:56320
	global_load_lds_dwordx4 v[144:145], off
	v_lshl_add_u64 v[144:145], v[228:229], 0, s[6:7]
	s_mov_b32 m0, s43
	s_nop 0
	global_load_lds_dwordx4 v[144:145], off
	s_barrier
;     __device__ __forceinline__ void operator()(const f32x4 (&acc)[2][2][4][2], const Unit& u, int wr, int wc, int fr, int fq) const {
;     ...
;         const int row0 = u.pm * BM + wr * 64 + fr, col0 = u.pn * BM + wc * 32 + 8 * fq, bcol0 = wc * 32 + 8 * fq;
;         f32x4 bv[2][2];
; #pragma unroll
;         for (int bj = 0; bj < 2; ++bj)
; #pragma unroll
;             for (int n = 0; n < 2; ++n) bv[bj][n] = bias ? *(const f32x4*)(bias + bcol0 + bj * HALF + 4 * n) : (f32x4){0.f, 0.f, 0.f, 0.f};
; #pragma unroll
;         for (int ai = 0; ai < 2; ++ai)
; #pragma unroll
;             for (int m = 0; m < 4; ++m) { bf16_t* rowp = O + (size_t)(row0 + ai * HALF + m * 16) * ldc + col0;
; #pragma unroll
;                 for (int bj = 0; bj < 2; ++bj) { f32x4 v0 = acc[ai][bj][m][0] + bv[bj][0], v1 = acc[ai][bj][m][1] + bv[bj][1];
;                     if (act == 1) {
; #pragma unroll
;                         for (int j = 0; j < 1; ++j) { v0 = v0 * sigmoid4(v0); v1 = v1 * sigmoid4(v1); } }
;                     else if (act == 2) {
; #pragma unroll
;                         for (int j = 0; j < 1; ++j) { v0 = sigmoid4(v0); v1 = sigmoid4(v1); } }
;                     else if (act == 3) {
; #pragma unroll
;                         for (int j = 0; j < 4; ++j) { v0[j] = flogsig16(v0[j]); v1[j] = flogsig16(v1[j]); } }
;                     u32x4 w; w.x = cvt_pk_bf16(v0[0], v0[1]); w.y = cvt_pk_bf16(v0[2], v0[3]); w.z = cvt_pk_bf16(v1[0], v1[1]); w.w = cvt_pk_bf16(v1[2], v1[3]);
;                     *(u32x4*)(rowp + bj * HALF) = w; } }
; template <class Epi, class Sched>
; __device__ __forceinline__ void gemm_phase(PG8_LAS unsigned char* lds, const Gemm g, const Sched& S, const Epi& E) {
;     ...
;             PG8_WAIT_V(6); PG8_BAR; PG8_MMA(1, 1, At, B1); PG8_BAR;
;             PG8_LDB(B0, 1, 0); PG8_SCHED; PG8_LDA(At, 1, 0); PG8_STAGE(PG8_SA(0, 1), a2 + hstep, voffA);
;             PG8_WAIT_L(8); PG8_BAR; PG8_WAIT_L(0); PG8_MMA(0, 0, At, B0); PG8_BAR; PG8_SCHED;
;             PG8_LDB(B1, 1, 1); PG8_STAGE(PG8_SB(1, 0), b3, voffB);
;             PG8_BAR; PG8_WAIT_L(0); PG8_MMA(0, 1, At, B1); PG8_BAR;
;             PG8_LDA(At, 1, 1); PG8_STAGE(PG8_SA(1, 0), a3, voffA);
;             PG8_BAR; PG8_WAIT_L(0); PG8_MMA(1, 0, At, B0); PG8_BAR; PG8_SCHED;
;             PG8_STAGE(PG8_SB(1, 1), b3 + hstep, voffB);
;             PG8_WAIT_V(6); PG8_BAR; PG8_MMA(1, 1, At, B1); PG8_BAR;
	s_waitcnt lgkmcnt(0)
	s_waitcnt lgkmcnt(0)
	v_mfma_f32_16x16x32_bf16 v[60:63], v[152:155], v[168:171], v[60:63]
	v_mfma_f32_16x16x32_bf16 v[56:59], v[160:163], v[168:171], v[56:59]
	v_mfma_f32_16x16x32_bf16 v[48:51], v[152:155], v[182:185], v[48:51]
	v_mfma_f32_16x16x32_bf16 v[40:43], v[160:163], v[182:185], v[40:43]
	v_mfma_f32_16x16x32_bf16 v[32:35], v[152:155], v[194:197], v[32:35]
	v_mfma_f32_16x16x32_bf16 v[24:27], v[160:163], v[194:197], v[24:27]
	v_mfma_f32_16x16x32_bf16 v[16:19], v[152:155], v[202:205], v[16:19]
	v_mfma_f32_16x16x32_bf16 v[8:11], v[160:163], v[202:205], v[8:11]
	v_mfma_f32_16x16x32_bf16 v[60:63], v[156:159], v[172:175], v[60:63]
	v_mfma_f32_16x16x32_bf16 v[56:59], v[164:167], v[172:175], v[56:59]
	v_mfma_f32_16x16x32_bf16 v[48:51], v[156:159], v[190:193], v[48:51]
	v_mfma_f32_16x16x32_bf16 v[40:43], v[164:167], v[190:193], v[40:43]
	v_mfma_f32_16x16x32_bf16 v[32:35], v[156:159], v[198:201], v[32:35]
	v_mfma_f32_16x16x32_bf16 v[24:27], v[164:167], v[198:201], v[24:27]
	v_mfma_f32_16x16x32_bf16 v[16:19], v[156:159], v[206:209], v[16:19]
	v_mfma_f32_16x16x32_bf16 v[8:11], v[164:167], v[206:209], v[8:11]
	s_barrier
	s_add_u32 s26, s26, 0x40080
	s_addc_u32 s27, s27, 0
	s_add_i32 s28, s28, s37
	v_lshl_add_u64 v[144:145], s[26:27], 0, v[130:131]
	s_mov_b32 m0, s28
	s_nop 0
	global_load_lds_dwordx4 v[144:145], off
	v_lshl_add_u64 v[144:145], s[26:27], 0, v[134:135]
	s_add_i32 m0, s28, 0x2000
	s_nop 0
	global_load_lds_dwordx4 v[144:145], off
	s_waitcnt vmcnt(6)
	s_barrier
	v_mfma_f32_16x16x32_bf16 v[52:55], v[210:213], v[168:171], v[52:55]
	v_mfma_f32_16x16x32_bf16 v[44:47], v[218:221], v[168:171], v[44:47]
	v_mfma_f32_16x16x32_bf16 v[36:39], v[210:213], v[182:185], v[36:39]
	v_mfma_f32_16x16x32_bf16 v[28:31], v[218:221], v[182:185], v[28:31]
	v_mfma_f32_16x16x32_bf16 v[20:23], v[210:213], v[194:197], v[20:23]
	v_mfma_f32_16x16x32_bf16 v[12:15], v[218:221], v[194:197], v[12:15]
	v_mfma_f32_16x16x32_bf16 v[4:7], v[210:213], v[202:205], v[4:7]
	v_mfma_f32_16x16x32_bf16 v[0:3], v[218:221], v[202:205], v[0:3]
	v_mfma_f32_16x16x32_bf16 v[52:55], v[214:217], v[172:175], v[52:55]
	v_mfma_f32_16x16x32_bf16 v[44:47], v[222:225], v[172:175], v[44:47]
	v_mfma_f32_16x16x32_bf16 v[36:39], v[214:217], v[190:193], v[36:39]
	v_mfma_f32_16x16x32_bf16 v[28:31], v[222:225], v[190:193], v[28:31]
	v_mfma_f32_16x16x32_bf16 v[20:23], v[214:217], v[198:201], v[20:23]
	v_mfma_f32_16x16x32_bf16 v[12:15], v[222:225], v[198:201], v[12:15]
	v_mfma_f32_16x16x32_bf16 v[4:7], v[214:217], v[206:209], v[4:7]
	v_mfma_f32_16x16x32_bf16 v[0:3], v[222:225], v[206:209], v[0:3]
	s_add_i32 s56, s56, 2
	s_add_u32 s24, s24, 0x100
	s_addc_u32 s25, s25, 0
	s_add_u32 s54, s54, 0x100
	s_addc_u32 s55, s55, 0
	s_cmp_gt_u32 s56, 13
	s_barrier
	s_cbranch_scc0 .LBB0_1083
	v_lshl_add_u32 v152, s22, 8, v146
	v_lshl_or_b32 v144, s51, 8, v148
	v_ashrrev_i32_e32 v153, 31, v152
	v_ashrrev_i32_e32 v145, 31, v144
	v_lshlrev_b64 v[154:155], 11, v[152:153]
	v_lshl_add_u64 v[154:155], s[4:5], 0, v[154:155]
	v_lshlrev_b64 v[156:157], 1, v[144:145]
	v_lshl_add_u64 v[144:145], v[154:155], 0, v[156:157]
	v_pk_add_f32 v[126:127], v[126:127], 0 op_sel_hi:[1,0]
	v_pk_add_f32 v[124:125], v[124:125], 0 op_sel_hi:[1,0]
	v_pk_add_f32 v[154:155], v[122:123], 0 op_sel_hi:[1,0]
	v_pk_add_f32 v[122:123], v[120:121], 0 op_sel_hi:[1,0]
	v_cvt_pk_bf16_f32 v120, v124, v125
	v_cvt_pk_bf16_f32 v121, v126, v127
	v_pk_add_f32 v[116:117], v[116:117], 0 op_sel_hi:[1,0]
	v_cvt_pk_bf16_f32 v122, v122, v123
	v_cvt_pk_bf16_f32 v123, v154, v155
	global_store_dwordx4 v[144:145], v[120:123], off
	v_pk_add_f32 v[118:119], v[118:119], 0 op_sel_hi:[1,0]
	v_pk_add_f32 v[110:111], v[110:111], 0 op_sel_hi:[1,0]
	v_pk_add_f32 v[120:121], v[114:115], 0 op_sel_hi:[1,0]
	v_pk_add_f32 v[114:115], v[112:113], 0 op_sel_hi:[1,0]
	v_cvt_pk_bf16_f32 v112, v116, v117
	v_cvt_pk_bf16_f32 v113, v118, v119
	v_pk_add_f32 v[108:109], v[108:109], 0 op_sel_hi:[1,0]
	v_cvt_pk_bf16_f32 v114, v114, v115
	v_cvt_pk_bf16_f32 v115, v120, v121
	global_store_dwordx4 v[144:145], v[112:115], off offset:256
	v_pk_add_f32 v[100:101], v[100:101], 0 op_sel_hi:[1,0]
	v_pk_add_f32 v[102:103], v[102:103], 0 op_sel_hi:[1,0]
	v_or_b32_e32 v112, 16, v152
	v_ashrrev_i32_e32 v113, 31, v112
	v_lshlrev_b64 v[112:113], 11, v[112:113]
	v_lshl_add_u64 v[112:113], s[4:5], 0, v[112:113]
	v_lshl_add_u64 v[112:113], v[112:113], 0, v[156:157]
	v_pk_add_f32 v[114:115], v[106:107], 0 op_sel_hi:[1,0]
	v_pk_add_f32 v[106:107], v[104:105], 0 op_sel_hi:[1,0]
	v_cvt_pk_bf16_f32 v104, v108, v109
	v_cvt_pk_bf16_f32 v105, v110, v111
	v_pk_add_f32 v[94:95], v[94:95], 0 op_sel_hi:[1,0]
	v_cvt_pk_bf16_f32 v106, v106, v107
	v_cvt_pk_bf16_f32 v107, v114, v115
	global_store_dwordx4 v[112:113], v[104:107], off
	v_pk_add_f32 v[92:93], v[92:93], 0 op_sel_hi:[1,0]
	v_pk_add_f32 v[84:85], v[84:85], 0 op_sel_hi:[1,0]
	v_pk_add_f32 v[104:105], v[98:99], 0 op_sel_hi:[1,0]
	v_pk_add_f32 v[98:99], v[96:97], 0 op_sel_hi:[1,0]
	v_cvt_pk_bf16_f32 v96, v100, v101
	v_cvt_pk_bf16_f32 v97, v102, v103
	v_pk_add_f32 v[86:87], v[86:87], 0 op_sel_hi:[1,0]
	v_cvt_pk_bf16_f32 v98, v98, v99
	v_cvt_pk_bf16_f32 v99, v104, v105
	global_store_dwordx4 v[112:113], v[96:99], off offset:256
	v_pk_add_f32 v[78:79], v[78:79], 0 op_sel_hi:[1,0]
	v_pk_add_f32 v[76:77], v[76:77], 0 op_sel_hi:[1,0]
	v_or_b32_e32 v96, 32, v152
	v_ashrrev_i32_e32 v97, 31, v96
	v_lshlrev_b64 v[96:97], 11, v[96:97]
	v_lshl_add_u64 v[96:97], s[4:5], 0, v[96:97]
; __device__ __forceinline__ unsigned cvt_pk_bf16(float lo, float hi) { unsigned r; asm volatile("v_cvt_pk_bf16_f32 %0, %1, %2" : "=v"(r) : "v"(lo), "v"(hi)); return r; }
; __device__ __forceinline__ float flogsig16(float x) { return (fminf(x, 0.f) - __logf(1.0f + __expf(-fabsf(x)))) * 0.0625f; }
;     __device__ __forceinline__ void operator()(const f32x4 (&acc)[2][2][4][2], const Unit& u, int wr, int wc, int fr, int fq) const {
;     ...
;             for (int m = 0; m < 4; ++m) { bf16_t* rowp = O + (size_t)(row0 + ai * HALF + m * 16) * ldc + col0;
; #pragma unroll
;                 for (int bj = 0; bj < 2; ++bj) { f32x4 v0 = acc[ai][bj][m][0] + bv[bj][0], v1 = acc[ai][bj][m][1] + bv[bj][1];
;                     if (act == 1) {
; #pragma unroll
;                         for (int j = 0; j < 1; ++j) { v0 = v0 * sigmoid4(v0); v1 = v1 * sigmoid4(v1); } }
;                     else if (act == 2) {
; #pragma unroll
;                         for (int j = 0; j < 1; ++j) { v0 = sigmoid4(v0); v1 = sigmoid4(v1); } }
;                     else if (act == 3) {
; #pragma unroll
;                         for (int j = 0; j < 4; ++j) { v0[j] = flogsig16(v0[j]); v1[j] = flogsig16(v1[j]); } }
;                     u32x4 w; w.x = cvt_pk_bf16(v0[0], v0[1]); w.y = cvt_pk_bf16(v0[2], v0[3]); w.z = cvt_pk_bf16(v1[0], v1[1]); w.w = cvt_pk_bf16(v1[2], v1[3]);
;                     *(u32x4*)(rowp + bj * HALF) = w; } }
; template <class Epi, class Sched>
; __device__ __forceinline__ void gemm_phase(PG8_LAS unsigned char* lds, const Gemm g, const Sched& S, const Epi& E) {
;     ...
;         if (!has_next) break;
; #pragma unroll
;         for (int a = 0; a < 2; ++a)
; #pragma unroll
;             for (int b = 0; b < 2; ++b)
; #pragma unroll
;                 for (int m = 0; m < 4; ++m)
; #pragma unroll
;                     for (int n = 0; n < 2; ++n) acc[a][b][m][n] = (f32x4){0.f, 0.f, 0.f, 0.f};
;         cur = nxt; cA = nA; cB = nB; ++ui;
;     }
	v_lshl_add_u64 v[96:97], v[96:97], 0, v[156:157]
	v_pk_add_f32 v[98:99], v[90:91], 0 op_sel_hi:[1,0]
	v_pk_add_f32 v[90:91], v[88:89], 0 op_sel_hi:[1,0]
	v_cvt_pk_bf16_f32 v88, v92, v93
	v_cvt_pk_bf16_f32 v89, v94, v95
	v_pk_add_f32 v[70:71], v[70:71], 0 op_sel_hi:[1,0]
	v_cvt_pk_bf16_f32 v90, v90, v91
	v_cvt_pk_bf16_f32 v91, v98, v99
	global_store_dwordx4 v[96:97], v[88:91], off
	v_pk_add_f32 v[68:69], v[68:69], 0 op_sel_hi:[1,0]
	v_pk_add_f32 v[60:61], v[60:61], 0 op_sel_hi:[1,0]
	v_pk_add_f32 v[88:89], v[82:83], 0 op_sel_hi:[1,0]
	v_pk_add_f32 v[82:83], v[80:81], 0 op_sel_hi:[1,0]
	v_cvt_pk_bf16_f32 v80, v84, v85
	v_cvt_pk_bf16_f32 v81, v86, v87
	v_pk_add_f32 v[62:63], v[62:63], 0 op_sel_hi:[1,0]
	v_cvt_pk_bf16_f32 v82, v82, v83
	v_cvt_pk_bf16_f32 v83, v88, v89
	global_store_dwordx4 v[96:97], v[80:83], off offset:256
	v_pk_add_f32 v[54:55], v[54:55], 0 op_sel_hi:[1,0]
	v_pk_add_f32 v[52:53], v[52:53], 0 op_sel_hi:[1,0]
	v_or_b32_e32 v80, 48, v152
	v_ashrrev_i32_e32 v81, 31, v80
	v_lshlrev_b64 v[80:81], 11, v[80:81]
	v_lshl_add_u64 v[80:81], s[4:5], 0, v[80:81]
	v_lshl_add_u64 v[80:81], v[80:81], 0, v[156:157]
	v_pk_add_f32 v[82:83], v[74:75], 0 op_sel_hi:[1,0]
	v_pk_add_f32 v[74:75], v[72:73], 0 op_sel_hi:[1,0]
	v_cvt_pk_bf16_f32 v72, v76, v77
	v_cvt_pk_bf16_f32 v73, v78, v79
	v_pk_add_f32 v[48:49], v[48:49], 0 op_sel_hi:[1,0]
	v_cvt_pk_bf16_f32 v74, v74, v75
	v_cvt_pk_bf16_f32 v75, v82, v83
	global_store_dwordx4 v[80:81], v[72:75], off
	v_pk_add_f32 v[38:39], v[38:39], 0 op_sel_hi:[1,0]
	v_pk_add_f32 v[36:37], v[36:37], 0 op_sel_hi:[1,0]
	v_pk_add_f32 v[72:73], v[66:67], 0 op_sel_hi:[1,0]
	v_pk_add_f32 v[66:67], v[64:65], 0 op_sel_hi:[1,0]
	v_cvt_pk_bf16_f32 v64, v68, v69
	v_cvt_pk_bf16_f32 v65, v70, v71
	v_pk_add_f32 v[32:33], v[32:33], 0 op_sel_hi:[1,0]
	v_cvt_pk_bf16_f32 v66, v66, v67
	v_cvt_pk_bf16_f32 v67, v72, v73
	global_store_dwordx4 v[80:81], v[64:67], off offset:256
	v_pk_add_f32 v[22:23], v[22:23], 0 op_sel_hi:[1,0]
	v_pk_add_f32 v[20:21], v[20:21], 0 op_sel_hi:[1,0]
	v_pk_add_f32 v[66:67], v[58:59], 0 op_sel_hi:[1,0]
	v_pk_add_f32 v[58:59], v[56:57], 0 op_sel_hi:[1,0]
	v_cvt_pk_bf16_f32 v56, v60, v61
	v_add_co_u32_e32 v60, vcc, s47, v144
	v_cvt_pk_bf16_f32 v57, v62, v63
	v_cvt_pk_bf16_f32 v58, v58, v59
	v_cvt_pk_bf16_f32 v59, v66, v67
	v_lshl_add_u64 v[64:65], v[144:145], 0, s[0:1]
	s_nop 0
	v_addc_co_u32_e32 v61, vcc, 0, v145, vcc
	global_store_dwordx4 v[60:61], v[56:59], off
	v_pk_add_f32 v[16:17], v[16:17], 0 op_sel_hi:[1,0]
	s_mov_b32 s51, s14
	v_pk_add_f32 v[56:57], v[46:47], 0 op_sel_hi:[1,0]
	v_pk_add_f32 v[46:47], v[44:45], 0 op_sel_hi:[1,0]
	v_cvt_pk_bf16_f32 v44, v52, v53
	v_cvt_pk_bf16_f32 v45, v54, v55
	s_mov_b32 s22, s16
	v_cvt_pk_bf16_f32 v46, v46, v47
	v_cvt_pk_bf16_f32 v47, v56, v57
	global_store_dwordx4 v[64:65], v[44:47], off offset:256
	s_mov_b64 s[26:27], s[20:21]
	s_mov_b64 s[24:25], s[18:19]
	v_pk_add_f32 v[46:47], v[50:51], 0 op_sel_hi:[1,0]
	v_pk_add_f32 v[50:51], v[42:43], 0 op_sel_hi:[1,0]
	v_pk_add_f32 v[42:43], v[40:41], 0 op_sel_hi:[1,0]
	v_cvt_pk_bf16_f32 v40, v48, v49
	v_cvt_pk_bf16_f32 v41, v46, v47
	v_add_co_u32_e32 v46, vcc, s48, v144
	v_cvt_pk_bf16_f32 v42, v42, v43
	v_cvt_pk_bf16_f32 v43, v50, v51
	v_lshl_add_u64 v[44:45], v[144:145], 0, s[8:9]
	s_nop 0
	v_addc_co_u32_e32 v47, vcc, 0, v145, vcc
	global_store_dwordx4 v[46:47], v[40:43], off
	v_pk_add_f32 v[6:7], v[6:7], 0 op_sel_hi:[1,0]
	v_pk_add_f32 v[4:5], v[4:5], 0 op_sel_hi:[1,0]
	v_pk_add_f32 v[40:41], v[30:31], 0 op_sel_hi:[1,0]
	v_pk_add_f32 v[30:31], v[28:29], 0 op_sel_hi:[1,0]
	v_cvt_pk_bf16_f32 v28, v36, v37
	v_cvt_pk_bf16_f32 v29, v38, v39
	s_nop 0
	v_cvt_pk_bf16_f32 v30, v30, v31
	v_cvt_pk_bf16_f32 v31, v40, v41
	global_store_dwordx4 v[44:45], v[28:31], off offset:256
	s_nop 1
	v_pk_add_f32 v[30:31], v[34:35], 0 op_sel_hi:[1,0]
	v_pk_add_f32 v[34:35], v[26:27], 0 op_sel_hi:[1,0]
	v_pk_add_f32 v[26:27], v[24:25], 0 op_sel_hi:[1,0]
	v_cvt_pk_bf16_f32 v24, v32, v33
	v_cvt_pk_bf16_f32 v25, v30, v31
	v_add_co_u32_e32 v30, vcc, s49, v144
	v_cvt_pk_bf16_f32 v26, v26, v27
	v_cvt_pk_bf16_f32 v27, v34, v35
	v_lshl_add_u64 v[28:29], v[144:145], 0, s[10:11]
	s_nop 0
	v_addc_co_u32_e32 v31, vcc, 0, v145, vcc
	global_store_dwordx4 v[30:31], v[24:27], off
	s_nop 1
	v_pk_add_f32 v[24:25], v[14:15], 0 op_sel_hi:[1,0]
	v_pk_add_f32 v[14:15], v[12:13], 0 op_sel_hi:[1,0]
	v_cvt_pk_bf16_f32 v12, v20, v21
	v_cvt_pk_bf16_f32 v13, v22, v23
	s_nop 0
	v_cvt_pk_bf16_f32 v14, v14, v15
	v_cvt_pk_bf16_f32 v15, v24, v25
	global_store_dwordx4 v[28:29], v[12:15], off offset:256
	s_nop 1
	v_pk_add_f32 v[14:15], v[18:19], 0 op_sel_hi:[1,0]
	v_pk_add_f32 v[18:19], v[10:11], 0 op_sel_hi:[1,0]
	v_pk_add_f32 v[10:11], v[8:9], 0 op_sel_hi:[1,0]
	v_cvt_pk_bf16_f32 v8, v16, v17
	v_cvt_pk_bf16_f32 v9, v14, v15
	v_add_co_u32_e32 v14, vcc, s50, v144
	v_lshl_add_u64 v[12:13], v[144:145], 0, s[12:13]
	s_nop 0
	v_addc_co_u32_e32 v15, vcc, 0, v145, vcc
	v_cvt_pk_bf16_f32 v10, v10, v11
	v_cvt_pk_bf16_f32 v11, v18, v19
	global_store_dwordx4 v[14:15], v[8:11], off
	s_and_b64 vcc, exec, s[2:3]
	s_nop 0
	v_pk_add_f32 v[8:9], v[2:3], 0 op_sel_hi:[1,0]
	v_pk_add_f32 v[2:3], v[0:1], 0 op_sel_hi:[1,0]
	v_cvt_pk_bf16_f32 v0, v4, v5
	v_cvt_pk_bf16_f32 v1, v6, v7
	s_nop 0
	v_cvt_pk_bf16_f32 v2, v2, v3
	v_cvt_pk_bf16_f32 v3, v8, v9
	global_store_dwordx4 v[12:13], v[0:3], off offset:256
	s_cbranch_vccz .LBB0_1076
	s_waitcnt vmcnt(0)
	s_cmpk_gt_u32 s31, 0xff
	s_cbranch_scc1 .LBB0_1087
	s_barrier

; #define PG8_STAGE(bufoff, gbase, voff) do { _Pragma("unroll") for (int _i = 0; _i < 2; ++_i) \
;         __builtin_amdgcn_global_load_lds((const unsigned*)((const char*)(gbase) + (voff)[_i]), (PG8_LAS unsigned*)(lds + (bufoff) + ldsw + _i * 8192), 16, 0, 0); } while (0)
; #define PG8_LDA(dst, b, h) do { _Pragma("unroll") for (int m = 0; m < 4; ++m) _Pragma("unroll") for (int k = 0; k < 2; ++k) dst[m][k] = *(const PG8_LAS bf16x8*)(lds + PG8_SA(b, h) + aoff + m * 2048 + k * 1024); } while (0)
; #define PG8_LDB(dst, b, h) do { _Pragma("unroll") for (int n = 0; n < 2; ++n) _Pragma("unroll") for (int k = 0; k < 2; ++k) dst[n][k] = *(const PG8_LAS bf16x8*)(lds + PG8_SB(b, h) + boff + n * 2048 + k * 1024); } while (0)
; #define PG8_MMA(ai, bj, At, Bt) do { __builtin_amdgcn_s_setprio(1); _Pragma("unroll") for (int m = 0; m < 4; ++m) _Pragma("unroll") for (int n = 0; n < 2; ++n) _Pragma("unroll") for (int k = 0; k < 2; ++k) \
;         acc[ai][bj][m][n] = __builtin_amdgcn_mfma_f32_16x16x32_bf16(Bt[n][k], At[m][k], acc[ai][bj][m][n], 0, 0, 0); __builtin_amdgcn_s_setprio(0); } while (0)
; #define PG8_WAIT_V(n) asm volatile("s_waitcnt vmcnt(" #n ")" ::: "memory")
; #define PG8_WAIT_L(n) asm volatile("s_waitcnt lgkmcnt(" #n ")" ::: "memory")
; #define PG8_BAR __builtin_amdgcn_s_barrier()
; #define PG8_SCHED __builtin_amdgcn_sched_barrier(0)
; template <class Epi, class Sched>
; __device__ __forceinline__ void gemm_phase(PG8_LAS unsigned char* lds, const Gemm g, const Sched& S, const Epi& E) {
;     ...
;             PG8_LDB(B0, 0, 0); PG8_SCHED; PG8_LDA(At, 0, 0); PG8_STAGE(PG8_SA(1, 1), a1 + hstep, voffA);
;             PG8_WAIT_L(8); PG8_BAR; PG8_WAIT_L(0); PG8_MMA(0, 0, At, B0); PG8_BAR; PG8_SCHED;
;             PG8_LDB(B1, 0, 1); PG8_STAGE(PG8_SB(0, 0), b2, voffB);
;             PG8_BAR; PG8_WAIT_L(0); PG8_MMA(0, 1, At, B1); PG8_BAR;
;             PG8_LDA(At, 0, 1); PG8_STAGE(PG8_SA(0, 0), a2, voffA);
;             PG8_BAR; PG8_WAIT_L(0); PG8_MMA(1, 0, At, B0); PG8_BAR; PG8_SCHED;
;             PG8_STAGE(PG8_SB(0, 1), b2 + hstep, voffB);
;             PG8_WAIT_V(6); PG8_BAR; PG8_MMA(1, 1, At, B1); PG8_BAR;
.LBB0_1202:
	ds_read_b128 v[144:147], v151
	ds_read_b128 v[154:157], v151 offset:1024
	ds_read_b128 v[158:161], v151 offset:2048
	ds_read_b128 v[162:165], v151 offset:3072
	s_add_u32 s18, s16, 0xfffc0080
	s_addc_u32 s19, s17, -1
	s_cmp_eq_u32 s46, 12
	s_cselect_b32 s21, s9, s19
	s_cselect_b32 s20, s42, s18
	s_cselect_b32 s19, s7, s45
	s_cselect_b32 s18, s43, s44
	v_lshl_add_u64 v[174:175], s[16:17], 0, v[136:137]
	s_add_i32 m0, s15, 0xc000
	ds_read_b128 v[166:169], v152
	ds_read_b128 v[170:173], v152 offset:1024
	ds_read_b128 v[182:185], v152 offset:2048
	ds_read_b128 v[190:193], v152 offset:3072
	ds_read_b128 v[194:197], v152 offset:4096
	ds_read_b128 v[198:201], v152 offset:5120
	ds_read_b128 v[202:205], v152 offset:6144
	ds_read_b128 v[206:209], v152 offset:7168
	global_load_lds_dwordx4 v[174:175], off
	v_lshl_add_u64 v[174:175], s[16:17], 0, v[138:139]
	s_add_i32 m0, s15, 0xe000
	s_nop 0
	global_load_lds_dwordx4 v[174:175], off
	s_waitcnt lgkmcnt(8)
	s_barrier
	s_waitcnt lgkmcnt(0)
	s_waitcnt lgkmcnt(0)
	v_mfma_f32_16x16x32_bf16 v[124:127], v[144:147], v[166:169], v[124:127]
	v_mfma_f32_16x16x32_bf16 v[120:123], v[158:161], v[166:169], v[120:123]
	v_mfma_f32_16x16x32_bf16 v[108:111], v[144:147], v[182:185], v[108:111]
	v_mfma_f32_16x16x32_bf16 v[104:107], v[158:161], v[182:185], v[104:107]
	v_mfma_f32_16x16x32_bf16 v[92:95], v[144:147], v[194:197], v[92:95]
	v_mfma_f32_16x16x32_bf16 v[88:91], v[158:161], v[194:197], v[88:91]
	v_mfma_f32_16x16x32_bf16 v[76:79], v[144:147], v[202:205], v[76:79]
	v_mfma_f32_16x16x32_bf16 v[72:75], v[158:161], v[202:205], v[72:75]
	v_mfma_f32_16x16x32_bf16 v[124:127], v[154:157], v[170:173], v[124:127]
	v_mfma_f32_16x16x32_bf16 v[120:123], v[162:165], v[170:173], v[120:123]
	v_mfma_f32_16x16x32_bf16 v[108:111], v[154:157], v[190:193], v[108:111]
	v_mfma_f32_16x16x32_bf16 v[104:107], v[162:165], v[190:193], v[104:107]
	v_mfma_f32_16x16x32_bf16 v[92:95], v[154:157], v[198:201], v[92:95]
	v_mfma_f32_16x16x32_bf16 v[88:91], v[162:165], v[198:201], v[88:91]
	v_mfma_f32_16x16x32_bf16 v[76:79], v[154:157], v[206:209], v[76:79]
	v_mfma_f32_16x16x32_bf16 v[72:75], v[162:165], v[206:209], v[72:75]
	s_barrier
	s_add_i32 s47, s38, s26
	v_lshl_add_u64 v[174:175], s[18:19], 0, v[132:133]
	s_mov_b32 m0, s47
	ds_read_b128 v[210:213], v153
	ds_read_b128 v[214:217], v153 offset:1024
	ds_read_b128 v[218:221], v153 offset:2048
	ds_read_b128 v[222:225], v153 offset:3072
	global_load_lds_dwordx4 v[174:175], off
	v_lshl_add_u64 v[186:187], s[18:19], 0, v[128:129]
	s_add_i32 m0, s47, 0x2000
	s_nop 0
	global_load_lds_dwordx4 v[186:187], off
	s_barrier
	s_waitcnt lgkmcnt(0)
	s_waitcnt lgkmcnt(0)
	v_mfma_f32_16x16x32_bf16 v[116:119], v[210:213], v[166:169], v[116:119]
	v_mfma_f32_16x16x32_bf16 v[112:115], v[218:221], v[166:169], v[112:115]
	v_mfma_f32_16x16x32_bf16 v[100:103], v[210:213], v[182:185], v[100:103]
	v_mfma_f32_16x16x32_bf16 v[96:99], v[218:221], v[182:185], v[96:99]
	v_mfma_f32_16x16x32_bf16 v[84:87], v[210:213], v[194:197], v[84:87]
	v_mfma_f32_16x16x32_bf16 v[80:83], v[218:221], v[194:197], v[80:83]
	v_mfma_f32_16x16x32_bf16 v[68:71], v[210:213], v[202:205], v[68:71]
	v_mfma_f32_16x16x32_bf16 v[64:67], v[218:221], v[202:205], v[64:67]
	v_mfma_f32_16x16x32_bf16 v[116:119], v[214:217], v[170:173], v[116:119]
	v_mfma_f32_16x16x32_bf16 v[112:115], v[222:225], v[170:173], v[112:115]
	v_mfma_f32_16x16x32_bf16 v[100:103], v[214:217], v[190:193], v[100:103]
	v_mfma_f32_16x16x32_bf16 v[96:99], v[222:225], v[190:193], v[96:99]
	v_mfma_f32_16x16x32_bf16 v[84:87], v[214:217], v[198:201], v[84:87]
	v_mfma_f32_16x16x32_bf16 v[80:83], v[222:225], v[198:201], v[80:83]
	v_mfma_f32_16x16x32_bf16 v[68:71], v[214:217], v[206:209], v[68:71]
	v_mfma_f32_16x16x32_bf16 v[64:67], v[222:225], v[206:209], v[64:67]
	s_mov_b32 m0, s15
	v_lshl_add_u64 v[226:227], s[20:21], 0, v[134:135]
	s_barrier
	ds_read_b128 v[166:169], v152 offset:16384
	ds_read_b128 v[170:173], v152 offset:17408
	ds_read_b128 v[182:185], v152 offset:18432
	ds_read_b128 v[190:193], v152 offset:19456
	ds_read_b128 v[194:197], v152 offset:20480
	ds_read_b128 v[198:201], v152 offset:21504
	ds_read_b128 v[202:205], v152 offset:22528
	ds_read_b128 v[206:209], v152 offset:23552
	global_load_lds_dwordx4 v[226:227], off
	v_lshl_add_u64 v[228:229], s[20:21], 0, v[130:131]
	s_mov_b32 m0, s29
	s_nop 0
	global_load_lds_dwordx4 v[228:229], off
	s_barrier
	s_waitcnt lgkmcnt(0)
	s_waitcnt lgkmcnt(0)
	v_mfma_f32_16x16x32_bf16 v[60:63], v[144:147], v[166:169], v[60:63]
	v_mfma_f32_16x16x32_bf16 v[56:59], v[158:161], v[166:169], v[56:59]
	v_mfma_f32_16x16x32_bf16 v[44:47], v[144:147], v[182:185], v[44:47]
	v_mfma_f32_16x16x32_bf16 v[40:43], v[158:161], v[182:185], v[40:43]
	v_mfma_f32_16x16x32_bf16 v[28:31], v[144:147], v[194:197], v[28:31]
	v_mfma_f32_16x16x32_bf16 v[24:27], v[158:161], v[194:197], v[24:27]
	v_mfma_f32_16x16x32_bf16 v[12:15], v[144:147], v[202:205], v[12:15]
	v_mfma_f32_16x16x32_bf16 v[8:11], v[158:161], v[202:205], v[8:11]
	v_mfma_f32_16x16x32_bf16 v[60:63], v[154:157], v[170:173], v[60:63]
	v_mfma_f32_16x16x32_bf16 v[56:59], v[162:165], v[170:173], v[56:59]
	v_mfma_f32_16x16x32_bf16 v[44:47], v[154:157], v[190:193], v[44:47]
	v_mfma_f32_16x16x32_bf16 v[40:43], v[162:165], v[190:193], v[40:43]
	v_mfma_f32_16x16x32_bf16 v[28:31], v[154:157], v[198:201], v[28:31]
	v_mfma_f32_16x16x32_bf16 v[24:27], v[162:165], v[198:201], v[24:27]
	v_mfma_f32_16x16x32_bf16 v[12:15], v[154:157], v[206:209], v[12:15]
	v_mfma_f32_16x16x32_bf16 v[8:11], v[162:165], v[206:209], v[8:11]
	s_barrier
; #define PG8_STAGE(bufoff, gbase, voff) do { _Pragma("unroll") for (int _i = 0; _i < 2; ++_i) \
;         __builtin_amdgcn_global_load_lds((const unsigned*)((const char*)(gbase) + (voff)[_i]), (PG8_LAS unsigned*)(lds + (bufoff) + ldsw + _i * 8192), 16, 0, 0); } while (0)
; #define PG8_LDA(dst, b, h) do { _Pragma("unroll") for (int m = 0; m < 4; ++m) _Pragma("unroll") for (int k = 0; k < 2; ++k) dst[m][k] = *(const PG8_LAS bf16x8*)(lds + PG8_SA(b, h) + aoff + m * 2048 + k * 1024); } while (0)
; #define PG8_LDB(dst, b, h) do { _Pragma("unroll") for (int n = 0; n < 2; ++n) _Pragma("unroll") for (int k = 0; k < 2; ++k) dst[n][k] = *(const PG8_LAS bf16x8*)(lds + PG8_SB(b, h) + boff + n * 2048 + k * 1024); } while (0)
; #define PG8_MMA(ai, bj, At, Bt) do { __builtin_amdgcn_s_setprio(1); _Pragma("unroll") for (int m = 0; m < 4; ++m) _Pragma("unroll") for (int n = 0; n < 2; ++n) _Pragma("unroll") for (int k = 0; k < 2; ++k) \
;         acc[ai][bj][m][n] = __builtin_amdgcn_mfma_f32_16x16x32_bf16(Bt[n][k], At[m][k], acc[ai][bj][m][n], 0, 0, 0); __builtin_amdgcn_s_setprio(0); } while (0)
; #define PG8_WAIT_V(n) asm volatile("s_waitcnt vmcnt(" #n ")" ::: "memory")
; #define PG8_WAIT_L(n) asm volatile("s_waitcnt lgkmcnt(" #n ")" ::: "memory")
; #define PG8_BAR __builtin_amdgcn_s_barrier()
; #define PG8_SCHED __builtin_amdgcn_sched_barrier(0)
; template <class Epi, class Sched>
; __device__ __forceinline__ void gemm_phase(PG8_LAS unsigned char* lds, const Gemm g, const Sched& S, const Epi& E) {
;     ...
;             PG8_WAIT_V(6); PG8_BAR; PG8_MMA(1, 1, At, B1); PG8_BAR;
;             PG8_LDB(B0, 1, 0); PG8_SCHED; PG8_LDA(At, 1, 0); PG8_STAGE(PG8_SA(0, 1), a2 + hstep, voffA);
;             PG8_WAIT_L(8); PG8_BAR; PG8_WAIT_L(0); PG8_MMA(0, 0, At, B0); PG8_BAR; PG8_SCHED;
;             PG8_LDB(B1, 1, 1); PG8_STAGE(PG8_SB(1, 0), b3, voffB);
;             PG8_BAR; PG8_WAIT_L(0); PG8_MMA(0, 1, At, B1); PG8_BAR;
;             PG8_LDA(At, 1, 1); PG8_STAGE(PG8_SA(1, 0), a3, voffA);
;             PG8_BAR; PG8_WAIT_L(0); PG8_MMA(1, 0, At, B0); PG8_BAR; PG8_SCHED;
	s_add_u32 s48, s18, 0x40000
	s_addc_u32 s49, s19, 0
	s_add_i32 s47, s39, s26
	v_lshl_add_u64 v[144:145], s[48:49], 0, v[132:133]
	s_mov_b32 m0, s47
	s_nop 0
	global_load_lds_dwordx4 v[144:145], off
	v_lshl_add_u64 v[144:145], s[48:49], 0, v[128:129]
	s_add_i32 m0, s47, 0x2000
	s_nop 0
	global_load_lds_dwordx4 v[144:145], off
	s_waitcnt vmcnt(6)
	s_barrier
	v_mfma_f32_16x16x32_bf16 v[52:55], v[210:213], v[166:169], v[52:55]
	v_mfma_f32_16x16x32_bf16 v[48:51], v[218:221], v[166:169], v[48:51]
	v_mfma_f32_16x16x32_bf16 v[36:39], v[210:213], v[182:185], v[36:39]
	v_mfma_f32_16x16x32_bf16 v[32:35], v[218:221], v[182:185], v[32:35]
	v_mfma_f32_16x16x32_bf16 v[20:23], v[210:213], v[194:197], v[20:23]
	v_mfma_f32_16x16x32_bf16 v[16:19], v[218:221], v[194:197], v[16:19]
	v_mfma_f32_16x16x32_bf16 v[4:7], v[210:213], v[202:205], v[4:7]
	v_mfma_f32_16x16x32_bf16 v[0:3], v[218:221], v[202:205], v[0:3]
	v_mfma_f32_16x16x32_bf16 v[52:55], v[214:217], v[170:173], v[52:55]
	v_mfma_f32_16x16x32_bf16 v[48:51], v[222:225], v[170:173], v[48:51]
	v_mfma_f32_16x16x32_bf16 v[36:39], v[214:217], v[190:193], v[36:39]
	v_mfma_f32_16x16x32_bf16 v[32:35], v[222:225], v[190:193], v[32:35]
	v_mfma_f32_16x16x32_bf16 v[20:23], v[214:217], v[198:201], v[20:23]
	v_mfma_f32_16x16x32_bf16 v[16:19], v[222:225], v[198:201], v[16:19]
	v_mfma_f32_16x16x32_bf16 v[4:7], v[214:217], v[206:209], v[4:7]
	v_mfma_f32_16x16x32_bf16 v[0:3], v[222:225], v[206:209], v[0:3]
	s_add_i32 s47, 0, 0x18000
	v_add_u32_e32 v162, s47, v149
	s_barrier
	ds_read_b128 v[144:147], v162
	ds_read_b128 v[154:157], v162 offset:1024
	ds_read_b128 v[158:161], v162 offset:2048
	ds_read_b128 v[162:165], v162 offset:3072
	s_add_u32 s20, s20, 0x40000
	s_addc_u32 s21, s21, 0
	s_mov_b32 m0, s30
	v_lshl_add_u64 v[210:211], s[20:21], 0, v[134:135]
	ds_read_b128 v[166:169], v152 offset:32768
	ds_read_b128 v[170:173], v152 offset:33792
	ds_read_b128 v[182:185], v152 offset:34816
	ds_read_b128 v[190:193], v152 offset:35840
	ds_read_b128 v[194:197], v152 offset:36864
	ds_read_b128 v[198:201], v152 offset:37888
	ds_read_b128 v[202:205], v152 offset:38912
	ds_read_b128 v[206:209], v152 offset:39936
	global_load_lds_dwordx4 v[210:211], off
	v_lshl_add_u64 v[210:211], s[20:21], 0, v[130:131]
	s_mov_b32 m0, s31
	s_nop 0
	global_load_lds_dwordx4 v[210:211], off
	s_waitcnt lgkmcnt(8)
	s_barrier
	s_waitcnt lgkmcnt(0)
	s_waitcnt lgkmcnt(0)
	v_mfma_f32_16x16x32_bf16 v[124:127], v[144:147], v[166:169], v[124:127]
	v_mfma_f32_16x16x32_bf16 v[120:123], v[158:161], v[166:169], v[120:123]
	v_mfma_f32_16x16x32_bf16 v[108:111], v[144:147], v[182:185], v[108:111]
	v_mfma_f32_16x16x32_bf16 v[104:107], v[158:161], v[182:185], v[104:107]
	v_mfma_f32_16x16x32_bf16 v[92:95], v[144:147], v[194:197], v[92:95]
	v_mfma_f32_16x16x32_bf16 v[88:91], v[158:161], v[194:197], v[88:91]
	v_mfma_f32_16x16x32_bf16 v[76:79], v[144:147], v[202:205], v[76:79]
	v_mfma_f32_16x16x32_bf16 v[72:75], v[158:161], v[202:205], v[72:75]
	v_mfma_f32_16x16x32_bf16 v[124:127], v[154:157], v[170:173], v[124:127]
	v_mfma_f32_16x16x32_bf16 v[120:123], v[162:165], v[170:173], v[120:123]
	v_mfma_f32_16x16x32_bf16 v[108:111], v[154:157], v[190:193], v[108:111]
	v_mfma_f32_16x16x32_bf16 v[104:107], v[162:165], v[190:193], v[104:107]
	v_mfma_f32_16x16x32_bf16 v[92:95], v[154:157], v[198:201], v[92:95]
	v_mfma_f32_16x16x32_bf16 v[88:91], v[162:165], v[198:201], v[88:91]
	v_mfma_f32_16x16x32_bf16 v[76:79], v[154:157], v[206:209], v[76:79]
	v_mfma_f32_16x16x32_bf16 v[72:75], v[162:165], v[206:209], v[72:75]
	s_barrier
	s_add_i32 s20, 0, 0x1c000
	s_add_i32 s21, s47, s26
	v_add_u32_e32 v179, s20, v149
	v_lshl_add_u64 v[174:175], v[174:175], 0, s[4:5]
	s_mov_b32 m0, s21
	ds_read_b128 v[210:213], v179
	ds_read_b128 v[214:217], v179 offset:1024
	ds_read_b128 v[218:221], v179 offset:2048
	ds_read_b128 v[222:225], v179 offset:3072
	global_load_lds_dwordx4 v[174:175], off
	v_lshl_add_u64 v[174:175], v[186:187], 0, s[4:5]
	s_add_i32 m0, s21, 0x2000
	s_nop 0
	global_load_lds_dwordx4 v[174:175], off
	s_barrier
	s_waitcnt lgkmcnt(0)
	s_waitcnt lgkmcnt(0)
	v_mfma_f32_16x16x32_bf16 v[116:119], v[210:213], v[166:169], v[116:119]
	v_mfma_f32_16x16x32_bf16 v[112:115], v[218:221], v[166:169], v[112:115]
	v_mfma_f32_16x16x32_bf16 v[100:103], v[210:213], v[182:185], v[100:103]
	v_mfma_f32_16x16x32_bf16 v[96:99], v[218:221], v[182:185], v[96:99]
	v_mfma_f32_16x16x32_bf16 v[84:87], v[210:213], v[194:197], v[84:87]
	v_mfma_f32_16x16x32_bf16 v[80:83], v[218:221], v[194:197], v[80:83]
	v_mfma_f32_16x16x32_bf16 v[68:71], v[210:213], v[202:205], v[68:71]
	v_mfma_f32_16x16x32_bf16 v[64:67], v[218:221], v[202:205], v[64:67]
	v_mfma_f32_16x16x32_bf16 v[116:119], v[214:217], v[170:173], v[116:119]
	v_mfma_f32_16x16x32_bf16 v[112:115], v[222:225], v[170:173], v[112:115]
	v_mfma_f32_16x16x32_bf16 v[100:103], v[214:217], v[190:193], v[100:103]
	v_mfma_f32_16x16x32_bf16 v[96:99], v[222:225], v[190:193], v[96:99]
	v_mfma_f32_16x16x32_bf16 v[84:87], v[214:217], v[198:201], v[84:87]
	v_mfma_f32_16x16x32_bf16 v[80:83], v[222:225], v[198:201], v[80:83]
	v_mfma_f32_16x16x32_bf16 v[68:71], v[214:217], v[206:209], v[68:71]
	v_mfma_f32_16x16x32_bf16 v[64:67], v[222:225], v[206:209], v[64:67]
	s_mov_b32 m0, s35
	v_lshl_add_u64 v[174:175], v[226:227], 0, s[4:5]
	s_barrier
	ds_read_b128 v[166:169], v152 offset:49152
	ds_read_b128 v[170:173], v152 offset:50176
	ds_read_b128 v[182:185], v152 offset:51200
	ds_read_b128 v[190:193], v152 offset:52224
	ds_read_b128 v[194:197], v152 offset:53248
	ds_read_b128 v[198:201], v152 offset:54272
	ds_read_b128 v[202:205], v152 offset:55296
	ds_read_b128 v[206:209], v152 offset:56320
	global_load_lds_dwordx4 v[174:175], off
	v_lshl_add_u64 v[174:175], v[228:229], 0, s[4:5]
	s_mov_b32 m0, s36
	s_nop 0
	global_load_lds_dwordx4 v[174:175], off
	s_barrier
; __device__ __forceinline__ unsigned cvt_pk_bf16(float lo, float hi) { unsigned r; asm volatile("v_cvt_pk_bf16_f32 %0, %1, %2" : "=v"(r) : "v"(lo), "v"(hi)); return r; }
; #define PG8_STAGE(bufoff, gbase, voff) do { _Pragma("unroll") for (int _i = 0; _i < 2; ++_i) \
;         __builtin_amdgcn_global_load_lds((const unsigned*)((const char*)(gbase) + (voff)[_i]), (PG8_LAS unsigned*)(lds + (bufoff) + ldsw + _i * 8192), 16, 0, 0); } while (0)
; #define PG8_MMA(ai, bj, At, Bt) do { __builtin_amdgcn_s_setprio(1); _Pragma("unroll") for (int m = 0; m < 4; ++m) _Pragma("unroll") for (int n = 0; n < 2; ++n) _Pragma("unroll") for (int k = 0; k < 2; ++k) \
;         acc[ai][bj][m][n] = __builtin_amdgcn_mfma_f32_16x16x32_bf16(Bt[n][k], At[m][k], acc[ai][bj][m][n], 0, 0, 0); __builtin_amdgcn_s_setprio(0); } while (0)
; #define PG8_WAIT_V(n) asm volatile("s_waitcnt vmcnt(" #n ")" ::: "memory")
; #define PG8_WAIT_L(n) asm volatile("s_waitcnt lgkmcnt(" #n ")" ::: "memory")
; #define PG8_BAR __builtin_amdgcn_s_barrier()
; #define PG8_SCHED __builtin_amdgcn_sched_barrier(0)
;     __device__ __forceinline__ void operator()(const f32x4 (&acc)[2][2][4][2], const Unit& u, int wr, int wc, int fr, int fq) const {
;         const int row0 = u.pm * BM + wr * 64 + fr, col0 = u.pn * HALF + wc * 32 + 8 * fq;
; #pragma unroll
;         for (int ai = 0; ai < 2; ++ai)
; #pragma unroll
;             for (int m = 0; m < 4; ++m) { bf16_t* rowp = O + (size_t)(row0 + ai * HALF + m * 16) * ldc + col0;
;                 f32x4 v0, v1;
; #pragma unroll
;                 for (int j = 0; j < 1; ++j) { v0 = acc[ai][0][m][0] * sigmoid4(acc[ai][0][m][0]) * acc[ai][1][m][0]; v1 = acc[ai][0][m][1] * sigmoid4(acc[ai][0][m][1]) * acc[ai][1][m][1]; }
;                 u32x4 w; w.x = cvt_pk_bf16(v0[0], v0[1]); w.y = cvt_pk_bf16(v0[2], v0[3]); w.z = cvt_pk_bf16(v1[0], v1[1]); w.w = cvt_pk_bf16(v1[2], v1[3]);
;                 *(u32x4*)rowp = w; }
; template <class Epi, class Sched>
; __device__ __forceinline__ void gemm_phase(PG8_LAS unsigned char* lds, const Gemm g, const Sched& S, const Epi& E) {
;     ...
;             PG8_BAR; PG8_WAIT_L(0); PG8_MMA(1, 0, At, B0); PG8_BAR; PG8_SCHED;
;             PG8_STAGE(PG8_SB(1, 1), b3 + hstep, voffB);
;             PG8_WAIT_V(6); PG8_BAR; PG8_MMA(1, 1, At, B1); PG8_BAR;
	s_waitcnt lgkmcnt(0)
	s_waitcnt lgkmcnt(0)
	v_mfma_f32_16x16x32_bf16 v[60:63], v[144:147], v[166:169], v[60:63]
	v_mfma_f32_16x16x32_bf16 v[56:59], v[158:161], v[166:169], v[56:59]
	v_mfma_f32_16x16x32_bf16 v[44:47], v[144:147], v[182:185], v[44:47]
	v_mfma_f32_16x16x32_bf16 v[40:43], v[158:161], v[182:185], v[40:43]
	v_mfma_f32_16x16x32_bf16 v[28:31], v[144:147], v[194:197], v[28:31]
	v_mfma_f32_16x16x32_bf16 v[24:27], v[158:161], v[194:197], v[24:27]
	v_mfma_f32_16x16x32_bf16 v[12:15], v[144:147], v[202:205], v[12:15]
	v_mfma_f32_16x16x32_bf16 v[8:11], v[158:161], v[202:205], v[8:11]
	v_mfma_f32_16x16x32_bf16 v[60:63], v[154:157], v[170:173], v[60:63]
	v_mfma_f32_16x16x32_bf16 v[56:59], v[162:165], v[170:173], v[56:59]
	v_mfma_f32_16x16x32_bf16 v[44:47], v[154:157], v[190:193], v[44:47]
	v_mfma_f32_16x16x32_bf16 v[40:43], v[162:165], v[190:193], v[40:43]
	v_mfma_f32_16x16x32_bf16 v[28:31], v[154:157], v[198:201], v[28:31]
	v_mfma_f32_16x16x32_bf16 v[24:27], v[162:165], v[198:201], v[24:27]
	v_mfma_f32_16x16x32_bf16 v[12:15], v[154:157], v[206:209], v[12:15]
	v_mfma_f32_16x16x32_bf16 v[8:11], v[162:165], v[206:209], v[8:11]
	s_barrier
	s_add_u32 s18, s18, 0x40080
	s_addc_u32 s19, s19, 0
	s_add_i32 s20, s20, s26
	v_lshl_add_u64 v[144:145], s[18:19], 0, v[132:133]
	s_mov_b32 m0, s20
	s_nop 0
	global_load_lds_dwordx4 v[144:145], off
	v_lshl_add_u64 v[144:145], s[18:19], 0, v[128:129]
	s_add_i32 m0, s20, 0x2000
	s_nop 0
	global_load_lds_dwordx4 v[144:145], off
	s_waitcnt vmcnt(6)
	s_barrier
	v_mfma_f32_16x16x32_bf16 v[52:55], v[210:213], v[166:169], v[52:55]
	v_mfma_f32_16x16x32_bf16 v[48:51], v[218:221], v[166:169], v[48:51]
	v_mfma_f32_16x16x32_bf16 v[36:39], v[210:213], v[182:185], v[36:39]
	v_mfma_f32_16x16x32_bf16 v[32:35], v[218:221], v[182:185], v[32:35]
	v_mfma_f32_16x16x32_bf16 v[20:23], v[210:213], v[194:197], v[20:23]
	v_mfma_f32_16x16x32_bf16 v[16:19], v[218:221], v[194:197], v[16:19]
	v_mfma_f32_16x16x32_bf16 v[4:7], v[210:213], v[202:205], v[4:7]
	v_mfma_f32_16x16x32_bf16 v[0:3], v[218:221], v[202:205], v[0:3]
	v_mfma_f32_16x16x32_bf16 v[52:55], v[214:217], v[170:173], v[52:55]
	v_mfma_f32_16x16x32_bf16 v[48:51], v[222:225], v[170:173], v[48:51]
	v_mfma_f32_16x16x32_bf16 v[36:39], v[214:217], v[190:193], v[36:39]
	v_mfma_f32_16x16x32_bf16 v[32:35], v[222:225], v[190:193], v[32:35]
	v_mfma_f32_16x16x32_bf16 v[20:23], v[214:217], v[198:201], v[20:23]
	v_mfma_f32_16x16x32_bf16 v[16:19], v[222:225], v[198:201], v[16:19]
	v_mfma_f32_16x16x32_bf16 v[4:7], v[214:217], v[206:209], v[4:7]
	v_mfma_f32_16x16x32_bf16 v[0:3], v[222:225], v[206:209], v[0:3]
	s_add_i32 s46, s46, 2
	s_add_u32 s16, s16, 0x100
	s_addc_u32 s17, s17, 0
	s_add_u32 s44, s44, 0x100
	s_addc_u32 s45, s45, 0
	s_cmp_gt_u32 s46, 13
	s_barrier
	s_cbranch_scc0 .LBB0_1202
	v_max_f32_e32 v144, v124, v124
	v_max_f32_e32 v144, 0xc1a00000, v144
	v_mul_f32_e32 v144, 0xbfb8aa3b, v144
	v_exp_f32_e32 v157, v144
	v_max_f32_e32 v144, v125, v125
	v_max_f32_e32 v144, 0xc1a00000, v144
	v_mul_f32_e32 v144, 0xbfb8aa3b, v144
	v_exp_f32_e32 v156, v144
	v_max_f32_e32 v144, v126, v126
	v_max_f32_e32 v144, 0xc1a00000, v144
	v_mul_f32_e32 v144, 0xbfb8aa3b, v144
	v_exp_f32_e32 v159, v144
	v_max_f32_e32 v144, v127, v127
	v_max_f32_e32 v144, 0xc1a00000, v144
	v_mul_f32_e32 v144, 0xbfb8aa3b, v144
	v_exp_f32_e32 v158, v144
	v_pk_add_f32 v[156:157], v[156:157], 1.0 op_sel_hi:[1,0]
	v_lshl_or_b32 v146, s41, 7, v150
	v_mov_b32_e32 v160, v157
	v_pk_add_f32 v[158:159], v[158:159], 1.0 op_sel_hi:[1,0]
	v_mov_b32_e32 v162, v156
	v_mov_b32_e32 v161, v159
	v_mov_b32_e32 v163, v158
	v_pk_mul_f32 v[160:161], v[160:161], v[162:163]
	v_lshl_add_u32 v154, s14, 8, v148
	v_mul_f32_e32 v155, v160, v161
	v_rcp_f32_e32 v155, v155
	v_ashrrev_i32_e32 v147, 31, v146
	v_mov_b64_e32 v[144:145], s[0:1]
	v_mad_i64_i32 v[162:163], s[16:17], v154, s40, v[144:145]
	v_mul_f32_e32 v164, v161, v155
	v_mul_f32_e32 v160, v160, v155
	v_max_f32_e32 v155, v120, v120
	v_max_f32_e32 v155, 0xc1a00000, v155
	v_mul_f32_e32 v155, 0xbfb8aa3b, v155
	v_pk_mul_f32 v[158:159], v[158:159], v[160:161] op_sel_hi:[1,0]
	v_exp_f32_e32 v161, v155
	v_max_f32_e32 v155, v121, v121
	v_max_f32_e32 v155, 0xc1a00000, v155
	v_mul_f32_e32 v155, 0xbfb8aa3b, v155
	v_exp_f32_e32 v160, v155
	v_max_f32_e32 v155, v122, v122
	v_max_f32_e32 v155, 0xc1a00000, v155
	v_mul_f32_e32 v155, 0xbfb8aa3b, v155
	v_exp_f32_e32 v167, v155
	v_max_f32_e32 v155, v123, v123
	v_max_f32_e32 v155, 0xc1a00000, v155
	v_mul_f32_e32 v155, 0xbfb8aa3b, v155
	v_exp_f32_e32 v166, v155
	v_pk_mul_f32 v[156:157], v[156:157], v[164:165] op_sel_hi:[1,0]
	v_pk_mul_f32 v[126:127], v[126:127], v[158:159]
	v_pk_mul_f32 v[124:125], v[124:125], v[156:157]
	v_pk_add_f32 v[156:157], v[160:161], 1.0 op_sel_hi:[1,0]
	v_pk_add_f32 v[160:161], v[166:167], 1.0 op_sel_hi:[1,0]
	v_mov_b32_e32 v164, v157
	v_mov_b32_e32 v165, v161
	v_mov_b32_e32 v166, v156
	v_mov_b32_e32 v167, v160
	v_pk_mul_f32 v[164:165], v[164:165], v[166:167]
	v_pk_mul_f32 v[118:119], v[126:127], v[118:119]
	v_mul_f32_e32 v155, v164, v165
	v_rcp_f32_e32 v155, v155
	v_pk_mul_f32 v[116:117], v[124:125], v[116:117]
	v_lshlrev_b64 v[146:147], 1, v[146:147]
	v_lshl_add_u64 v[162:163], v[162:163], 0, v[146:147]
	v_mul_f32_e32 v124, v165, v155
	v_mul_f32_e32 v126, v164, v155
	v_pk_mul_f32 v[126:127], v[160:161], v[126:127] op_sel_hi:[1,0]
	v_pk_mul_f32 v[124:125], v[156:157], v[124:125] op_sel_hi:[1,0]
	v_pk_mul_f32 v[122:123], v[122:123], v[126:127]
	v_pk_mul_f32 v[120:121], v[120:121], v[124:125]
	v_pk_mul_f32 v[122:123], v[122:123], v[114:115]
	v_pk_mul_f32 v[114:115], v[120:121], v[112:113]
	v_cvt_pk_bf16_f32 v112, v116, v117
	v_cvt_pk_bf16_f32 v113, v118, v119
; __device__ __forceinline__ unsigned cvt_pk_bf16(float lo, float hi) { unsigned r; asm volatile("v_cvt_pk_bf16_f32 %0, %1, %2" : "=v"(r) : "v"(lo), "v"(hi)); return r; }
;     __device__ __forceinline__ void operator()(const f32x4 (&acc)[2][2][4][2], const Unit& u, int wr, int wc, int fr, int fq) const {
;     ...
;         for (int ai = 0; ai < 2; ++ai)
; #pragma unroll
;             for (int m = 0; m < 4; ++m) { bf16_t* rowp = O + (size_t)(row0 + ai * HALF + m * 16) * ldc + col0;
;                 f32x4 v0, v1;
; #pragma unroll
;                 for (int j = 0; j < 1; ++j) { v0 = acc[ai][0][m][0] * sigmoid4(acc[ai][0][m][0]) * acc[ai][1][m][0]; v1 = acc[ai][0][m][1] * sigmoid4(acc[ai][0][m][1]) * acc[ai][1][m][1]; }
;                 u32x4 w; w.x = cvt_pk_bf16(v0[0], v0[1]); w.y = cvt_pk_bf16(v0[2], v0[3]); w.z = cvt_pk_bf16(v1[0], v1[1]); w.w = cvt_pk_bf16(v1[2], v1[3]);
;                 *(u32x4*)rowp = w; }
	v_max_f32_e32 v116, v108, v108
	v_max_f32_e32 v118, v110, v110
	v_max_f32_e32 v116, 0xc1a00000, v116
	v_max_f32_e32 v118, 0xc1a00000, v118
	v_mul_f32_e32 v116, 0xbfb8aa3b, v116
	v_mul_f32_e32 v118, 0xbfb8aa3b, v118
	v_exp_f32_e32 v117, v116
	v_max_f32_e32 v116, v109, v109
	v_exp_f32_e32 v119, v118
	v_max_f32_e32 v118, v111, v111
	v_max_f32_e32 v116, 0xc1a00000, v116
	v_max_f32_e32 v118, 0xc1a00000, v118
	v_mul_f32_e32 v116, 0xbfb8aa3b, v116
	v_mul_f32_e32 v118, 0xbfb8aa3b, v118
	v_exp_f32_e32 v116, v116
	v_exp_f32_e32 v118, v118
	v_cvt_pk_bf16_f32 v114, v114, v115
	v_cvt_pk_bf16_f32 v115, v122, v123
	global_store_dwordx4 v[162:163], v[112:115], off
	v_or_b32_e32 v120, 16, v154
	s_and_b64 vcc, exec, s[2:3]
	v_pk_add_f32 v[112:113], v[116:117], 1.0 op_sel_hi:[1,0]
	v_pk_add_f32 v[114:115], v[118:119], 1.0 op_sel_hi:[1,0]
	v_mov_b32_e32 v116, v113
	v_mov_b32_e32 v117, v115
	v_mov_b32_e32 v118, v112
	v_mov_b32_e32 v119, v114
	v_pk_mul_f32 v[116:117], v[116:117], v[118:119]
	s_mov_b32 s41, s6
	v_mul_f32_e32 v118, v116, v117
	v_rcp_f32_e32 v121, v118
	v_mad_i64_i32 v[118:119], s[16:17], v120, s40, v[144:145]
	v_lshl_add_u64 v[118:119], v[118:119], 0, v[146:147]
	v_mul_f32_e32 v116, v116, v121
	v_mul_f32_e32 v120, v117, v121
	v_pk_mul_f32 v[114:115], v[114:115], v[116:117] op_sel_hi:[1,0]
	v_max_f32_e32 v116, v104, v104
	v_max_f32_e32 v121, v106, v106
	v_max_f32_e32 v116, 0xc1a00000, v116
	v_max_f32_e32 v121, 0xc1a00000, v121
	v_mul_f32_e32 v116, 0xbfb8aa3b, v116
	v_mul_f32_e32 v121, 0xbfb8aa3b, v121
	v_exp_f32_e32 v117, v116
	v_max_f32_e32 v116, v105, v105
	v_exp_f32_e32 v123, v121
	v_max_f32_e32 v121, v107, v107
	v_max_f32_e32 v116, 0xc1a00000, v116
	v_max_f32_e32 v121, 0xc1a00000, v121
	v_mul_f32_e32 v116, 0xbfb8aa3b, v116
	v_mul_f32_e32 v121, 0xbfb8aa3b, v121
	v_exp_f32_e32 v116, v116
	v_exp_f32_e32 v122, v121
	v_pk_mul_f32 v[112:113], v[112:113], v[120:121] op_sel_hi:[1,0]
	v_pk_mul_f32 v[110:111], v[110:111], v[114:115]
	v_pk_mul_f32 v[108:109], v[108:109], v[112:113]
	v_pk_add_f32 v[112:113], v[116:117], 1.0 op_sel_hi:[1,0]
	v_pk_add_f32 v[116:117], v[122:123], 1.0 op_sel_hi:[1,0]
	v_mov_b32_e32 v120, v113
	v_mov_b32_e32 v121, v117
	v_mov_b32_e32 v122, v112
	v_mov_b32_e32 v123, v116
	v_pk_mul_f32 v[120:121], v[120:121], v[122:123]
	v_pk_mul_f32 v[102:103], v[110:111], v[102:103]
	v_mul_f32_e32 v122, v120, v121
	v_rcp_f32_e32 v122, v122
	v_pk_mul_f32 v[100:101], v[108:109], v[100:101]
	s_mov_b32 s14, s8
	s_mov_b64 s[18:19], s[12:13]
	v_mul_f32_e32 v108, v121, v122
	v_mul_f32_e32 v110, v120, v122
	v_pk_mul_f32 v[110:111], v[116:117], v[110:111] op_sel_hi:[1,0]
	v_pk_mul_f32 v[108:109], v[112:113], v[108:109] op_sel_hi:[1,0]
	v_pk_mul_f32 v[106:107], v[106:107], v[110:111]
	v_pk_mul_f32 v[104:105], v[104:105], v[108:109]
	v_pk_mul_f32 v[106:107], v[106:107], v[98:99]
	v_pk_mul_f32 v[98:99], v[104:105], v[96:97]
	v_cvt_pk_bf16_f32 v96, v100, v101
	v_cvt_pk_bf16_f32 v97, v102, v103
	v_max_f32_e32 v100, v92, v92
	v_max_f32_e32 v102, v94, v94
	v_max_f32_e32 v100, 0xc1a00000, v100
	v_max_f32_e32 v102, 0xc1a00000, v102
	v_mul_f32_e32 v100, 0xbfb8aa3b, v100
	v_mul_f32_e32 v102, 0xbfb8aa3b, v102
	v_exp_f32_e32 v101, v100
	v_max_f32_e32 v100, v93, v93
	v_exp_f32_e32 v103, v102
	v_max_f32_e32 v102, v95, v95
	v_max_f32_e32 v100, 0xc1a00000, v100
	v_max_f32_e32 v102, 0xc1a00000, v102
	v_mul_f32_e32 v100, 0xbfb8aa3b, v100
	v_mul_f32_e32 v102, 0xbfb8aa3b, v102
	v_exp_f32_e32 v100, v100
	v_exp_f32_e32 v102, v102
	v_cvt_pk_bf16_f32 v98, v98, v99
	v_cvt_pk_bf16_f32 v99, v106, v107
	global_store_dwordx4 v[118:119], v[96:99], off
	v_or_b32_e32 v104, 32, v154
	s_nop 0
	v_pk_add_f32 v[96:97], v[100:101], 1.0 op_sel_hi:[1,0]
	v_pk_add_f32 v[98:99], v[102:103], 1.0 op_sel_hi:[1,0]
	v_mov_b32_e32 v100, v97
	v_mov_b32_e32 v101, v99
	v_mov_b32_e32 v102, v96
	v_mov_b32_e32 v103, v98
	v_pk_mul_f32 v[100:101], v[100:101], v[102:103]
	s_nop 0
	v_mul_f32_e32 v102, v100, v101
	v_rcp_f32_e32 v105, v102
	v_mad_i64_i32 v[102:103], s[16:17], v104, s40, v[144:145]
	v_lshl_add_u64 v[102:103], v[102:103], 0, v[146:147]
	v_mul_f32_e32 v100, v100, v105
	v_mul_f32_e32 v104, v101, v105
	v_pk_mul_f32 v[98:99], v[98:99], v[100:101] op_sel_hi:[1,0]
	v_max_f32_e32 v100, v88, v88
	v_max_f32_e32 v105, v90, v90
	v_max_f32_e32 v100, 0xc1a00000, v100
	v_max_f32_e32 v105, 0xc1a00000, v105
	v_mul_f32_e32 v100, 0xbfb8aa3b, v100
	v_mul_f32_e32 v105, 0xbfb8aa3b, v105
	v_exp_f32_e32 v101, v100
	v_max_f32_e32 v100, v89, v89
	v_exp_f32_e32 v107, v105
	v_max_f32_e32 v105, v91, v91
	v_max_f32_e32 v100, 0xc1a00000, v100
	v_max_f32_e32 v105, 0xc1a00000, v105
	v_mul_f32_e32 v100, 0xbfb8aa3b, v100
	v_mul_f32_e32 v105, 0xbfb8aa3b, v105
	v_exp_f32_e32 v100, v100
	v_exp_f32_e32 v106, v105
	v_pk_mul_f32 v[96:97], v[96:97], v[104:105] op_sel_hi:[1,0]
	v_pk_mul_f32 v[94:95], v[94:95], v[98:99]
	v_pk_mul_f32 v[92:93], v[92:93], v[96:97]
	v_pk_add_f32 v[96:97], v[100:101], 1.0 op_sel_hi:[1,0]
	v_pk_add_f32 v[100:101], v[106:107], 1.0 op_sel_hi:[1,0]
	v_mov_b32_e32 v104, v97
	v_mov_b32_e32 v105, v101
	v_mov_b32_e32 v106, v96
	v_mov_b32_e32 v107, v100
	v_pk_mul_f32 v[104:105], v[104:105], v[106:107]
	v_pk_mul_f32 v[86:87], v[94:95], v[86:87]
	v_mul_f32_e32 v106, v104, v105
	v_rcp_f32_e32 v106, v106
	v_pk_mul_f32 v[84:85], v[92:93], v[84:85]
	v_mul_f32_e32 v92, v105, v106
	v_mul_f32_e32 v94, v104, v106
	v_pk_mul_f32 v[94:95], v[100:101], v[94:95] op_sel_hi:[1,0]
	v_pk_mul_f32 v[92:93], v[96:97], v[92:93] op_sel_hi:[1,0]
	v_pk_mul_f32 v[90:91], v[90:91], v[94:95]
	v_pk_mul_f32 v[88:89], v[88:89], v[92:93]
	v_pk_mul_f32 v[90:91], v[90:91], v[82:83]
	v_pk_mul_f32 v[82:83], v[88:89], v[80:81]
	v_cvt_pk_bf16_f32 v80, v84, v85
; __device__ __forceinline__ unsigned cvt_pk_bf16(float lo, float hi) { unsigned r; asm volatile("v_cvt_pk_bf16_f32 %0, %1, %2" : "=v"(r) : "v"(lo), "v"(hi)); return r; }
;     __device__ __forceinline__ void operator()(const f32x4 (&acc)[2][2][4][2], const Unit& u, int wr, int wc, int fr, int fq) const {
;     ...
;         for (int ai = 0; ai < 2; ++ai)
; #pragma unroll
;             for (int m = 0; m < 4; ++m) { bf16_t* rowp = O + (size_t)(row0 + ai * HALF + m * 16) * ldc + col0;
;                 f32x4 v0, v1;
; #pragma unroll
;                 for (int j = 0; j < 1; ++j) { v0 = acc[ai][0][m][0] * sigmoid4(acc[ai][0][m][0]) * acc[ai][1][m][0]; v1 = acc[ai][0][m][1] * sigmoid4(acc[ai][0][m][1]) * acc[ai][1][m][1]; }
;                 u32x4 w; w.x = cvt_pk_bf16(v0[0], v0[1]); w.y = cvt_pk_bf16(v0[2], v0[3]); w.z = cvt_pk_bf16(v1[0], v1[1]); w.w = cvt_pk_bf16(v1[2], v1[3]);
;                 *(u32x4*)rowp = w; }
	v_cvt_pk_bf16_f32 v81, v86, v87
	v_max_f32_e32 v84, v76, v76
	v_max_f32_e32 v86, v78, v78
	v_max_f32_e32 v84, 0xc1a00000, v84
	v_max_f32_e32 v86, 0xc1a00000, v86
	v_mul_f32_e32 v84, 0xbfb8aa3b, v84
	v_mul_f32_e32 v86, 0xbfb8aa3b, v86
	v_exp_f32_e32 v85, v84
	v_max_f32_e32 v84, v77, v77
	v_exp_f32_e32 v87, v86
	v_max_f32_e32 v86, v79, v79
	v_max_f32_e32 v84, 0xc1a00000, v84
	v_max_f32_e32 v86, 0xc1a00000, v86
	v_mul_f32_e32 v84, 0xbfb8aa3b, v84
	v_mul_f32_e32 v86, 0xbfb8aa3b, v86
	v_exp_f32_e32 v84, v84
	v_exp_f32_e32 v86, v86
	v_cvt_pk_bf16_f32 v82, v82, v83
	v_cvt_pk_bf16_f32 v83, v90, v91
	global_store_dwordx4 v[102:103], v[80:83], off
	v_or_b32_e32 v88, 48, v154
	s_nop 0
	v_pk_add_f32 v[80:81], v[84:85], 1.0 op_sel_hi:[1,0]
	v_pk_add_f32 v[82:83], v[86:87], 1.0 op_sel_hi:[1,0]
	v_mov_b32_e32 v84, v81
	v_mov_b32_e32 v85, v83
	v_mov_b32_e32 v86, v80
	v_mov_b32_e32 v87, v82
	v_pk_mul_f32 v[84:85], v[84:85], v[86:87]
	s_nop 0
	v_mul_f32_e32 v86, v84, v85
	v_rcp_f32_e32 v89, v86
	v_mad_i64_i32 v[86:87], s[16:17], v88, s40, v[144:145]
	v_lshl_add_u64 v[86:87], v[86:87], 0, v[146:147]
	v_mul_f32_e32 v84, v84, v89
	v_mul_f32_e32 v88, v85, v89
	v_pk_mul_f32 v[82:83], v[82:83], v[84:85] op_sel_hi:[1,0]
	v_max_f32_e32 v84, v72, v72
	v_max_f32_e32 v89, v74, v74
	v_max_f32_e32 v84, 0xc1a00000, v84
	v_max_f32_e32 v89, 0xc1a00000, v89
	v_mul_f32_e32 v84, 0xbfb8aa3b, v84
	v_mul_f32_e32 v89, 0xbfb8aa3b, v89
	v_exp_f32_e32 v85, v84
	v_max_f32_e32 v84, v73, v73
	v_exp_f32_e32 v91, v89
	v_max_f32_e32 v89, v75, v75
	v_max_f32_e32 v84, 0xc1a00000, v84
	v_max_f32_e32 v89, 0xc1a00000, v89
	v_mul_f32_e32 v84, 0xbfb8aa3b, v84
	v_mul_f32_e32 v89, 0xbfb8aa3b, v89
	v_exp_f32_e32 v84, v84
	v_exp_f32_e32 v90, v89
	v_pk_mul_f32 v[80:81], v[80:81], v[88:89] op_sel_hi:[1,0]
	v_pk_mul_f32 v[78:79], v[78:79], v[82:83]
	v_pk_mul_f32 v[76:77], v[76:77], v[80:81]
	v_pk_add_f32 v[80:81], v[84:85], 1.0 op_sel_hi:[1,0]
	v_pk_add_f32 v[84:85], v[90:91], 1.0 op_sel_hi:[1,0]
	v_mov_b32_e32 v88, v81
	v_mov_b32_e32 v89, v85
	v_mov_b32_e32 v90, v80
	v_mov_b32_e32 v91, v84
	v_pk_mul_f32 v[88:89], v[88:89], v[90:91]
	v_pk_mul_f32 v[70:71], v[78:79], v[70:71]
	v_mul_f32_e32 v90, v88, v89
	v_rcp_f32_e32 v90, v90
	v_pk_mul_f32 v[68:69], v[76:77], v[68:69]
	v_mul_f32_e32 v76, v89, v90
	v_mul_f32_e32 v78, v88, v90
	v_pk_mul_f32 v[78:79], v[84:85], v[78:79] op_sel_hi:[1,0]
	v_pk_mul_f32 v[76:77], v[80:81], v[76:77] op_sel_hi:[1,0]
	v_pk_mul_f32 v[74:75], v[74:75], v[78:79]
	v_pk_mul_f32 v[72:73], v[72:73], v[76:77]
	v_pk_mul_f32 v[74:75], v[74:75], v[66:67]
	v_pk_mul_f32 v[66:67], v[72:73], v[64:65]
	v_cvt_pk_bf16_f32 v64, v68, v69
	v_cvt_pk_bf16_f32 v65, v70, v71
	v_max_f32_e32 v68, v60, v60
	v_max_f32_e32 v70, v62, v62
	v_max_f32_e32 v68, 0xc1a00000, v68
	v_max_f32_e32 v70, 0xc1a00000, v70
	v_mul_f32_e32 v68, 0xbfb8aa3b, v68
	v_mul_f32_e32 v70, 0xbfb8aa3b, v70
	v_exp_f32_e32 v69, v68
	v_max_f32_e32 v68, v61, v61
	v_exp_f32_e32 v71, v70
	v_max_f32_e32 v70, v63, v63
	v_max_f32_e32 v68, 0xc1a00000, v68
	v_max_f32_e32 v70, 0xc1a00000, v70
	v_mul_f32_e32 v68, 0xbfb8aa3b, v68
	v_mul_f32_e32 v70, 0xbfb8aa3b, v70
	v_exp_f32_e32 v68, v68
	v_exp_f32_e32 v70, v70
	v_cvt_pk_bf16_f32 v66, v66, v67
	v_cvt_pk_bf16_f32 v67, v74, v75
	global_store_dwordx4 v[86:87], v[64:67], off
	v_add_u32_e32 v72, 0x80, v154
	s_nop 0
	v_pk_add_f32 v[64:65], v[68:69], 1.0 op_sel_hi:[1,0]
	v_pk_add_f32 v[66:67], v[70:71], 1.0 op_sel_hi:[1,0]
	v_mov_b32_e32 v68, v65
	v_mov_b32_e32 v69, v67
	v_mov_b32_e32 v70, v64
	v_mov_b32_e32 v71, v66
	v_pk_mul_f32 v[68:69], v[68:69], v[70:71]
	s_nop 0
	v_mul_f32_e32 v70, v68, v69
	v_rcp_f32_e32 v73, v70
	v_mad_i64_i32 v[70:71], s[16:17], v72, s40, v[144:145]
	v_lshl_add_u64 v[70:71], v[70:71], 0, v[146:147]
	v_mul_f32_e32 v68, v68, v73
	v_mul_f32_e32 v72, v69, v73
	v_pk_mul_f32 v[66:67], v[66:67], v[68:69] op_sel_hi:[1,0]
	v_max_f32_e32 v68, v56, v56
	v_max_f32_e32 v73, v58, v58
	v_max_f32_e32 v68, 0xc1a00000, v68
	v_max_f32_e32 v73, 0xc1a00000, v73
	v_mul_f32_e32 v68, 0xbfb8aa3b, v68
	v_mul_f32_e32 v73, 0xbfb8aa3b, v73
	v_exp_f32_e32 v69, v68
	v_max_f32_e32 v68, v57, v57
	v_exp_f32_e32 v75, v73
	v_max_f32_e32 v73, v59, v59
	v_max_f32_e32 v68, 0xc1a00000, v68
	v_max_f32_e32 v73, 0xc1a00000, v73
	v_mul_f32_e32 v68, 0xbfb8aa3b, v68
	v_mul_f32_e32 v73, 0xbfb8aa3b, v73
	v_exp_f32_e32 v68, v68
	v_exp_f32_e32 v74, v73
	v_pk_mul_f32 v[64:65], v[64:65], v[72:73] op_sel_hi:[1,0]
	v_pk_mul_f32 v[62:63], v[62:63], v[66:67]
	v_pk_mul_f32 v[60:61], v[60:61], v[64:65]
	v_pk_add_f32 v[64:65], v[68:69], 1.0 op_sel_hi:[1,0]
	v_pk_add_f32 v[68:69], v[74:75], 1.0 op_sel_hi:[1,0]
	v_mov_b32_e32 v72, v65
	v_mov_b32_e32 v73, v69
	v_mov_b32_e32 v74, v64
	v_mov_b32_e32 v75, v68
	v_pk_mul_f32 v[72:73], v[72:73], v[74:75]
	v_pk_mul_f32 v[54:55], v[62:63], v[54:55]
	v_mul_f32_e32 v74, v72, v73
	v_rcp_f32_e32 v74, v74
	v_pk_mul_f32 v[52:53], v[60:61], v[52:53]
	v_mul_f32_e32 v60, v73, v74
	v_mul_f32_e32 v62, v72, v74
	v_pk_mul_f32 v[62:63], v[68:69], v[62:63] op_sel_hi:[1,0]
	v_pk_mul_f32 v[60:61], v[64:65], v[60:61] op_sel_hi:[1,0]
	v_pk_mul_f32 v[58:59], v[58:59], v[62:63]
	v_pk_mul_f32 v[56:57], v[56:57], v[60:61]
	v_pk_mul_f32 v[58:59], v[58:59], v[50:51]
	v_pk_mul_f32 v[50:51], v[56:57], v[48:49]
	v_cvt_pk_bf16_f32 v48, v52, v53
	v_cvt_pk_bf16_f32 v49, v54, v55
	v_max_f32_e32 v52, v44, v44
	v_max_f32_e32 v54, v46, v46
	v_max_f32_e32 v52, 0xc1a00000, v52
	v_max_f32_e32 v54, 0xc1a00000, v54
	v_mul_f32_e32 v52, 0xbfb8aa3b, v52
	v_mul_f32_e32 v54, 0xbfb8aa3b, v54
	v_exp_f32_e32 v53, v52
	v_max_f32_e32 v52, v45, v45
	v_exp_f32_e32 v55, v54
	v_max_f32_e32 v54, v47, v47
	v_max_f32_e32 v52, 0xc1a00000, v52
; __device__ __forceinline__ unsigned cvt_pk_bf16(float lo, float hi) { unsigned r; asm volatile("v_cvt_pk_bf16_f32 %0, %1, %2" : "=v"(r) : "v"(lo), "v"(hi)); return r; }
;     __device__ __forceinline__ void operator()(const f32x4 (&acc)[2][2][4][2], const Unit& u, int wr, int wc, int fr, int fq) const {
;     ...
;         for (int ai = 0; ai < 2; ++ai)
; #pragma unroll
;             for (int m = 0; m < 4; ++m) { bf16_t* rowp = O + (size_t)(row0 + ai * HALF + m * 16) * ldc + col0;
;                 f32x4 v0, v1;
; #pragma unroll
;                 for (int j = 0; j < 1; ++j) { v0 = acc[ai][0][m][0] * sigmoid4(acc[ai][0][m][0]) * acc[ai][1][m][0]; v1 = acc[ai][0][m][1] * sigmoid4(acc[ai][0][m][1]) * acc[ai][1][m][1]; }
;                 u32x4 w; w.x = cvt_pk_bf16(v0[0], v0[1]); w.y = cvt_pk_bf16(v0[2], v0[3]); w.z = cvt_pk_bf16(v1[0], v1[1]); w.w = cvt_pk_bf16(v1[2], v1[3]);
;                 *(u32x4*)rowp = w; }
	v_max_f32_e32 v54, 0xc1a00000, v54
	v_mul_f32_e32 v52, 0xbfb8aa3b, v52
	v_mul_f32_e32 v54, 0xbfb8aa3b, v54
	v_exp_f32_e32 v52, v52
	v_exp_f32_e32 v54, v54
	v_cvt_pk_bf16_f32 v50, v50, v51
	v_cvt_pk_bf16_f32 v51, v58, v59
	global_store_dwordx4 v[70:71], v[48:51], off
	v_add_u32_e32 v56, 0x90, v154
	s_nop 0
	v_pk_add_f32 v[48:49], v[52:53], 1.0 op_sel_hi:[1,0]
	v_pk_add_f32 v[50:51], v[54:55], 1.0 op_sel_hi:[1,0]
	v_mov_b32_e32 v52, v49
	v_mov_b32_e32 v53, v51
	v_mov_b32_e32 v54, v48
	v_mov_b32_e32 v55, v50
	v_pk_mul_f32 v[52:53], v[52:53], v[54:55]
	s_nop 0
	v_mul_f32_e32 v54, v52, v53
	v_rcp_f32_e32 v57, v54
	v_mad_i64_i32 v[54:55], s[16:17], v56, s40, v[144:145]
	v_lshl_add_u64 v[54:55], v[54:55], 0, v[146:147]
	v_mul_f32_e32 v52, v52, v57
	v_mul_f32_e32 v56, v53, v57
	v_pk_mul_f32 v[50:51], v[50:51], v[52:53] op_sel_hi:[1,0]
	v_max_f32_e32 v52, v40, v40
	v_max_f32_e32 v57, v42, v42
	v_max_f32_e32 v52, 0xc1a00000, v52
	v_max_f32_e32 v57, 0xc1a00000, v57
	v_mul_f32_e32 v52, 0xbfb8aa3b, v52
	v_mul_f32_e32 v57, 0xbfb8aa3b, v57
	v_exp_f32_e32 v53, v52
	v_max_f32_e32 v52, v41, v41
	v_exp_f32_e32 v59, v57
	v_max_f32_e32 v57, v43, v43
	v_max_f32_e32 v52, 0xc1a00000, v52
	v_max_f32_e32 v57, 0xc1a00000, v57
	v_mul_f32_e32 v52, 0xbfb8aa3b, v52
	v_mul_f32_e32 v57, 0xbfb8aa3b, v57
	v_exp_f32_e32 v52, v52
	v_exp_f32_e32 v58, v57
	v_pk_mul_f32 v[48:49], v[48:49], v[56:57] op_sel_hi:[1,0]
	v_pk_mul_f32 v[46:47], v[46:47], v[50:51]
	v_pk_mul_f32 v[44:45], v[44:45], v[48:49]
	v_pk_add_f32 v[48:49], v[52:53], 1.0 op_sel_hi:[1,0]
	v_pk_add_f32 v[52:53], v[58:59], 1.0 op_sel_hi:[1,0]
	v_mov_b32_e32 v56, v49
	v_mov_b32_e32 v57, v53
	v_mov_b32_e32 v58, v48
	v_mov_b32_e32 v59, v52
	v_pk_mul_f32 v[56:57], v[56:57], v[58:59]
	v_pk_mul_f32 v[38:39], v[46:47], v[38:39]
	v_mul_f32_e32 v58, v56, v57
	v_rcp_f32_e32 v58, v58
	v_pk_mul_f32 v[36:37], v[44:45], v[36:37]
	v_mul_f32_e32 v44, v57, v58
	v_mul_f32_e32 v46, v56, v58
	v_pk_mul_f32 v[46:47], v[52:53], v[46:47] op_sel_hi:[1,0]
	v_pk_mul_f32 v[44:45], v[48:49], v[44:45] op_sel_hi:[1,0]
	v_pk_mul_f32 v[42:43], v[42:43], v[46:47]
	v_pk_mul_f32 v[40:41], v[40:41], v[44:45]
	v_pk_mul_f32 v[42:43], v[42:43], v[34:35]
	v_pk_mul_f32 v[34:35], v[40:41], v[32:33]
	v_cvt_pk_bf16_f32 v32, v36, v37
	v_cvt_pk_bf16_f32 v33, v38, v39
	v_max_f32_e32 v36, v28, v28
	v_max_f32_e32 v38, v30, v30
	v_max_f32_e32 v36, 0xc1a00000, v36
	v_max_f32_e32 v38, 0xc1a00000, v38
	v_mul_f32_e32 v36, 0xbfb8aa3b, v36
	v_mul_f32_e32 v38, 0xbfb8aa3b, v38
	v_exp_f32_e32 v37, v36
	v_max_f32_e32 v36, v29, v29
	v_exp_f32_e32 v39, v38
	v_max_f32_e32 v38, v31, v31
	v_max_f32_e32 v36, 0xc1a00000, v36
	v_max_f32_e32 v38, 0xc1a00000, v38
	v_mul_f32_e32 v36, 0xbfb8aa3b, v36
	v_mul_f32_e32 v38, 0xbfb8aa3b, v38
	v_exp_f32_e32 v36, v36
	v_exp_f32_e32 v38, v38
	v_cvt_pk_bf16_f32 v34, v34, v35
	v_cvt_pk_bf16_f32 v35, v42, v43
	global_store_dwordx4 v[54:55], v[32:35], off
	v_add_u32_e32 v40, 0xa0, v154
	s_nop 0
	v_pk_add_f32 v[32:33], v[36:37], 1.0 op_sel_hi:[1,0]
	v_pk_add_f32 v[34:35], v[38:39], 1.0 op_sel_hi:[1,0]
	v_mov_b32_e32 v36, v33
	v_mov_b32_e32 v37, v35
	v_mov_b32_e32 v38, v32
	v_mov_b32_e32 v39, v34
	v_pk_mul_f32 v[36:37], v[36:37], v[38:39]
	s_nop 0
	v_mul_f32_e32 v38, v36, v37
	v_rcp_f32_e32 v41, v38
	v_mad_i64_i32 v[38:39], s[16:17], v40, s40, v[144:145]
	v_lshl_add_u64 v[38:39], v[38:39], 0, v[146:147]
	v_mul_f32_e32 v36, v36, v41
	v_mul_f32_e32 v40, v37, v41
	v_pk_mul_f32 v[34:35], v[34:35], v[36:37] op_sel_hi:[1,0]
	v_max_f32_e32 v36, v24, v24
	v_max_f32_e32 v41, v26, v26
	v_max_f32_e32 v36, 0xc1a00000, v36
	v_max_f32_e32 v41, 0xc1a00000, v41
	v_mul_f32_e32 v36, 0xbfb8aa3b, v36
	v_mul_f32_e32 v41, 0xbfb8aa3b, v41
	v_exp_f32_e32 v37, v36
	v_max_f32_e32 v36, v25, v25
	v_exp_f32_e32 v43, v41
	v_max_f32_e32 v41, v27, v27
	v_max_f32_e32 v36, 0xc1a00000, v36
	v_max_f32_e32 v41, 0xc1a00000, v41
	v_mul_f32_e32 v36, 0xbfb8aa3b, v36
; __device__ __forceinline__ unsigned cvt_pk_bf16(float lo, float hi) { unsigned r; asm volatile("v_cvt_pk_bf16_f32 %0, %1, %2" : "=v"(r) : "v"(lo), "v"(hi)); return r; }
;     __device__ __forceinline__ void operator()(const f32x4 (&acc)[2][2][4][2], const Unit& u, int wr, int wc, int fr, int fq) const {
;     ...
;         for (int ai = 0; ai < 2; ++ai)
; #pragma unroll
;             for (int m = 0; m < 4; ++m) { bf16_t* rowp = O + (size_t)(row0 + ai * HALF + m * 16) * ldc + col0;
;                 f32x4 v0, v1;
; #pragma unroll
;                 for (int j = 0; j < 1; ++j) { v0 = acc[ai][0][m][0] * sigmoid4(acc[ai][0][m][0]) * acc[ai][1][m][0]; v1 = acc[ai][0][m][1] * sigmoid4(acc[ai][0][m][1]) * acc[ai][1][m][1]; }
;                 u32x4 w; w.x = cvt_pk_bf16(v0[0], v0[1]); w.y = cvt_pk_bf16(v0[2], v0[3]); w.z = cvt_pk_bf16(v1[0], v1[1]); w.w = cvt_pk_bf16(v1[2], v1[3]);
;                 *(u32x4*)rowp = w; }
; template <class Epi, class Sched>
; __device__ __forceinline__ void gemm_phase(PG8_LAS unsigned char* lds, const Gemm g, const Sched& S, const Epi& E) {
;     ...
;         if (!has_next) break;
; #pragma unroll
;         for (int a = 0; a < 2; ++a)
; #pragma unroll
;             for (int b = 0; b < 2; ++b)
; #pragma unroll
;                 for (int m = 0; m < 4; ++m)
; #pragma unroll
;                     for (int n = 0; n < 2; ++n) acc[a][b][m][n] = (f32x4){0.f, 0.f, 0.f, 0.f};
;         cur = nxt; cA = nA; cB = nB; ++ui;
;     }
	v_mul_f32_e32 v41, 0xbfb8aa3b, v41
	v_exp_f32_e32 v36, v36
	v_exp_f32_e32 v42, v41
	v_pk_mul_f32 v[32:33], v[32:33], v[40:41] op_sel_hi:[1,0]
	v_pk_mul_f32 v[30:31], v[30:31], v[34:35]
	v_pk_mul_f32 v[28:29], v[28:29], v[32:33]
	v_pk_add_f32 v[32:33], v[36:37], 1.0 op_sel_hi:[1,0]
	v_pk_add_f32 v[36:37], v[42:43], 1.0 op_sel_hi:[1,0]
	v_mov_b32_e32 v40, v33
	v_mov_b32_e32 v41, v37
	v_mov_b32_e32 v42, v32
	v_mov_b32_e32 v43, v36
	v_pk_mul_f32 v[40:41], v[40:41], v[42:43]
	v_pk_mul_f32 v[22:23], v[30:31], v[22:23]
	v_mul_f32_e32 v42, v40, v41
	v_rcp_f32_e32 v42, v42
	v_pk_mul_f32 v[20:21], v[28:29], v[20:21]
	v_mul_f32_e32 v28, v41, v42
	v_mul_f32_e32 v30, v40, v42
	v_pk_mul_f32 v[30:31], v[36:37], v[30:31] op_sel_hi:[1,0]
	v_pk_mul_f32 v[28:29], v[32:33], v[28:29] op_sel_hi:[1,0]
	v_pk_mul_f32 v[26:27], v[26:27], v[30:31]
	v_pk_mul_f32 v[24:25], v[24:25], v[28:29]
	v_pk_mul_f32 v[26:27], v[26:27], v[18:19]
	v_pk_mul_f32 v[18:19], v[24:25], v[16:17]
	v_cvt_pk_bf16_f32 v16, v20, v21
	v_cvt_pk_bf16_f32 v17, v22, v23
	v_max_f32_e32 v20, v12, v12
	v_max_f32_e32 v22, v14, v14
	v_max_f32_e32 v20, 0xc1a00000, v20
	v_max_f32_e32 v22, 0xc1a00000, v22
	v_mul_f32_e32 v20, 0xbfb8aa3b, v20
	v_mul_f32_e32 v22, 0xbfb8aa3b, v22
	v_exp_f32_e32 v21, v20
	v_max_f32_e32 v20, v13, v13
	v_exp_f32_e32 v23, v22
	v_max_f32_e32 v22, v15, v15
	v_max_f32_e32 v20, 0xc1a00000, v20
	v_max_f32_e32 v22, 0xc1a00000, v22
	v_mul_f32_e32 v20, 0xbfb8aa3b, v20
	v_mul_f32_e32 v22, 0xbfb8aa3b, v22
	v_exp_f32_e32 v20, v20
	v_exp_f32_e32 v22, v22
	v_cvt_pk_bf16_f32 v18, v18, v19
	v_cvt_pk_bf16_f32 v19, v26, v27
	global_store_dwordx4 v[38:39], v[16:19], off
	v_add_u32_e32 v24, 0xb0, v154
	s_nop 0
	v_pk_add_f32 v[16:17], v[20:21], 1.0 op_sel_hi:[1,0]
	v_pk_add_f32 v[18:19], v[22:23], 1.0 op_sel_hi:[1,0]
	v_mov_b32_e32 v20, v17
	v_mov_b32_e32 v21, v19
	v_mov_b32_e32 v22, v16
	v_mov_b32_e32 v23, v18
	v_pk_mul_f32 v[20:21], v[20:21], v[22:23]
	s_nop 0
	v_mul_f32_e32 v22, v20, v21
	v_rcp_f32_e32 v25, v22
	v_mad_i64_i32 v[22:23], s[16:17], v24, s40, v[144:145]
	v_lshl_add_u64 v[22:23], v[22:23], 0, v[146:147]
	v_mul_f32_e32 v20, v20, v25
	v_mul_f32_e32 v24, v21, v25
	v_pk_mul_f32 v[18:19], v[18:19], v[20:21] op_sel_hi:[1,0]
	v_max_f32_e32 v20, v8, v8
	v_max_f32_e32 v25, v10, v10
	v_max_f32_e32 v20, 0xc1a00000, v20
	v_max_f32_e32 v25, 0xc1a00000, v25
	v_mul_f32_e32 v20, 0xbfb8aa3b, v20
	v_mul_f32_e32 v25, 0xbfb8aa3b, v25
	v_exp_f32_e32 v21, v20
	v_max_f32_e32 v20, v9, v9
	v_exp_f32_e32 v27, v25
	v_max_f32_e32 v25, v11, v11
	v_max_f32_e32 v20, 0xc1a00000, v20
	v_max_f32_e32 v25, 0xc1a00000, v25
	v_mul_f32_e32 v20, 0xbfb8aa3b, v20
	v_mul_f32_e32 v25, 0xbfb8aa3b, v25
	v_exp_f32_e32 v20, v20
	v_exp_f32_e32 v26, v25
	v_pk_mul_f32 v[16:17], v[16:17], v[24:25] op_sel_hi:[1,0]
	v_pk_mul_f32 v[14:15], v[14:15], v[18:19]
	v_pk_mul_f32 v[12:13], v[12:13], v[16:17]
	v_pk_add_f32 v[16:17], v[20:21], 1.0 op_sel_hi:[1,0]
	v_pk_add_f32 v[20:21], v[26:27], 1.0 op_sel_hi:[1,0]
	v_mov_b32_e32 v24, v17
	v_mov_b32_e32 v25, v21
	v_mov_b32_e32 v26, v16
	v_mov_b32_e32 v27, v20
	v_pk_mul_f32 v[24:25], v[24:25], v[26:27]
	v_pk_mul_f32 v[6:7], v[14:15], v[6:7]
	v_mul_f32_e32 v26, v24, v25
	v_rcp_f32_e32 v26, v26
	v_pk_mul_f32 v[4:5], v[12:13], v[4:5]
	s_mov_b64 s[16:17], s[10:11]
	v_mul_f32_e32 v12, v25, v26
	v_mul_f32_e32 v14, v24, v26
	v_pk_mul_f32 v[14:15], v[20:21], v[14:15] op_sel_hi:[1,0]
	v_pk_mul_f32 v[12:13], v[16:17], v[12:13] op_sel_hi:[1,0]
	v_pk_mul_f32 v[10:11], v[10:11], v[14:15]
	v_pk_mul_f32 v[8:9], v[8:9], v[12:13]
	v_pk_mul_f32 v[10:11], v[10:11], v[2:3]
	v_pk_mul_f32 v[2:3], v[8:9], v[0:1]
	v_cvt_pk_bf16_f32 v0, v4, v5
	v_cvt_pk_bf16_f32 v1, v6, v7
	s_nop 0
	v_cvt_pk_bf16_f32 v2, v2, v3
	v_cvt_pk_bf16_f32 v3, v10, v11
	global_store_dwordx4 v[22:23], v[0:3], off
	s_cbranch_vccz .LBB0_1199
	s_waitcnt vmcnt(0)
	s_cmpk_gt_u32 s23, 0xff
	s_cbranch_scc1 .LBB0_1206
	s_barrier

; #define PG8_STAGE(bufoff, gbase, voff) do { _Pragma("unroll") for (int _i = 0; _i < 2; ++_i) \
;         __builtin_amdgcn_global_load_lds((const unsigned*)((const char*)(gbase) + (voff)[_i]), (PG8_LAS unsigned*)(lds + (bufoff) + ldsw + _i * 8192), 16, 0, 0); } while (0)
; #define PG8_LDA(dst, b, h) do { _Pragma("unroll") for (int m = 0; m < 4; ++m) _Pragma("unroll") for (int k = 0; k < 2; ++k) dst[m][k] = *(const PG8_LAS bf16x8*)(lds + PG8_SA(b, h) + aoff + m * 2048 + k * 1024); } while (0)
; #define PG8_LDB(dst, b, h) do { _Pragma("unroll") for (int n = 0; n < 2; ++n) _Pragma("unroll") for (int k = 0; k < 2; ++k) dst[n][k] = *(const PG8_LAS bf16x8*)(lds + PG8_SB(b, h) + boff + n * 2048 + k * 1024); } while (0)
; #define PG8_MMA(ai, bj, At, Bt) do { __builtin_amdgcn_s_setprio(1); _Pragma("unroll") for (int m = 0; m < 4; ++m) _Pragma("unroll") for (int n = 0; n < 2; ++n) _Pragma("unroll") for (int k = 0; k < 2; ++k) \
;         acc[ai][bj][m][n] = __builtin_amdgcn_mfma_f32_16x16x32_bf16(Bt[n][k], At[m][k], acc[ai][bj][m][n], 0, 0, 0); __builtin_amdgcn_s_setprio(0); } while (0)
; #define PG8_WAIT_V(n) asm volatile("s_waitcnt vmcnt(" #n ")" ::: "memory")
; #define PG8_WAIT_L(n) asm volatile("s_waitcnt lgkmcnt(" #n ")" ::: "memory")
; #define PG8_BAR __builtin_amdgcn_s_barrier()
; #define PG8_SCHED __builtin_amdgcn_sched_barrier(0)
; template <class Epi, class Sched>
; __device__ __forceinline__ void gemm_phase(PG8_LAS unsigned char* lds, const Gemm g, const Sched& S, const Epi& E) {
;     ...
;             PG8_LDB(B0, 0, 0); PG8_SCHED; PG8_LDA(At, 0, 0); PG8_STAGE(PG8_SA(1, 1), a1 + hstep, voffA);
;             PG8_WAIT_L(8); PG8_BAR; PG8_WAIT_L(0); PG8_MMA(0, 0, At, B0); PG8_BAR; PG8_SCHED;
;             PG8_LDB(B1, 0, 1); PG8_STAGE(PG8_SB(0, 0), b2, voffB);
;             PG8_BAR; PG8_WAIT_L(0); PG8_MMA(0, 1, At, B1); PG8_BAR;
;             PG8_LDA(At, 0, 1); PG8_STAGE(PG8_SA(0, 0), a2, voffA);
;             PG8_BAR; PG8_WAIT_L(0); PG8_MMA(1, 0, At, B0); PG8_BAR; PG8_SCHED;
;             PG8_STAGE(PG8_SB(0, 1), b2 + hstep, voffB);
;             PG8_WAIT_V(6); PG8_BAR; PG8_MMA(1, 1, At, B1); PG8_BAR;
.LBB0_1278:
	ds_read_b128 v[152:155], v149
	ds_read_b128 v[156:159], v149 offset:1024
	ds_read_b128 v[160:163], v149 offset:2048
	ds_read_b128 v[164:167], v149 offset:3072
	s_add_u32 s20, s18, 0x100
	s_addc_u32 s21, s19, 0
	s_cmp_eq_u32 s54, 40
	s_cselect_b32 s25, s1, s21
	s_cselect_b32 s24, s0, s20
	s_cselect_b32 s23, s5, s53
	s_cselect_b32 s22, s4, s52
	v_lshl_add_u64 v[144:145], s[18:19], 0, v[136:137]
	s_add_i32 m0, s34, 0xc000
	ds_read_b128 v[168:171], v150
	ds_read_b128 v[172:175], v150 offset:1024
	ds_read_b128 v[182:185], v150 offset:2048
	ds_read_b128 v[190:193], v150 offset:3072
	ds_read_b128 v[194:197], v150 offset:4096
	ds_read_b128 v[198:201], v150 offset:5120
	ds_read_b128 v[202:205], v150 offset:6144
	ds_read_b128 v[206:209], v150 offset:7168
	global_load_lds_dwordx4 v[144:145], off
	v_lshl_add_u64 v[144:145], s[18:19], 0, v[138:139]
	s_add_i32 m0, s34, 0xe000
	s_nop 0
	global_load_lds_dwordx4 v[144:145], off
	s_waitcnt lgkmcnt(8)
	s_barrier
	s_waitcnt lgkmcnt(0)
	s_waitcnt lgkmcnt(0)
	v_mfma_f32_16x16x32_bf16 v[124:127], v[152:155], v[168:171], v[124:127]
	v_mfma_f32_16x16x32_bf16 v[120:123], v[160:163], v[168:171], v[120:123]
	v_mfma_f32_16x16x32_bf16 v[108:111], v[152:155], v[182:185], v[108:111]
	v_mfma_f32_16x16x32_bf16 v[104:107], v[160:163], v[182:185], v[104:107]
	v_mfma_f32_16x16x32_bf16 v[92:95], v[152:155], v[194:197], v[92:95]
	v_mfma_f32_16x16x32_bf16 v[88:91], v[160:163], v[194:197], v[88:91]
	v_mfma_f32_16x16x32_bf16 v[76:79], v[152:155], v[202:205], v[76:79]
	v_mfma_f32_16x16x32_bf16 v[72:75], v[160:163], v[202:205], v[72:75]
	v_mfma_f32_16x16x32_bf16 v[124:127], v[156:159], v[172:175], v[124:127]
	v_mfma_f32_16x16x32_bf16 v[120:123], v[164:167], v[172:175], v[120:123]
	v_mfma_f32_16x16x32_bf16 v[108:111], v[156:159], v[190:193], v[108:111]
	v_mfma_f32_16x16x32_bf16 v[104:107], v[164:167], v[190:193], v[104:107]
	v_mfma_f32_16x16x32_bf16 v[92:95], v[156:159], v[198:201], v[92:95]
	v_mfma_f32_16x16x32_bf16 v[88:91], v[164:167], v[198:201], v[88:91]
	v_mfma_f32_16x16x32_bf16 v[76:79], v[156:159], v[206:209], v[76:79]
	v_mfma_f32_16x16x32_bf16 v[72:75], v[164:167], v[206:209], v[72:75]
	s_barrier
	s_add_i32 s18, s42, s31
	v_lshl_add_u64 v[144:145], s[22:23], 0, v[130:131]
	s_mov_b32 m0, s18
	ds_read_b128 v[210:213], v151
	ds_read_b128 v[214:217], v151 offset:1024
	ds_read_b128 v[218:221], v151 offset:2048
	ds_read_b128 v[222:225], v151 offset:3072
	global_load_lds_dwordx4 v[144:145], off
	v_lshl_add_u64 v[186:187], s[22:23], 0, v[134:135]
	s_add_i32 m0, s18, 0x2000
	s_nop 0
	global_load_lds_dwordx4 v[186:187], off
	s_barrier
	s_waitcnt lgkmcnt(0)
	s_waitcnt lgkmcnt(0)
	v_mfma_f32_16x16x32_bf16 v[116:119], v[210:213], v[168:171], v[116:119]
	v_mfma_f32_16x16x32_bf16 v[112:115], v[218:221], v[168:171], v[112:115]
	v_mfma_f32_16x16x32_bf16 v[100:103], v[210:213], v[182:185], v[100:103]
	v_mfma_f32_16x16x32_bf16 v[96:99], v[218:221], v[182:185], v[96:99]
	v_mfma_f32_16x16x32_bf16 v[84:87], v[210:213], v[194:197], v[84:87]
	v_mfma_f32_16x16x32_bf16 v[80:83], v[218:221], v[194:197], v[80:83]
	v_mfma_f32_16x16x32_bf16 v[68:71], v[210:213], v[202:205], v[68:71]
	v_mfma_f32_16x16x32_bf16 v[64:67], v[218:221], v[202:205], v[64:67]
	v_mfma_f32_16x16x32_bf16 v[116:119], v[214:217], v[172:175], v[116:119]
	v_mfma_f32_16x16x32_bf16 v[112:115], v[222:225], v[172:175], v[112:115]
	v_mfma_f32_16x16x32_bf16 v[100:103], v[214:217], v[190:193], v[100:103]
	v_mfma_f32_16x16x32_bf16 v[96:99], v[222:225], v[190:193], v[96:99]
	v_mfma_f32_16x16x32_bf16 v[84:87], v[214:217], v[198:201], v[84:87]
	v_mfma_f32_16x16x32_bf16 v[80:83], v[222:225], v[198:201], v[80:83]
	v_mfma_f32_16x16x32_bf16 v[68:71], v[214:217], v[206:209], v[68:71]
	v_mfma_f32_16x16x32_bf16 v[64:67], v[222:225], v[206:209], v[64:67]
	s_mov_b32 m0, s34
	v_lshl_add_u64 v[226:227], s[24:25], 0, v[128:129]
	s_barrier
	ds_read_b128 v[168:171], v150 offset:16384
	ds_read_b128 v[172:175], v150 offset:17408
	ds_read_b128 v[182:185], v150 offset:18432
	ds_read_b128 v[190:193], v150 offset:19456
	ds_read_b128 v[194:197], v150 offset:20480
	ds_read_b128 v[198:201], v150 offset:21504
	ds_read_b128 v[202:205], v150 offset:22528
	ds_read_b128 v[206:209], v150 offset:23552
	global_load_lds_dwordx4 v[226:227], off
	v_lshl_add_u64 v[228:229], s[24:25], 0, v[132:133]
	s_mov_b32 m0, s35
	s_nop 0
	global_load_lds_dwordx4 v[228:229], off
	s_barrier
	s_waitcnt lgkmcnt(0)
	s_waitcnt lgkmcnt(0)
	v_mfma_f32_16x16x32_bf16 v[60:63], v[152:155], v[168:171], v[60:63]
	v_mfma_f32_16x16x32_bf16 v[56:59], v[160:163], v[168:171], v[56:59]
	v_mfma_f32_16x16x32_bf16 v[48:51], v[152:155], v[182:185], v[48:51]
	v_mfma_f32_16x16x32_bf16 v[40:43], v[160:163], v[182:185], v[40:43]
	v_mfma_f32_16x16x32_bf16 v[32:35], v[152:155], v[194:197], v[32:35]
	v_mfma_f32_16x16x32_bf16 v[24:27], v[160:163], v[194:197], v[24:27]
	v_mfma_f32_16x16x32_bf16 v[16:19], v[152:155], v[202:205], v[16:19]
	v_mfma_f32_16x16x32_bf16 v[8:11], v[160:163], v[202:205], v[8:11]
	v_mfma_f32_16x16x32_bf16 v[60:63], v[156:159], v[172:175], v[60:63]
	v_mfma_f32_16x16x32_bf16 v[56:59], v[164:167], v[172:175], v[56:59]
	v_mfma_f32_16x16x32_bf16 v[48:51], v[156:159], v[190:193], v[48:51]
	v_mfma_f32_16x16x32_bf16 v[40:43], v[164:167], v[190:193], v[40:43]
	v_mfma_f32_16x16x32_bf16 v[32:35], v[156:159], v[198:201], v[32:35]
	v_mfma_f32_16x16x32_bf16 v[24:27], v[164:167], v[198:201], v[24:27]
	v_mfma_f32_16x16x32_bf16 v[16:19], v[156:159], v[206:209], v[16:19]
	v_mfma_f32_16x16x32_bf16 v[8:11], v[164:167], v[206:209], v[8:11]
	s_barrier
; #define PG8_STAGE(bufoff, gbase, voff) do { _Pragma("unroll") for (int _i = 0; _i < 2; ++_i) \
;         __builtin_amdgcn_global_load_lds((const unsigned*)((const char*)(gbase) + (voff)[_i]), (PG8_LAS unsigned*)(lds + (bufoff) + ldsw + _i * 8192), 16, 0, 0); } while (0)
; #define PG8_LDA(dst, b, h) do { _Pragma("unroll") for (int m = 0; m < 4; ++m) _Pragma("unroll") for (int k = 0; k < 2; ++k) dst[m][k] = *(const PG8_LAS bf16x8*)(lds + PG8_SA(b, h) + aoff + m * 2048 + k * 1024); } while (0)
; #define PG8_LDB(dst, b, h) do { _Pragma("unroll") for (int n = 0; n < 2; ++n) _Pragma("unroll") for (int k = 0; k < 2; ++k) dst[n][k] = *(const PG8_LAS bf16x8*)(lds + PG8_SB(b, h) + boff + n * 2048 + k * 1024); } while (0)
; #define PG8_MMA(ai, bj, At, Bt) do { __builtin_amdgcn_s_setprio(1); _Pragma("unroll") for (int m = 0; m < 4; ++m) _Pragma("unroll") for (int n = 0; n < 2; ++n) _Pragma("unroll") for (int k = 0; k < 2; ++k) \
;         acc[ai][bj][m][n] = __builtin_amdgcn_mfma_f32_16x16x32_bf16(Bt[n][k], At[m][k], acc[ai][bj][m][n], 0, 0, 0); __builtin_amdgcn_s_setprio(0); } while (0)
; #define PG8_WAIT_V(n) asm volatile("s_waitcnt vmcnt(" #n ")" ::: "memory")
; #define PG8_WAIT_L(n) asm volatile("s_waitcnt lgkmcnt(" #n ")" ::: "memory")
; #define PG8_BAR __builtin_amdgcn_s_barrier()
; #define PG8_SCHED __builtin_amdgcn_sched_barrier(0)
; template <class Epi, class Sched>
; __device__ __forceinline__ void gemm_phase(PG8_LAS unsigned char* lds, const Gemm g, const Sched& S, const Epi& E) {
;     ...
;             PG8_WAIT_V(6); PG8_BAR; PG8_MMA(1, 1, At, B1); PG8_BAR;
;             PG8_LDB(B0, 1, 0); PG8_SCHED; PG8_LDA(At, 1, 0); PG8_STAGE(PG8_SA(0, 1), a2 + hstep, voffA);
;             PG8_WAIT_L(8); PG8_BAR; PG8_WAIT_L(0); PG8_MMA(0, 0, At, B0); PG8_BAR; PG8_SCHED;
;             PG8_LDB(B1, 1, 1); PG8_STAGE(PG8_SB(1, 0), b3, voffB);
;             PG8_BAR; PG8_WAIT_L(0); PG8_MMA(0, 1, At, B1); PG8_BAR;
;             PG8_LDA(At, 1, 1); PG8_STAGE(PG8_SA(1, 0), a3, voffA);
;             PG8_BAR; PG8_WAIT_L(0); PG8_MMA(1, 0, At, B0); PG8_BAR; PG8_SCHED;
	s_add_u32 s18, s22, 0xb0000
	s_addc_u32 s19, s23, 0
	s_add_i32 s55, s43, s31
	v_lshl_add_u64 v[152:153], s[18:19], 0, v[130:131]
	s_mov_b32 m0, s55
	s_nop 0
	global_load_lds_dwordx4 v[152:153], off
	v_lshl_add_u64 v[152:153], s[18:19], 0, v[134:135]
	s_add_i32 m0, s55, 0x2000
	s_nop 0
	global_load_lds_dwordx4 v[152:153], off
	s_waitcnt vmcnt(6)
	s_barrier
	v_mfma_f32_16x16x32_bf16 v[52:55], v[210:213], v[168:171], v[52:55]
	v_mfma_f32_16x16x32_bf16 v[44:47], v[218:221], v[168:171], v[44:47]
	v_mfma_f32_16x16x32_bf16 v[36:39], v[210:213], v[182:185], v[36:39]
	v_mfma_f32_16x16x32_bf16 v[28:31], v[218:221], v[182:185], v[28:31]
	v_mfma_f32_16x16x32_bf16 v[20:23], v[210:213], v[194:197], v[20:23]
	v_mfma_f32_16x16x32_bf16 v[12:15], v[218:221], v[194:197], v[12:15]
	v_mfma_f32_16x16x32_bf16 v[4:7], v[210:213], v[202:205], v[4:7]
	v_mfma_f32_16x16x32_bf16 v[0:3], v[218:221], v[202:205], v[0:3]
	v_mfma_f32_16x16x32_bf16 v[52:55], v[214:217], v[172:175], v[52:55]
	v_mfma_f32_16x16x32_bf16 v[44:47], v[222:225], v[172:175], v[44:47]
	v_mfma_f32_16x16x32_bf16 v[36:39], v[214:217], v[190:193], v[36:39]
	v_mfma_f32_16x16x32_bf16 v[28:31], v[222:225], v[190:193], v[28:31]
	v_mfma_f32_16x16x32_bf16 v[20:23], v[214:217], v[198:201], v[20:23]
	v_mfma_f32_16x16x32_bf16 v[12:15], v[222:225], v[198:201], v[12:15]
	v_mfma_f32_16x16x32_bf16 v[4:7], v[214:217], v[206:209], v[4:7]
	v_mfma_f32_16x16x32_bf16 v[0:3], v[222:225], v[206:209], v[0:3]
	s_add_i32 s55, 0, 0x18000
	v_add_u32_e32 v164, s55, v147
	s_barrier
	ds_read_b128 v[152:155], v164
	ds_read_b128 v[156:159], v164 offset:1024
	ds_read_b128 v[160:163], v164 offset:2048
	ds_read_b128 v[164:167], v164 offset:3072
	s_add_u32 s18, s24, 0xb0000
	s_addc_u32 s19, s25, 0
	s_mov_b32 m0, s36
	v_lshl_add_u64 v[210:211], s[18:19], 0, v[128:129]
	ds_read_b128 v[168:171], v150 offset:32768
	ds_read_b128 v[172:175], v150 offset:33792
	ds_read_b128 v[182:185], v150 offset:34816
	ds_read_b128 v[190:193], v150 offset:35840
	ds_read_b128 v[194:197], v150 offset:36864
	ds_read_b128 v[198:201], v150 offset:37888
	ds_read_b128 v[202:205], v150 offset:38912
	ds_read_b128 v[206:209], v150 offset:39936
	global_load_lds_dwordx4 v[210:211], off
	v_lshl_add_u64 v[210:211], s[18:19], 0, v[132:133]
	s_mov_b32 m0, s37
	s_nop 0
	global_load_lds_dwordx4 v[210:211], off
	s_waitcnt lgkmcnt(8)
	s_barrier
	s_waitcnt lgkmcnt(0)
	s_waitcnt lgkmcnt(0)
	v_mfma_f32_16x16x32_bf16 v[124:127], v[152:155], v[168:171], v[124:127]
	v_mfma_f32_16x16x32_bf16 v[120:123], v[160:163], v[168:171], v[120:123]
	v_mfma_f32_16x16x32_bf16 v[108:111], v[152:155], v[182:185], v[108:111]
	v_mfma_f32_16x16x32_bf16 v[104:107], v[160:163], v[182:185], v[104:107]
	v_mfma_f32_16x16x32_bf16 v[92:95], v[152:155], v[194:197], v[92:95]
	v_mfma_f32_16x16x32_bf16 v[88:91], v[160:163], v[194:197], v[88:91]
	v_mfma_f32_16x16x32_bf16 v[76:79], v[152:155], v[202:205], v[76:79]
	v_mfma_f32_16x16x32_bf16 v[72:75], v[160:163], v[202:205], v[72:75]
	v_mfma_f32_16x16x32_bf16 v[124:127], v[156:159], v[172:175], v[124:127]
	v_mfma_f32_16x16x32_bf16 v[120:123], v[164:167], v[172:175], v[120:123]
	v_mfma_f32_16x16x32_bf16 v[108:111], v[156:159], v[190:193], v[108:111]
	v_mfma_f32_16x16x32_bf16 v[104:107], v[164:167], v[190:193], v[104:107]
	v_mfma_f32_16x16x32_bf16 v[92:95], v[156:159], v[198:201], v[92:95]
	v_mfma_f32_16x16x32_bf16 v[88:91], v[164:167], v[198:201], v[88:91]
	v_mfma_f32_16x16x32_bf16 v[76:79], v[156:159], v[206:209], v[76:79]
	v_mfma_f32_16x16x32_bf16 v[72:75], v[164:167], v[206:209], v[72:75]
	s_barrier
	s_add_i32 s24, 0, 0x1c000
	s_add_i32 s18, s55, s31
	v_add_u32_e32 v179, s24, v147
	v_lshl_add_u64 v[144:145], v[144:145], 0, s[8:9]
	s_mov_b32 m0, s18
	ds_read_b128 v[210:213], v179
	ds_read_b128 v[214:217], v179 offset:1024
	ds_read_b128 v[218:221], v179 offset:2048
	ds_read_b128 v[222:225], v179 offset:3072
	global_load_lds_dwordx4 v[144:145], off
	v_lshl_add_u64 v[144:145], v[186:187], 0, s[8:9]
	s_add_i32 m0, s18, 0x2000
	s_nop 0
	global_load_lds_dwordx4 v[144:145], off
	s_barrier
	s_waitcnt lgkmcnt(0)
	s_waitcnt lgkmcnt(0)
	v_mfma_f32_16x16x32_bf16 v[116:119], v[210:213], v[168:171], v[116:119]
	v_mfma_f32_16x16x32_bf16 v[112:115], v[218:221], v[168:171], v[112:115]
	v_mfma_f32_16x16x32_bf16 v[100:103], v[210:213], v[182:185], v[100:103]
	v_mfma_f32_16x16x32_bf16 v[96:99], v[218:221], v[182:185], v[96:99]
	v_mfma_f32_16x16x32_bf16 v[84:87], v[210:213], v[194:197], v[84:87]
	v_mfma_f32_16x16x32_bf16 v[80:83], v[218:221], v[194:197], v[80:83]
	v_mfma_f32_16x16x32_bf16 v[68:71], v[210:213], v[202:205], v[68:71]
	v_mfma_f32_16x16x32_bf16 v[64:67], v[218:221], v[202:205], v[64:67]
	v_mfma_f32_16x16x32_bf16 v[116:119], v[214:217], v[172:175], v[116:119]
	v_mfma_f32_16x16x32_bf16 v[112:115], v[222:225], v[172:175], v[112:115]
	v_mfma_f32_16x16x32_bf16 v[100:103], v[214:217], v[190:193], v[100:103]
	v_mfma_f32_16x16x32_bf16 v[96:99], v[222:225], v[190:193], v[96:99]
	v_mfma_f32_16x16x32_bf16 v[84:87], v[214:217], v[198:201], v[84:87]
	v_mfma_f32_16x16x32_bf16 v[80:83], v[222:225], v[198:201], v[80:83]
	v_mfma_f32_16x16x32_bf16 v[68:71], v[214:217], v[206:209], v[68:71]
	v_mfma_f32_16x16x32_bf16 v[64:67], v[222:225], v[206:209], v[64:67]
	s_mov_b32 m0, s39
	v_lshl_add_u64 v[144:145], v[226:227], 0, s[8:9]
	s_barrier
	ds_read_b128 v[168:171], v150 offset:49152
	ds_read_b128 v[172:175], v150 offset:50176
	ds_read_b128 v[182:185], v150 offset:51200
	ds_read_b128 v[190:193], v150 offset:52224
	ds_read_b128 v[194:197], v150 offset:53248
	ds_read_b128 v[198:201], v150 offset:54272
	ds_read_b128 v[202:205], v150 offset:55296
	ds_read_b128 v[206:209], v150 offset:56320
	global_load_lds_dwordx4 v[144:145], off
	v_lshl_add_u64 v[144:145], v[228:229], 0, s[8:9]
	s_mov_b32 m0, s40
	s_nop 0
	global_load_lds_dwordx4 v[144:145], off
	s_barrier
; __device__ __forceinline__ unsigned cvt_pk_bf16(float lo, float hi) { unsigned r; asm volatile("v_cvt_pk_bf16_f32 %0, %1, %2" : "=v"(r) : "v"(lo), "v"(hi)); return r; }
; __device__ __forceinline__ float flogsig16(float x) { return (fminf(x, 0.f) - __logf(1.0f + __expf(-fabsf(x)))) * 0.0625f; }
; #define PG8_WAIT_V(n) asm volatile("s_waitcnt vmcnt(" #n ")" ::: "memory")
; #define PG8_WAIT_L(n) asm volatile("s_waitcnt lgkmcnt(" #n ")" ::: "memory")
;     __device__ __forceinline__ void operator()(const f32x4 (&acc)[2][2][4][2], const Unit& u, int wr, int wc, int fr, int fq) const {
;     ...
;         const int row0 = u.pm * BM + wr * 64 + fr, col0 = u.pn * BM + wc * 32 + 8 * fq, bcol0 = wc * 32 + 8 * fq;
;         f32x4 bv[2][2];
; #pragma unroll
;         for (int bj = 0; bj < 2; ++bj)
; #pragma unroll
;             for (int n = 0; n < 2; ++n) bv[bj][n] = bias ? *(const f32x4*)(bias + bcol0 + bj * HALF + 4 * n) : (f32x4){0.f, 0.f, 0.f, 0.f};
; #pragma unroll
;         for (int ai = 0; ai < 2; ++ai)
; #pragma unroll
;             for (int m = 0; m < 4; ++m) { bf16_t* rowp = O + (size_t)(row0 + ai * HALF + m * 16) * ldc + col0;
; #pragma unroll
;                 for (int bj = 0; bj < 2; ++bj) { f32x4 v0 = acc[ai][bj][m][0] + bv[bj][0], v1 = acc[ai][bj][m][1] + bv[bj][1];
;                     if (act == 1) {
; #pragma unroll
;                         for (int j = 0; j < 1; ++j) { v0 = v0 * sigmoid4(v0); v1 = v1 * sigmoid4(v1); } }
;                     else if (act == 2) {
; #pragma unroll
;                         for (int j = 0; j < 1; ++j) { v0 = sigmoid4(v0); v1 = sigmoid4(v1); } }
;                     else if (act == 3) {
; #pragma unroll
;                         for (int j = 0; j < 4; ++j) { v0[j] = flogsig16(v0[j]); v1[j] = flogsig16(v1[j]); } }
;                     u32x4 w; w.x = cvt_pk_bf16(v0[0], v0[1]); w.y = cvt_pk_bf16(v0[2], v0[3]); w.z = cvt_pk_bf16(v1[0], v1[1]); w.w = cvt_pk_bf16(v1[2], v1[3]);
;                     *(u32x4*)(rowp + bj * HALF) = w; } }
; template <class Epi, class Sched>
; __device__ __forceinline__ void gemm_phase(PG8_LAS unsigned char* lds, const Gemm g, const Sched& S, const Epi& E) {
;     ...
;             PG8_BAR; PG8_WAIT_L(0); PG8_MMA(1, 0, At, B0); PG8_BAR; PG8_SCHED;
;             PG8_STAGE(PG8_SB(1, 1), b3 + hstep, voffB);
;             PG8_WAIT_V(6); PG8_BAR; PG8_MMA(1, 1, At, B1); PG8_BAR;
	s_waitcnt lgkmcnt(0)
	s_waitcnt lgkmcnt(0)
	v_mfma_f32_16x16x32_bf16 v[60:63], v[152:155], v[168:171], v[60:63]
	v_mfma_f32_16x16x32_bf16 v[56:59], v[160:163], v[168:171], v[56:59]
	v_mfma_f32_16x16x32_bf16 v[48:51], v[152:155], v[182:185], v[48:51]
	v_mfma_f32_16x16x32_bf16 v[40:43], v[160:163], v[182:185], v[40:43]
	v_mfma_f32_16x16x32_bf16 v[32:35], v[152:155], v[194:197], v[32:35]
	v_mfma_f32_16x16x32_bf16 v[24:27], v[160:163], v[194:197], v[24:27]
	v_mfma_f32_16x16x32_bf16 v[16:19], v[152:155], v[202:205], v[16:19]
	v_mfma_f32_16x16x32_bf16 v[8:11], v[160:163], v[202:205], v[8:11]
	v_mfma_f32_16x16x32_bf16 v[60:63], v[156:159], v[172:175], v[60:63]
	v_mfma_f32_16x16x32_bf16 v[56:59], v[164:167], v[172:175], v[56:59]
	v_mfma_f32_16x16x32_bf16 v[48:51], v[156:159], v[190:193], v[48:51]
	v_mfma_f32_16x16x32_bf16 v[40:43], v[164:167], v[190:193], v[40:43]
	v_mfma_f32_16x16x32_bf16 v[32:35], v[156:159], v[198:201], v[32:35]
	v_mfma_f32_16x16x32_bf16 v[24:27], v[164:167], v[198:201], v[24:27]
	v_mfma_f32_16x16x32_bf16 v[16:19], v[156:159], v[206:209], v[16:19]
	v_mfma_f32_16x16x32_bf16 v[8:11], v[164:167], v[206:209], v[8:11]
	s_barrier
	s_add_u32 s18, s22, 0xb0080
	s_addc_u32 s19, s23, 0
	s_add_i32 s22, s24, s31
	v_lshl_add_u64 v[144:145], s[18:19], 0, v[130:131]
	s_mov_b32 m0, s22
	s_nop 0
	global_load_lds_dwordx4 v[144:145], off
	v_lshl_add_u64 v[144:145], s[18:19], 0, v[134:135]
	s_add_i32 m0, s22, 0x2000
	s_nop 0
	global_load_lds_dwordx4 v[144:145], off
	s_waitcnt vmcnt(6)
	s_barrier
	v_mfma_f32_16x16x32_bf16 v[52:55], v[210:213], v[168:171], v[52:55]
	v_mfma_f32_16x16x32_bf16 v[44:47], v[218:221], v[168:171], v[44:47]
	v_mfma_f32_16x16x32_bf16 v[36:39], v[210:213], v[182:185], v[36:39]
	v_mfma_f32_16x16x32_bf16 v[28:31], v[218:221], v[182:185], v[28:31]
	v_mfma_f32_16x16x32_bf16 v[20:23], v[210:213], v[194:197], v[20:23]
	v_mfma_f32_16x16x32_bf16 v[12:15], v[218:221], v[194:197], v[12:15]
	v_mfma_f32_16x16x32_bf16 v[4:7], v[210:213], v[202:205], v[4:7]
	v_mfma_f32_16x16x32_bf16 v[0:3], v[218:221], v[202:205], v[0:3]
	v_mfma_f32_16x16x32_bf16 v[52:55], v[214:217], v[172:175], v[52:55]
	v_mfma_f32_16x16x32_bf16 v[44:47], v[222:225], v[172:175], v[44:47]
	v_mfma_f32_16x16x32_bf16 v[36:39], v[214:217], v[190:193], v[36:39]
	v_mfma_f32_16x16x32_bf16 v[28:31], v[222:225], v[190:193], v[28:31]
	v_mfma_f32_16x16x32_bf16 v[20:23], v[214:217], v[198:201], v[20:23]
	v_mfma_f32_16x16x32_bf16 v[12:15], v[222:225], v[198:201], v[12:15]
	v_mfma_f32_16x16x32_bf16 v[4:7], v[214:217], v[206:209], v[4:7]
	v_mfma_f32_16x16x32_bf16 v[0:3], v[222:225], v[206:209], v[0:3]
	s_add_i32 s54, s54, 2
	s_add_u32 s52, s52, 0x100
	s_addc_u32 s53, s53, 0
	s_cmp_gt_u32 s54, 41
	s_mov_b64 s[18:19], s[20:21]
	s_barrier
	s_cbranch_scc0 .LBB0_1278
	v_lshl_add_u32 v152, s50, 8, v146
	v_lshl_or_b32 v144, s51, 8, v148
	v_ashrrev_i32_e32 v153, 31, v152
	v_ashrrev_i32_e32 v145, 31, v144
	v_lshlrev_b64 v[154:155], 11, v[152:153]
	v_lshl_add_u64 v[154:155], s[6:7], 0, v[154:155]
	v_lshlrev_b64 v[156:157], 1, v[144:145]
	v_lshl_add_u64 v[144:145], v[154:155], 0, v[156:157]
	v_pk_add_f32 v[126:127], v[126:127], 0 op_sel_hi:[1,0]
	v_pk_add_f32 v[124:125], v[124:125], 0 op_sel_hi:[1,0]
	v_pk_add_f32 v[154:155], v[122:123], 0 op_sel_hi:[1,0]
	v_pk_add_f32 v[122:123], v[120:121], 0 op_sel_hi:[1,0]
	v_cvt_pk_bf16_f32 v120, v124, v125
	v_cvt_pk_bf16_f32 v121, v126, v127
	v_pk_add_f32 v[116:117], v[116:117], 0 op_sel_hi:[1,0]
	v_cvt_pk_bf16_f32 v122, v122, v123
	v_cvt_pk_bf16_f32 v123, v154, v155
	global_store_dwordx4 v[144:145], v[120:123], off
	v_pk_add_f32 v[118:119], v[118:119], 0 op_sel_hi:[1,0]
	v_pk_add_f32 v[110:111], v[110:111], 0 op_sel_hi:[1,0]
	v_pk_add_f32 v[120:121], v[114:115], 0 op_sel_hi:[1,0]
	v_pk_add_f32 v[114:115], v[112:113], 0 op_sel_hi:[1,0]
	v_cvt_pk_bf16_f32 v112, v116, v117
	v_cvt_pk_bf16_f32 v113, v118, v119
	v_pk_add_f32 v[108:109], v[108:109], 0 op_sel_hi:[1,0]
	v_cvt_pk_bf16_f32 v114, v114, v115
	v_cvt_pk_bf16_f32 v115, v120, v121
	global_store_dwordx4 v[144:145], v[112:115], off offset:256
	v_pk_add_f32 v[100:101], v[100:101], 0 op_sel_hi:[1,0]
	v_pk_add_f32 v[102:103], v[102:103], 0 op_sel_hi:[1,0]
	v_or_b32_e32 v112, 16, v152
	v_ashrrev_i32_e32 v113, 31, v112
	v_lshlrev_b64 v[112:113], 11, v[112:113]
	v_lshl_add_u64 v[112:113], s[6:7], 0, v[112:113]
	v_lshl_add_u64 v[112:113], v[112:113], 0, v[156:157]
	v_pk_add_f32 v[114:115], v[106:107], 0 op_sel_hi:[1,0]
	v_pk_add_f32 v[106:107], v[104:105], 0 op_sel_hi:[1,0]
	v_cvt_pk_bf16_f32 v104, v108, v109
	v_cvt_pk_bf16_f32 v105, v110, v111
	v_pk_add_f32 v[94:95], v[94:95], 0 op_sel_hi:[1,0]
	v_cvt_pk_bf16_f32 v106, v106, v107
	v_cvt_pk_bf16_f32 v107, v114, v115
	global_store_dwordx4 v[112:113], v[104:107], off
	v_pk_add_f32 v[92:93], v[92:93], 0 op_sel_hi:[1,0]
	v_pk_add_f32 v[84:85], v[84:85], 0 op_sel_hi:[1,0]
	v_pk_add_f32 v[104:105], v[98:99], 0 op_sel_hi:[1,0]
	v_pk_add_f32 v[98:99], v[96:97], 0 op_sel_hi:[1,0]
	v_cvt_pk_bf16_f32 v96, v100, v101
	v_cvt_pk_bf16_f32 v97, v102, v103
	v_pk_add_f32 v[86:87], v[86:87], 0 op_sel_hi:[1,0]
	v_cvt_pk_bf16_f32 v98, v98, v99
	v_cvt_pk_bf16_f32 v99, v104, v105
	global_store_dwordx4 v[112:113], v[96:99], off offset:256
	v_pk_add_f32 v[78:79], v[78:79], 0 op_sel_hi:[1,0]
	v_pk_add_f32 v[76:77], v[76:77], 0 op_sel_hi:[1,0]
	v_or_b32_e32 v96, 32, v152
	v_ashrrev_i32_e32 v97, 31, v96
	v_lshlrev_b64 v[96:97], 11, v[96:97]
	v_lshl_add_u64 v[96:97], s[6:7], 0, v[96:97]
; __device__ __forceinline__ unsigned cvt_pk_bf16(float lo, float hi) { unsigned r; asm volatile("v_cvt_pk_bf16_f32 %0, %1, %2" : "=v"(r) : "v"(lo), "v"(hi)); return r; }
; __device__ __forceinline__ float flogsig16(float x) { return (fminf(x, 0.f) - __logf(1.0f + __expf(-fabsf(x)))) * 0.0625f; }
;     __device__ __forceinline__ void operator()(const f32x4 (&acc)[2][2][4][2], const Unit& u, int wr, int wc, int fr, int fq) const {
;     ...
;             for (int m = 0; m < 4; ++m) { bf16_t* rowp = O + (size_t)(row0 + ai * HALF + m * 16) * ldc + col0;
; #pragma unroll
;                 for (int bj = 0; bj < 2; ++bj) { f32x4 v0 = acc[ai][bj][m][0] + bv[bj][0], v1 = acc[ai][bj][m][1] + bv[bj][1];
;                     if (act == 1) {
; #pragma unroll
;                         for (int j = 0; j < 1; ++j) { v0 = v0 * sigmoid4(v0); v1 = v1 * sigmoid4(v1); } }
;                     else if (act == 2) {
; #pragma unroll
;                         for (int j = 0; j < 1; ++j) { v0 = sigmoid4(v0); v1 = sigmoid4(v1); } }
;                     else if (act == 3) {
; #pragma unroll
;                         for (int j = 0; j < 4; ++j) { v0[j] = flogsig16(v0[j]); v1[j] = flogsig16(v1[j]); } }
;                     u32x4 w; w.x = cvt_pk_bf16(v0[0], v0[1]); w.y = cvt_pk_bf16(v0[2], v0[3]); w.z = cvt_pk_bf16(v1[0], v1[1]); w.w = cvt_pk_bf16(v1[2], v1[3]);
;                     *(u32x4*)(rowp + bj * HALF) = w; } }
; template <class Epi, class Sched>
; __device__ __forceinline__ void gemm_phase(PG8_LAS unsigned char* lds, const Gemm g, const Sched& S, const Epi& E) {
;     ...
;         if (!has_next) break;
; #pragma unroll
;         for (int a = 0; a < 2; ++a)
; #pragma unroll
;             for (int b = 0; b < 2; ++b)
; #pragma unroll
;                 for (int m = 0; m < 4; ++m)
; #pragma unroll
;                     for (int n = 0; n < 2; ++n) acc[a][b][m][n] = (f32x4){0.f, 0.f, 0.f, 0.f};
;         cur = nxt; cA = nA; cB = nB; ++ui;
;     }
	v_lshl_add_u64 v[96:97], v[96:97], 0, v[156:157]
	v_pk_add_f32 v[98:99], v[90:91], 0 op_sel_hi:[1,0]
	v_pk_add_f32 v[90:91], v[88:89], 0 op_sel_hi:[1,0]
	v_cvt_pk_bf16_f32 v88, v92, v93
	v_cvt_pk_bf16_f32 v89, v94, v95
	v_pk_add_f32 v[70:71], v[70:71], 0 op_sel_hi:[1,0]
	v_cvt_pk_bf16_f32 v90, v90, v91
	v_cvt_pk_bf16_f32 v91, v98, v99
	global_store_dwordx4 v[96:97], v[88:91], off
	v_pk_add_f32 v[68:69], v[68:69], 0 op_sel_hi:[1,0]
	v_pk_add_f32 v[60:61], v[60:61], 0 op_sel_hi:[1,0]
	v_pk_add_f32 v[88:89], v[82:83], 0 op_sel_hi:[1,0]
	v_pk_add_f32 v[82:83], v[80:81], 0 op_sel_hi:[1,0]
	v_cvt_pk_bf16_f32 v80, v84, v85
	v_cvt_pk_bf16_f32 v81, v86, v87
	v_pk_add_f32 v[62:63], v[62:63], 0 op_sel_hi:[1,0]
	v_cvt_pk_bf16_f32 v82, v82, v83
	v_cvt_pk_bf16_f32 v83, v88, v89
	global_store_dwordx4 v[96:97], v[80:83], off offset:256
	v_pk_add_f32 v[54:55], v[54:55], 0 op_sel_hi:[1,0]
	v_pk_add_f32 v[52:53], v[52:53], 0 op_sel_hi:[1,0]
	v_or_b32_e32 v80, 48, v152
	v_ashrrev_i32_e32 v81, 31, v80
	v_lshlrev_b64 v[80:81], 11, v[80:81]
	v_lshl_add_u64 v[80:81], s[6:7], 0, v[80:81]
	v_lshl_add_u64 v[80:81], v[80:81], 0, v[156:157]
	v_pk_add_f32 v[82:83], v[74:75], 0 op_sel_hi:[1,0]
	v_pk_add_f32 v[74:75], v[72:73], 0 op_sel_hi:[1,0]
	v_cvt_pk_bf16_f32 v72, v76, v77
	v_cvt_pk_bf16_f32 v73, v78, v79
	v_pk_add_f32 v[48:49], v[48:49], 0 op_sel_hi:[1,0]
	v_cvt_pk_bf16_f32 v74, v74, v75
	v_cvt_pk_bf16_f32 v75, v82, v83
	global_store_dwordx4 v[80:81], v[72:75], off
	v_pk_add_f32 v[38:39], v[38:39], 0 op_sel_hi:[1,0]
	v_pk_add_f32 v[36:37], v[36:37], 0 op_sel_hi:[1,0]
	v_pk_add_f32 v[72:73], v[66:67], 0 op_sel_hi:[1,0]
	v_pk_add_f32 v[66:67], v[64:65], 0 op_sel_hi:[1,0]
	v_cvt_pk_bf16_f32 v64, v68, v69
	v_cvt_pk_bf16_f32 v65, v70, v71
	v_pk_add_f32 v[32:33], v[32:33], 0 op_sel_hi:[1,0]
	v_cvt_pk_bf16_f32 v66, v66, v67
	v_cvt_pk_bf16_f32 v67, v72, v73
	global_store_dwordx4 v[80:81], v[64:67], off offset:256
	v_pk_add_f32 v[22:23], v[22:23], 0 op_sel_hi:[1,0]
	v_pk_add_f32 v[20:21], v[20:21], 0 op_sel_hi:[1,0]
	v_pk_add_f32 v[66:67], v[58:59], 0 op_sel_hi:[1,0]
	v_pk_add_f32 v[58:59], v[56:57], 0 op_sel_hi:[1,0]
	v_cvt_pk_bf16_f32 v56, v60, v61
	v_add_co_u32_e32 v60, vcc, s44, v144
	v_cvt_pk_bf16_f32 v57, v62, v63
	v_cvt_pk_bf16_f32 v58, v58, v59
	v_cvt_pk_bf16_f32 v59, v66, v67
	v_lshl_add_u64 v[64:65], v[144:145], 0, s[10:11]
	s_nop 0
	v_addc_co_u32_e32 v61, vcc, 0, v145, vcc
	global_store_dwordx4 v[60:61], v[56:59], off
	v_pk_add_f32 v[16:17], v[16:17], 0 op_sel_hi:[1,0]
	s_mov_b32 s51, s48
	v_pk_add_f32 v[56:57], v[46:47], 0 op_sel_hi:[1,0]
	v_pk_add_f32 v[46:47], v[44:45], 0 op_sel_hi:[1,0]
	v_cvt_pk_bf16_f32 v44, v52, v53
	v_cvt_pk_bf16_f32 v45, v54, v55
	s_mov_b32 s50, s49
	v_cvt_pk_bf16_f32 v46, v46, v47
	v_cvt_pk_bf16_f32 v47, v56, v57
	global_store_dwordx4 v[64:65], v[44:47], off offset:256
	s_mov_b64 s[20:21], s[4:5]
	s_mov_b64 s[18:19], s[0:1]
	v_pk_add_f32 v[46:47], v[50:51], 0 op_sel_hi:[1,0]
	v_pk_add_f32 v[50:51], v[42:43], 0 op_sel_hi:[1,0]
	v_pk_add_f32 v[42:43], v[40:41], 0 op_sel_hi:[1,0]
	v_cvt_pk_bf16_f32 v40, v48, v49
	v_cvt_pk_bf16_f32 v41, v46, v47
	v_add_co_u32_e32 v46, vcc, s45, v144
	v_cvt_pk_bf16_f32 v42, v42, v43
	v_cvt_pk_bf16_f32 v43, v50, v51
	v_lshl_add_u64 v[44:45], v[144:145], 0, s[12:13]
	s_nop 0
	v_addc_co_u32_e32 v47, vcc, 0, v145, vcc
	global_store_dwordx4 v[46:47], v[40:43], off
	v_pk_add_f32 v[6:7], v[6:7], 0 op_sel_hi:[1,0]
	v_pk_add_f32 v[4:5], v[4:5], 0 op_sel_hi:[1,0]
	v_pk_add_f32 v[40:41], v[30:31], 0 op_sel_hi:[1,0]
	v_pk_add_f32 v[30:31], v[28:29], 0 op_sel_hi:[1,0]
	v_cvt_pk_bf16_f32 v28, v36, v37
	v_cvt_pk_bf16_f32 v29, v38, v39
	s_nop 0
	v_cvt_pk_bf16_f32 v30, v30, v31
	v_cvt_pk_bf16_f32 v31, v40, v41
	global_store_dwordx4 v[44:45], v[28:31], off offset:256
	s_nop 1
	v_pk_add_f32 v[30:31], v[34:35], 0 op_sel_hi:[1,0]
	v_pk_add_f32 v[34:35], v[26:27], 0 op_sel_hi:[1,0]
	v_pk_add_f32 v[26:27], v[24:25], 0 op_sel_hi:[1,0]
	v_cvt_pk_bf16_f32 v24, v32, v33
	v_cvt_pk_bf16_f32 v25, v30, v31
	v_add_co_u32_e32 v30, vcc, s46, v144
	v_cvt_pk_bf16_f32 v26, v26, v27
	v_cvt_pk_bf16_f32 v27, v34, v35
	v_lshl_add_u64 v[28:29], v[144:145], 0, s[14:15]
	s_nop 0
	v_addc_co_u32_e32 v31, vcc, 0, v145, vcc
	global_store_dwordx4 v[30:31], v[24:27], off
	s_nop 1
	v_pk_add_f32 v[24:25], v[14:15], 0 op_sel_hi:[1,0]
	v_pk_add_f32 v[14:15], v[12:13], 0 op_sel_hi:[1,0]
	v_cvt_pk_bf16_f32 v12, v20, v21
	v_cvt_pk_bf16_f32 v13, v22, v23
	s_nop 0
	v_cvt_pk_bf16_f32 v14, v14, v15
	v_cvt_pk_bf16_f32 v15, v24, v25
	global_store_dwordx4 v[28:29], v[12:15], off offset:256
	s_nop 1
	v_pk_add_f32 v[14:15], v[18:19], 0 op_sel_hi:[1,0]
	v_pk_add_f32 v[18:19], v[10:11], 0 op_sel_hi:[1,0]
	v_pk_add_f32 v[10:11], v[8:9], 0 op_sel_hi:[1,0]
	v_cvt_pk_bf16_f32 v8, v16, v17
	v_cvt_pk_bf16_f32 v9, v14, v15
	v_add_co_u32_e32 v14, vcc, s47, v144
	v_lshl_add_u64 v[12:13], v[144:145], 0, s[16:17]
	s_nop 0
	v_addc_co_u32_e32 v15, vcc, 0, v145, vcc
	v_cvt_pk_bf16_f32 v10, v10, v11
	v_cvt_pk_bf16_f32 v11, v18, v19
	global_store_dwordx4 v[14:15], v[8:11], off
	s_and_b64 vcc, exec, s[2:3]
	s_nop 0
	v_pk_add_f32 v[8:9], v[2:3], 0 op_sel_hi:[1,0]
	v_pk_add_f32 v[2:3], v[0:1], 0 op_sel_hi:[1,0]
	v_cvt_pk_bf16_f32 v0, v4, v5
	v_cvt_pk_bf16_f32 v1, v6, v7
	s_nop 0
	v_cvt_pk_bf16_f32 v2, v2, v3
	v_cvt_pk_bf16_f32 v3, v8, v9
	global_store_dwordx4 v[12:13], v[0:3], off offset:256
	s_cbranch_vccz .LBB0_1267
	s_waitcnt vmcnt(0)
	s_cmpk_gt_u32 s27, 0xff
	s_cbranch_scc1 .LBB0_1282
	s_barrier
